# GEMM K-loops: removed the per-MMA-block s_setprio 1/0 flips (on top of double-snake MFMA order)
# speedup vs baseline: 1.0284x; 1.0172x over previous
; #define PG8_STAGE(bufoff, gbase, voff) do { _Pragma("unroll") for (int _i = 0; _i < 2; ++_i) \
;         __builtin_amdgcn_global_load_lds((const unsigned*)((const char*)(gbase) + (voff)[_i]), (LAS unsigned*)(lds + (bufoff) + ldsw + _i * 8192), 16, 0, 0); } while (0)
; #define PG8_LDA(dst, b, h) do { _Pragma("unroll") for (int m = 0; m < 4; ++m) _Pragma("unroll") for (int k = 0; k < 2; ++k) dst[m][k] = *(const LAS bf16x8*)(lds + PG8_SA(b, h) + aoff + m * 2048 + k * 1024); } while (0)
; #define PG8_LDB(dst, b, h) do { _Pragma("unroll") for (int n = 0; n < 2; ++n) _Pragma("unroll") for (int k = 0; k < 2; ++k) dst[n][k] = *(const LAS bf16x8*)(lds + PG8_SB(b, h) + boff + n * 2048 + k * 1024); } while (0)
; #define PG8_MMA(ai, bj, At, Bt) do { __builtin_amdgcn_s_setprio(1); _Pragma("unroll") for (int m = 0; m < 4; ++m) _Pragma("unroll") for (int n = 0; n < 2; ++n) _Pragma("unroll") for (int k = 0; k < 2; ++k) \
;         acc[ai][bj][m][n] = __builtin_amdgcn_mfma_f32_16x16x32_bf16(Bt[n][k], At[m][k], acc[ai][bj][m][n], 0, 0, 0); __builtin_amdgcn_s_setprio(0); } while (0)
; #define PG8_WAIT_L(n) asm volatile("s_waitcnt lgkmcnt(" #n ")" ::: "memory")
; #define PG8_BAR __builtin_amdgcn_s_barrier()
; #define PG8_SCHED __builtin_amdgcn_sched_barrier(0)
; template <class Epi>
; DEVINL void gemm_phase(LAS unsigned char* lds, const Gemm g, const Order& S, const Epi& E) {
;     ...
;             const char* a1 = cA + (size_t)(t + 1) * kstep;
;             const char* a2 = last ? nA : cA + (size_t)(t + 2) * kstep; const char* b2 = last ? nB : cB + (size_t)(t + 2) * kstep;
;             const char* a3 = a2 + kstep; const char* b3 = b2 + kstep;
;             PG8_LDB(B0, 0, 0); PG8_SCHED; PG8_LDA(At, 0, 0); PG8_STAGE(PG8_SA(1, 1), a1 + hstepA, voffA);
;             PG8_WAIT_L(8); PG8_BAR; PG8_WAIT_L(0); PG8_MMA(0, 0, At, B0); PG8_BAR; PG8_SCHED;
;             PG8_LDB(B1, 0, 1); PG8_STAGE(PG8_SB(0, 0), b2, voffB);
;             PG8_BAR; PG8_WAIT_L(0); PG8_MMA(0, 1, At, B1); PG8_BAR;
;             PG8_LDA(At, 0, 1); PG8_STAGE(PG8_SA(0, 0), a2, voffA);
;             PG8_BAR; PG8_WAIT_L(0); PG8_MMA(1, 0, At, B0); PG8_BAR; PG8_SCHED;
.LBB0_340:
	ds_read_b128 v[152:155], v149
	ds_read_b128 v[156:159], v149 offset:1024
	ds_read_b128 v[160:163], v149 offset:2048
	ds_read_b128 v[164:167], v149 offset:3072
	s_add_i32 s93, s10, 2
	s_add_u32 s2, s12, 0xfff80080
	s_addc_u32 s3, s13, -1
	s_cmp_eq_u32 s76, s10
	s_cselect_b32 s10, s85, s86
	s_cselect_b32 s15, s17, s3
	s_cselect_b32 s14, s61, s2
	s_cselect_b32 s11, s84, s87
	v_lshl_add_u64 v[144:145], s[12:13], 0, v[136:137]
	s_add_i32 m0, s67, 0xc000
	ds_read_b128 v[168:171], v150
	ds_read_b128 v[172:175], v150 offset:1024
	ds_read_b128 v[176:179], v150 offset:2048
	ds_read_b128 v[180:183], v150 offset:3072
	ds_read_b128 v[184:187], v150 offset:4096
	ds_read_b128 v[188:191], v150 offset:5120
	ds_read_b128 v[192:195], v150 offset:6144
	ds_read_b128 v[196:199], v150 offset:7168
	global_load_lds_dwordx4 v[144:145], off
	v_lshl_add_u64 v[144:145], s[12:13], 0, v[138:139]
	s_add_i32 m0, s67, 0xe000
	s_nop 0
	global_load_lds_dwordx4 v[144:145], off
	s_waitcnt lgkmcnt(8)
	s_barrier
	s_waitcnt lgkmcnt(0)
	s_waitcnt lgkmcnt(0)
	v_mfma_f32_16x16x32_bf16 v[124:127], v[152:155], v[168:171], v[124:127]
	v_mfma_f32_16x16x32_bf16 v[124:127], v[156:159], v[172:175], v[124:127]
	v_mfma_f32_16x16x32_bf16 v[116:119], v[164:167], v[172:175], v[116:119]
	v_mfma_f32_16x16x32_bf16 v[116:119], v[160:163], v[168:171], v[116:119]
	v_mfma_f32_16x16x32_bf16 v[100:103], v[160:163], v[176:179], v[100:103]
	v_mfma_f32_16x16x32_bf16 v[100:103], v[164:167], v[180:183], v[100:103]
	v_mfma_f32_16x16x32_bf16 v[108:111], v[156:159], v[180:183], v[108:111]
	v_mfma_f32_16x16x32_bf16 v[108:111], v[152:155], v[176:179], v[108:111]
	v_mfma_f32_16x16x32_bf16 v[92:95], v[152:155], v[184:187], v[92:95]
	v_mfma_f32_16x16x32_bf16 v[92:95], v[156:159], v[188:191], v[92:95]
	v_mfma_f32_16x16x32_bf16 v[84:87], v[164:167], v[188:191], v[84:87]
	v_mfma_f32_16x16x32_bf16 v[84:87], v[160:163], v[184:187], v[84:87]
	v_mfma_f32_16x16x32_bf16 v[68:71], v[160:163], v[192:195], v[68:71]
	v_mfma_f32_16x16x32_bf16 v[68:71], v[164:167], v[196:199], v[68:71]
	v_mfma_f32_16x16x32_bf16 v[76:79], v[156:159], v[196:199], v[76:79]
	v_mfma_f32_16x16x32_bf16 v[76:79], v[152:155], v[192:195], v[76:79]
	s_barrier
	s_add_i32 s2, s80, s38
	v_lshl_add_u64 v[144:145], s[10:11], 0, v[132:133]
	s_mov_b32 m0, s2
	ds_read_b128 v[200:203], v151
	ds_read_b128 v[204:207], v151 offset:1024
	ds_read_b128 v[208:211], v151 offset:2048
	ds_read_b128 v[218:221], v151 offset:3072
	global_load_lds_dwordx4 v[144:145], off
	v_lshl_add_u64 v[212:213], s[10:11], 0, v[128:129]
	s_add_i32 m0, s2, 0x2000
	s_nop 0
	global_load_lds_dwordx4 v[212:213], off
	s_barrier
	s_waitcnt lgkmcnt(0)
	s_waitcnt lgkmcnt(0)
	v_mfma_f32_16x16x32_bf16 v[120:123], v[200:203], v[168:171], v[120:123]
	v_mfma_f32_16x16x32_bf16 v[120:123], v[204:207], v[172:175], v[120:123]
	v_mfma_f32_16x16x32_bf16 v[112:115], v[218:221], v[172:175], v[112:115]
	v_mfma_f32_16x16x32_bf16 v[112:115], v[208:211], v[168:171], v[112:115]
	v_mfma_f32_16x16x32_bf16 v[96:99], v[208:211], v[176:179], v[96:99]
	v_mfma_f32_16x16x32_bf16 v[96:99], v[218:221], v[180:183], v[96:99]
	v_mfma_f32_16x16x32_bf16 v[104:107], v[204:207], v[180:183], v[104:107]
	v_mfma_f32_16x16x32_bf16 v[104:107], v[200:203], v[176:179], v[104:107]
	v_mfma_f32_16x16x32_bf16 v[88:91], v[200:203], v[184:187], v[88:91]
	v_mfma_f32_16x16x32_bf16 v[88:91], v[204:207], v[188:191], v[88:91]
	v_mfma_f32_16x16x32_bf16 v[80:83], v[218:221], v[188:191], v[80:83]
	v_mfma_f32_16x16x32_bf16 v[80:83], v[208:211], v[184:187], v[80:83]
	v_mfma_f32_16x16x32_bf16 v[64:67], v[208:211], v[192:195], v[64:67]
	v_mfma_f32_16x16x32_bf16 v[64:67], v[218:221], v[196:199], v[64:67]
	v_mfma_f32_16x16x32_bf16 v[72:75], v[204:207], v[196:199], v[72:75]
	v_mfma_f32_16x16x32_bf16 v[72:75], v[200:203], v[192:195], v[72:75]
	s_mov_b32 m0, s67
	v_lshl_add_u64 v[222:223], s[14:15], 0, v[134:135]
	s_barrier
	ds_read_b128 v[168:171], v150 offset:16384
	ds_read_b128 v[172:175], v150 offset:17408
	ds_read_b128 v[176:179], v150 offset:18432
	ds_read_b128 v[180:183], v150 offset:19456
	ds_read_b128 v[184:187], v150 offset:20480
	ds_read_b128 v[188:191], v150 offset:21504
	ds_read_b128 v[192:195], v150 offset:22528
	ds_read_b128 v[196:199], v150 offset:23552
	global_load_lds_dwordx4 v[222:223], off
	v_lshl_add_u64 v[224:225], s[14:15], 0, v[130:131]
	s_mov_b32 m0, s68
	s_nop 0
	global_load_lds_dwordx4 v[224:225], off
	s_barrier
	s_waitcnt lgkmcnt(0)
	s_waitcnt lgkmcnt(0)
	v_mfma_f32_16x16x32_bf16 v[60:63], v[152:155], v[168:171], v[60:63]
	v_mfma_f32_16x16x32_bf16 v[60:63], v[156:159], v[172:175], v[60:63]
	v_mfma_f32_16x16x32_bf16 v[52:55], v[164:167], v[172:175], v[52:55]
	v_mfma_f32_16x16x32_bf16 v[52:55], v[160:163], v[168:171], v[52:55]
	v_mfma_f32_16x16x32_bf16 v[36:39], v[160:163], v[176:179], v[36:39]
	v_mfma_f32_16x16x32_bf16 v[36:39], v[164:167], v[180:183], v[36:39]
	v_mfma_f32_16x16x32_bf16 v[44:47], v[156:159], v[180:183], v[44:47]
	v_mfma_f32_16x16x32_bf16 v[44:47], v[152:155], v[176:179], v[44:47]
	v_mfma_f32_16x16x32_bf16 v[28:31], v[152:155], v[184:187], v[28:31]
	v_mfma_f32_16x16x32_bf16 v[28:31], v[156:159], v[188:191], v[28:31]
	v_mfma_f32_16x16x32_bf16 v[20:23], v[164:167], v[188:191], v[20:23]
	v_mfma_f32_16x16x32_bf16 v[20:23], v[160:163], v[184:187], v[20:23]
	v_mfma_f32_16x16x32_bf16 v[4:7], v[160:163], v[192:195], v[4:7]
	v_mfma_f32_16x16x32_bf16 v[4:7], v[164:167], v[196:199], v[4:7]
	v_mfma_f32_16x16x32_bf16 v[12:15], v[156:159], v[196:199], v[12:15]
	v_mfma_f32_16x16x32_bf16 v[12:15], v[152:155], v[192:195], v[12:15]
	s_barrier
; #define PG8_STAGE(bufoff, gbase, voff) do { _Pragma("unroll") for (int _i = 0; _i < 2; ++_i) \
;         __builtin_amdgcn_global_load_lds((const unsigned*)((const char*)(gbase) + (voff)[_i]), (LAS unsigned*)(lds + (bufoff) + ldsw + _i * 8192), 16, 0, 0); } while (0)
; #define PG8_LDA(dst, b, h) do { _Pragma("unroll") for (int m = 0; m < 4; ++m) _Pragma("unroll") for (int k = 0; k < 2; ++k) dst[m][k] = *(const LAS bf16x8*)(lds + PG8_SA(b, h) + aoff + m * 2048 + k * 1024); } while (0)
; #define PG8_LDB(dst, b, h) do { _Pragma("unroll") for (int n = 0; n < 2; ++n) _Pragma("unroll") for (int k = 0; k < 2; ++k) dst[n][k] = *(const LAS bf16x8*)(lds + PG8_SB(b, h) + boff + n * 2048 + k * 1024); } while (0)
; #define PG8_MMA(ai, bj, At, Bt) do { __builtin_amdgcn_s_setprio(1); _Pragma("unroll") for (int m = 0; m < 4; ++m) _Pragma("unroll") for (int n = 0; n < 2; ++n) _Pragma("unroll") for (int k = 0; k < 2; ++k) \
;         acc[ai][bj][m][n] = __builtin_amdgcn_mfma_f32_16x16x32_bf16(Bt[n][k], At[m][k], acc[ai][bj][m][n], 0, 0, 0); __builtin_amdgcn_s_setprio(0); } while (0)
; #define PG8_WAIT_V(n) asm volatile("s_waitcnt vmcnt(" #n ")" ::: "memory")
; #define PG8_WAIT_L(n) asm volatile("s_waitcnt lgkmcnt(" #n ")" ::: "memory")
; #define PG8_BAR __builtin_amdgcn_s_barrier()
; #define PG8_SCHED __builtin_amdgcn_sched_barrier(0)
; template <class Epi>
; DEVINL void gemm_phase(LAS unsigned char* lds, const Gemm g, const Order& S, const Epi& E) {
;     ...
;             PG8_STAGE(PG8_SB(0, 1), b2 + hstepB, voffB);
;             PG8_WAIT_V(6); PG8_BAR; PG8_MMA(1, 1, At, B1); PG8_BAR;
;             PG8_LDB(B0, 1, 0); PG8_SCHED; PG8_LDA(At, 1, 0); PG8_STAGE(PG8_SA(0, 1), a2 + hstepA, voffA);
;             PG8_WAIT_L(8); PG8_BAR; PG8_WAIT_L(0); PG8_MMA(0, 0, At, B0); PG8_BAR; PG8_SCHED;
;             PG8_LDB(B1, 1, 1); PG8_STAGE(PG8_SB(1, 0), b3, voffB);
	s_add_u32 s96, s10, 0x80000
	s_addc_u32 s97, s11, 0
	s_add_i32 s2, s81, s38
	v_lshl_add_u64 v[152:153], s[96:97], 0, v[132:133]
	s_mov_b32 m0, s2
	s_nop 0
	global_load_lds_dwordx4 v[152:153], off
	v_lshl_add_u64 v[152:153], s[96:97], 0, v[128:129]
	s_add_i32 m0, s2, 0x2000
	s_nop 0
	global_load_lds_dwordx4 v[152:153], off
	s_waitcnt vmcnt(6)
	s_barrier
	v_mfma_f32_16x16x32_bf16 v[56:59], v[200:203], v[168:171], v[56:59]
	v_mfma_f32_16x16x32_bf16 v[56:59], v[204:207], v[172:175], v[56:59]
	v_mfma_f32_16x16x32_bf16 v[48:51], v[218:221], v[172:175], v[48:51]
	v_mfma_f32_16x16x32_bf16 v[48:51], v[208:211], v[168:171], v[48:51]
	v_mfma_f32_16x16x32_bf16 v[32:35], v[208:211], v[176:179], v[32:35]
	v_mfma_f32_16x16x32_bf16 v[32:35], v[218:221], v[180:183], v[32:35]
	v_mfma_f32_16x16x32_bf16 v[40:43], v[204:207], v[180:183], v[40:43]
	v_mfma_f32_16x16x32_bf16 v[40:43], v[200:203], v[176:179], v[40:43]
	v_mfma_f32_16x16x32_bf16 v[24:27], v[200:203], v[184:187], v[24:27]
	v_mfma_f32_16x16x32_bf16 v[24:27], v[204:207], v[188:191], v[24:27]
	v_mfma_f32_16x16x32_bf16 v[16:19], v[218:221], v[188:191], v[16:19]
	v_mfma_f32_16x16x32_bf16 v[16:19], v[208:211], v[184:187], v[16:19]
	v_mfma_f32_16x16x32_bf16 v[0:3], v[208:211], v[192:195], v[0:3]
	v_mfma_f32_16x16x32_bf16 v[0:3], v[218:221], v[196:199], v[0:3]
	v_mfma_f32_16x16x32_bf16 v[8:11], v[204:207], v[196:199], v[8:11]
	v_mfma_f32_16x16x32_bf16 v[8:11], v[200:203], v[192:195], v[8:11]
	s_add_i32 s2, 16, 0x18000
	v_add_u32_e32 v164, s2, v147
	s_barrier
	ds_read_b128 v[152:155], v164
	ds_read_b128 v[156:159], v164 offset:1024
	ds_read_b128 v[160:163], v164 offset:2048
	ds_read_b128 v[164:167], v164 offset:3072
	s_add_u32 s14, s14, 0x80000
	s_addc_u32 s15, s15, 0
	s_mov_b32 m0, s69
	v_lshl_add_u64 v[200:201], s[14:15], 0, v[134:135]
	ds_read_b128 v[168:171], v150 offset:32768
	ds_read_b128 v[172:175], v150 offset:33792
	ds_read_b128 v[176:179], v150 offset:34816
	ds_read_b128 v[180:183], v150 offset:35840
	ds_read_b128 v[184:187], v150 offset:36864
	ds_read_b128 v[188:191], v150 offset:37888
	ds_read_b128 v[192:195], v150 offset:38912
	ds_read_b128 v[196:199], v150 offset:39936
	global_load_lds_dwordx4 v[200:201], off
	v_lshl_add_u64 v[200:201], s[14:15], 0, v[130:131]
	s_mov_b32 m0, s72
	s_nop 0
	global_load_lds_dwordx4 v[200:201], off
	s_waitcnt lgkmcnt(8)
	s_barrier
	s_waitcnt lgkmcnt(0)
	s_waitcnt lgkmcnt(0)
	v_mfma_f32_16x16x32_bf16 v[124:127], v[152:155], v[168:171], v[124:127]
	v_mfma_f32_16x16x32_bf16 v[124:127], v[156:159], v[172:175], v[124:127]
	v_mfma_f32_16x16x32_bf16 v[116:119], v[164:167], v[172:175], v[116:119]
	v_mfma_f32_16x16x32_bf16 v[116:119], v[160:163], v[168:171], v[116:119]
	v_mfma_f32_16x16x32_bf16 v[100:103], v[160:163], v[176:179], v[100:103]
	v_mfma_f32_16x16x32_bf16 v[100:103], v[164:167], v[180:183], v[100:103]
	v_mfma_f32_16x16x32_bf16 v[108:111], v[156:159], v[180:183], v[108:111]
	v_mfma_f32_16x16x32_bf16 v[108:111], v[152:155], v[176:179], v[108:111]
	v_mfma_f32_16x16x32_bf16 v[92:95], v[152:155], v[184:187], v[92:95]
	v_mfma_f32_16x16x32_bf16 v[92:95], v[156:159], v[188:191], v[92:95]
	v_mfma_f32_16x16x32_bf16 v[84:87], v[164:167], v[188:191], v[84:87]
	v_mfma_f32_16x16x32_bf16 v[84:87], v[160:163], v[184:187], v[84:87]
	v_mfma_f32_16x16x32_bf16 v[68:71], v[160:163], v[192:195], v[68:71]
	v_mfma_f32_16x16x32_bf16 v[68:71], v[164:167], v[196:199], v[68:71]
	v_mfma_f32_16x16x32_bf16 v[76:79], v[156:159], v[196:199], v[76:79]
	v_mfma_f32_16x16x32_bf16 v[76:79], v[152:155], v[192:195], v[76:79]
	s_barrier
	s_add_i32 s3, 16, 0x1c000
	s_add_i32 s2, s2, s38
	v_add_u32_e32 v214, s3, v147
	v_lshl_add_u64 v[144:145], v[144:145], 0, s[6:7]
	s_mov_b32 m0, s2
	ds_read_b128 v[200:203], v214
	ds_read_b128 v[204:207], v214 offset:1024
	ds_read_b128 v[208:211], v214 offset:2048
	ds_read_b128 v[218:221], v214 offset:3072
	global_load_lds_dwordx4 v[144:145], off
	v_lshl_add_u64 v[144:145], v[212:213], 0, s[6:7]
	s_add_i32 m0, s2, 0x2000
	s_nop 0
	global_load_lds_dwordx4 v[144:145], off
	s_barrier
; #define PG8_STAGE(bufoff, gbase, voff) do { _Pragma("unroll") for (int _i = 0; _i < 2; ++_i) \
;         __builtin_amdgcn_global_load_lds((const unsigned*)((const char*)(gbase) + (voff)[_i]), (LAS unsigned*)(lds + (bufoff) + ldsw + _i * 8192), 16, 0, 0); } while (0)
; #define PG8_LDA(dst, b, h) do { _Pragma("unroll") for (int m = 0; m < 4; ++m) _Pragma("unroll") for (int k = 0; k < 2; ++k) dst[m][k] = *(const LAS bf16x8*)(lds + PG8_SA(b, h) + aoff + m * 2048 + k * 1024); } while (0)
; #define PG8_LDB(dst, b, h) do { _Pragma("unroll") for (int n = 0; n < 2; ++n) _Pragma("unroll") for (int k = 0; k < 2; ++k) dst[n][k] = *(const LAS bf16x8*)(lds + PG8_SB(b, h) + boff + n * 2048 + k * 1024); } while (0)
; #define PG8_MMA(ai, bj, At, Bt) do { __builtin_amdgcn_s_setprio(1); _Pragma("unroll") for (int m = 0; m < 4; ++m) _Pragma("unroll") for (int n = 0; n < 2; ++n) _Pragma("unroll") for (int k = 0; k < 2; ++k) \
;         acc[ai][bj][m][n] = __builtin_amdgcn_mfma_f32_16x16x32_bf16(Bt[n][k], At[m][k], acc[ai][bj][m][n], 0, 0, 0); __builtin_amdgcn_s_setprio(0); } while (0)
; #define PG8_WAIT_V(n) asm volatile("s_waitcnt vmcnt(" #n ")" ::: "memory")
; #define PG8_WAIT_L(n) asm volatile("s_waitcnt lgkmcnt(" #n ")" ::: "memory")
; #define PG8_BAR __builtin_amdgcn_s_barrier()
; #define PG8_SCHED __builtin_amdgcn_sched_barrier(0)
; template <class Epi>
; DEVINL void gemm_phase(LAS unsigned char* lds, const Gemm g, const Order& S, const Epi& E) {
;     ...
;         for (int t = 0; t < nt; t += 2) {
;     ...
;             PG8_LDB(B1, 1, 1); PG8_STAGE(PG8_SB(1, 0), b3, voffB);
;             PG8_BAR; PG8_WAIT_L(0); PG8_MMA(0, 1, At, B1); PG8_BAR;
;             PG8_LDA(At, 1, 1); PG8_STAGE(PG8_SA(1, 0), a3, voffA);
;             PG8_BAR; PG8_WAIT_L(0); PG8_MMA(1, 0, At, B0); PG8_BAR; PG8_SCHED;
;             PG8_STAGE(PG8_SB(1, 1), b3 + hstepB, voffB);
;             PG8_WAIT_V(6); PG8_BAR; PG8_MMA(1, 1, At, B1); PG8_BAR;
	s_waitcnt lgkmcnt(0)
	s_waitcnt lgkmcnt(0)
	v_mfma_f32_16x16x32_bf16 v[120:123], v[200:203], v[168:171], v[120:123]
	v_mfma_f32_16x16x32_bf16 v[120:123], v[204:207], v[172:175], v[120:123]
	v_mfma_f32_16x16x32_bf16 v[112:115], v[218:221], v[172:175], v[112:115]
	v_mfma_f32_16x16x32_bf16 v[112:115], v[208:211], v[168:171], v[112:115]
	v_mfma_f32_16x16x32_bf16 v[96:99], v[208:211], v[176:179], v[96:99]
	v_mfma_f32_16x16x32_bf16 v[96:99], v[218:221], v[180:183], v[96:99]
	v_mfma_f32_16x16x32_bf16 v[104:107], v[204:207], v[180:183], v[104:107]
	v_mfma_f32_16x16x32_bf16 v[104:107], v[200:203], v[176:179], v[104:107]
	v_mfma_f32_16x16x32_bf16 v[88:91], v[200:203], v[184:187], v[88:91]
	v_mfma_f32_16x16x32_bf16 v[88:91], v[204:207], v[188:191], v[88:91]
	v_mfma_f32_16x16x32_bf16 v[80:83], v[218:221], v[188:191], v[80:83]
	v_mfma_f32_16x16x32_bf16 v[80:83], v[208:211], v[184:187], v[80:83]
	v_mfma_f32_16x16x32_bf16 v[64:67], v[208:211], v[192:195], v[64:67]
	v_mfma_f32_16x16x32_bf16 v[64:67], v[218:221], v[196:199], v[64:67]
	v_mfma_f32_16x16x32_bf16 v[72:75], v[204:207], v[196:199], v[72:75]
	v_mfma_f32_16x16x32_bf16 v[72:75], v[200:203], v[192:195], v[72:75]
	s_mov_b32 m0, s74
	v_lshl_add_u64 v[144:145], v[222:223], 0, s[6:7]
	s_barrier
	ds_read_b128 v[168:171], v150 offset:49152
	ds_read_b128 v[172:175], v150 offset:50176
	ds_read_b128 v[176:179], v150 offset:51200
	ds_read_b128 v[180:183], v150 offset:52224
	ds_read_b128 v[184:187], v150 offset:53248
	ds_read_b128 v[188:191], v150 offset:54272
	ds_read_b128 v[192:195], v150 offset:55296
	ds_read_b128 v[196:199], v150 offset:56320
	global_load_lds_dwordx4 v[144:145], off
	v_lshl_add_u64 v[144:145], v[224:225], 0, s[6:7]
	s_mov_b32 m0, s75
	s_nop 0
	global_load_lds_dwordx4 v[144:145], off
	s_barrier
	s_waitcnt lgkmcnt(0)
	s_waitcnt lgkmcnt(0)
	v_mfma_f32_16x16x32_bf16 v[60:63], v[152:155], v[168:171], v[60:63]
	v_mfma_f32_16x16x32_bf16 v[60:63], v[156:159], v[172:175], v[60:63]
	v_mfma_f32_16x16x32_bf16 v[52:55], v[164:167], v[172:175], v[52:55]
	v_mfma_f32_16x16x32_bf16 v[52:55], v[160:163], v[168:171], v[52:55]
	v_mfma_f32_16x16x32_bf16 v[36:39], v[160:163], v[176:179], v[36:39]
	v_mfma_f32_16x16x32_bf16 v[36:39], v[164:167], v[180:183], v[36:39]
	v_mfma_f32_16x16x32_bf16 v[44:47], v[156:159], v[180:183], v[44:47]
	v_mfma_f32_16x16x32_bf16 v[44:47], v[152:155], v[176:179], v[44:47]
	v_mfma_f32_16x16x32_bf16 v[28:31], v[152:155], v[184:187], v[28:31]
	v_mfma_f32_16x16x32_bf16 v[28:31], v[156:159], v[188:191], v[28:31]
	v_mfma_f32_16x16x32_bf16 v[20:23], v[164:167], v[188:191], v[20:23]
	v_mfma_f32_16x16x32_bf16 v[20:23], v[160:163], v[184:187], v[20:23]
	v_mfma_f32_16x16x32_bf16 v[4:7], v[160:163], v[192:195], v[4:7]
	v_mfma_f32_16x16x32_bf16 v[4:7], v[164:167], v[196:199], v[4:7]
	v_mfma_f32_16x16x32_bf16 v[12:15], v[156:159], v[196:199], v[12:15]
	v_mfma_f32_16x16x32_bf16 v[12:15], v[152:155], v[192:195], v[12:15]
	s_barrier
	s_add_u32 s10, s10, 0x80080
	s_addc_u32 s11, s11, 0
	s_add_i32 s2, s3, s38
	v_lshl_add_u64 v[144:145], s[10:11], 0, v[132:133]
	s_mov_b32 m0, s2
	s_nop 0
	global_load_lds_dwordx4 v[144:145], off
	v_lshl_add_u64 v[144:145], s[10:11], 0, v[128:129]
	s_add_i32 m0, s2, 0x2000
	s_nop 0
	global_load_lds_dwordx4 v[144:145], off
	s_waitcnt vmcnt(6)
	s_barrier
	v_mfma_f32_16x16x32_bf16 v[56:59], v[200:203], v[168:171], v[56:59]
	v_mfma_f32_16x16x32_bf16 v[56:59], v[204:207], v[172:175], v[56:59]
	v_mfma_f32_16x16x32_bf16 v[48:51], v[218:221], v[172:175], v[48:51]
	v_mfma_f32_16x16x32_bf16 v[48:51], v[208:211], v[168:171], v[48:51]
	v_mfma_f32_16x16x32_bf16 v[32:35], v[208:211], v[176:179], v[32:35]
	v_mfma_f32_16x16x32_bf16 v[32:35], v[218:221], v[180:183], v[32:35]
	v_mfma_f32_16x16x32_bf16 v[40:43], v[204:207], v[180:183], v[40:43]
	v_mfma_f32_16x16x32_bf16 v[40:43], v[200:203], v[176:179], v[40:43]
	v_mfma_f32_16x16x32_bf16 v[24:27], v[200:203], v[184:187], v[24:27]
	v_mfma_f32_16x16x32_bf16 v[24:27], v[204:207], v[188:191], v[24:27]
	v_mfma_f32_16x16x32_bf16 v[16:19], v[218:221], v[188:191], v[16:19]
	v_mfma_f32_16x16x32_bf16 v[16:19], v[208:211], v[184:187], v[16:19]
	v_mfma_f32_16x16x32_bf16 v[0:3], v[208:211], v[192:195], v[0:3]
	v_mfma_f32_16x16x32_bf16 v[0:3], v[218:221], v[196:199], v[0:3]
	v_mfma_f32_16x16x32_bf16 v[8:11], v[204:207], v[196:199], v[8:11]
	v_mfma_f32_16x16x32_bf16 v[8:11], v[200:203], v[192:195], v[8:11]
	s_add_u32 s12, s12, 0x100
	s_addc_u32 s13, s13, 0
	s_add_u32 s86, s86, 0x100
	s_addc_u32 s87, s87, 0
	s_cmp_ge_i32 s93, s73
	s_mov_b32 s10, s93
	s_barrier
	s_cbranch_scc0 .LBB0_340
	s_branch .LBB0_335

; #define PG8_STAGE(bufoff, gbase, voff) do { _Pragma("unroll") for (int _i = 0; _i < 2; ++_i) \
;         __builtin_amdgcn_global_load_lds((const unsigned*)((const char*)(gbase) + (voff)[_i]), (LAS unsigned*)(lds + (bufoff) + ldsw + _i * 8192), 16, 0, 0); } while (0)
; #define PG8_LDA(dst, b, h) do { _Pragma("unroll") for (int m = 0; m < 4; ++m) _Pragma("unroll") for (int k = 0; k < 2; ++k) dst[m][k] = *(const LAS bf16x8*)(lds + PG8_SA(b, h) + aoff + m * 2048 + k * 1024); } while (0)
; #define PG8_LDB(dst, b, h) do { _Pragma("unroll") for (int n = 0; n < 2; ++n) _Pragma("unroll") for (int k = 0; k < 2; ++k) dst[n][k] = *(const LAS bf16x8*)(lds + PG8_SB(b, h) + boff + n * 2048 + k * 1024); } while (0)
; #define PG8_MMA(ai, bj, At, Bt) do { __builtin_amdgcn_s_setprio(1); _Pragma("unroll") for (int m = 0; m < 4; ++m) _Pragma("unroll") for (int n = 0; n < 2; ++n) _Pragma("unroll") for (int k = 0; k < 2; ++k) \
;         acc[ai][bj][m][n] = __builtin_amdgcn_mfma_f32_16x16x32_bf16(Bt[n][k], At[m][k], acc[ai][bj][m][n], 0, 0, 0); __builtin_amdgcn_s_setprio(0); } while (0)
; #define PG8_WAIT_L(n) asm volatile("s_waitcnt lgkmcnt(" #n ")" ::: "memory")
; #define PG8_BAR __builtin_amdgcn_s_barrier()
; #define PG8_SCHED __builtin_amdgcn_sched_barrier(0)
; template <class Epi>
; DEVINL void gemm_phase(LAS unsigned char* lds, const Gemm g, const Order& S, const Epi& E) {
;     ...
;             const char* a1 = cA + (size_t)(t + 1) * kstep;
;             const char* a2 = last ? nA : cA + (size_t)(t + 2) * kstep; const char* b2 = last ? nB : cB + (size_t)(t + 2) * kstep;
;             const char* a3 = a2 + kstep; const char* b3 = b2 + kstep;
;             PG8_LDB(B0, 0, 0); PG8_SCHED; PG8_LDA(At, 0, 0); PG8_STAGE(PG8_SA(1, 1), a1 + hstepA, voffA);
;             PG8_WAIT_L(8); PG8_BAR; PG8_WAIT_L(0); PG8_MMA(0, 0, At, B0); PG8_BAR; PG8_SCHED;
;             PG8_LDB(B1, 0, 1); PG8_STAGE(PG8_SB(0, 0), b2, voffB);
;             PG8_BAR; PG8_WAIT_L(0); PG8_MMA(0, 1, At, B1); PG8_BAR;
;             PG8_LDA(At, 0, 1); PG8_STAGE(PG8_SA(0, 0), a2, voffA);
;             PG8_BAR; PG8_WAIT_L(0); PG8_MMA(1, 0, At, B0); PG8_BAR; PG8_SCHED;
.LBB0_361:
	ds_read_b128 v[146:149], v143
	ds_read_b128 v[150:153], v143 offset:1024
	ds_read_b128 v[154:157], v143 offset:2048
	ds_read_b128 v[158:161], v143 offset:3072
	s_add_i32 s87, s10, 2
	s_add_u32 s2, s12, 0xfff80080
	s_addc_u32 s3, s13, -1
	s_cmp_eq_u32 s36, s10
	s_cselect_b32 s10, s84, s85
	s_cselect_b32 s15, s63, s3
	s_cselect_b32 s14, s65, s2
	s_cselect_b32 s11, s83, s86
	v_lshl_add_u64 v[194:195], s[12:13], 0, v[136:137]
	s_add_i32 m0, s5, 0xc000
	ds_read_b128 v[162:165], v144
	ds_read_b128 v[166:169], v144 offset:1024
	ds_read_b128 v[170:173], v144 offset:2048
	ds_read_b128 v[174:177], v144 offset:3072
	ds_read_b128 v[178:181], v144 offset:4096
	ds_read_b128 v[182:185], v144 offset:5120
	ds_read_b128 v[186:189], v144 offset:6144
	ds_read_b128 v[190:193], v144 offset:7168
	global_load_lds_dwordx4 v[194:195], off
	v_lshl_add_u64 v[194:195], s[12:13], 0, v[138:139]
	s_add_i32 m0, s5, 0xe000
	s_nop 0
	global_load_lds_dwordx4 v[194:195], off
	s_waitcnt lgkmcnt(8)
	s_barrier
	s_waitcnt lgkmcnt(0)
	s_waitcnt lgkmcnt(0)
	v_mfma_f32_16x16x32_bf16 v[120:123], v[146:149], v[162:165], v[120:123]
	v_mfma_f32_16x16x32_bf16 v[120:123], v[150:153], v[166:169], v[120:123]
	v_mfma_f32_16x16x32_bf16 v[124:127], v[158:161], v[166:169], v[124:127]
	v_mfma_f32_16x16x32_bf16 v[124:127], v[154:157], v[162:165], v[124:127]
	v_mfma_f32_16x16x32_bf16 v[104:107], v[154:157], v[170:173], v[104:107]
	v_mfma_f32_16x16x32_bf16 v[104:107], v[158:161], v[174:177], v[104:107]
	v_mfma_f32_16x16x32_bf16 v[108:111], v[150:153], v[174:177], v[108:111]
	v_mfma_f32_16x16x32_bf16 v[108:111], v[146:149], v[170:173], v[108:111]
	v_mfma_f32_16x16x32_bf16 v[92:95], v[146:149], v[178:181], v[92:95]
	v_mfma_f32_16x16x32_bf16 v[92:95], v[150:153], v[182:185], v[92:95]
	v_mfma_f32_16x16x32_bf16 v[88:91], v[158:161], v[182:185], v[88:91]
	v_mfma_f32_16x16x32_bf16 v[88:91], v[154:157], v[178:181], v[88:91]
	v_mfma_f32_16x16x32_bf16 v[72:75], v[154:157], v[186:189], v[72:75]
	v_mfma_f32_16x16x32_bf16 v[72:75], v[158:161], v[190:193], v[72:75]
	v_mfma_f32_16x16x32_bf16 v[76:79], v[150:153], v[190:193], v[76:79]
	v_mfma_f32_16x16x32_bf16 v[76:79], v[146:149], v[186:189], v[76:79]
	s_barrier
	s_add_i32 s2, s80, s68
	v_lshl_add_u64 v[210:211], s[10:11], 0, v[130:131]
	s_mov_b32 m0, s2
	ds_read_b128 v[194:197], v145
	ds_read_b128 v[198:201], v145 offset:1024
	ds_read_b128 v[202:205], v145 offset:2048
	ds_read_b128 v[206:209], v145 offset:3072
	global_load_lds_dwordx4 v[210:211], off
	v_lshl_add_u64 v[212:213], s[10:11], 0, v[134:135]
	s_add_i32 m0, s2, 0x2000
	s_nop 0
	global_load_lds_dwordx4 v[212:213], off
	s_barrier
	s_waitcnt lgkmcnt(0)
	s_waitcnt lgkmcnt(0)
	v_mfma_f32_16x16x32_bf16 v[116:119], v[194:197], v[162:165], v[116:119]
	v_mfma_f32_16x16x32_bf16 v[116:119], v[198:201], v[166:169], v[116:119]
	v_mfma_f32_16x16x32_bf16 v[112:115], v[206:209], v[166:169], v[112:115]
	v_mfma_f32_16x16x32_bf16 v[112:115], v[202:205], v[162:165], v[112:115]
	v_mfma_f32_16x16x32_bf16 v[96:99], v[202:205], v[170:173], v[96:99]
	v_mfma_f32_16x16x32_bf16 v[96:99], v[206:209], v[174:177], v[96:99]
	v_mfma_f32_16x16x32_bf16 v[100:103], v[198:201], v[174:177], v[100:103]
	v_mfma_f32_16x16x32_bf16 v[100:103], v[194:197], v[170:173], v[100:103]
	v_mfma_f32_16x16x32_bf16 v[84:87], v[194:197], v[178:181], v[84:87]
	v_mfma_f32_16x16x32_bf16 v[84:87], v[198:201], v[182:185], v[84:87]
	v_mfma_f32_16x16x32_bf16 v[80:83], v[206:209], v[182:185], v[80:83]
	v_mfma_f32_16x16x32_bf16 v[80:83], v[202:205], v[178:181], v[80:83]
	v_mfma_f32_16x16x32_bf16 v[64:67], v[202:205], v[186:189], v[64:67]
	v_mfma_f32_16x16x32_bf16 v[64:67], v[206:209], v[190:193], v[64:67]
	v_mfma_f32_16x16x32_bf16 v[68:71], v[198:201], v[190:193], v[68:71]
	v_mfma_f32_16x16x32_bf16 v[68:71], v[194:197], v[186:189], v[68:71]
	s_mov_b32 m0, s5
	v_lshl_add_u64 v[218:219], s[14:15], 0, v[128:129]
	s_barrier
	ds_read_b128 v[162:165], v144 offset:16384
	ds_read_b128 v[166:169], v144 offset:17408
	ds_read_b128 v[170:173], v144 offset:18432
	ds_read_b128 v[174:177], v144 offset:19456
	ds_read_b128 v[178:181], v144 offset:20480
	ds_read_b128 v[182:185], v144 offset:21504
	ds_read_b128 v[186:189], v144 offset:22528
	ds_read_b128 v[190:193], v144 offset:23552
	global_load_lds_dwordx4 v[218:219], off
	v_lshl_add_u64 v[220:221], s[14:15], 0, v[132:133]
	s_mov_b32 m0, s69
	s_nop 0
	global_load_lds_dwordx4 v[220:221], off
	s_barrier
	s_waitcnt lgkmcnt(0)
	s_waitcnt lgkmcnt(0)
	v_mfma_f32_16x16x32_bf16 v[60:63], v[146:149], v[162:165], v[60:63]
	v_mfma_f32_16x16x32_bf16 v[60:63], v[150:153], v[166:169], v[60:63]
	v_mfma_f32_16x16x32_bf16 v[56:59], v[158:161], v[166:169], v[56:59]
	v_mfma_f32_16x16x32_bf16 v[56:59], v[154:157], v[162:165], v[56:59]
	v_mfma_f32_16x16x32_bf16 v[40:43], v[154:157], v[170:173], v[40:43]
	v_mfma_f32_16x16x32_bf16 v[40:43], v[158:161], v[174:177], v[40:43]
	v_mfma_f32_16x16x32_bf16 v[44:47], v[150:153], v[174:177], v[44:47]
	v_mfma_f32_16x16x32_bf16 v[44:47], v[146:149], v[170:173], v[44:47]
	v_mfma_f32_16x16x32_bf16 v[28:31], v[146:149], v[178:181], v[28:31]
	v_mfma_f32_16x16x32_bf16 v[28:31], v[150:153], v[182:185], v[28:31]
	v_mfma_f32_16x16x32_bf16 v[24:27], v[158:161], v[182:185], v[24:27]
	v_mfma_f32_16x16x32_bf16 v[24:27], v[154:157], v[178:181], v[24:27]
	v_mfma_f32_16x16x32_bf16 v[8:11], v[154:157], v[186:189], v[8:11]
	v_mfma_f32_16x16x32_bf16 v[8:11], v[158:161], v[190:193], v[8:11]
	v_mfma_f32_16x16x32_bf16 v[12:15], v[150:153], v[190:193], v[12:15]
	v_mfma_f32_16x16x32_bf16 v[12:15], v[146:149], v[186:189], v[12:15]
	s_barrier
; #define PG8_STAGE(bufoff, gbase, voff) do { _Pragma("unroll") for (int _i = 0; _i < 2; ++_i) \
;         __builtin_amdgcn_global_load_lds((const unsigned*)((const char*)(gbase) + (voff)[_i]), (LAS unsigned*)(lds + (bufoff) + ldsw + _i * 8192), 16, 0, 0); } while (0)
; #define PG8_LDA(dst, b, h) do { _Pragma("unroll") for (int m = 0; m < 4; ++m) _Pragma("unroll") for (int k = 0; k < 2; ++k) dst[m][k] = *(const LAS bf16x8*)(lds + PG8_SA(b, h) + aoff + m * 2048 + k * 1024); } while (0)
; #define PG8_LDB(dst, b, h) do { _Pragma("unroll") for (int n = 0; n < 2; ++n) _Pragma("unroll") for (int k = 0; k < 2; ++k) dst[n][k] = *(const LAS bf16x8*)(lds + PG8_SB(b, h) + boff + n * 2048 + k * 1024); } while (0)
; #define PG8_MMA(ai, bj, At, Bt) do { __builtin_amdgcn_s_setprio(1); _Pragma("unroll") for (int m = 0; m < 4; ++m) _Pragma("unroll") for (int n = 0; n < 2; ++n) _Pragma("unroll") for (int k = 0; k < 2; ++k) \
;         acc[ai][bj][m][n] = __builtin_amdgcn_mfma_f32_16x16x32_bf16(Bt[n][k], At[m][k], acc[ai][bj][m][n], 0, 0, 0); __builtin_amdgcn_s_setprio(0); } while (0)
; #define PG8_WAIT_V(n) asm volatile("s_waitcnt vmcnt(" #n ")" ::: "memory")
; #define PG8_WAIT_L(n) asm volatile("s_waitcnt lgkmcnt(" #n ")" ::: "memory")
; #define PG8_BAR __builtin_amdgcn_s_barrier()
; #define PG8_SCHED __builtin_amdgcn_sched_barrier(0)
; template <class Epi>
; DEVINL void gemm_phase(LAS unsigned char* lds, const Gemm g, const Order& S, const Epi& E) {
;     ...
;             PG8_STAGE(PG8_SB(0, 1), b2 + hstepB, voffB);
;             PG8_WAIT_V(6); PG8_BAR; PG8_MMA(1, 1, At, B1); PG8_BAR;
;             PG8_LDB(B0, 1, 0); PG8_SCHED; PG8_LDA(At, 1, 0); PG8_STAGE(PG8_SA(0, 1), a2 + hstepA, voffA);
;             PG8_WAIT_L(8); PG8_BAR; PG8_WAIT_L(0); PG8_MMA(0, 0, At, B0); PG8_BAR; PG8_SCHED;
;             PG8_LDB(B1, 1, 1); PG8_STAGE(PG8_SB(1, 0), b3, voffB);
	s_add_u32 vcc_lo, s10, 0x80000
	s_addc_u32 vcc_hi, s11, 0
	s_add_i32 s2, s81, s68
	v_lshl_add_u64 v[146:147], vcc, 0, v[130:131]
	s_mov_b32 m0, s2
	s_nop 0
	global_load_lds_dwordx4 v[146:147], off
	v_lshl_add_u64 v[146:147], vcc, 0, v[134:135]
	s_add_i32 m0, s2, 0x2000
	s_nop 0
	global_load_lds_dwordx4 v[146:147], off
	s_waitcnt vmcnt(6)
	s_barrier
	v_mfma_f32_16x16x32_bf16 v[52:55], v[194:197], v[162:165], v[52:55]
	v_mfma_f32_16x16x32_bf16 v[52:55], v[198:201], v[166:169], v[52:55]
	v_mfma_f32_16x16x32_bf16 v[48:51], v[206:209], v[166:169], v[48:51]
	v_mfma_f32_16x16x32_bf16 v[48:51], v[202:205], v[162:165], v[48:51]
	v_mfma_f32_16x16x32_bf16 v[32:35], v[202:205], v[170:173], v[32:35]
	v_mfma_f32_16x16x32_bf16 v[32:35], v[206:209], v[174:177], v[32:35]
	v_mfma_f32_16x16x32_bf16 v[36:39], v[198:201], v[174:177], v[36:39]
	v_mfma_f32_16x16x32_bf16 v[36:39], v[194:197], v[170:173], v[36:39]
	v_mfma_f32_16x16x32_bf16 v[20:23], v[194:197], v[178:181], v[20:23]
	v_mfma_f32_16x16x32_bf16 v[20:23], v[198:201], v[182:185], v[20:23]
	v_mfma_f32_16x16x32_bf16 v[16:19], v[206:209], v[182:185], v[16:19]
	v_mfma_f32_16x16x32_bf16 v[16:19], v[202:205], v[178:181], v[16:19]
	v_mfma_f32_16x16x32_bf16 v[0:3], v[202:205], v[186:189], v[0:3]
	v_mfma_f32_16x16x32_bf16 v[0:3], v[206:209], v[190:193], v[0:3]
	v_mfma_f32_16x16x32_bf16 v[4:7], v[198:201], v[190:193], v[4:7]
	v_mfma_f32_16x16x32_bf16 v[4:7], v[194:197], v[186:189], v[4:7]
	s_add_i32 s2, 16, 0x18000
	v_add_u32_e32 v158, s2, v141
	s_barrier
	ds_read_b128 v[146:149], v158
	ds_read_b128 v[150:153], v158 offset:1024
	ds_read_b128 v[154:157], v158 offset:2048
	ds_read_b128 v[158:161], v158 offset:3072
	s_add_u32 s14, s14, 0x80000
	s_addc_u32 s15, s15, 0
	s_mov_b32 m0, s72
	v_lshl_add_u64 v[194:195], s[14:15], 0, v[128:129]
	ds_read_b128 v[162:165], v144 offset:32768
	ds_read_b128 v[166:169], v144 offset:33792
	ds_read_b128 v[170:173], v144 offset:34816
	ds_read_b128 v[174:177], v144 offset:35840
	ds_read_b128 v[178:181], v144 offset:36864
	ds_read_b128 v[182:185], v144 offset:37888
	ds_read_b128 v[186:189], v144 offset:38912
	ds_read_b128 v[190:193], v144 offset:39936
	global_load_lds_dwordx4 v[194:195], off
	v_lshl_add_u64 v[194:195], s[14:15], 0, v[132:133]
	s_mov_b32 m0, s73
	s_nop 0
	global_load_lds_dwordx4 v[194:195], off
	s_waitcnt lgkmcnt(8)
	s_barrier
	s_waitcnt lgkmcnt(0)
	s_waitcnt lgkmcnt(0)
	v_mfma_f32_16x16x32_bf16 v[120:123], v[146:149], v[162:165], v[120:123]
	v_mfma_f32_16x16x32_bf16 v[120:123], v[150:153], v[166:169], v[120:123]
	v_mfma_f32_16x16x32_bf16 v[124:127], v[158:161], v[166:169], v[124:127]
	v_mfma_f32_16x16x32_bf16 v[124:127], v[154:157], v[162:165], v[124:127]
	v_mfma_f32_16x16x32_bf16 v[104:107], v[154:157], v[170:173], v[104:107]
	v_mfma_f32_16x16x32_bf16 v[104:107], v[158:161], v[174:177], v[104:107]
	v_mfma_f32_16x16x32_bf16 v[108:111], v[150:153], v[174:177], v[108:111]
	v_mfma_f32_16x16x32_bf16 v[108:111], v[146:149], v[170:173], v[108:111]
	v_mfma_f32_16x16x32_bf16 v[92:95], v[146:149], v[178:181], v[92:95]
	v_mfma_f32_16x16x32_bf16 v[92:95], v[150:153], v[182:185], v[92:95]
	v_mfma_f32_16x16x32_bf16 v[88:91], v[158:161], v[182:185], v[88:91]
	v_mfma_f32_16x16x32_bf16 v[88:91], v[154:157], v[178:181], v[88:91]
	v_mfma_f32_16x16x32_bf16 v[72:75], v[154:157], v[186:189], v[72:75]
	v_mfma_f32_16x16x32_bf16 v[72:75], v[158:161], v[190:193], v[72:75]
	v_mfma_f32_16x16x32_bf16 v[76:79], v[150:153], v[190:193], v[76:79]
	v_mfma_f32_16x16x32_bf16 v[76:79], v[146:149], v[186:189], v[76:79]
	s_barrier
	s_add_i32 s3, 16, 0x1c000
	s_add_i32 s2, s2, s68
	v_add_u32_e32 v206, s3, v141
	v_lshl_add_u64 v[210:211], v[210:211], 0, s[0:1]
	s_mov_b32 m0, s2
	ds_read_b128 v[194:197], v206
	ds_read_b128 v[198:201], v206 offset:1024
	ds_read_b128 v[202:205], v206 offset:2048
	ds_read_b128 v[206:209], v206 offset:3072
	global_load_lds_dwordx4 v[210:211], off
	v_lshl_add_u64 v[210:211], v[212:213], 0, s[0:1]
	s_add_i32 m0, s2, 0x2000
	s_nop 0
	global_load_lds_dwordx4 v[210:211], off
	s_barrier
; #define PG8_STAGE(bufoff, gbase, voff) do { _Pragma("unroll") for (int _i = 0; _i < 2; ++_i) \
;         __builtin_amdgcn_global_load_lds((const unsigned*)((const char*)(gbase) + (voff)[_i]), (LAS unsigned*)(lds + (bufoff) + ldsw + _i * 8192), 16, 0, 0); } while (0)
; #define PG8_LDA(dst, b, h) do { _Pragma("unroll") for (int m = 0; m < 4; ++m) _Pragma("unroll") for (int k = 0; k < 2; ++k) dst[m][k] = *(const LAS bf16x8*)(lds + PG8_SA(b, h) + aoff + m * 2048 + k * 1024); } while (0)
; #define PG8_LDB(dst, b, h) do { _Pragma("unroll") for (int n = 0; n < 2; ++n) _Pragma("unroll") for (int k = 0; k < 2; ++k) dst[n][k] = *(const LAS bf16x8*)(lds + PG8_SB(b, h) + boff + n * 2048 + k * 1024); } while (0)
; #define PG8_MMA(ai, bj, At, Bt) do { __builtin_amdgcn_s_setprio(1); _Pragma("unroll") for (int m = 0; m < 4; ++m) _Pragma("unroll") for (int n = 0; n < 2; ++n) _Pragma("unroll") for (int k = 0; k < 2; ++k) \
;         acc[ai][bj][m][n] = __builtin_amdgcn_mfma_f32_16x16x32_bf16(Bt[n][k], At[m][k], acc[ai][bj][m][n], 0, 0, 0); __builtin_amdgcn_s_setprio(0); } while (0)
; #define PG8_WAIT_V(n) asm volatile("s_waitcnt vmcnt(" #n ")" ::: "memory")
; #define PG8_WAIT_L(n) asm volatile("s_waitcnt lgkmcnt(" #n ")" ::: "memory")
; #define PG8_BAR __builtin_amdgcn_s_barrier()
; #define PG8_SCHED __builtin_amdgcn_sched_barrier(0)
; template <class Epi>
; DEVINL void gemm_phase(LAS unsigned char* lds, const Gemm g, const Order& S, const Epi& E) {
;     ...
;         for (int t = 0; t < nt; t += 2) {
;     ...
;             PG8_LDB(B1, 1, 1); PG8_STAGE(PG8_SB(1, 0), b3, voffB);
;             PG8_BAR; PG8_WAIT_L(0); PG8_MMA(0, 1, At, B1); PG8_BAR;
;             PG8_LDA(At, 1, 1); PG8_STAGE(PG8_SA(1, 0), a3, voffA);
;             PG8_BAR; PG8_WAIT_L(0); PG8_MMA(1, 0, At, B0); PG8_BAR; PG8_SCHED;
;             PG8_STAGE(PG8_SB(1, 1), b3 + hstepB, voffB);
;             PG8_WAIT_V(6); PG8_BAR; PG8_MMA(1, 1, At, B1); PG8_BAR;
	s_waitcnt lgkmcnt(0)
	s_waitcnt lgkmcnt(0)
	v_mfma_f32_16x16x32_bf16 v[116:119], v[194:197], v[162:165], v[116:119]
	v_mfma_f32_16x16x32_bf16 v[116:119], v[198:201], v[166:169], v[116:119]
	v_mfma_f32_16x16x32_bf16 v[112:115], v[206:209], v[166:169], v[112:115]
	v_mfma_f32_16x16x32_bf16 v[112:115], v[202:205], v[162:165], v[112:115]
	v_mfma_f32_16x16x32_bf16 v[96:99], v[202:205], v[170:173], v[96:99]
	v_mfma_f32_16x16x32_bf16 v[96:99], v[206:209], v[174:177], v[96:99]
	v_mfma_f32_16x16x32_bf16 v[100:103], v[198:201], v[174:177], v[100:103]
	v_mfma_f32_16x16x32_bf16 v[100:103], v[194:197], v[170:173], v[100:103]
	v_mfma_f32_16x16x32_bf16 v[84:87], v[194:197], v[178:181], v[84:87]
	v_mfma_f32_16x16x32_bf16 v[84:87], v[198:201], v[182:185], v[84:87]
	v_mfma_f32_16x16x32_bf16 v[80:83], v[206:209], v[182:185], v[80:83]
	v_mfma_f32_16x16x32_bf16 v[80:83], v[202:205], v[178:181], v[80:83]
	v_mfma_f32_16x16x32_bf16 v[64:67], v[202:205], v[186:189], v[64:67]
	v_mfma_f32_16x16x32_bf16 v[64:67], v[206:209], v[190:193], v[64:67]
	v_mfma_f32_16x16x32_bf16 v[68:71], v[198:201], v[190:193], v[68:71]
	v_mfma_f32_16x16x32_bf16 v[68:71], v[194:197], v[186:189], v[68:71]
	s_mov_b32 m0, s75
	v_lshl_add_u64 v[210:211], v[218:219], 0, s[0:1]
	s_barrier
	ds_read_b128 v[162:165], v144 offset:49152
	ds_read_b128 v[166:169], v144 offset:50176
	ds_read_b128 v[170:173], v144 offset:51200
	ds_read_b128 v[174:177], v144 offset:52224
	ds_read_b128 v[178:181], v144 offset:53248
	ds_read_b128 v[182:185], v144 offset:54272
	ds_read_b128 v[186:189], v144 offset:55296
	ds_read_b128 v[190:193], v144 offset:56320
	global_load_lds_dwordx4 v[210:211], off
	v_lshl_add_u64 v[210:211], v[220:221], 0, s[0:1]
	s_mov_b32 m0, s76
	s_nop 0
	global_load_lds_dwordx4 v[210:211], off
	s_barrier
	s_waitcnt lgkmcnt(0)
	s_waitcnt lgkmcnt(0)
	v_mfma_f32_16x16x32_bf16 v[60:63], v[146:149], v[162:165], v[60:63]
	v_mfma_f32_16x16x32_bf16 v[60:63], v[150:153], v[166:169], v[60:63]
	v_mfma_f32_16x16x32_bf16 v[56:59], v[158:161], v[166:169], v[56:59]
	v_mfma_f32_16x16x32_bf16 v[56:59], v[154:157], v[162:165], v[56:59]
	v_mfma_f32_16x16x32_bf16 v[40:43], v[154:157], v[170:173], v[40:43]
	v_mfma_f32_16x16x32_bf16 v[40:43], v[158:161], v[174:177], v[40:43]
	v_mfma_f32_16x16x32_bf16 v[44:47], v[150:153], v[174:177], v[44:47]
	v_mfma_f32_16x16x32_bf16 v[44:47], v[146:149], v[170:173], v[44:47]
	v_mfma_f32_16x16x32_bf16 v[28:31], v[146:149], v[178:181], v[28:31]
	v_mfma_f32_16x16x32_bf16 v[28:31], v[150:153], v[182:185], v[28:31]
	v_mfma_f32_16x16x32_bf16 v[24:27], v[158:161], v[182:185], v[24:27]
	v_mfma_f32_16x16x32_bf16 v[24:27], v[154:157], v[178:181], v[24:27]
	v_mfma_f32_16x16x32_bf16 v[8:11], v[154:157], v[186:189], v[8:11]
	v_mfma_f32_16x16x32_bf16 v[8:11], v[158:161], v[190:193], v[8:11]
	v_mfma_f32_16x16x32_bf16 v[12:15], v[150:153], v[190:193], v[12:15]
	v_mfma_f32_16x16x32_bf16 v[12:15], v[146:149], v[186:189], v[12:15]
	s_barrier
	s_add_u32 s10, s10, 0x80080
	s_addc_u32 s11, s11, 0
	s_add_i32 s2, s3, s68
	v_lshl_add_u64 v[146:147], s[10:11], 0, v[130:131]
	s_mov_b32 m0, s2
	s_nop 0
	global_load_lds_dwordx4 v[146:147], off
	v_lshl_add_u64 v[146:147], s[10:11], 0, v[134:135]
	s_add_i32 m0, s2, 0x2000
	s_nop 0
	global_load_lds_dwordx4 v[146:147], off
	s_waitcnt vmcnt(6)
	s_barrier
	v_mfma_f32_16x16x32_bf16 v[52:55], v[194:197], v[162:165], v[52:55]
	v_mfma_f32_16x16x32_bf16 v[52:55], v[198:201], v[166:169], v[52:55]
	v_mfma_f32_16x16x32_bf16 v[48:51], v[206:209], v[166:169], v[48:51]
	v_mfma_f32_16x16x32_bf16 v[48:51], v[202:205], v[162:165], v[48:51]
	v_mfma_f32_16x16x32_bf16 v[32:35], v[202:205], v[170:173], v[32:35]
	v_mfma_f32_16x16x32_bf16 v[32:35], v[206:209], v[174:177], v[32:35]
	v_mfma_f32_16x16x32_bf16 v[36:39], v[198:201], v[174:177], v[36:39]
	v_mfma_f32_16x16x32_bf16 v[36:39], v[194:197], v[170:173], v[36:39]
	v_mfma_f32_16x16x32_bf16 v[20:23], v[194:197], v[178:181], v[20:23]
	v_mfma_f32_16x16x32_bf16 v[20:23], v[198:201], v[182:185], v[20:23]
	v_mfma_f32_16x16x32_bf16 v[16:19], v[206:209], v[182:185], v[16:19]
	v_mfma_f32_16x16x32_bf16 v[16:19], v[202:205], v[178:181], v[16:19]
	v_mfma_f32_16x16x32_bf16 v[0:3], v[202:205], v[186:189], v[0:3]
	v_mfma_f32_16x16x32_bf16 v[0:3], v[206:209], v[190:193], v[0:3]
	v_mfma_f32_16x16x32_bf16 v[4:7], v[198:201], v[190:193], v[4:7]
	v_mfma_f32_16x16x32_bf16 v[4:7], v[194:197], v[186:189], v[4:7]
	s_add_u32 s12, s12, 0x100
	s_addc_u32 s13, s13, 0
	s_add_u32 s85, s85, 0x100
	s_addc_u32 s86, s86, 0
	s_cmp_ge_i32 s87, s74
	s_mov_b32 s10, s87
	s_barrier
	s_cbranch_scc0 .LBB0_361
	s_branch .LBB0_352

; #define PG8_STAGE(bufoff, gbase, voff) do { _Pragma("unroll") for (int _i = 0; _i < 2; ++_i) \
;         __builtin_amdgcn_global_load_lds((const unsigned*)((const char*)(gbase) + (voff)[_i]), (LAS unsigned*)(lds + (bufoff) + ldsw + _i * 8192), 16, 0, 0); } while (0)
; #define PG8_LDA(dst, b, h) do { _Pragma("unroll") for (int m = 0; m < 4; ++m) _Pragma("unroll") for (int k = 0; k < 2; ++k) dst[m][k] = *(const LAS bf16x8*)(lds + PG8_SA(b, h) + aoff + m * 2048 + k * 1024); } while (0)
; #define PG8_LDB(dst, b, h) do { _Pragma("unroll") for (int n = 0; n < 2; ++n) _Pragma("unroll") for (int k = 0; k < 2; ++k) dst[n][k] = *(const LAS bf16x8*)(lds + PG8_SB(b, h) + boff + n * 2048 + k * 1024); } while (0)
; #define PG8_MMA(ai, bj, At, Bt) do { __builtin_amdgcn_s_setprio(1); _Pragma("unroll") for (int m = 0; m < 4; ++m) _Pragma("unroll") for (int n = 0; n < 2; ++n) _Pragma("unroll") for (int k = 0; k < 2; ++k) \
;         acc[ai][bj][m][n] = __builtin_amdgcn_mfma_f32_16x16x32_bf16(Bt[n][k], At[m][k], acc[ai][bj][m][n], 0, 0, 0); __builtin_amdgcn_s_setprio(0); } while (0)
; #define PG8_WAIT_L(n) asm volatile("s_waitcnt lgkmcnt(" #n ")" ::: "memory")
; #define PG8_BAR __builtin_amdgcn_s_barrier()
; #define PG8_SCHED __builtin_amdgcn_sched_barrier(0)
; template <class Epi>
; DEVINL void gemm_phase(LAS unsigned char* lds, const Gemm g, const Order& S, const Epi& E) {
;     ...
;             const char* a1 = cA + (size_t)(t + 1) * kstep;
;             const char* a2 = last ? nA : cA + (size_t)(t + 2) * kstep; const char* b2 = last ? nB : cB + (size_t)(t + 2) * kstep;
;             const char* a3 = a2 + kstep; const char* b3 = b2 + kstep;
;             PG8_LDB(B0, 0, 0); PG8_SCHED; PG8_LDA(At, 0, 0); PG8_STAGE(PG8_SA(1, 1), a1 + hstepA, voffA);
;             PG8_WAIT_L(8); PG8_BAR; PG8_WAIT_L(0); PG8_MMA(0, 0, At, B0); PG8_BAR; PG8_SCHED;
;             PG8_LDB(B1, 0, 1); PG8_STAGE(PG8_SB(0, 0), b2, voffB);
;             PG8_BAR; PG8_WAIT_L(0); PG8_MMA(0, 1, At, B1); PG8_BAR;
;             PG8_LDA(At, 0, 1); PG8_STAGE(PG8_SA(0, 0), a2, voffA);
;             PG8_BAR; PG8_WAIT_L(0); PG8_MMA(1, 0, At, B0); PG8_BAR; PG8_SCHED;
.LBB0_382:
	ds_read_b128 v[146:149], v143
	ds_read_b128 v[150:153], v143 offset:1024
	ds_read_b128 v[154:157], v143 offset:2048
	ds_read_b128 v[158:161], v143 offset:3072
	s_add_i32 s87, s12, 2
	s_add_u32 s2, s14, 0xfff80080
	s_addc_u32 s3, s15, -1
	s_cmp_eq_u32 s78, s12
	s_cselect_b32 s12, s84, s85
	s_cselect_b32 vcc_hi, s65, s3
	s_cselect_b32 vcc_lo, s66, s2
	s_cselect_b32 s13, s67, s86
	v_lshl_add_u64 v[194:195], s[14:15], 0, v[136:137]
	s_add_i32 m0, s5, 0xc000
	ds_read_b128 v[162:165], v144
	ds_read_b128 v[166:169], v144 offset:1024
	ds_read_b128 v[170:173], v144 offset:2048
	ds_read_b128 v[174:177], v144 offset:3072
	ds_read_b128 v[178:181], v144 offset:4096
	ds_read_b128 v[182:185], v144 offset:5120
	ds_read_b128 v[186:189], v144 offset:6144
	ds_read_b128 v[190:193], v144 offset:7168
	global_load_lds_dwordx4 v[194:195], off
	v_lshl_add_u64 v[194:195], s[14:15], 0, v[138:139]
	s_add_i32 m0, s5, 0xe000
	s_nop 0
	global_load_lds_dwordx4 v[194:195], off
	s_waitcnt lgkmcnt(8)
	s_barrier
	s_waitcnt lgkmcnt(0)
	s_waitcnt lgkmcnt(0)
	v_mfma_f32_16x16x32_bf16 v[120:123], v[146:149], v[162:165], v[120:123]
	v_mfma_f32_16x16x32_bf16 v[120:123], v[150:153], v[166:169], v[120:123]
	v_mfma_f32_16x16x32_bf16 v[124:127], v[158:161], v[166:169], v[124:127]
	v_mfma_f32_16x16x32_bf16 v[124:127], v[154:157], v[162:165], v[124:127]
	v_mfma_f32_16x16x32_bf16 v[104:107], v[154:157], v[170:173], v[104:107]
	v_mfma_f32_16x16x32_bf16 v[104:107], v[158:161], v[174:177], v[104:107]
	v_mfma_f32_16x16x32_bf16 v[108:111], v[150:153], v[174:177], v[108:111]
	v_mfma_f32_16x16x32_bf16 v[108:111], v[146:149], v[170:173], v[108:111]
	v_mfma_f32_16x16x32_bf16 v[92:95], v[146:149], v[178:181], v[92:95]
	v_mfma_f32_16x16x32_bf16 v[92:95], v[150:153], v[182:185], v[92:95]
	v_mfma_f32_16x16x32_bf16 v[88:91], v[158:161], v[182:185], v[88:91]
	v_mfma_f32_16x16x32_bf16 v[88:91], v[154:157], v[178:181], v[88:91]
	v_mfma_f32_16x16x32_bf16 v[72:75], v[154:157], v[186:189], v[72:75]
	v_mfma_f32_16x16x32_bf16 v[72:75], v[158:161], v[190:193], v[72:75]
	v_mfma_f32_16x16x32_bf16 v[76:79], v[150:153], v[190:193], v[76:79]
	v_mfma_f32_16x16x32_bf16 v[76:79], v[146:149], v[186:189], v[76:79]
	s_barrier
	s_add_i32 s2, s81, s68
	v_lshl_add_u64 v[210:211], s[12:13], 0, v[130:131]
	s_mov_b32 m0, s2
	ds_read_b128 v[194:197], v145
	ds_read_b128 v[198:201], v145 offset:1024
	ds_read_b128 v[202:205], v145 offset:2048
	ds_read_b128 v[206:209], v145 offset:3072
	global_load_lds_dwordx4 v[210:211], off
	v_lshl_add_u64 v[212:213], s[12:13], 0, v[134:135]
	s_add_i32 m0, s2, 0x2000
	s_nop 0
	global_load_lds_dwordx4 v[212:213], off
	s_barrier
	s_waitcnt lgkmcnt(0)
	s_waitcnt lgkmcnt(0)
	v_mfma_f32_16x16x32_bf16 v[116:119], v[194:197], v[162:165], v[116:119]
	v_mfma_f32_16x16x32_bf16 v[116:119], v[198:201], v[166:169], v[116:119]
	v_mfma_f32_16x16x32_bf16 v[112:115], v[206:209], v[166:169], v[112:115]
	v_mfma_f32_16x16x32_bf16 v[112:115], v[202:205], v[162:165], v[112:115]
	v_mfma_f32_16x16x32_bf16 v[96:99], v[202:205], v[170:173], v[96:99]
	v_mfma_f32_16x16x32_bf16 v[96:99], v[206:209], v[174:177], v[96:99]
	v_mfma_f32_16x16x32_bf16 v[100:103], v[198:201], v[174:177], v[100:103]
	v_mfma_f32_16x16x32_bf16 v[100:103], v[194:197], v[170:173], v[100:103]
	v_mfma_f32_16x16x32_bf16 v[84:87], v[194:197], v[178:181], v[84:87]
	v_mfma_f32_16x16x32_bf16 v[84:87], v[198:201], v[182:185], v[84:87]
	v_mfma_f32_16x16x32_bf16 v[80:83], v[206:209], v[182:185], v[80:83]
	v_mfma_f32_16x16x32_bf16 v[80:83], v[202:205], v[178:181], v[80:83]
	v_mfma_f32_16x16x32_bf16 v[64:67], v[202:205], v[186:189], v[64:67]
	v_mfma_f32_16x16x32_bf16 v[64:67], v[206:209], v[190:193], v[64:67]
	v_mfma_f32_16x16x32_bf16 v[68:71], v[198:201], v[190:193], v[68:71]
	v_mfma_f32_16x16x32_bf16 v[68:71], v[194:197], v[186:189], v[68:71]
	s_mov_b32 m0, s5
	v_lshl_add_u64 v[218:219], vcc, 0, v[128:129]
	s_barrier
	ds_read_b128 v[162:165], v144 offset:16384
	ds_read_b128 v[166:169], v144 offset:17408
	ds_read_b128 v[170:173], v144 offset:18432
	ds_read_b128 v[174:177], v144 offset:19456
	ds_read_b128 v[178:181], v144 offset:20480
	ds_read_b128 v[182:185], v144 offset:21504
	ds_read_b128 v[186:189], v144 offset:22528
	ds_read_b128 v[190:193], v144 offset:23552
	global_load_lds_dwordx4 v[218:219], off
	v_lshl_add_u64 v[220:221], vcc, 0, v[132:133]
	s_mov_b32 m0, s69
	s_nop 0
	global_load_lds_dwordx4 v[220:221], off
	s_barrier
	s_waitcnt lgkmcnt(0)
	s_waitcnt lgkmcnt(0)
	v_mfma_f32_16x16x32_bf16 v[60:63], v[146:149], v[162:165], v[60:63]
	v_mfma_f32_16x16x32_bf16 v[60:63], v[150:153], v[166:169], v[60:63]
	v_mfma_f32_16x16x32_bf16 v[56:59], v[158:161], v[166:169], v[56:59]
	v_mfma_f32_16x16x32_bf16 v[56:59], v[154:157], v[162:165], v[56:59]
	v_mfma_f32_16x16x32_bf16 v[40:43], v[154:157], v[170:173], v[40:43]
	v_mfma_f32_16x16x32_bf16 v[40:43], v[158:161], v[174:177], v[40:43]
	v_mfma_f32_16x16x32_bf16 v[44:47], v[150:153], v[174:177], v[44:47]
	v_mfma_f32_16x16x32_bf16 v[44:47], v[146:149], v[170:173], v[44:47]
	v_mfma_f32_16x16x32_bf16 v[28:31], v[146:149], v[178:181], v[28:31]
	v_mfma_f32_16x16x32_bf16 v[28:31], v[150:153], v[182:185], v[28:31]
	v_mfma_f32_16x16x32_bf16 v[24:27], v[158:161], v[182:185], v[24:27]
	v_mfma_f32_16x16x32_bf16 v[24:27], v[154:157], v[178:181], v[24:27]
	v_mfma_f32_16x16x32_bf16 v[8:11], v[154:157], v[186:189], v[8:11]
	v_mfma_f32_16x16x32_bf16 v[8:11], v[158:161], v[190:193], v[8:11]
	v_mfma_f32_16x16x32_bf16 v[12:15], v[150:153], v[190:193], v[12:15]
	v_mfma_f32_16x16x32_bf16 v[12:15], v[146:149], v[186:189], v[12:15]
	s_barrier
; #define PG8_STAGE(bufoff, gbase, voff) do { _Pragma("unroll") for (int _i = 0; _i < 2; ++_i) \
;         __builtin_amdgcn_global_load_lds((const unsigned*)((const char*)(gbase) + (voff)[_i]), (LAS unsigned*)(lds + (bufoff) + ldsw + _i * 8192), 16, 0, 0); } while (0)
; #define PG8_LDA(dst, b, h) do { _Pragma("unroll") for (int m = 0; m < 4; ++m) _Pragma("unroll") for (int k = 0; k < 2; ++k) dst[m][k] = *(const LAS bf16x8*)(lds + PG8_SA(b, h) + aoff + m * 2048 + k * 1024); } while (0)
; #define PG8_LDB(dst, b, h) do { _Pragma("unroll") for (int n = 0; n < 2; ++n) _Pragma("unroll") for (int k = 0; k < 2; ++k) dst[n][k] = *(const LAS bf16x8*)(lds + PG8_SB(b, h) + boff + n * 2048 + k * 1024); } while (0)
; #define PG8_MMA(ai, bj, At, Bt) do { __builtin_amdgcn_s_setprio(1); _Pragma("unroll") for (int m = 0; m < 4; ++m) _Pragma("unroll") for (int n = 0; n < 2; ++n) _Pragma("unroll") for (int k = 0; k < 2; ++k) \
;         acc[ai][bj][m][n] = __builtin_amdgcn_mfma_f32_16x16x32_bf16(Bt[n][k], At[m][k], acc[ai][bj][m][n], 0, 0, 0); __builtin_amdgcn_s_setprio(0); } while (0)
; #define PG8_WAIT_V(n) asm volatile("s_waitcnt vmcnt(" #n ")" ::: "memory")
; #define PG8_WAIT_L(n) asm volatile("s_waitcnt lgkmcnt(" #n ")" ::: "memory")
; #define PG8_BAR __builtin_amdgcn_s_barrier()
; #define PG8_SCHED __builtin_amdgcn_sched_barrier(0)
; template <class Epi>
; DEVINL void gemm_phase(LAS unsigned char* lds, const Gemm g, const Order& S, const Epi& E) {
;     ...
;             PG8_STAGE(PG8_SB(0, 1), b2 + hstepB, voffB);
;             PG8_WAIT_V(6); PG8_BAR; PG8_MMA(1, 1, At, B1); PG8_BAR;
;             PG8_LDB(B0, 1, 0); PG8_SCHED; PG8_LDA(At, 1, 0); PG8_STAGE(PG8_SA(0, 1), a2 + hstepA, voffA);
;             PG8_WAIT_L(8); PG8_BAR; PG8_WAIT_L(0); PG8_MMA(0, 0, At, B0); PG8_BAR; PG8_SCHED;
;             PG8_LDB(B1, 1, 1); PG8_STAGE(PG8_SB(1, 0), b3, voffB);
	s_add_u32 s2, s12, 0x80000
	s_addc_u32 s3, s13, 0
	s_add_i32 s93, s82, s68
	v_lshl_add_u64 v[146:147], s[2:3], 0, v[130:131]
	s_mov_b32 m0, s93
	s_nop 0
	global_load_lds_dwordx4 v[146:147], off
	v_lshl_add_u64 v[146:147], s[2:3], 0, v[134:135]
	s_add_i32 m0, s93, 0x2000
	s_nop 0
	global_load_lds_dwordx4 v[146:147], off
	s_waitcnt vmcnt(6)
	s_barrier
	v_mfma_f32_16x16x32_bf16 v[52:55], v[194:197], v[162:165], v[52:55]
	v_mfma_f32_16x16x32_bf16 v[52:55], v[198:201], v[166:169], v[52:55]
	v_mfma_f32_16x16x32_bf16 v[48:51], v[206:209], v[166:169], v[48:51]
	v_mfma_f32_16x16x32_bf16 v[48:51], v[202:205], v[162:165], v[48:51]
	v_mfma_f32_16x16x32_bf16 v[32:35], v[202:205], v[170:173], v[32:35]
	v_mfma_f32_16x16x32_bf16 v[32:35], v[206:209], v[174:177], v[32:35]
	v_mfma_f32_16x16x32_bf16 v[36:39], v[198:201], v[174:177], v[36:39]
	v_mfma_f32_16x16x32_bf16 v[36:39], v[194:197], v[170:173], v[36:39]
	v_mfma_f32_16x16x32_bf16 v[20:23], v[194:197], v[178:181], v[20:23]
	v_mfma_f32_16x16x32_bf16 v[20:23], v[198:201], v[182:185], v[20:23]
	v_mfma_f32_16x16x32_bf16 v[16:19], v[206:209], v[182:185], v[16:19]
	v_mfma_f32_16x16x32_bf16 v[16:19], v[202:205], v[178:181], v[16:19]
	v_mfma_f32_16x16x32_bf16 v[0:3], v[202:205], v[186:189], v[0:3]
	v_mfma_f32_16x16x32_bf16 v[0:3], v[206:209], v[190:193], v[0:3]
	v_mfma_f32_16x16x32_bf16 v[4:7], v[198:201], v[190:193], v[4:7]
	v_mfma_f32_16x16x32_bf16 v[4:7], v[194:197], v[186:189], v[4:7]
	s_add_i32 s93, 16, 0x18000
	v_add_u32_e32 v158, s93, v141
	s_barrier
	ds_read_b128 v[146:149], v158
	ds_read_b128 v[150:153], v158 offset:1024
	ds_read_b128 v[154:157], v158 offset:2048
	ds_read_b128 v[158:161], v158 offset:3072
	s_add_u32 s2, vcc_lo, 0x80000
	s_addc_u32 s3, vcc_hi, 0
	s_mov_b32 m0, s72
	v_lshl_add_u64 v[194:195], s[2:3], 0, v[128:129]
	ds_read_b128 v[162:165], v144 offset:32768
	ds_read_b128 v[166:169], v144 offset:33792
	ds_read_b128 v[170:173], v144 offset:34816
	ds_read_b128 v[174:177], v144 offset:35840
	ds_read_b128 v[178:181], v144 offset:36864
	ds_read_b128 v[182:185], v144 offset:37888
	ds_read_b128 v[186:189], v144 offset:38912
	ds_read_b128 v[190:193], v144 offset:39936
	global_load_lds_dwordx4 v[194:195], off
	v_lshl_add_u64 v[194:195], s[2:3], 0, v[132:133]
	s_mov_b32 m0, s73
	s_nop 0
	global_load_lds_dwordx4 v[194:195], off
	s_waitcnt lgkmcnt(8)
	s_barrier
	s_waitcnt lgkmcnt(0)
	s_waitcnt lgkmcnt(0)
	v_mfma_f32_16x16x32_bf16 v[120:123], v[146:149], v[162:165], v[120:123]
	v_mfma_f32_16x16x32_bf16 v[120:123], v[150:153], v[166:169], v[120:123]
	v_mfma_f32_16x16x32_bf16 v[124:127], v[158:161], v[166:169], v[124:127]
	v_mfma_f32_16x16x32_bf16 v[124:127], v[154:157], v[162:165], v[124:127]
	v_mfma_f32_16x16x32_bf16 v[104:107], v[154:157], v[170:173], v[104:107]
	v_mfma_f32_16x16x32_bf16 v[104:107], v[158:161], v[174:177], v[104:107]
	v_mfma_f32_16x16x32_bf16 v[108:111], v[150:153], v[174:177], v[108:111]
	v_mfma_f32_16x16x32_bf16 v[108:111], v[146:149], v[170:173], v[108:111]
	v_mfma_f32_16x16x32_bf16 v[92:95], v[146:149], v[178:181], v[92:95]
	v_mfma_f32_16x16x32_bf16 v[92:95], v[150:153], v[182:185], v[92:95]
	v_mfma_f32_16x16x32_bf16 v[88:91], v[158:161], v[182:185], v[88:91]
	v_mfma_f32_16x16x32_bf16 v[88:91], v[154:157], v[178:181], v[88:91]
	v_mfma_f32_16x16x32_bf16 v[72:75], v[154:157], v[186:189], v[72:75]
	v_mfma_f32_16x16x32_bf16 v[72:75], v[158:161], v[190:193], v[72:75]
	v_mfma_f32_16x16x32_bf16 v[76:79], v[150:153], v[190:193], v[76:79]
	v_mfma_f32_16x16x32_bf16 v[76:79], v[146:149], v[186:189], v[76:79]
	s_barrier
	s_add_i32 vcc_lo, 16, 0x1c000
	s_add_i32 s2, s93, s68
	v_add_u32_e32 v206, vcc_lo, v141
	v_lshl_add_u64 v[210:211], v[210:211], 0, s[0:1]
	s_mov_b32 m0, s2
	ds_read_b128 v[194:197], v206
	ds_read_b128 v[198:201], v206 offset:1024
	ds_read_b128 v[202:205], v206 offset:2048
	ds_read_b128 v[206:209], v206 offset:3072
	global_load_lds_dwordx4 v[210:211], off
	v_lshl_add_u64 v[210:211], v[212:213], 0, s[0:1]
	s_add_i32 m0, s2, 0x2000
	s_nop 0
	global_load_lds_dwordx4 v[210:211], off
	s_barrier
; #define PG8_STAGE(bufoff, gbase, voff) do { _Pragma("unroll") for (int _i = 0; _i < 2; ++_i) \
;         __builtin_amdgcn_global_load_lds((const unsigned*)((const char*)(gbase) + (voff)[_i]), (LAS unsigned*)(lds + (bufoff) + ldsw + _i * 8192), 16, 0, 0); } while (0)
; #define PG8_LDA(dst, b, h) do { _Pragma("unroll") for (int m = 0; m < 4; ++m) _Pragma("unroll") for (int k = 0; k < 2; ++k) dst[m][k] = *(const LAS bf16x8*)(lds + PG8_SA(b, h) + aoff + m * 2048 + k * 1024); } while (0)
; #define PG8_LDB(dst, b, h) do { _Pragma("unroll") for (int n = 0; n < 2; ++n) _Pragma("unroll") for (int k = 0; k < 2; ++k) dst[n][k] = *(const LAS bf16x8*)(lds + PG8_SB(b, h) + boff + n * 2048 + k * 1024); } while (0)
; #define PG8_MMA(ai, bj, At, Bt) do { __builtin_amdgcn_s_setprio(1); _Pragma("unroll") for (int m = 0; m < 4; ++m) _Pragma("unroll") for (int n = 0; n < 2; ++n) _Pragma("unroll") for (int k = 0; k < 2; ++k) \
;         acc[ai][bj][m][n] = __builtin_amdgcn_mfma_f32_16x16x32_bf16(Bt[n][k], At[m][k], acc[ai][bj][m][n], 0, 0, 0); __builtin_amdgcn_s_setprio(0); } while (0)
; #define PG8_WAIT_V(n) asm volatile("s_waitcnt vmcnt(" #n ")" ::: "memory")
; #define PG8_WAIT_L(n) asm volatile("s_waitcnt lgkmcnt(" #n ")" ::: "memory")
; #define PG8_BAR __builtin_amdgcn_s_barrier()
; #define PG8_SCHED __builtin_amdgcn_sched_barrier(0)
; template <class Epi>
; DEVINL void gemm_phase(LAS unsigned char* lds, const Gemm g, const Order& S, const Epi& E) {
;     ...
;         for (int t = 0; t < nt; t += 2) {
;     ...
;             PG8_LDB(B1, 1, 1); PG8_STAGE(PG8_SB(1, 0), b3, voffB);
;             PG8_BAR; PG8_WAIT_L(0); PG8_MMA(0, 1, At, B1); PG8_BAR;
;             PG8_LDA(At, 1, 1); PG8_STAGE(PG8_SA(1, 0), a3, voffA);
;             PG8_BAR; PG8_WAIT_L(0); PG8_MMA(1, 0, At, B0); PG8_BAR; PG8_SCHED;
;             PG8_STAGE(PG8_SB(1, 1), b3 + hstepB, voffB);
;             PG8_WAIT_V(6); PG8_BAR; PG8_MMA(1, 1, At, B1); PG8_BAR;
	s_waitcnt lgkmcnt(0)
	s_waitcnt lgkmcnt(0)
	v_mfma_f32_16x16x32_bf16 v[116:119], v[194:197], v[162:165], v[116:119]
	v_mfma_f32_16x16x32_bf16 v[116:119], v[198:201], v[166:169], v[116:119]
	v_mfma_f32_16x16x32_bf16 v[112:115], v[206:209], v[166:169], v[112:115]
	v_mfma_f32_16x16x32_bf16 v[112:115], v[202:205], v[162:165], v[112:115]
	v_mfma_f32_16x16x32_bf16 v[96:99], v[202:205], v[170:173], v[96:99]
	v_mfma_f32_16x16x32_bf16 v[96:99], v[206:209], v[174:177], v[96:99]
	v_mfma_f32_16x16x32_bf16 v[100:103], v[198:201], v[174:177], v[100:103]
	v_mfma_f32_16x16x32_bf16 v[100:103], v[194:197], v[170:173], v[100:103]
	v_mfma_f32_16x16x32_bf16 v[84:87], v[194:197], v[178:181], v[84:87]
	v_mfma_f32_16x16x32_bf16 v[84:87], v[198:201], v[182:185], v[84:87]
	v_mfma_f32_16x16x32_bf16 v[80:83], v[206:209], v[182:185], v[80:83]
	v_mfma_f32_16x16x32_bf16 v[80:83], v[202:205], v[178:181], v[80:83]
	v_mfma_f32_16x16x32_bf16 v[64:67], v[202:205], v[186:189], v[64:67]
	v_mfma_f32_16x16x32_bf16 v[64:67], v[206:209], v[190:193], v[64:67]
	v_mfma_f32_16x16x32_bf16 v[68:71], v[198:201], v[190:193], v[68:71]
	v_mfma_f32_16x16x32_bf16 v[68:71], v[194:197], v[186:189], v[68:71]
	s_mov_b32 m0, s76
	v_lshl_add_u64 v[210:211], v[218:219], 0, s[0:1]
	s_barrier
	ds_read_b128 v[162:165], v144 offset:49152
	ds_read_b128 v[166:169], v144 offset:50176
	ds_read_b128 v[170:173], v144 offset:51200
	ds_read_b128 v[174:177], v144 offset:52224
	ds_read_b128 v[178:181], v144 offset:53248
	ds_read_b128 v[182:185], v144 offset:54272
	ds_read_b128 v[186:189], v144 offset:55296
	ds_read_b128 v[190:193], v144 offset:56320
	global_load_lds_dwordx4 v[210:211], off
	v_lshl_add_u64 v[210:211], v[220:221], 0, s[0:1]
	s_mov_b32 m0, s77
	s_nop 0
	global_load_lds_dwordx4 v[210:211], off
	s_barrier
	s_waitcnt lgkmcnt(0)
	s_waitcnt lgkmcnt(0)
	v_mfma_f32_16x16x32_bf16 v[60:63], v[146:149], v[162:165], v[60:63]
	v_mfma_f32_16x16x32_bf16 v[60:63], v[150:153], v[166:169], v[60:63]
	v_mfma_f32_16x16x32_bf16 v[56:59], v[158:161], v[166:169], v[56:59]
	v_mfma_f32_16x16x32_bf16 v[56:59], v[154:157], v[162:165], v[56:59]
	v_mfma_f32_16x16x32_bf16 v[40:43], v[154:157], v[170:173], v[40:43]
	v_mfma_f32_16x16x32_bf16 v[40:43], v[158:161], v[174:177], v[40:43]
	v_mfma_f32_16x16x32_bf16 v[44:47], v[150:153], v[174:177], v[44:47]
	v_mfma_f32_16x16x32_bf16 v[44:47], v[146:149], v[170:173], v[44:47]
	v_mfma_f32_16x16x32_bf16 v[28:31], v[146:149], v[178:181], v[28:31]
	v_mfma_f32_16x16x32_bf16 v[28:31], v[150:153], v[182:185], v[28:31]
	v_mfma_f32_16x16x32_bf16 v[24:27], v[158:161], v[182:185], v[24:27]
	v_mfma_f32_16x16x32_bf16 v[24:27], v[154:157], v[178:181], v[24:27]
	v_mfma_f32_16x16x32_bf16 v[8:11], v[154:157], v[186:189], v[8:11]
	v_mfma_f32_16x16x32_bf16 v[8:11], v[158:161], v[190:193], v[8:11]
	v_mfma_f32_16x16x32_bf16 v[12:15], v[150:153], v[190:193], v[12:15]
	v_mfma_f32_16x16x32_bf16 v[12:15], v[146:149], v[186:189], v[12:15]
	s_barrier
	s_add_u32 s2, s12, 0x80080
	s_addc_u32 s3, s13, 0
	s_add_i32 s12, vcc_lo, s68
	v_lshl_add_u64 v[146:147], s[2:3], 0, v[130:131]
	s_mov_b32 m0, s12
	s_nop 0
	global_load_lds_dwordx4 v[146:147], off
	v_lshl_add_u64 v[146:147], s[2:3], 0, v[134:135]
	s_add_i32 m0, s12, 0x2000
	s_nop 0
	global_load_lds_dwordx4 v[146:147], off
	s_waitcnt vmcnt(6)
	s_barrier
	v_mfma_f32_16x16x32_bf16 v[52:55], v[194:197], v[162:165], v[52:55]
	v_mfma_f32_16x16x32_bf16 v[52:55], v[198:201], v[166:169], v[52:55]
	v_mfma_f32_16x16x32_bf16 v[48:51], v[206:209], v[166:169], v[48:51]
	v_mfma_f32_16x16x32_bf16 v[48:51], v[202:205], v[162:165], v[48:51]
	v_mfma_f32_16x16x32_bf16 v[32:35], v[202:205], v[170:173], v[32:35]
	v_mfma_f32_16x16x32_bf16 v[32:35], v[206:209], v[174:177], v[32:35]
	v_mfma_f32_16x16x32_bf16 v[36:39], v[198:201], v[174:177], v[36:39]
	v_mfma_f32_16x16x32_bf16 v[36:39], v[194:197], v[170:173], v[36:39]
	v_mfma_f32_16x16x32_bf16 v[20:23], v[194:197], v[178:181], v[20:23]
	v_mfma_f32_16x16x32_bf16 v[20:23], v[198:201], v[182:185], v[20:23]
	v_mfma_f32_16x16x32_bf16 v[16:19], v[206:209], v[182:185], v[16:19]
	v_mfma_f32_16x16x32_bf16 v[16:19], v[202:205], v[178:181], v[16:19]
	v_mfma_f32_16x16x32_bf16 v[0:3], v[202:205], v[186:189], v[0:3]
	v_mfma_f32_16x16x32_bf16 v[0:3], v[206:209], v[190:193], v[0:3]
	v_mfma_f32_16x16x32_bf16 v[4:7], v[198:201], v[190:193], v[4:7]
	v_mfma_f32_16x16x32_bf16 v[4:7], v[194:197], v[186:189], v[4:7]
	s_add_u32 s14, s14, 0x100
	s_addc_u32 s15, s15, 0
	s_add_u32 s85, s85, 0x100
	s_addc_u32 s86, s86, 0
	s_cmp_ge_i32 s87, s75
	s_mov_b32 s12, s87
	s_barrier
	s_cbranch_scc0 .LBB0_382
	s_branch .LBB0_373

; #define PG8_STAGE(bufoff, gbase, voff) do { _Pragma("unroll") for (int _i = 0; _i < 2; ++_i) \
;         __builtin_amdgcn_global_load_lds((const unsigned*)((const char*)(gbase) + (voff)[_i]), (LAS unsigned*)(lds + (bufoff) + ldsw + _i * 8192), 16, 0, 0); } while (0)
; #define PG8_LDA(dst, b, h) do { _Pragma("unroll") for (int m = 0; m < 4; ++m) _Pragma("unroll") for (int k = 0; k < 2; ++k) dst[m][k] = *(const LAS bf16x8*)(lds + PG8_SA(b, h) + aoff + m * 2048 + k * 1024); } while (0)
; #define PG8_LDB(dst, b, h) do { _Pragma("unroll") for (int n = 0; n < 2; ++n) _Pragma("unroll") for (int k = 0; k < 2; ++k) dst[n][k] = *(const LAS bf16x8*)(lds + PG8_SB(b, h) + boff + n * 2048 + k * 1024); } while (0)
; #define PG8_MMA(ai, bj, At, Bt) do { __builtin_amdgcn_s_setprio(1); _Pragma("unroll") for (int m = 0; m < 4; ++m) _Pragma("unroll") for (int n = 0; n < 2; ++n) _Pragma("unroll") for (int k = 0; k < 2; ++k) \
;         acc[ai][bj][m][n] = __builtin_amdgcn_mfma_f32_16x16x32_bf16(Bt[n][k], At[m][k], acc[ai][bj][m][n], 0, 0, 0); __builtin_amdgcn_s_setprio(0); } while (0)
; #define PG8_WAIT_L(n) asm volatile("s_waitcnt lgkmcnt(" #n ")" ::: "memory")
; #define PG8_BAR __builtin_amdgcn_s_barrier()
; #define PG8_SCHED __builtin_amdgcn_sched_barrier(0)
; template <class Epi>
; DEVINL void gemm_phase(LAS unsigned char* lds, const Gemm g, const Order& S, const Epi& E) {
;     ...
;             const char* a1 = cA + (size_t)(t + 1) * kstep;
;             const char* a2 = last ? nA : cA + (size_t)(t + 2) * kstep; const char* b2 = last ? nB : cB + (size_t)(t + 2) * kstep;
;             const char* a3 = a2 + kstep; const char* b3 = b2 + kstep;
;             PG8_LDB(B0, 0, 0); PG8_SCHED; PG8_LDA(At, 0, 0); PG8_STAGE(PG8_SA(1, 1), a1 + hstepA, voffA);
;             PG8_WAIT_L(8); PG8_BAR; PG8_WAIT_L(0); PG8_MMA(0, 0, At, B0); PG8_BAR; PG8_SCHED;
;             PG8_LDB(B1, 0, 1); PG8_STAGE(PG8_SB(0, 0), b2, voffB);
;             PG8_BAR; PG8_WAIT_L(0); PG8_MMA(0, 1, At, B1); PG8_BAR;
;             PG8_LDA(At, 0, 1); PG8_STAGE(PG8_SA(0, 0), a2, voffA);
;             PG8_BAR; PG8_WAIT_L(0); PG8_MMA(1, 0, At, B0); PG8_BAR; PG8_SCHED;
.LBB0_459:
	ds_read_b128 v[150:153], v147
	ds_read_b128 v[154:157], v147 offset:1024
	ds_read_b128 v[158:161], v147 offset:2048
	ds_read_b128 v[162:165], v147 offset:3072
	s_add_i32 s85, s14, 2
	s_add_u32 s10, s12, 0x100
	s_addc_u32 s11, s13, 0
	s_cmp_eq_u32 s74, s14
	s_cselect_b32 s14, s4, s83
	s_cselect_b32 s65, s9, s11
	s_cselect_b32 s64, s8, s10
	s_cselect_b32 s15, s5, s84
	v_lshl_add_u64 v[198:199], s[12:13], 0, v[136:137]
	s_add_i32 m0, s38, 0xc000
	ds_read_b128 v[166:169], v148
	ds_read_b128 v[170:173], v148 offset:1024
	ds_read_b128 v[174:177], v148 offset:2048
	ds_read_b128 v[178:181], v148 offset:3072
	ds_read_b128 v[182:185], v148 offset:4096
	ds_read_b128 v[186:189], v148 offset:5120
	ds_read_b128 v[190:193], v148 offset:6144
	ds_read_b128 v[194:197], v148 offset:7168
	global_load_lds_dwordx4 v[198:199], off
	v_lshl_add_u64 v[198:199], s[12:13], 0, v[138:139]
	s_add_i32 m0, s38, 0xe000
	s_nop 0
	global_load_lds_dwordx4 v[198:199], off
	s_waitcnt lgkmcnt(8)
	s_barrier
	s_waitcnt lgkmcnt(0)
	s_waitcnt lgkmcnt(0)
	v_mfma_f32_16x16x32_bf16 v[120:123], v[150:153], v[166:169], v[120:123]
	v_mfma_f32_16x16x32_bf16 v[120:123], v[154:157], v[170:173], v[120:123]
	v_mfma_f32_16x16x32_bf16 v[124:127], v[162:165], v[170:173], v[124:127]
	v_mfma_f32_16x16x32_bf16 v[124:127], v[158:161], v[166:169], v[124:127]
	v_mfma_f32_16x16x32_bf16 v[104:107], v[158:161], v[174:177], v[104:107]
	v_mfma_f32_16x16x32_bf16 v[104:107], v[162:165], v[178:181], v[104:107]
	v_mfma_f32_16x16x32_bf16 v[108:111], v[154:157], v[178:181], v[108:111]
	v_mfma_f32_16x16x32_bf16 v[108:111], v[150:153], v[174:177], v[108:111]
	v_mfma_f32_16x16x32_bf16 v[92:95], v[150:153], v[182:185], v[92:95]
	v_mfma_f32_16x16x32_bf16 v[92:95], v[154:157], v[186:189], v[92:95]
	v_mfma_f32_16x16x32_bf16 v[88:91], v[162:165], v[186:189], v[88:91]
	v_mfma_f32_16x16x32_bf16 v[88:91], v[158:161], v[182:185], v[88:91]
	v_mfma_f32_16x16x32_bf16 v[72:75], v[158:161], v[190:193], v[72:75]
	v_mfma_f32_16x16x32_bf16 v[72:75], v[162:165], v[194:197], v[72:75]
	v_mfma_f32_16x16x32_bf16 v[76:79], v[154:157], v[194:197], v[76:79]
	v_mfma_f32_16x16x32_bf16 v[76:79], v[150:153], v[190:193], v[76:79]
	s_barrier
	s_add_i32 s2, s78, s37
	v_lshl_add_u64 v[218:219], s[14:15], 0, v[130:131]
	s_mov_b32 m0, s2
	ds_read_b128 v[198:201], v149
	ds_read_b128 v[202:205], v149 offset:1024
	ds_read_b128 v[206:209], v149 offset:2048
	ds_read_b128 v[210:213], v149 offset:3072
	global_load_lds_dwordx4 v[218:219], off
	v_lshl_add_u64 v[220:221], s[14:15], 0, v[134:135]
	s_add_i32 m0, s2, 0x2000
	s_nop 0
	global_load_lds_dwordx4 v[220:221], off
	s_barrier
	s_waitcnt lgkmcnt(0)
	s_waitcnt lgkmcnt(0)
	v_mfma_f32_16x16x32_bf16 v[116:119], v[198:201], v[166:169], v[116:119]
	v_mfma_f32_16x16x32_bf16 v[116:119], v[202:205], v[170:173], v[116:119]
	v_mfma_f32_16x16x32_bf16 v[112:115], v[210:213], v[170:173], v[112:115]
	v_mfma_f32_16x16x32_bf16 v[112:115], v[206:209], v[166:169], v[112:115]
	v_mfma_f32_16x16x32_bf16 v[96:99], v[206:209], v[174:177], v[96:99]
	v_mfma_f32_16x16x32_bf16 v[96:99], v[210:213], v[178:181], v[96:99]
	v_mfma_f32_16x16x32_bf16 v[100:103], v[202:205], v[178:181], v[100:103]
	v_mfma_f32_16x16x32_bf16 v[100:103], v[198:201], v[174:177], v[100:103]
	v_mfma_f32_16x16x32_bf16 v[84:87], v[198:201], v[182:185], v[84:87]
	v_mfma_f32_16x16x32_bf16 v[84:87], v[202:205], v[186:189], v[84:87]
	v_mfma_f32_16x16x32_bf16 v[80:83], v[210:213], v[186:189], v[80:83]
	v_mfma_f32_16x16x32_bf16 v[80:83], v[206:209], v[182:185], v[80:83]
	v_mfma_f32_16x16x32_bf16 v[64:67], v[206:209], v[190:193], v[64:67]
	v_mfma_f32_16x16x32_bf16 v[64:67], v[210:213], v[194:197], v[64:67]
	v_mfma_f32_16x16x32_bf16 v[68:71], v[202:205], v[194:197], v[68:71]
	v_mfma_f32_16x16x32_bf16 v[68:71], v[198:201], v[190:193], v[68:71]
	s_mov_b32 m0, s38
	v_lshl_add_u64 v[222:223], s[64:65], 0, v[128:129]
	s_barrier
	ds_read_b128 v[166:169], v148 offset:16384
	ds_read_b128 v[170:173], v148 offset:17408
	ds_read_b128 v[174:177], v148 offset:18432
	ds_read_b128 v[178:181], v148 offset:19456
	ds_read_b128 v[182:185], v148 offset:20480
	ds_read_b128 v[186:189], v148 offset:21504
	ds_read_b128 v[190:193], v148 offset:22528
	ds_read_b128 v[194:197], v148 offset:23552
	global_load_lds_dwordx4 v[222:223], off
	v_lshl_add_u64 v[224:225], s[64:65], 0, v[132:133]
	s_mov_b32 m0, s39
	s_nop 0
	global_load_lds_dwordx4 v[224:225], off
	s_barrier
	s_waitcnt lgkmcnt(0)
	s_waitcnt lgkmcnt(0)
	v_mfma_f32_16x16x32_bf16 v[60:63], v[150:153], v[166:169], v[60:63]
	v_mfma_f32_16x16x32_bf16 v[60:63], v[154:157], v[170:173], v[60:63]
	v_mfma_f32_16x16x32_bf16 v[56:59], v[162:165], v[170:173], v[56:59]
	v_mfma_f32_16x16x32_bf16 v[56:59], v[158:161], v[166:169], v[56:59]
	v_mfma_f32_16x16x32_bf16 v[40:43], v[158:161], v[174:177], v[40:43]
	v_mfma_f32_16x16x32_bf16 v[40:43], v[162:165], v[178:181], v[40:43]
	v_mfma_f32_16x16x32_bf16 v[44:47], v[154:157], v[178:181], v[44:47]
	v_mfma_f32_16x16x32_bf16 v[44:47], v[150:153], v[174:177], v[44:47]
	v_mfma_f32_16x16x32_bf16 v[28:31], v[150:153], v[182:185], v[28:31]
	v_mfma_f32_16x16x32_bf16 v[28:31], v[154:157], v[186:189], v[28:31]
	v_mfma_f32_16x16x32_bf16 v[24:27], v[162:165], v[186:189], v[24:27]
	v_mfma_f32_16x16x32_bf16 v[24:27], v[158:161], v[182:185], v[24:27]
	v_mfma_f32_16x16x32_bf16 v[8:11], v[158:161], v[190:193], v[8:11]
	v_mfma_f32_16x16x32_bf16 v[8:11], v[162:165], v[194:197], v[8:11]
	v_mfma_f32_16x16x32_bf16 v[12:15], v[154:157], v[194:197], v[12:15]
	v_mfma_f32_16x16x32_bf16 v[12:15], v[150:153], v[190:193], v[12:15]
	s_barrier
; #define PG8_STAGE(bufoff, gbase, voff) do { _Pragma("unroll") for (int _i = 0; _i < 2; ++_i) \
;         __builtin_amdgcn_global_load_lds((const unsigned*)((const char*)(gbase) + (voff)[_i]), (LAS unsigned*)(lds + (bufoff) + ldsw + _i * 8192), 16, 0, 0); } while (0)
; #define PG8_LDA(dst, b, h) do { _Pragma("unroll") for (int m = 0; m < 4; ++m) _Pragma("unroll") for (int k = 0; k < 2; ++k) dst[m][k] = *(const LAS bf16x8*)(lds + PG8_SA(b, h) + aoff + m * 2048 + k * 1024); } while (0)
; #define PG8_LDB(dst, b, h) do { _Pragma("unroll") for (int n = 0; n < 2; ++n) _Pragma("unroll") for (int k = 0; k < 2; ++k) dst[n][k] = *(const LAS bf16x8*)(lds + PG8_SB(b, h) + boff + n * 2048 + k * 1024); } while (0)
; #define PG8_MMA(ai, bj, At, Bt) do { __builtin_amdgcn_s_setprio(1); _Pragma("unroll") for (int m = 0; m < 4; ++m) _Pragma("unroll") for (int n = 0; n < 2; ++n) _Pragma("unroll") for (int k = 0; k < 2; ++k) \
;         acc[ai][bj][m][n] = __builtin_amdgcn_mfma_f32_16x16x32_bf16(Bt[n][k], At[m][k], acc[ai][bj][m][n], 0, 0, 0); __builtin_amdgcn_s_setprio(0); } while (0)
; #define PG8_WAIT_V(n) asm volatile("s_waitcnt vmcnt(" #n ")" ::: "memory")
; #define PG8_WAIT_L(n) asm volatile("s_waitcnt lgkmcnt(" #n ")" ::: "memory")
; #define PG8_BAR __builtin_amdgcn_s_barrier()
; #define PG8_SCHED __builtin_amdgcn_sched_barrier(0)
; template <class Epi>
; DEVINL void gemm_phase(LAS unsigned char* lds, const Gemm g, const Order& S, const Epi& E) {
;     ...
;             PG8_STAGE(PG8_SB(0, 1), b2 + hstepB, voffB);
;             PG8_WAIT_V(6); PG8_BAR; PG8_MMA(1, 1, At, B1); PG8_BAR;
;             PG8_LDB(B0, 1, 0); PG8_SCHED; PG8_LDA(At, 1, 0); PG8_STAGE(PG8_SA(0, 1), a2 + hstepA, voffA);
;             PG8_WAIT_L(8); PG8_BAR; PG8_WAIT_L(0); PG8_MMA(0, 0, At, B0); PG8_BAR; PG8_SCHED;
;             PG8_LDB(B1, 1, 1); PG8_STAGE(PG8_SB(1, 0), b3, voffB);
	s_add_u32 s2, s14, 0x158000
	s_addc_u32 s3, s15, 0
	s_add_i32 s12, s79, s37
	v_lshl_add_u64 v[150:151], s[2:3], 0, v[130:131]
	s_mov_b32 m0, s12
	s_nop 0
	global_load_lds_dwordx4 v[150:151], off
	v_lshl_add_u64 v[150:151], s[2:3], 0, v[134:135]
	s_add_i32 m0, s12, 0x2000
	s_nop 0
	global_load_lds_dwordx4 v[150:151], off
	s_waitcnt vmcnt(6)
	s_barrier
	v_mfma_f32_16x16x32_bf16 v[52:55], v[198:201], v[166:169], v[52:55]
	v_mfma_f32_16x16x32_bf16 v[52:55], v[202:205], v[170:173], v[52:55]
	v_mfma_f32_16x16x32_bf16 v[48:51], v[210:213], v[170:173], v[48:51]
	v_mfma_f32_16x16x32_bf16 v[48:51], v[206:209], v[166:169], v[48:51]
	v_mfma_f32_16x16x32_bf16 v[32:35], v[206:209], v[174:177], v[32:35]
	v_mfma_f32_16x16x32_bf16 v[32:35], v[210:213], v[178:181], v[32:35]
	v_mfma_f32_16x16x32_bf16 v[36:39], v[202:205], v[178:181], v[36:39]
	v_mfma_f32_16x16x32_bf16 v[36:39], v[198:201], v[174:177], v[36:39]
	v_mfma_f32_16x16x32_bf16 v[20:23], v[198:201], v[182:185], v[20:23]
	v_mfma_f32_16x16x32_bf16 v[20:23], v[202:205], v[186:189], v[20:23]
	v_mfma_f32_16x16x32_bf16 v[16:19], v[210:213], v[186:189], v[16:19]
	v_mfma_f32_16x16x32_bf16 v[16:19], v[206:209], v[182:185], v[16:19]
	v_mfma_f32_16x16x32_bf16 v[0:3], v[206:209], v[190:193], v[0:3]
	v_mfma_f32_16x16x32_bf16 v[0:3], v[210:213], v[194:197], v[0:3]
	v_mfma_f32_16x16x32_bf16 v[4:7], v[202:205], v[194:197], v[4:7]
	v_mfma_f32_16x16x32_bf16 v[4:7], v[198:201], v[190:193], v[4:7]
	s_add_i32 s12, 16, 0x18000
	v_add_u32_e32 v162, s12, v145
	s_barrier
	ds_read_b128 v[150:153], v162
	ds_read_b128 v[154:157], v162 offset:1024
	ds_read_b128 v[158:161], v162 offset:2048
	ds_read_b128 v[162:165], v162 offset:3072
	s_add_u32 s2, s64, 0x158000
	s_addc_u32 s3, s65, 0
	s_mov_b32 m0, s66
	v_lshl_add_u64 v[198:199], s[2:3], 0, v[128:129]
	ds_read_b128 v[166:169], v148 offset:32768
	ds_read_b128 v[170:173], v148 offset:33792
	ds_read_b128 v[174:177], v148 offset:34816
	ds_read_b128 v[178:181], v148 offset:35840
	ds_read_b128 v[182:185], v148 offset:36864
	ds_read_b128 v[186:189], v148 offset:37888
	ds_read_b128 v[190:193], v148 offset:38912
	ds_read_b128 v[194:197], v148 offset:39936
	global_load_lds_dwordx4 v[198:199], off
	v_lshl_add_u64 v[198:199], s[2:3], 0, v[132:133]
	s_mov_b32 m0, s67
	s_nop 0
	global_load_lds_dwordx4 v[198:199], off
	s_waitcnt lgkmcnt(8)
	s_barrier
	s_waitcnt lgkmcnt(0)
	s_waitcnt lgkmcnt(0)
	v_mfma_f32_16x16x32_bf16 v[120:123], v[150:153], v[166:169], v[120:123]
	v_mfma_f32_16x16x32_bf16 v[120:123], v[154:157], v[170:173], v[120:123]
	v_mfma_f32_16x16x32_bf16 v[124:127], v[162:165], v[170:173], v[124:127]
	v_mfma_f32_16x16x32_bf16 v[124:127], v[158:161], v[166:169], v[124:127]
	v_mfma_f32_16x16x32_bf16 v[104:107], v[158:161], v[174:177], v[104:107]
	v_mfma_f32_16x16x32_bf16 v[104:107], v[162:165], v[178:181], v[104:107]
	v_mfma_f32_16x16x32_bf16 v[108:111], v[154:157], v[178:181], v[108:111]
	v_mfma_f32_16x16x32_bf16 v[108:111], v[150:153], v[174:177], v[108:111]
	v_mfma_f32_16x16x32_bf16 v[92:95], v[150:153], v[182:185], v[92:95]
	v_mfma_f32_16x16x32_bf16 v[92:95], v[154:157], v[186:189], v[92:95]
	v_mfma_f32_16x16x32_bf16 v[88:91], v[162:165], v[186:189], v[88:91]
	v_mfma_f32_16x16x32_bf16 v[88:91], v[158:161], v[182:185], v[88:91]
	v_mfma_f32_16x16x32_bf16 v[72:75], v[158:161], v[190:193], v[72:75]
	v_mfma_f32_16x16x32_bf16 v[72:75], v[162:165], v[194:197], v[72:75]
	v_mfma_f32_16x16x32_bf16 v[76:79], v[154:157], v[194:197], v[76:79]
	v_mfma_f32_16x16x32_bf16 v[76:79], v[150:153], v[190:193], v[76:79]
	s_barrier
	s_add_i32 s13, 16, 0x1c000
	s_add_i32 s2, s12, s37
	v_add_u32_e32 v210, s13, v145
	v_lshl_add_u64 v[218:219], v[218:219], 0, s[6:7]
	s_mov_b32 m0, s2
	ds_read_b128 v[198:201], v210
	ds_read_b128 v[202:205], v210 offset:1024
	ds_read_b128 v[206:209], v210 offset:2048
	ds_read_b128 v[210:213], v210 offset:3072
	global_load_lds_dwordx4 v[218:219], off
	v_lshl_add_u64 v[218:219], v[220:221], 0, s[6:7]
	s_add_i32 m0, s2, 0x2000
	s_nop 0
	global_load_lds_dwordx4 v[218:219], off
	s_barrier
; #define PG8_STAGE(bufoff, gbase, voff) do { _Pragma("unroll") for (int _i = 0; _i < 2; ++_i) \
;         __builtin_amdgcn_global_load_lds((const unsigned*)((const char*)(gbase) + (voff)[_i]), (LAS unsigned*)(lds + (bufoff) + ldsw + _i * 8192), 16, 0, 0); } while (0)
; #define PG8_LDA(dst, b, h) do { _Pragma("unroll") for (int m = 0; m < 4; ++m) _Pragma("unroll") for (int k = 0; k < 2; ++k) dst[m][k] = *(const LAS bf16x8*)(lds + PG8_SA(b, h) + aoff + m * 2048 + k * 1024); } while (0)
; #define PG8_LDB(dst, b, h) do { _Pragma("unroll") for (int n = 0; n < 2; ++n) _Pragma("unroll") for (int k = 0; k < 2; ++k) dst[n][k] = *(const LAS bf16x8*)(lds + PG8_SB(b, h) + boff + n * 2048 + k * 1024); } while (0)
; #define PG8_MMA(ai, bj, At, Bt) do { __builtin_amdgcn_s_setprio(1); _Pragma("unroll") for (int m = 0; m < 4; ++m) _Pragma("unroll") for (int n = 0; n < 2; ++n) _Pragma("unroll") for (int k = 0; k < 2; ++k) \
;         acc[ai][bj][m][n] = __builtin_amdgcn_mfma_f32_16x16x32_bf16(Bt[n][k], At[m][k], acc[ai][bj][m][n], 0, 0, 0); __builtin_amdgcn_s_setprio(0); } while (0)
; #define PG8_WAIT_V(n) asm volatile("s_waitcnt vmcnt(" #n ")" ::: "memory")
; #define PG8_WAIT_L(n) asm volatile("s_waitcnt lgkmcnt(" #n ")" ::: "memory")
; #define PG8_BAR __builtin_amdgcn_s_barrier()
; #define PG8_SCHED __builtin_amdgcn_sched_barrier(0)
; template <class Epi>
; DEVINL void gemm_phase(LAS unsigned char* lds, const Gemm g, const Order& S, const Epi& E) {
;     ...
;         for (int t = 0; t < nt; t += 2) {
;     ...
;             PG8_LDB(B1, 1, 1); PG8_STAGE(PG8_SB(1, 0), b3, voffB);
;             PG8_BAR; PG8_WAIT_L(0); PG8_MMA(0, 1, At, B1); PG8_BAR;
;             PG8_LDA(At, 1, 1); PG8_STAGE(PG8_SA(1, 0), a3, voffA);
;             PG8_BAR; PG8_WAIT_L(0); PG8_MMA(1, 0, At, B0); PG8_BAR; PG8_SCHED;
;             PG8_STAGE(PG8_SB(1, 1), b3 + hstepB, voffB);
;             PG8_WAIT_V(6); PG8_BAR; PG8_MMA(1, 1, At, B1); PG8_BAR;
	s_waitcnt lgkmcnt(0)
	s_waitcnt lgkmcnt(0)
	v_mfma_f32_16x16x32_bf16 v[116:119], v[198:201], v[166:169], v[116:119]
	v_mfma_f32_16x16x32_bf16 v[116:119], v[202:205], v[170:173], v[116:119]
	v_mfma_f32_16x16x32_bf16 v[112:115], v[210:213], v[170:173], v[112:115]
	v_mfma_f32_16x16x32_bf16 v[112:115], v[206:209], v[166:169], v[112:115]
	v_mfma_f32_16x16x32_bf16 v[96:99], v[206:209], v[174:177], v[96:99]
	v_mfma_f32_16x16x32_bf16 v[96:99], v[210:213], v[178:181], v[96:99]
	v_mfma_f32_16x16x32_bf16 v[100:103], v[202:205], v[178:181], v[100:103]
	v_mfma_f32_16x16x32_bf16 v[100:103], v[198:201], v[174:177], v[100:103]
	v_mfma_f32_16x16x32_bf16 v[84:87], v[198:201], v[182:185], v[84:87]
	v_mfma_f32_16x16x32_bf16 v[84:87], v[202:205], v[186:189], v[84:87]
	v_mfma_f32_16x16x32_bf16 v[80:83], v[210:213], v[186:189], v[80:83]
	v_mfma_f32_16x16x32_bf16 v[80:83], v[206:209], v[182:185], v[80:83]
	v_mfma_f32_16x16x32_bf16 v[64:67], v[206:209], v[190:193], v[64:67]
	v_mfma_f32_16x16x32_bf16 v[64:67], v[210:213], v[194:197], v[64:67]
	v_mfma_f32_16x16x32_bf16 v[68:71], v[202:205], v[194:197], v[68:71]
	v_mfma_f32_16x16x32_bf16 v[68:71], v[198:201], v[190:193], v[68:71]
	s_mov_b32 m0, s69
	v_lshl_add_u64 v[218:219], v[222:223], 0, s[6:7]
	s_barrier
	ds_read_b128 v[166:169], v148 offset:49152
	ds_read_b128 v[170:173], v148 offset:50176
	ds_read_b128 v[174:177], v148 offset:51200
	ds_read_b128 v[178:181], v148 offset:52224
	ds_read_b128 v[182:185], v148 offset:53248
	ds_read_b128 v[186:189], v148 offset:54272
	ds_read_b128 v[190:193], v148 offset:55296
	ds_read_b128 v[194:197], v148 offset:56320
	global_load_lds_dwordx4 v[218:219], off
	v_lshl_add_u64 v[218:219], v[224:225], 0, s[6:7]
	s_mov_b32 m0, s72
	s_nop 0
	global_load_lds_dwordx4 v[218:219], off
	s_barrier
	s_waitcnt lgkmcnt(0)
	s_waitcnt lgkmcnt(0)
	v_mfma_f32_16x16x32_bf16 v[60:63], v[150:153], v[166:169], v[60:63]
	v_mfma_f32_16x16x32_bf16 v[60:63], v[154:157], v[170:173], v[60:63]
	v_mfma_f32_16x16x32_bf16 v[56:59], v[162:165], v[170:173], v[56:59]
	v_mfma_f32_16x16x32_bf16 v[56:59], v[158:161], v[166:169], v[56:59]
	v_mfma_f32_16x16x32_bf16 v[40:43], v[158:161], v[174:177], v[40:43]
	v_mfma_f32_16x16x32_bf16 v[40:43], v[162:165], v[178:181], v[40:43]
	v_mfma_f32_16x16x32_bf16 v[44:47], v[154:157], v[178:181], v[44:47]
	v_mfma_f32_16x16x32_bf16 v[44:47], v[150:153], v[174:177], v[44:47]
	v_mfma_f32_16x16x32_bf16 v[28:31], v[150:153], v[182:185], v[28:31]
	v_mfma_f32_16x16x32_bf16 v[28:31], v[154:157], v[186:189], v[28:31]
	v_mfma_f32_16x16x32_bf16 v[24:27], v[162:165], v[186:189], v[24:27]
	v_mfma_f32_16x16x32_bf16 v[24:27], v[158:161], v[182:185], v[24:27]
	v_mfma_f32_16x16x32_bf16 v[8:11], v[158:161], v[190:193], v[8:11]
	v_mfma_f32_16x16x32_bf16 v[8:11], v[162:165], v[194:197], v[8:11]
	v_mfma_f32_16x16x32_bf16 v[12:15], v[154:157], v[194:197], v[12:15]
	v_mfma_f32_16x16x32_bf16 v[12:15], v[150:153], v[190:193], v[12:15]
	s_barrier
	s_add_u32 s2, s14, 0x158080
	s_addc_u32 s3, s15, 0
	s_add_i32 s12, s13, s37
	v_lshl_add_u64 v[150:151], s[2:3], 0, v[130:131]
	s_mov_b32 m0, s12
	s_nop 0
	global_load_lds_dwordx4 v[150:151], off
	v_lshl_add_u64 v[150:151], s[2:3], 0, v[134:135]
	s_add_i32 m0, s12, 0x2000
	s_nop 0
	global_load_lds_dwordx4 v[150:151], off
	s_waitcnt vmcnt(6)
	s_barrier
	v_mfma_f32_16x16x32_bf16 v[52:55], v[198:201], v[166:169], v[52:55]
	v_mfma_f32_16x16x32_bf16 v[52:55], v[202:205], v[170:173], v[52:55]
	v_mfma_f32_16x16x32_bf16 v[48:51], v[210:213], v[170:173], v[48:51]
	v_mfma_f32_16x16x32_bf16 v[48:51], v[206:209], v[166:169], v[48:51]
	v_mfma_f32_16x16x32_bf16 v[32:35], v[206:209], v[174:177], v[32:35]
	v_mfma_f32_16x16x32_bf16 v[32:35], v[210:213], v[178:181], v[32:35]
	v_mfma_f32_16x16x32_bf16 v[36:39], v[202:205], v[178:181], v[36:39]
	v_mfma_f32_16x16x32_bf16 v[36:39], v[198:201], v[174:177], v[36:39]
	v_mfma_f32_16x16x32_bf16 v[20:23], v[198:201], v[182:185], v[20:23]
	v_mfma_f32_16x16x32_bf16 v[20:23], v[202:205], v[186:189], v[20:23]
	v_mfma_f32_16x16x32_bf16 v[16:19], v[210:213], v[186:189], v[16:19]
	v_mfma_f32_16x16x32_bf16 v[16:19], v[206:209], v[182:185], v[16:19]
	v_mfma_f32_16x16x32_bf16 v[0:3], v[206:209], v[190:193], v[0:3]
	v_mfma_f32_16x16x32_bf16 v[0:3], v[210:213], v[194:197], v[0:3]
	v_mfma_f32_16x16x32_bf16 v[4:7], v[202:205], v[194:197], v[4:7]
	v_mfma_f32_16x16x32_bf16 v[4:7], v[198:201], v[190:193], v[4:7]
	s_add_u32 s83, s83, 0x100
	s_addc_u32 s84, s84, 0
	s_cmp_ge_i32 s85, s68
	s_mov_b64 s[12:13], s[10:11]
	s_mov_b32 s14, s85
	s_barrier
	s_cbranch_scc0 .LBB0_459
	s_branch .LBB0_446

; #define PG8_STAGE(bufoff, gbase, voff) do { _Pragma("unroll") for (int _i = 0; _i < 2; ++_i) \
;         __builtin_amdgcn_global_load_lds((const unsigned*)((const char*)(gbase) + (voff)[_i]), (LAS unsigned*)(lds + (bufoff) + ldsw + _i * 8192), 16, 0, 0); } while (0)
; #define PG8_LDA(dst, b, h) do { _Pragma("unroll") for (int m = 0; m < 4; ++m) _Pragma("unroll") for (int k = 0; k < 2; ++k) dst[m][k] = *(const LAS bf16x8*)(lds + PG8_SA(b, h) + aoff + m * 2048 + k * 1024); } while (0)
; #define PG8_LDB(dst, b, h) do { _Pragma("unroll") for (int n = 0; n < 2; ++n) _Pragma("unroll") for (int k = 0; k < 2; ++k) dst[n][k] = *(const LAS bf16x8*)(lds + PG8_SB(b, h) + boff + n * 2048 + k * 1024); } while (0)
; #define PG8_MMA(ai, bj, At, Bt) do { __builtin_amdgcn_s_setprio(1); _Pragma("unroll") for (int m = 0; m < 4; ++m) _Pragma("unroll") for (int n = 0; n < 2; ++n) _Pragma("unroll") for (int k = 0; k < 2; ++k) \
;         acc[ai][bj][m][n] = __builtin_amdgcn_mfma_f32_16x16x32_bf16(Bt[n][k], At[m][k], acc[ai][bj][m][n], 0, 0, 0); __builtin_amdgcn_s_setprio(0); } while (0)
; #define PG8_WAIT_L(n) asm volatile("s_waitcnt lgkmcnt(" #n ")" ::: "memory")
; #define PG8_BAR __builtin_amdgcn_s_barrier()
; #define PG8_SCHED __builtin_amdgcn_sched_barrier(0)
; template <class Epi>
; DEVINL void gemm_phase(LAS unsigned char* lds, const Gemm g, const Order& S, const Epi& E) {
;     ...
;             const char* a1 = cA + (size_t)(t + 1) * kstep;
;             const char* a2 = last ? nA : cA + (size_t)(t + 2) * kstep; const char* b2 = last ? nB : cB + (size_t)(t + 2) * kstep;
;             const char* a3 = a2 + kstep; const char* b3 = b2 + kstep;
;             PG8_LDB(B0, 0, 0); PG8_SCHED; PG8_LDA(At, 0, 0); PG8_STAGE(PG8_SA(1, 1), a1 + hstepA, voffA);
;             PG8_WAIT_L(8); PG8_BAR; PG8_WAIT_L(0); PG8_MMA(0, 0, At, B0); PG8_BAR; PG8_SCHED;
;             PG8_LDB(B1, 0, 1); PG8_STAGE(PG8_SB(0, 0), b2, voffB);
;             PG8_BAR; PG8_WAIT_L(0); PG8_MMA(0, 1, At, B1); PG8_BAR;
;             PG8_LDA(At, 0, 1); PG8_STAGE(PG8_SA(0, 0), a2, voffA);
;             PG8_BAR; PG8_WAIT_L(0); PG8_MMA(1, 0, At, B0); PG8_BAR; PG8_SCHED;
.LBB0_650:
	ds_read_b128 v[128:131], v175
	ds_read_b128 v[132:135], v175 offset:1024
	ds_read_b128 v[136:139], v175 offset:2048
	ds_read_b128 v[140:143], v175 offset:3072
	s_add_i32 s64, s14, 2
	s_add_u32 s2, s12, 0xfff80080
	s_addc_u32 s3, s13, -1
	s_cmp_eq_u32 s49, s14
	s_cselect_b32 s14, s57, s58
	s_cselect_b32 s45, s11, s3
	s_cselect_b32 s44, s17, s2
	s_cselect_b32 s15, s56, s59
	v_lshl_add_u64 v[170:171], s[12:13], 0, v[156:157]
	s_add_i32 m0, s29, 0xc000
	ds_read_b128 v[166:169], v176
	ds_read_b128 v[178:181], v176 offset:1024
	ds_read_b128 v[182:185], v176 offset:2048
	ds_read_b128 v[186:189], v176 offset:3072
	ds_read_b128 v[190:193], v176 offset:4096
	ds_read_b128 v[194:197], v176 offset:5120
	ds_read_b128 v[198:201], v176 offset:6144
	ds_read_b128 v[202:205], v176 offset:7168
	global_load_lds_dwordx4 v[170:171], off
	v_lshl_add_u64 v[170:171], s[12:13], 0, v[158:159]
	s_add_i32 m0, s29, 0xe000
	s_nop 0
	global_load_lds_dwordx4 v[170:171], off
	s_waitcnt lgkmcnt(8)
	s_barrier
	s_waitcnt lgkmcnt(0)
	s_waitcnt lgkmcnt(0)
	v_mfma_f32_16x16x32_bf16 v[124:127], v[128:131], v[166:169], v[124:127]
	v_mfma_f32_16x16x32_bf16 v[124:127], v[132:135], v[178:181], v[124:127]
	v_mfma_f32_16x16x32_bf16 v[120:123], v[140:143], v[178:181], v[120:123]
	v_mfma_f32_16x16x32_bf16 v[120:123], v[136:139], v[166:169], v[120:123]
	v_mfma_f32_16x16x32_bf16 v[104:107], v[136:139], v[182:185], v[104:107]
	v_mfma_f32_16x16x32_bf16 v[104:107], v[140:143], v[186:189], v[104:107]
	v_mfma_f32_16x16x32_bf16 v[108:111], v[132:135], v[186:189], v[108:111]
	v_mfma_f32_16x16x32_bf16 v[108:111], v[128:131], v[182:185], v[108:111]
	v_mfma_f32_16x16x32_bf16 v[92:95], v[128:131], v[190:193], v[92:95]
	v_mfma_f32_16x16x32_bf16 v[92:95], v[132:135], v[194:197], v[92:95]
	v_mfma_f32_16x16x32_bf16 v[88:91], v[140:143], v[194:197], v[88:91]
	v_mfma_f32_16x16x32_bf16 v[88:91], v[136:139], v[190:193], v[88:91]
	v_mfma_f32_16x16x32_bf16 v[72:75], v[136:139], v[198:201], v[72:75]
	v_mfma_f32_16x16x32_bf16 v[72:75], v[140:143], v[202:205], v[72:75]
	v_mfma_f32_16x16x32_bf16 v[76:79], v[132:135], v[202:205], v[76:79]
	v_mfma_f32_16x16x32_bf16 v[76:79], v[128:131], v[198:201], v[76:79]
	s_barrier
	s_add_i32 s2, s52, s26
	v_lshl_add_u64 v[170:171], s[14:15], 0, v[148:149]
	s_mov_b32 m0, s2
	ds_read_b128 v[206:209], v177
	ds_read_b128 v[210:213], v177 offset:1024
	ds_read_b128 v[218:221], v177 offset:2048
	ds_read_b128 v[222:225], v177 offset:3072
	global_load_lds_dwordx4 v[170:171], off
	v_lshl_add_u64 v[226:227], s[14:15], 0, v[144:145]
	s_add_i32 m0, s2, 0x2000
	s_nop 0
	global_load_lds_dwordx4 v[226:227], off
	s_barrier
	s_waitcnt lgkmcnt(0)
	s_waitcnt lgkmcnt(0)
	v_mfma_f32_16x16x32_bf16 v[116:119], v[206:209], v[166:169], v[116:119]
	v_mfma_f32_16x16x32_bf16 v[116:119], v[210:213], v[178:181], v[116:119]
	v_mfma_f32_16x16x32_bf16 v[112:115], v[222:225], v[178:181], v[112:115]
	v_mfma_f32_16x16x32_bf16 v[112:115], v[218:221], v[166:169], v[112:115]
	v_mfma_f32_16x16x32_bf16 v[96:99], v[218:221], v[182:185], v[96:99]
	v_mfma_f32_16x16x32_bf16 v[96:99], v[222:225], v[186:189], v[96:99]
	v_mfma_f32_16x16x32_bf16 v[100:103], v[210:213], v[186:189], v[100:103]
	v_mfma_f32_16x16x32_bf16 v[100:103], v[206:209], v[182:185], v[100:103]
	v_mfma_f32_16x16x32_bf16 v[84:87], v[206:209], v[190:193], v[84:87]
	v_mfma_f32_16x16x32_bf16 v[84:87], v[210:213], v[194:197], v[84:87]
	v_mfma_f32_16x16x32_bf16 v[80:83], v[222:225], v[194:197], v[80:83]
	v_mfma_f32_16x16x32_bf16 v[80:83], v[218:221], v[190:193], v[80:83]
	v_mfma_f32_16x16x32_bf16 v[64:67], v[218:221], v[198:201], v[64:67]
	v_mfma_f32_16x16x32_bf16 v[64:67], v[222:225], v[202:205], v[64:67]
	v_mfma_f32_16x16x32_bf16 v[68:71], v[210:213], v[202:205], v[68:71]
	v_mfma_f32_16x16x32_bf16 v[68:71], v[206:209], v[198:201], v[68:71]
	s_mov_b32 m0, s29
	v_lshl_add_u64 v[228:229], s[44:45], 0, v[150:151]
	s_barrier
	ds_read_b128 v[166:169], v176 offset:16384
	ds_read_b128 v[178:181], v176 offset:17408
	ds_read_b128 v[182:185], v176 offset:18432
	ds_read_b128 v[186:189], v176 offset:19456
	ds_read_b128 v[190:193], v176 offset:20480
	ds_read_b128 v[194:197], v176 offset:21504
	ds_read_b128 v[198:201], v176 offset:22528
	ds_read_b128 v[202:205], v176 offset:23552
	global_load_lds_dwordx4 v[228:229], off
	v_lshl_add_u64 v[230:231], s[44:45], 0, v[146:147]
	s_mov_b32 m0, s30
	s_nop 0
	global_load_lds_dwordx4 v[230:231], off
	s_barrier
	s_waitcnt lgkmcnt(0)
	s_waitcnt lgkmcnt(0)
	v_mfma_f32_16x16x32_bf16 v[60:63], v[128:131], v[166:169], v[60:63]
	v_mfma_f32_16x16x32_bf16 v[60:63], v[132:135], v[178:181], v[60:63]
	v_mfma_f32_16x16x32_bf16 v[56:59], v[140:143], v[178:181], v[56:59]
	v_mfma_f32_16x16x32_bf16 v[56:59], v[136:139], v[166:169], v[56:59]
	v_mfma_f32_16x16x32_bf16 v[40:43], v[136:139], v[182:185], v[40:43]
	v_mfma_f32_16x16x32_bf16 v[40:43], v[140:143], v[186:189], v[40:43]
	v_mfma_f32_16x16x32_bf16 v[44:47], v[132:135], v[186:189], v[44:47]
	v_mfma_f32_16x16x32_bf16 v[44:47], v[128:131], v[182:185], v[44:47]
	v_mfma_f32_16x16x32_bf16 v[28:31], v[128:131], v[190:193], v[28:31]
	v_mfma_f32_16x16x32_bf16 v[28:31], v[132:135], v[194:197], v[28:31]
	v_mfma_f32_16x16x32_bf16 v[24:27], v[140:143], v[194:197], v[24:27]
	v_mfma_f32_16x16x32_bf16 v[24:27], v[136:139], v[190:193], v[24:27]
	v_mfma_f32_16x16x32_bf16 v[8:11], v[136:139], v[198:201], v[8:11]
	v_mfma_f32_16x16x32_bf16 v[8:11], v[140:143], v[202:205], v[8:11]
	v_mfma_f32_16x16x32_bf16 v[12:15], v[132:135], v[202:205], v[12:15]
	v_mfma_f32_16x16x32_bf16 v[12:15], v[128:131], v[198:201], v[12:15]
	s_barrier
; #define PG8_STAGE(bufoff, gbase, voff) do { _Pragma("unroll") for (int _i = 0; _i < 2; ++_i) \
;         __builtin_amdgcn_global_load_lds((const unsigned*)((const char*)(gbase) + (voff)[_i]), (LAS unsigned*)(lds + (bufoff) + ldsw + _i * 8192), 16, 0, 0); } while (0)
; #define PG8_LDA(dst, b, h) do { _Pragma("unroll") for (int m = 0; m < 4; ++m) _Pragma("unroll") for (int k = 0; k < 2; ++k) dst[m][k] = *(const LAS bf16x8*)(lds + PG8_SA(b, h) + aoff + m * 2048 + k * 1024); } while (0)
; #define PG8_LDB(dst, b, h) do { _Pragma("unroll") for (int n = 0; n < 2; ++n) _Pragma("unroll") for (int k = 0; k < 2; ++k) dst[n][k] = *(const LAS bf16x8*)(lds + PG8_SB(b, h) + boff + n * 2048 + k * 1024); } while (0)
; #define PG8_MMA(ai, bj, At, Bt) do { __builtin_amdgcn_s_setprio(1); _Pragma("unroll") for (int m = 0; m < 4; ++m) _Pragma("unroll") for (int n = 0; n < 2; ++n) _Pragma("unroll") for (int k = 0; k < 2; ++k) \
;         acc[ai][bj][m][n] = __builtin_amdgcn_mfma_f32_16x16x32_bf16(Bt[n][k], At[m][k], acc[ai][bj][m][n], 0, 0, 0); __builtin_amdgcn_s_setprio(0); } while (0)
; #define PG8_WAIT_V(n) asm volatile("s_waitcnt vmcnt(" #n ")" ::: "memory")
; #define PG8_WAIT_L(n) asm volatile("s_waitcnt lgkmcnt(" #n ")" ::: "memory")
; #define PG8_BAR __builtin_amdgcn_s_barrier()
; #define PG8_SCHED __builtin_amdgcn_sched_barrier(0)
; template <class Epi>
; DEVINL void gemm_phase(LAS unsigned char* lds, const Gemm g, const Order& S, const Epi& E) {
;     ...
;             PG8_STAGE(PG8_SB(0, 1), b2 + hstepB, voffB);
;             PG8_WAIT_V(6); PG8_BAR; PG8_MMA(1, 1, At, B1); PG8_BAR;
;             PG8_LDB(B0, 1, 0); PG8_SCHED; PG8_LDA(At, 1, 0); PG8_STAGE(PG8_SA(0, 1), a2 + hstepA, voffA);
;             PG8_WAIT_L(8); PG8_BAR; PG8_WAIT_L(0); PG8_MMA(0, 0, At, B0); PG8_BAR; PG8_SCHED;
;             PG8_LDB(B1, 1, 1); PG8_STAGE(PG8_SB(1, 0), b3, voffB);
	s_add_u32 s2, s14, 0x80000
	s_addc_u32 s3, s15, 0
	s_add_i32 s65, s53, s26
	v_lshl_add_u64 v[128:129], s[2:3], 0, v[148:149]
	s_mov_b32 m0, s65
	s_nop 0
	global_load_lds_dwordx4 v[128:129], off
	v_lshl_add_u64 v[128:129], s[2:3], 0, v[144:145]
	s_add_i32 m0, s65, 0x2000
	s_nop 0
	global_load_lds_dwordx4 v[128:129], off
	s_waitcnt vmcnt(6)
	s_barrier
	v_mfma_f32_16x16x32_bf16 v[52:55], v[206:209], v[166:169], v[52:55]
	v_mfma_f32_16x16x32_bf16 v[52:55], v[210:213], v[178:181], v[52:55]
	v_mfma_f32_16x16x32_bf16 v[48:51], v[222:225], v[178:181], v[48:51]
	v_mfma_f32_16x16x32_bf16 v[48:51], v[218:221], v[166:169], v[48:51]
	v_mfma_f32_16x16x32_bf16 v[32:35], v[218:221], v[182:185], v[32:35]
	v_mfma_f32_16x16x32_bf16 v[32:35], v[222:225], v[186:189], v[32:35]
	v_mfma_f32_16x16x32_bf16 v[36:39], v[210:213], v[186:189], v[36:39]
	v_mfma_f32_16x16x32_bf16 v[36:39], v[206:209], v[182:185], v[36:39]
	v_mfma_f32_16x16x32_bf16 v[20:23], v[206:209], v[190:193], v[20:23]
	v_mfma_f32_16x16x32_bf16 v[20:23], v[210:213], v[194:197], v[20:23]
	v_mfma_f32_16x16x32_bf16 v[16:19], v[222:225], v[194:197], v[16:19]
	v_mfma_f32_16x16x32_bf16 v[16:19], v[218:221], v[190:193], v[16:19]
	v_mfma_f32_16x16x32_bf16 v[0:3], v[218:221], v[198:201], v[0:3]
	v_mfma_f32_16x16x32_bf16 v[0:3], v[222:225], v[202:205], v[0:3]
	v_mfma_f32_16x16x32_bf16 v[4:7], v[210:213], v[202:205], v[4:7]
	v_mfma_f32_16x16x32_bf16 v[4:7], v[206:209], v[198:201], v[4:7]
	s_add_i32 s65, 16, 0x18000
	v_add_u32_e32 v140, s65, v173
	s_barrier
	ds_read_b128 v[128:131], v140
	ds_read_b128 v[132:135], v140 offset:1024
	ds_read_b128 v[136:139], v140 offset:2048
	ds_read_b128 v[140:143], v140 offset:3072
	s_add_u32 s2, s44, 0x80000
	s_addc_u32 s3, s45, 0
	s_mov_b32 m0, s31
	v_lshl_add_u64 v[206:207], s[2:3], 0, v[150:151]
	ds_read_b128 v[166:169], v176 offset:32768
	ds_read_b128 v[178:181], v176 offset:33792
	ds_read_b128 v[182:185], v176 offset:34816
	ds_read_b128 v[186:189], v176 offset:35840
	ds_read_b128 v[190:193], v176 offset:36864
	ds_read_b128 v[194:197], v176 offset:37888
	ds_read_b128 v[198:201], v176 offset:38912
	ds_read_b128 v[202:205], v176 offset:39936
	global_load_lds_dwordx4 v[206:207], off
	v_lshl_add_u64 v[206:207], s[2:3], 0, v[146:147]
	s_mov_b32 m0, s43
	s_nop 0
	global_load_lds_dwordx4 v[206:207], off
	s_waitcnt lgkmcnt(8)
	s_barrier
	s_waitcnt lgkmcnt(0)
	s_waitcnt lgkmcnt(0)
	v_mfma_f32_16x16x32_bf16 v[124:127], v[128:131], v[166:169], v[124:127]
	v_mfma_f32_16x16x32_bf16 v[124:127], v[132:135], v[178:181], v[124:127]
	v_mfma_f32_16x16x32_bf16 v[120:123], v[140:143], v[178:181], v[120:123]
	v_mfma_f32_16x16x32_bf16 v[120:123], v[136:139], v[166:169], v[120:123]
	v_mfma_f32_16x16x32_bf16 v[104:107], v[136:139], v[182:185], v[104:107]
	v_mfma_f32_16x16x32_bf16 v[104:107], v[140:143], v[186:189], v[104:107]
	v_mfma_f32_16x16x32_bf16 v[108:111], v[132:135], v[186:189], v[108:111]
	v_mfma_f32_16x16x32_bf16 v[108:111], v[128:131], v[182:185], v[108:111]
	v_mfma_f32_16x16x32_bf16 v[92:95], v[128:131], v[190:193], v[92:95]
	v_mfma_f32_16x16x32_bf16 v[92:95], v[132:135], v[194:197], v[92:95]
	v_mfma_f32_16x16x32_bf16 v[88:91], v[140:143], v[194:197], v[88:91]
	v_mfma_f32_16x16x32_bf16 v[88:91], v[136:139], v[190:193], v[88:91]
	v_mfma_f32_16x16x32_bf16 v[72:75], v[136:139], v[198:201], v[72:75]
	v_mfma_f32_16x16x32_bf16 v[72:75], v[140:143], v[202:205], v[72:75]
	v_mfma_f32_16x16x32_bf16 v[76:79], v[132:135], v[202:205], v[76:79]
	v_mfma_f32_16x16x32_bf16 v[76:79], v[128:131], v[198:201], v[76:79]
	s_barrier
	s_add_i32 s44, 16, 0x1c000
	s_add_i32 s2, s65, s26
	v_add_u32_e32 v152, s44, v173
	v_lshl_add_u64 v[170:171], v[170:171], 0, s[4:5]
	s_mov_b32 m0, s2
	ds_read_b128 v[206:209], v152
	ds_read_b128 v[210:213], v152 offset:1024
	ds_read_b128 v[218:221], v152 offset:2048
	ds_read_b128 v[222:225], v152 offset:3072
	global_load_lds_dwordx4 v[170:171], off
	v_lshl_add_u64 v[170:171], v[226:227], 0, s[4:5]
	s_add_i32 m0, s2, 0x2000
	s_nop 0
	global_load_lds_dwordx4 v[170:171], off
	s_barrier
; #define PG8_STAGE(bufoff, gbase, voff) do { _Pragma("unroll") for (int _i = 0; _i < 2; ++_i) \
;         __builtin_amdgcn_global_load_lds((const unsigned*)((const char*)(gbase) + (voff)[_i]), (LAS unsigned*)(lds + (bufoff) + ldsw + _i * 8192), 16, 0, 0); } while (0)
; #define PG8_LDA(dst, b, h) do { _Pragma("unroll") for (int m = 0; m < 4; ++m) _Pragma("unroll") for (int k = 0; k < 2; ++k) dst[m][k] = *(const LAS bf16x8*)(lds + PG8_SA(b, h) + aoff + m * 2048 + k * 1024); } while (0)
; #define PG8_LDB(dst, b, h) do { _Pragma("unroll") for (int n = 0; n < 2; ++n) _Pragma("unroll") for (int k = 0; k < 2; ++k) dst[n][k] = *(const LAS bf16x8*)(lds + PG8_SB(b, h) + boff + n * 2048 + k * 1024); } while (0)
; #define PG8_MMA(ai, bj, At, Bt) do { __builtin_amdgcn_s_setprio(1); _Pragma("unroll") for (int m = 0; m < 4; ++m) _Pragma("unroll") for (int n = 0; n < 2; ++n) _Pragma("unroll") for (int k = 0; k < 2; ++k) \
;         acc[ai][bj][m][n] = __builtin_amdgcn_mfma_f32_16x16x32_bf16(Bt[n][k], At[m][k], acc[ai][bj][m][n], 0, 0, 0); __builtin_amdgcn_s_setprio(0); } while (0)
; #define PG8_WAIT_V(n) asm volatile("s_waitcnt vmcnt(" #n ")" ::: "memory")
; #define PG8_WAIT_L(n) asm volatile("s_waitcnt lgkmcnt(" #n ")" ::: "memory")
; #define PG8_BAR __builtin_amdgcn_s_barrier()
; #define PG8_SCHED __builtin_amdgcn_sched_barrier(0)
; template <class Epi>
; DEVINL void gemm_phase(LAS unsigned char* lds, const Gemm g, const Order& S, const Epi& E) {
;     ...
;         for (int t = 0; t < nt; t += 2) {
;     ...
;             PG8_LDB(B1, 1, 1); PG8_STAGE(PG8_SB(1, 0), b3, voffB);
;             PG8_BAR; PG8_WAIT_L(0); PG8_MMA(0, 1, At, B1); PG8_BAR;
;             PG8_LDA(At, 1, 1); PG8_STAGE(PG8_SA(1, 0), a3, voffA);
;             PG8_BAR; PG8_WAIT_L(0); PG8_MMA(1, 0, At, B0); PG8_BAR; PG8_SCHED;
;             PG8_STAGE(PG8_SB(1, 1), b3 + hstepB, voffB);
;             PG8_WAIT_V(6); PG8_BAR; PG8_MMA(1, 1, At, B1); PG8_BAR;
	s_waitcnt lgkmcnt(0)
	s_waitcnt lgkmcnt(0)
	v_mfma_f32_16x16x32_bf16 v[116:119], v[206:209], v[166:169], v[116:119]
	v_mfma_f32_16x16x32_bf16 v[116:119], v[210:213], v[178:181], v[116:119]
	v_mfma_f32_16x16x32_bf16 v[112:115], v[222:225], v[178:181], v[112:115]
	v_mfma_f32_16x16x32_bf16 v[112:115], v[218:221], v[166:169], v[112:115]
	v_mfma_f32_16x16x32_bf16 v[96:99], v[218:221], v[182:185], v[96:99]
	v_mfma_f32_16x16x32_bf16 v[96:99], v[222:225], v[186:189], v[96:99]
	v_mfma_f32_16x16x32_bf16 v[100:103], v[210:213], v[186:189], v[100:103]
	v_mfma_f32_16x16x32_bf16 v[100:103], v[206:209], v[182:185], v[100:103]
	v_mfma_f32_16x16x32_bf16 v[84:87], v[206:209], v[190:193], v[84:87]
	v_mfma_f32_16x16x32_bf16 v[84:87], v[210:213], v[194:197], v[84:87]
	v_mfma_f32_16x16x32_bf16 v[80:83], v[222:225], v[194:197], v[80:83]
	v_mfma_f32_16x16x32_bf16 v[80:83], v[218:221], v[190:193], v[80:83]
	v_mfma_f32_16x16x32_bf16 v[64:67], v[218:221], v[198:201], v[64:67]
	v_mfma_f32_16x16x32_bf16 v[64:67], v[222:225], v[202:205], v[64:67]
	v_mfma_f32_16x16x32_bf16 v[68:71], v[210:213], v[202:205], v[68:71]
	v_mfma_f32_16x16x32_bf16 v[68:71], v[206:209], v[198:201], v[68:71]
	s_mov_b32 m0, s47
	v_lshl_add_u64 v[170:171], v[228:229], 0, s[4:5]
	s_barrier
	ds_read_b128 v[166:169], v176 offset:49152
	ds_read_b128 v[178:181], v176 offset:50176
	ds_read_b128 v[182:185], v176 offset:51200
	ds_read_b128 v[186:189], v176 offset:52224
	ds_read_b128 v[190:193], v176 offset:53248
	ds_read_b128 v[194:197], v176 offset:54272
	ds_read_b128 v[198:201], v176 offset:55296
	ds_read_b128 v[202:205], v176 offset:56320
	global_load_lds_dwordx4 v[170:171], off
	v_lshl_add_u64 v[170:171], v[230:231], 0, s[4:5]
	s_mov_b32 m0, s48
	s_nop 0
	global_load_lds_dwordx4 v[170:171], off
	s_barrier
	s_waitcnt lgkmcnt(0)
	s_waitcnt lgkmcnt(0)
	v_mfma_f32_16x16x32_bf16 v[60:63], v[128:131], v[166:169], v[60:63]
	v_mfma_f32_16x16x32_bf16 v[60:63], v[132:135], v[178:181], v[60:63]
	v_mfma_f32_16x16x32_bf16 v[56:59], v[140:143], v[178:181], v[56:59]
	v_mfma_f32_16x16x32_bf16 v[56:59], v[136:139], v[166:169], v[56:59]
	v_mfma_f32_16x16x32_bf16 v[40:43], v[136:139], v[182:185], v[40:43]
	v_mfma_f32_16x16x32_bf16 v[40:43], v[140:143], v[186:189], v[40:43]
	v_mfma_f32_16x16x32_bf16 v[44:47], v[132:135], v[186:189], v[44:47]
	v_mfma_f32_16x16x32_bf16 v[44:47], v[128:131], v[182:185], v[44:47]
	v_mfma_f32_16x16x32_bf16 v[28:31], v[128:131], v[190:193], v[28:31]
	v_mfma_f32_16x16x32_bf16 v[28:31], v[132:135], v[194:197], v[28:31]
	v_mfma_f32_16x16x32_bf16 v[24:27], v[140:143], v[194:197], v[24:27]
	v_mfma_f32_16x16x32_bf16 v[24:27], v[136:139], v[190:193], v[24:27]
	v_mfma_f32_16x16x32_bf16 v[8:11], v[136:139], v[198:201], v[8:11]
	v_mfma_f32_16x16x32_bf16 v[8:11], v[140:143], v[202:205], v[8:11]
	v_mfma_f32_16x16x32_bf16 v[12:15], v[132:135], v[202:205], v[12:15]
	v_mfma_f32_16x16x32_bf16 v[12:15], v[128:131], v[198:201], v[12:15]
	s_barrier
	s_add_u32 s2, s14, 0x80080
	s_addc_u32 s3, s15, 0
	s_add_i32 s14, s44, s26
	v_lshl_add_u64 v[128:129], s[2:3], 0, v[148:149]
	s_mov_b32 m0, s14
	s_nop 0
	global_load_lds_dwordx4 v[128:129], off
	v_lshl_add_u64 v[128:129], s[2:3], 0, v[144:145]
	s_add_i32 m0, s14, 0x2000
	s_nop 0
	global_load_lds_dwordx4 v[128:129], off
	s_waitcnt vmcnt(6)
	s_barrier
	v_mfma_f32_16x16x32_bf16 v[52:55], v[206:209], v[166:169], v[52:55]
	v_mfma_f32_16x16x32_bf16 v[52:55], v[210:213], v[178:181], v[52:55]
	v_mfma_f32_16x16x32_bf16 v[48:51], v[222:225], v[178:181], v[48:51]
	v_mfma_f32_16x16x32_bf16 v[48:51], v[218:221], v[166:169], v[48:51]
	v_mfma_f32_16x16x32_bf16 v[32:35], v[218:221], v[182:185], v[32:35]
	v_mfma_f32_16x16x32_bf16 v[32:35], v[222:225], v[186:189], v[32:35]
	v_mfma_f32_16x16x32_bf16 v[36:39], v[210:213], v[186:189], v[36:39]
	v_mfma_f32_16x16x32_bf16 v[36:39], v[206:209], v[182:185], v[36:39]
	v_mfma_f32_16x16x32_bf16 v[20:23], v[206:209], v[190:193], v[20:23]
	v_mfma_f32_16x16x32_bf16 v[20:23], v[210:213], v[194:197], v[20:23]
	v_mfma_f32_16x16x32_bf16 v[16:19], v[222:225], v[194:197], v[16:19]
	v_mfma_f32_16x16x32_bf16 v[16:19], v[218:221], v[190:193], v[16:19]
	v_mfma_f32_16x16x32_bf16 v[0:3], v[218:221], v[198:201], v[0:3]
	v_mfma_f32_16x16x32_bf16 v[0:3], v[222:225], v[202:205], v[0:3]
	v_mfma_f32_16x16x32_bf16 v[4:7], v[210:213], v[202:205], v[4:7]
	v_mfma_f32_16x16x32_bf16 v[4:7], v[206:209], v[198:201], v[4:7]
	s_add_u32 s12, s12, 0x100
	s_addc_u32 s13, s13, 0
	s_add_u32 s58, s58, 0x100
	s_addc_u32 s59, s59, 0
	s_cmp_ge_i32 s64, s46
	s_mov_b32 s14, s64
	s_barrier
	s_cbranch_scc0 .LBB0_650

; #define PG8_STAGE(bufoff, gbase, voff) do { _Pragma("unroll") for (int _i = 0; _i < 2; ++_i) \
;         __builtin_amdgcn_global_load_lds((const unsigned*)((const char*)(gbase) + (voff)[_i]), (LAS unsigned*)(lds + (bufoff) + ldsw + _i * 8192), 16, 0, 0); } while (0)
; #define PG8_LDA(dst, b, h) do { _Pragma("unroll") for (int m = 0; m < 4; ++m) _Pragma("unroll") for (int k = 0; k < 2; ++k) dst[m][k] = *(const LAS bf16x8*)(lds + PG8_SA(b, h) + aoff + m * 2048 + k * 1024); } while (0)
; #define PG8_LDB(dst, b, h) do { _Pragma("unroll") for (int n = 0; n < 2; ++n) _Pragma("unroll") for (int k = 0; k < 2; ++k) dst[n][k] = *(const LAS bf16x8*)(lds + PG8_SB(b, h) + boff + n * 2048 + k * 1024); } while (0)
; #define PG8_MMA(ai, bj, At, Bt) do { __builtin_amdgcn_s_setprio(1); _Pragma("unroll") for (int m = 0; m < 4; ++m) _Pragma("unroll") for (int n = 0; n < 2; ++n) _Pragma("unroll") for (int k = 0; k < 2; ++k) \
;         acc[ai][bj][m][n] = __builtin_amdgcn_mfma_f32_16x16x32_bf16(Bt[n][k], At[m][k], acc[ai][bj][m][n], 0, 0, 0); __builtin_amdgcn_s_setprio(0); } while (0)
; #define PG8_WAIT_L(n) asm volatile("s_waitcnt lgkmcnt(" #n ")" ::: "memory")
; #define PG8_BAR __builtin_amdgcn_s_barrier()
; #define PG8_SCHED __builtin_amdgcn_sched_barrier(0)
; template <class Epi>
; DEVINL void gemm_phase(LAS unsigned char* lds, const Gemm g, const Order& S, const Epi& E) {
;     ...
;             const char* a1 = cA + (size_t)(t + 1) * kstep;
;             const char* a2 = last ? nA : cA + (size_t)(t + 2) * kstep; const char* b2 = last ? nB : cB + (size_t)(t + 2) * kstep;
;             const char* a3 = a2 + kstep; const char* b3 = b2 + kstep;
;             PG8_LDB(B0, 0, 0); PG8_SCHED; PG8_LDA(At, 0, 0); PG8_STAGE(PG8_SA(1, 1), a1 + hstepA, voffA);
;             PG8_WAIT_L(8); PG8_BAR; PG8_WAIT_L(0); PG8_MMA(0, 0, At, B0); PG8_BAR; PG8_SCHED;
;             PG8_LDB(B1, 0, 1); PG8_STAGE(PG8_SB(0, 0), b2, voffB);
;             PG8_BAR; PG8_WAIT_L(0); PG8_MMA(0, 1, At, B1); PG8_BAR;
;             PG8_LDA(At, 0, 1); PG8_STAGE(PG8_SA(0, 0), a2, voffA);
;             PG8_BAR; PG8_WAIT_L(0); PG8_MMA(1, 0, At, B0); PG8_BAR; PG8_SCHED;
.LBB0_802:
	ds_read_b128 v[150:153], v147
	ds_read_b128 v[154:157], v147 offset:1024
	ds_read_b128 v[158:161], v147 offset:2048
	ds_read_b128 v[162:165], v147 offset:3072
	s_add_i32 s65, s38, 2
	s_add_u32 s4, s16, 0x100
	s_addc_u32 s5, s17, 0
	s_cmp_eq_u32 s49, s38
	s_cselect_b32 s38, s58, s59
	s_cselect_b32 s41, s13, s5
	s_cselect_b32 s40, s12, s4
	s_cselect_b32 s39, s11, s64
	v_lshl_add_u64 v[198:199], s[16:17], 0, v[136:137]
	s_add_i32 m0, s31, 0xc000
	ds_read_b128 v[166:169], v148
	ds_read_b128 v[170:173], v148 offset:1024
	ds_read_b128 v[174:177], v148 offset:2048
	ds_read_b128 v[178:181], v148 offset:3072
	ds_read_b128 v[182:185], v148 offset:4096
	ds_read_b128 v[186:189], v148 offset:5120
	ds_read_b128 v[190:193], v148 offset:6144
	ds_read_b128 v[194:197], v148 offset:7168
	global_load_lds_dwordx4 v[198:199], off
	v_lshl_add_u64 v[198:199], s[16:17], 0, v[138:139]
	s_add_i32 m0, s31, 0xe000
	s_nop 0
	global_load_lds_dwordx4 v[198:199], off
	s_waitcnt lgkmcnt(8)
	s_barrier
	s_waitcnt lgkmcnt(0)
	s_waitcnt lgkmcnt(0)
	v_mfma_f32_16x16x32_bf16 v[120:123], v[150:153], v[166:169], v[120:123]
	v_mfma_f32_16x16x32_bf16 v[120:123], v[154:157], v[170:173], v[120:123]
	v_mfma_f32_16x16x32_bf16 v[124:127], v[162:165], v[170:173], v[124:127]
	v_mfma_f32_16x16x32_bf16 v[124:127], v[158:161], v[166:169], v[124:127]
	v_mfma_f32_16x16x32_bf16 v[104:107], v[158:161], v[174:177], v[104:107]
	v_mfma_f32_16x16x32_bf16 v[104:107], v[162:165], v[178:181], v[104:107]
	v_mfma_f32_16x16x32_bf16 v[108:111], v[154:157], v[178:181], v[108:111]
	v_mfma_f32_16x16x32_bf16 v[108:111], v[150:153], v[174:177], v[108:111]
	v_mfma_f32_16x16x32_bf16 v[92:95], v[150:153], v[182:185], v[92:95]
	v_mfma_f32_16x16x32_bf16 v[92:95], v[154:157], v[186:189], v[92:95]
	v_mfma_f32_16x16x32_bf16 v[88:91], v[162:165], v[186:189], v[88:91]
	v_mfma_f32_16x16x32_bf16 v[88:91], v[158:161], v[182:185], v[88:91]
	v_mfma_f32_16x16x32_bf16 v[72:75], v[158:161], v[190:193], v[72:75]
	v_mfma_f32_16x16x32_bf16 v[72:75], v[162:165], v[194:197], v[72:75]
	v_mfma_f32_16x16x32_bf16 v[76:79], v[154:157], v[194:197], v[76:79]
	v_mfma_f32_16x16x32_bf16 v[76:79], v[150:153], v[190:193], v[76:79]
	s_barrier
	s_add_i32 s2, s52, s28
	v_lshl_add_u64 v[218:219], s[38:39], 0, v[132:133]
	s_mov_b32 m0, s2
	ds_read_b128 v[198:201], v149
	ds_read_b128 v[202:205], v149 offset:1024
	ds_read_b128 v[206:209], v149 offset:2048
	ds_read_b128 v[210:213], v149 offset:3072
	global_load_lds_dwordx4 v[218:219], off
	v_lshl_add_u64 v[220:221], s[38:39], 0, v[128:129]
	s_add_i32 m0, s2, 0x2000
	s_nop 0
	global_load_lds_dwordx4 v[220:221], off
	s_barrier
	s_waitcnt lgkmcnt(0)
	s_waitcnt lgkmcnt(0)
	v_mfma_f32_16x16x32_bf16 v[116:119], v[198:201], v[166:169], v[116:119]
	v_mfma_f32_16x16x32_bf16 v[116:119], v[202:205], v[170:173], v[116:119]
	v_mfma_f32_16x16x32_bf16 v[112:115], v[210:213], v[170:173], v[112:115]
	v_mfma_f32_16x16x32_bf16 v[112:115], v[206:209], v[166:169], v[112:115]
	v_mfma_f32_16x16x32_bf16 v[96:99], v[206:209], v[174:177], v[96:99]
	v_mfma_f32_16x16x32_bf16 v[96:99], v[210:213], v[178:181], v[96:99]
	v_mfma_f32_16x16x32_bf16 v[100:103], v[202:205], v[178:181], v[100:103]
	v_mfma_f32_16x16x32_bf16 v[100:103], v[198:201], v[174:177], v[100:103]
	v_mfma_f32_16x16x32_bf16 v[84:87], v[198:201], v[182:185], v[84:87]
	v_mfma_f32_16x16x32_bf16 v[84:87], v[202:205], v[186:189], v[84:87]
	v_mfma_f32_16x16x32_bf16 v[80:83], v[210:213], v[186:189], v[80:83]
	v_mfma_f32_16x16x32_bf16 v[80:83], v[206:209], v[182:185], v[80:83]
	v_mfma_f32_16x16x32_bf16 v[64:67], v[206:209], v[190:193], v[64:67]
	v_mfma_f32_16x16x32_bf16 v[64:67], v[210:213], v[194:197], v[64:67]
	v_mfma_f32_16x16x32_bf16 v[68:71], v[202:205], v[194:197], v[68:71]
	v_mfma_f32_16x16x32_bf16 v[68:71], v[198:201], v[190:193], v[68:71]
	s_mov_b32 m0, s31
	v_lshl_add_u64 v[222:223], s[40:41], 0, v[134:135]
	s_barrier
	ds_read_b128 v[166:169], v148 offset:16384
	ds_read_b128 v[170:173], v148 offset:17408
	ds_read_b128 v[174:177], v148 offset:18432
	ds_read_b128 v[178:181], v148 offset:19456
	ds_read_b128 v[182:185], v148 offset:20480
	ds_read_b128 v[186:189], v148 offset:21504
	ds_read_b128 v[190:193], v148 offset:22528
	ds_read_b128 v[194:197], v148 offset:23552
	global_load_lds_dwordx4 v[222:223], off
	v_lshl_add_u64 v[224:225], s[40:41], 0, v[130:131]
	s_mov_b32 m0, s42
	s_nop 0
	global_load_lds_dwordx4 v[224:225], off
	s_barrier
	s_waitcnt lgkmcnt(0)
	s_waitcnt lgkmcnt(0)
	v_mfma_f32_16x16x32_bf16 v[60:63], v[150:153], v[166:169], v[60:63]
	v_mfma_f32_16x16x32_bf16 v[60:63], v[154:157], v[170:173], v[60:63]
	v_mfma_f32_16x16x32_bf16 v[56:59], v[162:165], v[170:173], v[56:59]
	v_mfma_f32_16x16x32_bf16 v[56:59], v[158:161], v[166:169], v[56:59]
	v_mfma_f32_16x16x32_bf16 v[40:43], v[158:161], v[174:177], v[40:43]
	v_mfma_f32_16x16x32_bf16 v[40:43], v[162:165], v[178:181], v[40:43]
	v_mfma_f32_16x16x32_bf16 v[44:47], v[154:157], v[178:181], v[44:47]
	v_mfma_f32_16x16x32_bf16 v[44:47], v[150:153], v[174:177], v[44:47]
	v_mfma_f32_16x16x32_bf16 v[28:31], v[150:153], v[182:185], v[28:31]
	v_mfma_f32_16x16x32_bf16 v[28:31], v[154:157], v[186:189], v[28:31]
	v_mfma_f32_16x16x32_bf16 v[24:27], v[162:165], v[186:189], v[24:27]
	v_mfma_f32_16x16x32_bf16 v[24:27], v[158:161], v[182:185], v[24:27]
	v_mfma_f32_16x16x32_bf16 v[8:11], v[158:161], v[190:193], v[8:11]
	v_mfma_f32_16x16x32_bf16 v[8:11], v[162:165], v[194:197], v[8:11]
	v_mfma_f32_16x16x32_bf16 v[12:15], v[154:157], v[194:197], v[12:15]
	v_mfma_f32_16x16x32_bf16 v[12:15], v[150:153], v[190:193], v[12:15]
	s_barrier
; #define PG8_STAGE(bufoff, gbase, voff) do { _Pragma("unroll") for (int _i = 0; _i < 2; ++_i) \
;         __builtin_amdgcn_global_load_lds((const unsigned*)((const char*)(gbase) + (voff)[_i]), (LAS unsigned*)(lds + (bufoff) + ldsw + _i * 8192), 16, 0, 0); } while (0)
; #define PG8_LDA(dst, b, h) do { _Pragma("unroll") for (int m = 0; m < 4; ++m) _Pragma("unroll") for (int k = 0; k < 2; ++k) dst[m][k] = *(const LAS bf16x8*)(lds + PG8_SA(b, h) + aoff + m * 2048 + k * 1024); } while (0)
; #define PG8_LDB(dst, b, h) do { _Pragma("unroll") for (int n = 0; n < 2; ++n) _Pragma("unroll") for (int k = 0; k < 2; ++k) dst[n][k] = *(const LAS bf16x8*)(lds + PG8_SB(b, h) + boff + n * 2048 + k * 1024); } while (0)
; #define PG8_MMA(ai, bj, At, Bt) do { __builtin_amdgcn_s_setprio(1); _Pragma("unroll") for (int m = 0; m < 4; ++m) _Pragma("unroll") for (int n = 0; n < 2; ++n) _Pragma("unroll") for (int k = 0; k < 2; ++k) \
;         acc[ai][bj][m][n] = __builtin_amdgcn_mfma_f32_16x16x32_bf16(Bt[n][k], At[m][k], acc[ai][bj][m][n], 0, 0, 0); __builtin_amdgcn_s_setprio(0); } while (0)
; #define PG8_WAIT_V(n) asm volatile("s_waitcnt vmcnt(" #n ")" ::: "memory")
; #define PG8_WAIT_L(n) asm volatile("s_waitcnt lgkmcnt(" #n ")" ::: "memory")
; #define PG8_BAR __builtin_amdgcn_s_barrier()
; #define PG8_SCHED __builtin_amdgcn_sched_barrier(0)
; template <class Epi>
; DEVINL void gemm_phase(LAS unsigned char* lds, const Gemm g, const Order& S, const Epi& E) {
;     ...
;             PG8_STAGE(PG8_SB(0, 1), b2 + hstepB, voffB);
;             PG8_WAIT_V(6); PG8_BAR; PG8_MMA(1, 1, At, B1); PG8_BAR;
;             PG8_LDB(B0, 1, 0); PG8_SCHED; PG8_LDA(At, 1, 0); PG8_STAGE(PG8_SA(0, 1), a2 + hstepA, voffA);
;             PG8_WAIT_L(8); PG8_BAR; PG8_WAIT_L(0); PG8_MMA(0, 0, At, B0); PG8_BAR; PG8_SCHED;
;             PG8_LDB(B1, 1, 1); PG8_STAGE(PG8_SB(1, 0), b3, voffB);
	s_add_u32 s2, s38, 0x20000
	s_addc_u32 s3, s39, 0
	s_add_i32 s16, s53, s28
	v_lshl_add_u64 v[150:151], s[2:3], 0, v[132:133]
	s_mov_b32 m0, s16
	s_nop 0
	global_load_lds_dwordx4 v[150:151], off
	v_lshl_add_u64 v[150:151], s[2:3], 0, v[128:129]
	s_add_i32 m0, s16, 0x2000
	s_nop 0
	global_load_lds_dwordx4 v[150:151], off
	s_waitcnt vmcnt(6)
	s_barrier
	v_mfma_f32_16x16x32_bf16 v[52:55], v[198:201], v[166:169], v[52:55]
	v_mfma_f32_16x16x32_bf16 v[52:55], v[202:205], v[170:173], v[52:55]
	v_mfma_f32_16x16x32_bf16 v[48:51], v[210:213], v[170:173], v[48:51]
	v_mfma_f32_16x16x32_bf16 v[48:51], v[206:209], v[166:169], v[48:51]
	v_mfma_f32_16x16x32_bf16 v[32:35], v[206:209], v[174:177], v[32:35]
	v_mfma_f32_16x16x32_bf16 v[32:35], v[210:213], v[178:181], v[32:35]
	v_mfma_f32_16x16x32_bf16 v[36:39], v[202:205], v[178:181], v[36:39]
	v_mfma_f32_16x16x32_bf16 v[36:39], v[198:201], v[174:177], v[36:39]
	v_mfma_f32_16x16x32_bf16 v[20:23], v[198:201], v[182:185], v[20:23]
	v_mfma_f32_16x16x32_bf16 v[20:23], v[202:205], v[186:189], v[20:23]
	v_mfma_f32_16x16x32_bf16 v[16:19], v[210:213], v[186:189], v[16:19]
	v_mfma_f32_16x16x32_bf16 v[16:19], v[206:209], v[182:185], v[16:19]
	v_mfma_f32_16x16x32_bf16 v[0:3], v[206:209], v[190:193], v[0:3]
	v_mfma_f32_16x16x32_bf16 v[0:3], v[210:213], v[194:197], v[0:3]
	v_mfma_f32_16x16x32_bf16 v[4:7], v[202:205], v[194:197], v[4:7]
	v_mfma_f32_16x16x32_bf16 v[4:7], v[198:201], v[190:193], v[4:7]
	s_add_i32 s16, 16, 0x18000
	v_add_u32_e32 v162, s16, v145
	s_barrier
	ds_read_b128 v[150:153], v162
	ds_read_b128 v[154:157], v162 offset:1024
	ds_read_b128 v[158:161], v162 offset:2048
	ds_read_b128 v[162:165], v162 offset:3072
	s_add_u32 s2, s40, 0x30000
	s_addc_u32 s3, s41, 0
	s_mov_b32 m0, s43
	v_lshl_add_u64 v[198:199], s[2:3], 0, v[134:135]
	ds_read_b128 v[166:169], v148 offset:32768
	ds_read_b128 v[170:173], v148 offset:33792
	ds_read_b128 v[174:177], v148 offset:34816
	ds_read_b128 v[178:181], v148 offset:35840
	ds_read_b128 v[182:185], v148 offset:36864
	ds_read_b128 v[186:189], v148 offset:37888
	ds_read_b128 v[190:193], v148 offset:38912
	ds_read_b128 v[194:197], v148 offset:39936
	global_load_lds_dwordx4 v[198:199], off
	v_lshl_add_u64 v[198:199], s[2:3], 0, v[130:131]
	s_mov_b32 m0, s44
	s_nop 0
	global_load_lds_dwordx4 v[198:199], off
	s_waitcnt lgkmcnt(8)
	s_barrier
	s_waitcnt lgkmcnt(0)
	s_waitcnt lgkmcnt(0)
	v_mfma_f32_16x16x32_bf16 v[120:123], v[150:153], v[166:169], v[120:123]
	v_mfma_f32_16x16x32_bf16 v[120:123], v[154:157], v[170:173], v[120:123]
	v_mfma_f32_16x16x32_bf16 v[124:127], v[162:165], v[170:173], v[124:127]
	v_mfma_f32_16x16x32_bf16 v[124:127], v[158:161], v[166:169], v[124:127]
	v_mfma_f32_16x16x32_bf16 v[104:107], v[158:161], v[174:177], v[104:107]
	v_mfma_f32_16x16x32_bf16 v[104:107], v[162:165], v[178:181], v[104:107]
	v_mfma_f32_16x16x32_bf16 v[108:111], v[154:157], v[178:181], v[108:111]
	v_mfma_f32_16x16x32_bf16 v[108:111], v[150:153], v[174:177], v[108:111]
	v_mfma_f32_16x16x32_bf16 v[92:95], v[150:153], v[182:185], v[92:95]
	v_mfma_f32_16x16x32_bf16 v[92:95], v[154:157], v[186:189], v[92:95]
	v_mfma_f32_16x16x32_bf16 v[88:91], v[162:165], v[186:189], v[88:91]
	v_mfma_f32_16x16x32_bf16 v[88:91], v[158:161], v[182:185], v[88:91]
	v_mfma_f32_16x16x32_bf16 v[72:75], v[158:161], v[190:193], v[72:75]
	v_mfma_f32_16x16x32_bf16 v[72:75], v[162:165], v[194:197], v[72:75]
	v_mfma_f32_16x16x32_bf16 v[76:79], v[154:157], v[194:197], v[76:79]
	v_mfma_f32_16x16x32_bf16 v[76:79], v[150:153], v[190:193], v[76:79]
	s_barrier
	s_add_i32 s17, 16, 0x1c000
	s_add_i32 s2, s16, s28
	v_add_u32_e32 v210, s17, v145
	v_lshl_add_u64 v[218:219], v[218:219], 0, s[6:7]
	s_mov_b32 m0, s2
	ds_read_b128 v[198:201], v210
	ds_read_b128 v[202:205], v210 offset:1024
	ds_read_b128 v[206:209], v210 offset:2048
	ds_read_b128 v[210:213], v210 offset:3072
	global_load_lds_dwordx4 v[218:219], off
	v_lshl_add_u64 v[218:219], v[220:221], 0, s[6:7]
	s_add_i32 m0, s2, 0x2000
	s_nop 0
	global_load_lds_dwordx4 v[218:219], off
	s_barrier
; #define PG8_STAGE(bufoff, gbase, voff) do { _Pragma("unroll") for (int _i = 0; _i < 2; ++_i) \
;         __builtin_amdgcn_global_load_lds((const unsigned*)((const char*)(gbase) + (voff)[_i]), (LAS unsigned*)(lds + (bufoff) + ldsw + _i * 8192), 16, 0, 0); } while (0)
; #define PG8_LDA(dst, b, h) do { _Pragma("unroll") for (int m = 0; m < 4; ++m) _Pragma("unroll") for (int k = 0; k < 2; ++k) dst[m][k] = *(const LAS bf16x8*)(lds + PG8_SA(b, h) + aoff + m * 2048 + k * 1024); } while (0)
; #define PG8_MMA(ai, bj, At, Bt) do { __builtin_amdgcn_s_setprio(1); _Pragma("unroll") for (int m = 0; m < 4; ++m) _Pragma("unroll") for (int n = 0; n < 2; ++n) _Pragma("unroll") for (int k = 0; k < 2; ++k) \
;         acc[ai][bj][m][n] = __builtin_amdgcn_mfma_f32_16x16x32_bf16(Bt[n][k], At[m][k], acc[ai][bj][m][n], 0, 0, 0); __builtin_amdgcn_s_setprio(0); } while (0)
; #define PG8_WAIT_V(n) asm volatile("s_waitcnt vmcnt(" #n ")" ::: "memory")
; #define PG8_WAIT_L(n) asm volatile("s_waitcnt lgkmcnt(" #n ")" ::: "memory")
; #define PG8_BAR __builtin_amdgcn_s_barrier()
; #define PG8_SCHED __builtin_amdgcn_sched_barrier(0)
; template <class Epi>
; DEVINL void gemm_phase(LAS unsigned char* lds, const Gemm g, const Order& S, const Epi& E) {
;     ...
;             PG8_BAR; PG8_WAIT_L(0); PG8_MMA(0, 1, At, B1); PG8_BAR;
;             PG8_LDA(At, 1, 1); PG8_STAGE(PG8_SA(1, 0), a3, voffA);
;             PG8_BAR; PG8_WAIT_L(0); PG8_MMA(1, 0, At, B0); PG8_BAR; PG8_SCHED;
;             PG8_STAGE(PG8_SB(1, 1), b3 + hstepB, voffB);
;             PG8_WAIT_V(6); PG8_BAR; PG8_MMA(1, 1, At, B1); PG8_BAR;
	s_waitcnt lgkmcnt(0)
	s_waitcnt lgkmcnt(0)
	v_mfma_f32_16x16x32_bf16 v[116:119], v[198:201], v[166:169], v[116:119]
	v_mfma_f32_16x16x32_bf16 v[116:119], v[202:205], v[170:173], v[116:119]
	v_mfma_f32_16x16x32_bf16 v[112:115], v[210:213], v[170:173], v[112:115]
	v_mfma_f32_16x16x32_bf16 v[112:115], v[206:209], v[166:169], v[112:115]
	v_mfma_f32_16x16x32_bf16 v[96:99], v[206:209], v[174:177], v[96:99]
	v_mfma_f32_16x16x32_bf16 v[96:99], v[210:213], v[178:181], v[96:99]
	v_mfma_f32_16x16x32_bf16 v[100:103], v[202:205], v[178:181], v[100:103]
	v_mfma_f32_16x16x32_bf16 v[100:103], v[198:201], v[174:177], v[100:103]
	v_mfma_f32_16x16x32_bf16 v[84:87], v[198:201], v[182:185], v[84:87]
	v_mfma_f32_16x16x32_bf16 v[84:87], v[202:205], v[186:189], v[84:87]
	v_mfma_f32_16x16x32_bf16 v[80:83], v[210:213], v[186:189], v[80:83]
	v_mfma_f32_16x16x32_bf16 v[80:83], v[206:209], v[182:185], v[80:83]
	v_mfma_f32_16x16x32_bf16 v[64:67], v[206:209], v[190:193], v[64:67]
	v_mfma_f32_16x16x32_bf16 v[64:67], v[210:213], v[194:197], v[64:67]
	v_mfma_f32_16x16x32_bf16 v[68:71], v[202:205], v[194:197], v[68:71]
	v_mfma_f32_16x16x32_bf16 v[68:71], v[198:201], v[190:193], v[68:71]
	s_mov_b32 m0, s47
	v_lshl_add_u64 v[218:219], v[222:223], 0, s[6:7]
	s_barrier
	ds_read_b128 v[166:169], v148 offset:49152
	ds_read_b128 v[170:173], v148 offset:50176
	ds_read_b128 v[174:177], v148 offset:51200
	ds_read_b128 v[178:181], v148 offset:52224
	ds_read_b128 v[182:185], v148 offset:53248
	ds_read_b128 v[186:189], v148 offset:54272
	ds_read_b128 v[190:193], v148 offset:55296
	ds_read_b128 v[194:197], v148 offset:56320
	global_load_lds_dwordx4 v[218:219], off
	v_lshl_add_u64 v[218:219], v[224:225], 0, s[6:7]
	s_mov_b32 m0, s48
	s_nop 0
	global_load_lds_dwordx4 v[218:219], off
	s_barrier
	s_waitcnt lgkmcnt(0)
	s_waitcnt lgkmcnt(0)
	v_mfma_f32_16x16x32_bf16 v[60:63], v[150:153], v[166:169], v[60:63]
	v_mfma_f32_16x16x32_bf16 v[60:63], v[154:157], v[170:173], v[60:63]
	v_mfma_f32_16x16x32_bf16 v[56:59], v[162:165], v[170:173], v[56:59]
	v_mfma_f32_16x16x32_bf16 v[56:59], v[158:161], v[166:169], v[56:59]
	v_mfma_f32_16x16x32_bf16 v[40:43], v[158:161], v[174:177], v[40:43]
	v_mfma_f32_16x16x32_bf16 v[40:43], v[162:165], v[178:181], v[40:43]
	v_mfma_f32_16x16x32_bf16 v[44:47], v[154:157], v[178:181], v[44:47]
	v_mfma_f32_16x16x32_bf16 v[44:47], v[150:153], v[174:177], v[44:47]
	v_mfma_f32_16x16x32_bf16 v[28:31], v[150:153], v[182:185], v[28:31]
	v_mfma_f32_16x16x32_bf16 v[28:31], v[154:157], v[186:189], v[28:31]
	v_mfma_f32_16x16x32_bf16 v[24:27], v[162:165], v[186:189], v[24:27]
	v_mfma_f32_16x16x32_bf16 v[24:27], v[158:161], v[182:185], v[24:27]
	v_mfma_f32_16x16x32_bf16 v[8:11], v[158:161], v[190:193], v[8:11]
	v_mfma_f32_16x16x32_bf16 v[8:11], v[162:165], v[194:197], v[8:11]
	v_mfma_f32_16x16x32_bf16 v[12:15], v[154:157], v[194:197], v[12:15]
	v_mfma_f32_16x16x32_bf16 v[12:15], v[150:153], v[190:193], v[12:15]
	s_barrier
	s_add_u32 s2, s38, 0x20080
	s_addc_u32 s3, s39, 0
	s_add_i32 s16, s17, s28
	v_lshl_add_u64 v[150:151], s[2:3], 0, v[132:133]
	s_mov_b32 m0, s16
	s_nop 0
	global_load_lds_dwordx4 v[150:151], off
	v_lshl_add_u64 v[150:151], s[2:3], 0, v[128:129]
	s_add_i32 m0, s16, 0x2000
	s_nop 0
	global_load_lds_dwordx4 v[150:151], off
	s_waitcnt vmcnt(6)
	s_barrier
	v_mfma_f32_16x16x32_bf16 v[52:55], v[198:201], v[166:169], v[52:55]
	v_mfma_f32_16x16x32_bf16 v[52:55], v[202:205], v[170:173], v[52:55]
	v_mfma_f32_16x16x32_bf16 v[48:51], v[210:213], v[170:173], v[48:51]
	v_mfma_f32_16x16x32_bf16 v[48:51], v[206:209], v[166:169], v[48:51]
	v_mfma_f32_16x16x32_bf16 v[32:35], v[206:209], v[174:177], v[32:35]
	v_mfma_f32_16x16x32_bf16 v[32:35], v[210:213], v[178:181], v[32:35]
	v_mfma_f32_16x16x32_bf16 v[36:39], v[202:205], v[178:181], v[36:39]
	v_mfma_f32_16x16x32_bf16 v[36:39], v[198:201], v[174:177], v[36:39]
	v_mfma_f32_16x16x32_bf16 v[20:23], v[198:201], v[182:185], v[20:23]
	v_mfma_f32_16x16x32_bf16 v[20:23], v[202:205], v[186:189], v[20:23]
	v_mfma_f32_16x16x32_bf16 v[16:19], v[210:213], v[186:189], v[16:19]
	v_mfma_f32_16x16x32_bf16 v[16:19], v[206:209], v[182:185], v[16:19]
	v_mfma_f32_16x16x32_bf16 v[0:3], v[206:209], v[190:193], v[0:3]
	v_mfma_f32_16x16x32_bf16 v[0:3], v[210:213], v[194:197], v[0:3]
	v_mfma_f32_16x16x32_bf16 v[4:7], v[202:205], v[194:197], v[4:7]
	v_mfma_f32_16x16x32_bf16 v[4:7], v[198:201], v[190:193], v[4:7]
	s_add_u32 s59, s59, 0x100
	s_addc_u32 s64, s64, 0
	s_cmp_ge_i32 s65, s46
	s_mov_b64 s[16:17], s[4:5]
	s_mov_b32 s38, s65
	s_barrier
	s_cbranch_scc0 .LBB0_802
	s_branch .LBB0_795

; #define PG8_STAGE(bufoff, gbase, voff) do { _Pragma("unroll") for (int _i = 0; _i < 2; ++_i) \
;         __builtin_amdgcn_global_load_lds((const unsigned*)((const char*)(gbase) + (voff)[_i]), (LAS unsigned*)(lds + (bufoff) + ldsw + _i * 8192), 16, 0, 0); } while (0)
; #define PG8_LDA(dst, b, h) do { _Pragma("unroll") for (int m = 0; m < 4; ++m) _Pragma("unroll") for (int k = 0; k < 2; ++k) dst[m][k] = *(const LAS bf16x8*)(lds + PG8_SA(b, h) + aoff + m * 2048 + k * 1024); } while (0)
; #define PG8_LDB(dst, b, h) do { _Pragma("unroll") for (int n = 0; n < 2; ++n) _Pragma("unroll") for (int k = 0; k < 2; ++k) dst[n][k] = *(const LAS bf16x8*)(lds + PG8_SB(b, h) + boff + n * 2048 + k * 1024); } while (0)
; #define PG8_MMA(ai, bj, At, Bt) do { __builtin_amdgcn_s_setprio(1); _Pragma("unroll") for (int m = 0; m < 4; ++m) _Pragma("unroll") for (int n = 0; n < 2; ++n) _Pragma("unroll") for (int k = 0; k < 2; ++k) \
;         acc[ai][bj][m][n] = __builtin_amdgcn_mfma_f32_16x16x32_bf16(Bt[n][k], At[m][k], acc[ai][bj][m][n], 0, 0, 0); __builtin_amdgcn_s_setprio(0); } while (0)
; #define PG8_WAIT_L(n) asm volatile("s_waitcnt lgkmcnt(" #n ")" ::: "memory")
; #define PG8_BAR __builtin_amdgcn_s_barrier()
; #define PG8_SCHED __builtin_amdgcn_sched_barrier(0)
; template <class Epi>
; DEVINL void gemm_phase(LAS unsigned char* lds, const Gemm g, const Order& S, const Epi& E) {
;     ...
;         const char* nA = has_next ? (const char*)g.A + (size_t)nxt.pm * tstepA : cA; const char* nB = has_next ? (const char*)g.Bt + (size_t)nxt.pn * tstepB : cB;
;         for (int t = 0; t < nt; t += 2) {
;             const bool last = (t == nt - 2);
;             const char* a1 = cA + (size_t)(t + 1) * kstep;
;             const char* a2 = last ? nA : cA + (size_t)(t + 2) * kstep; const char* b2 = last ? nB : cB + (size_t)(t + 2) * kstep;
;             const char* a3 = a2 + kstep; const char* b3 = b2 + kstep;
;             PG8_LDB(B0, 0, 0); PG8_SCHED; PG8_LDA(At, 0, 0); PG8_STAGE(PG8_SA(1, 1), a1 + hstepA, voffA);
;             PG8_WAIT_L(8); PG8_BAR; PG8_WAIT_L(0); PG8_MMA(0, 0, At, B0); PG8_BAR; PG8_SCHED;
;             PG8_LDB(B1, 0, 1); PG8_STAGE(PG8_SB(0, 0), b2, voffB);
;             PG8_BAR; PG8_WAIT_L(0); PG8_MMA(0, 1, At, B1); PG8_BAR;
;             PG8_LDA(At, 0, 1); PG8_STAGE(PG8_SA(0, 0), a2, voffA);
;             PG8_BAR; PG8_WAIT_L(0); PG8_MMA(1, 0, At, B0); PG8_BAR; PG8_SCHED;
.LBB0_825:
	ds_read_b128 v[150:153], v147
	ds_read_b128 v[154:157], v147 offset:1024
	ds_read_b128 v[158:161], v147 offset:2048
	ds_read_b128 v[162:165], v147 offset:3072
	s_add_i32 s68, s42, 2
	s_add_u32 s4, s38, 0x100
	s_addc_u32 s5, s39, 0
	s_cmp_eq_u32 s53, s42
	s_cselect_b32 s42, s65, s66
	s_cselect_b32 s45, s15, s5
	s_cselect_b32 s44, s14, s4
	s_cselect_b32 s43, s13, s67
	v_lshl_add_u64 v[198:199], s[38:39], 0, v[136:137]
	s_add_i32 m0, s31, 0xc000
	ds_read_b128 v[166:169], v148
	ds_read_b128 v[170:173], v148 offset:1024
	ds_read_b128 v[174:177], v148 offset:2048
	ds_read_b128 v[178:181], v148 offset:3072
	ds_read_b128 v[182:185], v148 offset:4096
	ds_read_b128 v[186:189], v148 offset:5120
	ds_read_b128 v[190:193], v148 offset:6144
	ds_read_b128 v[194:197], v148 offset:7168
	global_load_lds_dwordx4 v[198:199], off
	v_lshl_add_u64 v[198:199], s[38:39], 0, v[138:139]
	s_add_i32 m0, s31, 0xe000
	s_nop 0
	global_load_lds_dwordx4 v[198:199], off
	s_waitcnt lgkmcnt(8)
	s_barrier
	s_waitcnt lgkmcnt(0)
	s_waitcnt lgkmcnt(0)
	v_mfma_f32_16x16x32_bf16 v[120:123], v[150:153], v[166:169], v[120:123]
	v_mfma_f32_16x16x32_bf16 v[120:123], v[154:157], v[170:173], v[120:123]
	v_mfma_f32_16x16x32_bf16 v[124:127], v[162:165], v[170:173], v[124:127]
	v_mfma_f32_16x16x32_bf16 v[124:127], v[158:161], v[166:169], v[124:127]
	v_mfma_f32_16x16x32_bf16 v[104:107], v[158:161], v[174:177], v[104:107]
	v_mfma_f32_16x16x32_bf16 v[104:107], v[162:165], v[178:181], v[104:107]
	v_mfma_f32_16x16x32_bf16 v[108:111], v[154:157], v[178:181], v[108:111]
	v_mfma_f32_16x16x32_bf16 v[108:111], v[150:153], v[174:177], v[108:111]
	v_mfma_f32_16x16x32_bf16 v[92:95], v[150:153], v[182:185], v[92:95]
	v_mfma_f32_16x16x32_bf16 v[92:95], v[154:157], v[186:189], v[92:95]
	v_mfma_f32_16x16x32_bf16 v[88:91], v[162:165], v[186:189], v[88:91]
	v_mfma_f32_16x16x32_bf16 v[88:91], v[158:161], v[182:185], v[88:91]
	v_mfma_f32_16x16x32_bf16 v[72:75], v[158:161], v[190:193], v[72:75]
	v_mfma_f32_16x16x32_bf16 v[72:75], v[162:165], v[194:197], v[72:75]
	v_mfma_f32_16x16x32_bf16 v[76:79], v[154:157], v[194:197], v[76:79]
	v_mfma_f32_16x16x32_bf16 v[76:79], v[150:153], v[190:193], v[76:79]
	s_barrier
	s_add_i32 s2, s57, s30
	v_lshl_add_u64 v[218:219], s[42:43], 0, v[130:131]
	s_mov_b32 m0, s2
	ds_read_b128 v[198:201], v149
	ds_read_b128 v[202:205], v149 offset:1024
	ds_read_b128 v[206:209], v149 offset:2048
	ds_read_b128 v[210:213], v149 offset:3072
	global_load_lds_dwordx4 v[218:219], off
	v_lshl_add_u64 v[220:221], s[42:43], 0, v[134:135]
	s_add_i32 m0, s2, 0x2000
	s_nop 0
	global_load_lds_dwordx4 v[220:221], off
	s_barrier
	s_waitcnt lgkmcnt(0)
	s_waitcnt lgkmcnt(0)
	v_mfma_f32_16x16x32_bf16 v[116:119], v[198:201], v[166:169], v[116:119]
	v_mfma_f32_16x16x32_bf16 v[116:119], v[202:205], v[170:173], v[116:119]
	v_mfma_f32_16x16x32_bf16 v[112:115], v[210:213], v[170:173], v[112:115]
	v_mfma_f32_16x16x32_bf16 v[112:115], v[206:209], v[166:169], v[112:115]
	v_mfma_f32_16x16x32_bf16 v[96:99], v[206:209], v[174:177], v[96:99]
	v_mfma_f32_16x16x32_bf16 v[96:99], v[210:213], v[178:181], v[96:99]
	v_mfma_f32_16x16x32_bf16 v[100:103], v[202:205], v[178:181], v[100:103]
	v_mfma_f32_16x16x32_bf16 v[100:103], v[198:201], v[174:177], v[100:103]
	v_mfma_f32_16x16x32_bf16 v[84:87], v[198:201], v[182:185], v[84:87]
	v_mfma_f32_16x16x32_bf16 v[84:87], v[202:205], v[186:189], v[84:87]
	v_mfma_f32_16x16x32_bf16 v[80:83], v[210:213], v[186:189], v[80:83]
	v_mfma_f32_16x16x32_bf16 v[80:83], v[206:209], v[182:185], v[80:83]
	v_mfma_f32_16x16x32_bf16 v[64:67], v[206:209], v[190:193], v[64:67]
	v_mfma_f32_16x16x32_bf16 v[64:67], v[210:213], v[194:197], v[64:67]
	v_mfma_f32_16x16x32_bf16 v[68:71], v[202:205], v[194:197], v[68:71]
	v_mfma_f32_16x16x32_bf16 v[68:71], v[198:201], v[190:193], v[68:71]
	s_mov_b32 m0, s31
	v_lshl_add_u64 v[222:223], s[44:45], 0, v[128:129]
	s_barrier
	ds_read_b128 v[166:169], v148 offset:16384
	ds_read_b128 v[170:173], v148 offset:17408
	ds_read_b128 v[174:177], v148 offset:18432
	ds_read_b128 v[178:181], v148 offset:19456
	ds_read_b128 v[182:185], v148 offset:20480
	ds_read_b128 v[186:189], v148 offset:21504
	ds_read_b128 v[190:193], v148 offset:22528
	ds_read_b128 v[194:197], v148 offset:23552
	global_load_lds_dwordx4 v[222:223], off
	v_lshl_add_u64 v[224:225], s[44:45], 0, v[132:133]
	s_mov_b32 m0, s46
	s_nop 0
	global_load_lds_dwordx4 v[224:225], off
	s_barrier
	s_waitcnt lgkmcnt(0)
	s_waitcnt lgkmcnt(0)
	v_mfma_f32_16x16x32_bf16 v[60:63], v[150:153], v[166:169], v[60:63]
	v_mfma_f32_16x16x32_bf16 v[60:63], v[154:157], v[170:173], v[60:63]
	v_mfma_f32_16x16x32_bf16 v[56:59], v[162:165], v[170:173], v[56:59]
	v_mfma_f32_16x16x32_bf16 v[56:59], v[158:161], v[166:169], v[56:59]
	v_mfma_f32_16x16x32_bf16 v[40:43], v[158:161], v[174:177], v[40:43]
	v_mfma_f32_16x16x32_bf16 v[40:43], v[162:165], v[178:181], v[40:43]
	v_mfma_f32_16x16x32_bf16 v[44:47], v[154:157], v[178:181], v[44:47]
	v_mfma_f32_16x16x32_bf16 v[44:47], v[150:153], v[174:177], v[44:47]
	v_mfma_f32_16x16x32_bf16 v[28:31], v[150:153], v[182:185], v[28:31]
	v_mfma_f32_16x16x32_bf16 v[28:31], v[154:157], v[186:189], v[28:31]
	v_mfma_f32_16x16x32_bf16 v[24:27], v[162:165], v[186:189], v[24:27]
	v_mfma_f32_16x16x32_bf16 v[24:27], v[158:161], v[182:185], v[24:27]
	v_mfma_f32_16x16x32_bf16 v[8:11], v[158:161], v[190:193], v[8:11]
	v_mfma_f32_16x16x32_bf16 v[8:11], v[162:165], v[194:197], v[8:11]
	v_mfma_f32_16x16x32_bf16 v[12:15], v[154:157], v[194:197], v[12:15]
	v_mfma_f32_16x16x32_bf16 v[12:15], v[150:153], v[190:193], v[12:15]
	s_barrier
; #define PG8_STAGE(bufoff, gbase, voff) do { _Pragma("unroll") for (int _i = 0; _i < 2; ++_i) \
;         __builtin_amdgcn_global_load_lds((const unsigned*)((const char*)(gbase) + (voff)[_i]), (LAS unsigned*)(lds + (bufoff) + ldsw + _i * 8192), 16, 0, 0); } while (0)
; #define PG8_LDA(dst, b, h) do { _Pragma("unroll") for (int m = 0; m < 4; ++m) _Pragma("unroll") for (int k = 0; k < 2; ++k) dst[m][k] = *(const LAS bf16x8*)(lds + PG8_SA(b, h) + aoff + m * 2048 + k * 1024); } while (0)
; #define PG8_LDB(dst, b, h) do { _Pragma("unroll") for (int n = 0; n < 2; ++n) _Pragma("unroll") for (int k = 0; k < 2; ++k) dst[n][k] = *(const LAS bf16x8*)(lds + PG8_SB(b, h) + boff + n * 2048 + k * 1024); } while (0)
; #define PG8_MMA(ai, bj, At, Bt) do { __builtin_amdgcn_s_setprio(1); _Pragma("unroll") for (int m = 0; m < 4; ++m) _Pragma("unroll") for (int n = 0; n < 2; ++n) _Pragma("unroll") for (int k = 0; k < 2; ++k) \
;         acc[ai][bj][m][n] = __builtin_amdgcn_mfma_f32_16x16x32_bf16(Bt[n][k], At[m][k], acc[ai][bj][m][n], 0, 0, 0); __builtin_amdgcn_s_setprio(0); } while (0)
; #define PG8_WAIT_V(n) asm volatile("s_waitcnt vmcnt(" #n ")" ::: "memory")
; #define PG8_WAIT_L(n) asm volatile("s_waitcnt lgkmcnt(" #n ")" ::: "memory")
; #define PG8_BAR __builtin_amdgcn_s_barrier()
; #define PG8_SCHED __builtin_amdgcn_sched_barrier(0)
; template <class Epi>
; DEVINL void gemm_phase(LAS unsigned char* lds, const Gemm g, const Order& S, const Epi& E) {
;     ...
;             PG8_STAGE(PG8_SB(0, 1), b2 + hstepB, voffB);
;             PG8_WAIT_V(6); PG8_BAR; PG8_MMA(1, 1, At, B1); PG8_BAR;
;             PG8_LDB(B0, 1, 0); PG8_SCHED; PG8_LDA(At, 1, 0); PG8_STAGE(PG8_SA(0, 1), a2 + hstepA, voffA);
;             PG8_WAIT_L(8); PG8_BAR; PG8_WAIT_L(0); PG8_MMA(0, 0, At, B0); PG8_BAR; PG8_SCHED;
;             PG8_LDB(B1, 1, 1); PG8_STAGE(PG8_SB(1, 0), b3, voffB);
	s_add_u32 s2, s42, 0x10000
	s_addc_u32 s3, s43, 0
	s_add_i32 s38, s58, s30
	v_lshl_add_u64 v[150:151], s[2:3], 0, v[130:131]
	s_mov_b32 m0, s38
	s_nop 0
	global_load_lds_dwordx4 v[150:151], off
	v_lshl_add_u64 v[150:151], s[2:3], 0, v[134:135]
	s_add_i32 m0, s38, 0x2000
	s_nop 0
	global_load_lds_dwordx4 v[150:151], off
	s_waitcnt vmcnt(6)
	s_barrier
	v_mfma_f32_16x16x32_bf16 v[52:55], v[198:201], v[166:169], v[52:55]
	v_mfma_f32_16x16x32_bf16 v[52:55], v[202:205], v[170:173], v[52:55]
	v_mfma_f32_16x16x32_bf16 v[48:51], v[210:213], v[170:173], v[48:51]
	v_mfma_f32_16x16x32_bf16 v[48:51], v[206:209], v[166:169], v[48:51]
	v_mfma_f32_16x16x32_bf16 v[32:35], v[206:209], v[174:177], v[32:35]
	v_mfma_f32_16x16x32_bf16 v[32:35], v[210:213], v[178:181], v[32:35]
	v_mfma_f32_16x16x32_bf16 v[36:39], v[202:205], v[178:181], v[36:39]
	v_mfma_f32_16x16x32_bf16 v[36:39], v[198:201], v[174:177], v[36:39]
	v_mfma_f32_16x16x32_bf16 v[20:23], v[198:201], v[182:185], v[20:23]
	v_mfma_f32_16x16x32_bf16 v[20:23], v[202:205], v[186:189], v[20:23]
	v_mfma_f32_16x16x32_bf16 v[16:19], v[210:213], v[186:189], v[16:19]
	v_mfma_f32_16x16x32_bf16 v[16:19], v[206:209], v[182:185], v[16:19]
	v_mfma_f32_16x16x32_bf16 v[0:3], v[206:209], v[190:193], v[0:3]
	v_mfma_f32_16x16x32_bf16 v[0:3], v[210:213], v[194:197], v[0:3]
	v_mfma_f32_16x16x32_bf16 v[4:7], v[202:205], v[194:197], v[4:7]
	v_mfma_f32_16x16x32_bf16 v[4:7], v[198:201], v[190:193], v[4:7]
	s_add_i32 s38, 16, 0x18000
	v_add_u32_e32 v162, s38, v145
	s_barrier
	ds_read_b128 v[150:153], v162
	ds_read_b128 v[154:157], v162 offset:1024
	ds_read_b128 v[158:161], v162 offset:2048
	ds_read_b128 v[162:165], v162 offset:3072
	s_add_u32 s2, s44, 0x30000
	s_addc_u32 s3, s45, 0
	s_mov_b32 m0, s47
	v_lshl_add_u64 v[198:199], s[2:3], 0, v[128:129]
	ds_read_b128 v[166:169], v148 offset:32768
	ds_read_b128 v[170:173], v148 offset:33792
	ds_read_b128 v[174:177], v148 offset:34816
	ds_read_b128 v[178:181], v148 offset:35840
	ds_read_b128 v[182:185], v148 offset:36864
	ds_read_b128 v[186:189], v148 offset:37888
	ds_read_b128 v[190:193], v148 offset:38912
	ds_read_b128 v[194:197], v148 offset:39936
	global_load_lds_dwordx4 v[198:199], off
	v_lshl_add_u64 v[198:199], s[2:3], 0, v[132:133]
	s_mov_b32 m0, s48
	s_nop 0
	global_load_lds_dwordx4 v[198:199], off
	s_waitcnt lgkmcnt(8)
	s_barrier
	s_waitcnt lgkmcnt(0)
	s_waitcnt lgkmcnt(0)
	v_mfma_f32_16x16x32_bf16 v[120:123], v[150:153], v[166:169], v[120:123]
	v_mfma_f32_16x16x32_bf16 v[120:123], v[154:157], v[170:173], v[120:123]
	v_mfma_f32_16x16x32_bf16 v[124:127], v[162:165], v[170:173], v[124:127]
	v_mfma_f32_16x16x32_bf16 v[124:127], v[158:161], v[166:169], v[124:127]
	v_mfma_f32_16x16x32_bf16 v[104:107], v[158:161], v[174:177], v[104:107]
	v_mfma_f32_16x16x32_bf16 v[104:107], v[162:165], v[178:181], v[104:107]
	v_mfma_f32_16x16x32_bf16 v[108:111], v[154:157], v[178:181], v[108:111]
	v_mfma_f32_16x16x32_bf16 v[108:111], v[150:153], v[174:177], v[108:111]
	v_mfma_f32_16x16x32_bf16 v[92:95], v[150:153], v[182:185], v[92:95]
	v_mfma_f32_16x16x32_bf16 v[92:95], v[154:157], v[186:189], v[92:95]
	v_mfma_f32_16x16x32_bf16 v[88:91], v[162:165], v[186:189], v[88:91]
	v_mfma_f32_16x16x32_bf16 v[88:91], v[158:161], v[182:185], v[88:91]
	v_mfma_f32_16x16x32_bf16 v[72:75], v[158:161], v[190:193], v[72:75]
	v_mfma_f32_16x16x32_bf16 v[72:75], v[162:165], v[194:197], v[72:75]
	v_mfma_f32_16x16x32_bf16 v[76:79], v[154:157], v[194:197], v[76:79]
	v_mfma_f32_16x16x32_bf16 v[76:79], v[150:153], v[190:193], v[76:79]
	s_barrier
	s_add_i32 s39, 16, 0x1c000
	s_add_i32 s2, s38, s30
	v_add_u32_e32 v210, s39, v145
	v_lshl_add_u64 v[218:219], v[218:219], 0, s[8:9]
	s_mov_b32 m0, s2
	ds_read_b128 v[198:201], v210
	ds_read_b128 v[202:205], v210 offset:1024
	ds_read_b128 v[206:209], v210 offset:2048
	ds_read_b128 v[210:213], v210 offset:3072
	global_load_lds_dwordx4 v[218:219], off
	v_lshl_add_u64 v[218:219], v[220:221], 0, s[8:9]
	s_add_i32 m0, s2, 0x2000
	s_nop 0
	global_load_lds_dwordx4 v[218:219], off
	s_barrier
; #define PG8_STAGE(bufoff, gbase, voff) do { _Pragma("unroll") for (int _i = 0; _i < 2; ++_i) \
;         __builtin_amdgcn_global_load_lds((const unsigned*)((const char*)(gbase) + (voff)[_i]), (LAS unsigned*)(lds + (bufoff) + ldsw + _i * 8192), 16, 0, 0); } while (0)
; #define PG8_LDA(dst, b, h) do { _Pragma("unroll") for (int m = 0; m < 4; ++m) _Pragma("unroll") for (int k = 0; k < 2; ++k) dst[m][k] = *(const LAS bf16x8*)(lds + PG8_SA(b, h) + aoff + m * 2048 + k * 1024); } while (0)
; #define PG8_MMA(ai, bj, At, Bt) do { __builtin_amdgcn_s_setprio(1); _Pragma("unroll") for (int m = 0; m < 4; ++m) _Pragma("unroll") for (int n = 0; n < 2; ++n) _Pragma("unroll") for (int k = 0; k < 2; ++k) \
;         acc[ai][bj][m][n] = __builtin_amdgcn_mfma_f32_16x16x32_bf16(Bt[n][k], At[m][k], acc[ai][bj][m][n], 0, 0, 0); __builtin_amdgcn_s_setprio(0); } while (0)
; #define PG8_WAIT_V(n) asm volatile("s_waitcnt vmcnt(" #n ")" ::: "memory")
; #define PG8_WAIT_L(n) asm volatile("s_waitcnt lgkmcnt(" #n ")" ::: "memory")
; #define PG8_BAR __builtin_amdgcn_s_barrier()
; #define PG8_SCHED __builtin_amdgcn_sched_barrier(0)
; template <class Epi>
; DEVINL void gemm_phase(LAS unsigned char* lds, const Gemm g, const Order& S, const Epi& E) {
;     ...
;             PG8_BAR; PG8_WAIT_L(0); PG8_MMA(0, 1, At, B1); PG8_BAR;
;             PG8_LDA(At, 1, 1); PG8_STAGE(PG8_SA(1, 0), a3, voffA);
;             PG8_BAR; PG8_WAIT_L(0); PG8_MMA(1, 0, At, B0); PG8_BAR; PG8_SCHED;
;             PG8_STAGE(PG8_SB(1, 1), b3 + hstepB, voffB);
;             PG8_WAIT_V(6); PG8_BAR; PG8_MMA(1, 1, At, B1); PG8_BAR;
	s_waitcnt lgkmcnt(0)
	s_waitcnt lgkmcnt(0)
	v_mfma_f32_16x16x32_bf16 v[116:119], v[198:201], v[166:169], v[116:119]
	v_mfma_f32_16x16x32_bf16 v[116:119], v[202:205], v[170:173], v[116:119]
	v_mfma_f32_16x16x32_bf16 v[112:115], v[210:213], v[170:173], v[112:115]
	v_mfma_f32_16x16x32_bf16 v[112:115], v[206:209], v[166:169], v[112:115]
	v_mfma_f32_16x16x32_bf16 v[96:99], v[206:209], v[174:177], v[96:99]
	v_mfma_f32_16x16x32_bf16 v[96:99], v[210:213], v[178:181], v[96:99]
	v_mfma_f32_16x16x32_bf16 v[100:103], v[202:205], v[178:181], v[100:103]
	v_mfma_f32_16x16x32_bf16 v[100:103], v[198:201], v[174:177], v[100:103]
	v_mfma_f32_16x16x32_bf16 v[84:87], v[198:201], v[182:185], v[84:87]
	v_mfma_f32_16x16x32_bf16 v[84:87], v[202:205], v[186:189], v[84:87]
	v_mfma_f32_16x16x32_bf16 v[80:83], v[210:213], v[186:189], v[80:83]
	v_mfma_f32_16x16x32_bf16 v[80:83], v[206:209], v[182:185], v[80:83]
	v_mfma_f32_16x16x32_bf16 v[64:67], v[206:209], v[190:193], v[64:67]
	v_mfma_f32_16x16x32_bf16 v[64:67], v[210:213], v[194:197], v[64:67]
	v_mfma_f32_16x16x32_bf16 v[68:71], v[202:205], v[194:197], v[68:71]
	v_mfma_f32_16x16x32_bf16 v[68:71], v[198:201], v[190:193], v[68:71]
	s_mov_b32 m0, s50
	v_lshl_add_u64 v[218:219], v[222:223], 0, s[8:9]
	s_barrier
	ds_read_b128 v[166:169], v148 offset:49152
	ds_read_b128 v[170:173], v148 offset:50176
	ds_read_b128 v[174:177], v148 offset:51200
	ds_read_b128 v[178:181], v148 offset:52224
	ds_read_b128 v[182:185], v148 offset:53248
	ds_read_b128 v[186:189], v148 offset:54272
	ds_read_b128 v[190:193], v148 offset:55296
	ds_read_b128 v[194:197], v148 offset:56320
	global_load_lds_dwordx4 v[218:219], off
	v_lshl_add_u64 v[218:219], v[224:225], 0, s[8:9]
	s_mov_b32 m0, s51
	s_nop 0
	global_load_lds_dwordx4 v[218:219], off
	s_barrier
	s_waitcnt lgkmcnt(0)
	s_waitcnt lgkmcnt(0)
	v_mfma_f32_16x16x32_bf16 v[60:63], v[150:153], v[166:169], v[60:63]
	v_mfma_f32_16x16x32_bf16 v[60:63], v[154:157], v[170:173], v[60:63]
	v_mfma_f32_16x16x32_bf16 v[56:59], v[162:165], v[170:173], v[56:59]
	v_mfma_f32_16x16x32_bf16 v[56:59], v[158:161], v[166:169], v[56:59]
	v_mfma_f32_16x16x32_bf16 v[40:43], v[158:161], v[174:177], v[40:43]
	v_mfma_f32_16x16x32_bf16 v[40:43], v[162:165], v[178:181], v[40:43]
	v_mfma_f32_16x16x32_bf16 v[44:47], v[154:157], v[178:181], v[44:47]
	v_mfma_f32_16x16x32_bf16 v[44:47], v[150:153], v[174:177], v[44:47]
	v_mfma_f32_16x16x32_bf16 v[28:31], v[150:153], v[182:185], v[28:31]
	v_mfma_f32_16x16x32_bf16 v[28:31], v[154:157], v[186:189], v[28:31]
	v_mfma_f32_16x16x32_bf16 v[24:27], v[162:165], v[186:189], v[24:27]
	v_mfma_f32_16x16x32_bf16 v[24:27], v[158:161], v[182:185], v[24:27]
	v_mfma_f32_16x16x32_bf16 v[8:11], v[158:161], v[190:193], v[8:11]
	v_mfma_f32_16x16x32_bf16 v[8:11], v[162:165], v[194:197], v[8:11]
	v_mfma_f32_16x16x32_bf16 v[12:15], v[154:157], v[194:197], v[12:15]
	v_mfma_f32_16x16x32_bf16 v[12:15], v[150:153], v[190:193], v[12:15]
	s_barrier
	s_add_u32 s2, s42, 0x10080
	s_addc_u32 s3, s43, 0
	s_add_i32 s38, s39, s30
	v_lshl_add_u64 v[150:151], s[2:3], 0, v[130:131]
	s_mov_b32 m0, s38
	s_nop 0
	global_load_lds_dwordx4 v[150:151], off
	v_lshl_add_u64 v[150:151], s[2:3], 0, v[134:135]
	s_add_i32 m0, s38, 0x2000
	s_nop 0
	global_load_lds_dwordx4 v[150:151], off
	s_waitcnt vmcnt(6)
	s_barrier
	v_mfma_f32_16x16x32_bf16 v[52:55], v[198:201], v[166:169], v[52:55]
	v_mfma_f32_16x16x32_bf16 v[52:55], v[202:205], v[170:173], v[52:55]
	v_mfma_f32_16x16x32_bf16 v[48:51], v[210:213], v[170:173], v[48:51]
	v_mfma_f32_16x16x32_bf16 v[48:51], v[206:209], v[166:169], v[48:51]
	v_mfma_f32_16x16x32_bf16 v[32:35], v[206:209], v[174:177], v[32:35]
	v_mfma_f32_16x16x32_bf16 v[32:35], v[210:213], v[178:181], v[32:35]
	v_mfma_f32_16x16x32_bf16 v[36:39], v[202:205], v[178:181], v[36:39]
	v_mfma_f32_16x16x32_bf16 v[36:39], v[198:201], v[174:177], v[36:39]
	v_mfma_f32_16x16x32_bf16 v[20:23], v[198:201], v[182:185], v[20:23]
	v_mfma_f32_16x16x32_bf16 v[20:23], v[202:205], v[186:189], v[20:23]
	v_mfma_f32_16x16x32_bf16 v[16:19], v[210:213], v[186:189], v[16:19]
	v_mfma_f32_16x16x32_bf16 v[16:19], v[206:209], v[182:185], v[16:19]
	v_mfma_f32_16x16x32_bf16 v[0:3], v[206:209], v[190:193], v[0:3]
	v_mfma_f32_16x16x32_bf16 v[0:3], v[210:213], v[194:197], v[0:3]
	v_mfma_f32_16x16x32_bf16 v[4:7], v[202:205], v[194:197], v[4:7]
	v_mfma_f32_16x16x32_bf16 v[4:7], v[198:201], v[190:193], v[4:7]
	s_add_u32 s66, s66, 0x100
	s_addc_u32 s67, s67, 0
	s_cmp_ge_i32 s68, s49
	s_mov_b64 s[38:39], s[4:5]
	s_mov_b32 s42, s68
	s_barrier
	s_cbranch_scc0 .LBB0_825
	s_branch .LBB0_814

; #define PG8_STAGE(bufoff, gbase, voff) do { _Pragma("unroll") for (int _i = 0; _i < 2; ++_i) \
;         __builtin_amdgcn_global_load_lds((const unsigned*)((const char*)(gbase) + (voff)[_i]), (LAS unsigned*)(lds + (bufoff) + ldsw + _i * 8192), 16, 0, 0); } while (0)
; #define PG8_LDA(dst, b, h) do { _Pragma("unroll") for (int m = 0; m < 4; ++m) _Pragma("unroll") for (int k = 0; k < 2; ++k) dst[m][k] = *(const LAS bf16x8*)(lds + PG8_SA(b, h) + aoff + m * 2048 + k * 1024); } while (0)
; #define PG8_LDB(dst, b, h) do { _Pragma("unroll") for (int n = 0; n < 2; ++n) _Pragma("unroll") for (int k = 0; k < 2; ++k) dst[n][k] = *(const LAS bf16x8*)(lds + PG8_SB(b, h) + boff + n * 2048 + k * 1024); } while (0)
; #define PG8_MMA(ai, bj, At, Bt) do { __builtin_amdgcn_s_setprio(1); _Pragma("unroll") for (int m = 0; m < 4; ++m) _Pragma("unroll") for (int n = 0; n < 2; ++n) _Pragma("unroll") for (int k = 0; k < 2; ++k) \
;         acc[ai][bj][m][n] = __builtin_amdgcn_mfma_f32_16x16x32_bf16(Bt[n][k], At[m][k], acc[ai][bj][m][n], 0, 0, 0); __builtin_amdgcn_s_setprio(0); } while (0)
; #define PG8_WAIT_L(n) asm volatile("s_waitcnt lgkmcnt(" #n ")" ::: "memory")
; #define PG8_BAR __builtin_amdgcn_s_barrier()
; #define PG8_SCHED __builtin_amdgcn_sched_barrier(0)
; template <class Epi>
; DEVINL void gemm_phase(LAS unsigned char* lds, const Gemm g, const Order& S, const Epi& E) {
;     ...
;         const char* nA = has_next ? (const char*)g.A + (size_t)nxt.pm * tstepA : cA; const char* nB = has_next ? (const char*)g.Bt + (size_t)nxt.pn * tstepB : cB;
;         for (int t = 0; t < nt; t += 2) {
;             const bool last = (t == nt - 2);
;             const char* a1 = cA + (size_t)(t + 1) * kstep;
;             const char* a2 = last ? nA : cA + (size_t)(t + 2) * kstep; const char* b2 = last ? nB : cB + (size_t)(t + 2) * kstep;
;             const char* a3 = a2 + kstep; const char* b3 = b2 + kstep;
;             PG8_LDB(B0, 0, 0); PG8_SCHED; PG8_LDA(At, 0, 0); PG8_STAGE(PG8_SA(1, 1), a1 + hstepA, voffA);
;             PG8_WAIT_L(8); PG8_BAR; PG8_WAIT_L(0); PG8_MMA(0, 0, At, B0); PG8_BAR; PG8_SCHED;
;             PG8_LDB(B1, 0, 1); PG8_STAGE(PG8_SB(0, 0), b2, voffB);
;             PG8_BAR; PG8_WAIT_L(0); PG8_MMA(0, 1, At, B1); PG8_BAR;
;             PG8_LDA(At, 0, 1); PG8_STAGE(PG8_SA(0, 0), a2, voffA);
;             PG8_BAR; PG8_WAIT_L(0); PG8_MMA(1, 0, At, B0); PG8_BAR; PG8_SCHED;
.LBB0_848:
	ds_read_b128 v[150:153], v147
	ds_read_b128 v[154:157], v147 offset:1024
	ds_read_b128 v[158:161], v147 offset:2048
	ds_read_b128 v[162:165], v147 offset:3072
	s_add_i32 s67, s44, 2
	s_add_u32 s2, s4, 0xffff0080
	s_addc_u32 s3, s5, -1
	s_cmp_eq_u32 s25, s44
	s_cselect_b32 s44, s16, s65
	s_cselect_b32 s47, s13, s3
	s_cselect_b32 s46, s64, s2
	s_cselect_b32 s45, s17, s66
	v_lshl_add_u64 v[198:199], s[4:5], 0, v[136:137]
	s_add_i32 m0, s9, 0xc000
	ds_read_b128 v[166:169], v148
	ds_read_b128 v[170:173], v148 offset:1024
	ds_read_b128 v[174:177], v148 offset:2048
	ds_read_b128 v[178:181], v148 offset:3072
	ds_read_b128 v[182:185], v148 offset:4096
	ds_read_b128 v[186:189], v148 offset:5120
	ds_read_b128 v[190:193], v148 offset:6144
	ds_read_b128 v[194:197], v148 offset:7168
	global_load_lds_dwordx4 v[198:199], off
	v_lshl_add_u64 v[198:199], s[4:5], 0, v[138:139]
	s_add_i32 m0, s9, 0xe000
	s_nop 0
	global_load_lds_dwordx4 v[198:199], off
	s_waitcnt lgkmcnt(8)
	s_barrier
	s_waitcnt lgkmcnt(0)
	s_waitcnt lgkmcnt(0)
	v_mfma_f32_16x16x32_bf16 v[120:123], v[150:153], v[166:169], v[120:123]
	v_mfma_f32_16x16x32_bf16 v[120:123], v[154:157], v[170:173], v[120:123]
	v_mfma_f32_16x16x32_bf16 v[124:127], v[162:165], v[170:173], v[124:127]
	v_mfma_f32_16x16x32_bf16 v[124:127], v[158:161], v[166:169], v[124:127]
	v_mfma_f32_16x16x32_bf16 v[104:107], v[158:161], v[174:177], v[104:107]
	v_mfma_f32_16x16x32_bf16 v[104:107], v[162:165], v[178:181], v[104:107]
	v_mfma_f32_16x16x32_bf16 v[108:111], v[154:157], v[178:181], v[108:111]
	v_mfma_f32_16x16x32_bf16 v[108:111], v[150:153], v[174:177], v[108:111]
	v_mfma_f32_16x16x32_bf16 v[92:95], v[150:153], v[182:185], v[92:95]
	v_mfma_f32_16x16x32_bf16 v[92:95], v[154:157], v[186:189], v[92:95]
	v_mfma_f32_16x16x32_bf16 v[88:91], v[162:165], v[186:189], v[88:91]
	v_mfma_f32_16x16x32_bf16 v[88:91], v[158:161], v[182:185], v[88:91]
	v_mfma_f32_16x16x32_bf16 v[72:75], v[158:161], v[190:193], v[72:75]
	v_mfma_f32_16x16x32_bf16 v[72:75], v[162:165], v[194:197], v[72:75]
	v_mfma_f32_16x16x32_bf16 v[76:79], v[154:157], v[194:197], v[76:79]
	v_mfma_f32_16x16x32_bf16 v[76:79], v[150:153], v[190:193], v[76:79]
	s_barrier
	s_add_i32 s2, s56, s30
	v_lshl_add_u64 v[218:219], s[44:45], 0, v[130:131]
	s_mov_b32 m0, s2
	ds_read_b128 v[198:201], v149
	ds_read_b128 v[202:205], v149 offset:1024
	ds_read_b128 v[206:209], v149 offset:2048
	ds_read_b128 v[210:213], v149 offset:3072
	global_load_lds_dwordx4 v[218:219], off
	v_lshl_add_u64 v[220:221], s[44:45], 0, v[134:135]
	s_add_i32 m0, s2, 0x2000
	s_nop 0
	global_load_lds_dwordx4 v[220:221], off
	s_barrier
	s_waitcnt lgkmcnt(0)
	s_waitcnt lgkmcnt(0)
	v_mfma_f32_16x16x32_bf16 v[116:119], v[198:201], v[166:169], v[116:119]
	v_mfma_f32_16x16x32_bf16 v[116:119], v[202:205], v[170:173], v[116:119]
	v_mfma_f32_16x16x32_bf16 v[112:115], v[210:213], v[170:173], v[112:115]
	v_mfma_f32_16x16x32_bf16 v[112:115], v[206:209], v[166:169], v[112:115]
	v_mfma_f32_16x16x32_bf16 v[96:99], v[206:209], v[174:177], v[96:99]
	v_mfma_f32_16x16x32_bf16 v[96:99], v[210:213], v[178:181], v[96:99]
	v_mfma_f32_16x16x32_bf16 v[100:103], v[202:205], v[178:181], v[100:103]
	v_mfma_f32_16x16x32_bf16 v[100:103], v[198:201], v[174:177], v[100:103]
	v_mfma_f32_16x16x32_bf16 v[84:87], v[198:201], v[182:185], v[84:87]
	v_mfma_f32_16x16x32_bf16 v[84:87], v[202:205], v[186:189], v[84:87]
	v_mfma_f32_16x16x32_bf16 v[80:83], v[210:213], v[186:189], v[80:83]
	v_mfma_f32_16x16x32_bf16 v[80:83], v[206:209], v[182:185], v[80:83]
	v_mfma_f32_16x16x32_bf16 v[64:67], v[206:209], v[190:193], v[64:67]
	v_mfma_f32_16x16x32_bf16 v[64:67], v[210:213], v[194:197], v[64:67]
	v_mfma_f32_16x16x32_bf16 v[68:71], v[202:205], v[194:197], v[68:71]
	v_mfma_f32_16x16x32_bf16 v[68:71], v[198:201], v[190:193], v[68:71]
	s_mov_b32 m0, s9
	v_lshl_add_u64 v[222:223], s[46:47], 0, v[128:129]
	s_barrier
	ds_read_b128 v[166:169], v148 offset:16384
	ds_read_b128 v[170:173], v148 offset:17408
	ds_read_b128 v[174:177], v148 offset:18432
	ds_read_b128 v[178:181], v148 offset:19456
	ds_read_b128 v[182:185], v148 offset:20480
	ds_read_b128 v[186:189], v148 offset:21504
	ds_read_b128 v[190:193], v148 offset:22528
	ds_read_b128 v[194:197], v148 offset:23552
	global_load_lds_dwordx4 v[222:223], off
	v_lshl_add_u64 v[224:225], s[46:47], 0, v[132:133]
	s_mov_b32 m0, s31
	s_nop 0
	global_load_lds_dwordx4 v[224:225], off
	s_barrier
	s_waitcnt lgkmcnt(0)
	s_waitcnt lgkmcnt(0)
	v_mfma_f32_16x16x32_bf16 v[60:63], v[150:153], v[166:169], v[60:63]
	v_mfma_f32_16x16x32_bf16 v[60:63], v[154:157], v[170:173], v[60:63]
	v_mfma_f32_16x16x32_bf16 v[56:59], v[162:165], v[170:173], v[56:59]
	v_mfma_f32_16x16x32_bf16 v[56:59], v[158:161], v[166:169], v[56:59]
	v_mfma_f32_16x16x32_bf16 v[40:43], v[158:161], v[174:177], v[40:43]
	v_mfma_f32_16x16x32_bf16 v[40:43], v[162:165], v[178:181], v[40:43]
	v_mfma_f32_16x16x32_bf16 v[44:47], v[154:157], v[178:181], v[44:47]
	v_mfma_f32_16x16x32_bf16 v[44:47], v[150:153], v[174:177], v[44:47]
	v_mfma_f32_16x16x32_bf16 v[28:31], v[150:153], v[182:185], v[28:31]
	v_mfma_f32_16x16x32_bf16 v[28:31], v[154:157], v[186:189], v[28:31]
	v_mfma_f32_16x16x32_bf16 v[24:27], v[162:165], v[186:189], v[24:27]
	v_mfma_f32_16x16x32_bf16 v[24:27], v[158:161], v[182:185], v[24:27]
	v_mfma_f32_16x16x32_bf16 v[8:11], v[158:161], v[190:193], v[8:11]
	v_mfma_f32_16x16x32_bf16 v[8:11], v[162:165], v[194:197], v[8:11]
	v_mfma_f32_16x16x32_bf16 v[12:15], v[154:157], v[194:197], v[12:15]
	v_mfma_f32_16x16x32_bf16 v[12:15], v[150:153], v[190:193], v[12:15]
	s_barrier
; #define PG8_STAGE(bufoff, gbase, voff) do { _Pragma("unroll") for (int _i = 0; _i < 2; ++_i) \
;         __builtin_amdgcn_global_load_lds((const unsigned*)((const char*)(gbase) + (voff)[_i]), (LAS unsigned*)(lds + (bufoff) + ldsw + _i * 8192), 16, 0, 0); } while (0)
; #define PG8_LDA(dst, b, h) do { _Pragma("unroll") for (int m = 0; m < 4; ++m) _Pragma("unroll") for (int k = 0; k < 2; ++k) dst[m][k] = *(const LAS bf16x8*)(lds + PG8_SA(b, h) + aoff + m * 2048 + k * 1024); } while (0)
; #define PG8_LDB(dst, b, h) do { _Pragma("unroll") for (int n = 0; n < 2; ++n) _Pragma("unroll") for (int k = 0; k < 2; ++k) dst[n][k] = *(const LAS bf16x8*)(lds + PG8_SB(b, h) + boff + n * 2048 + k * 1024); } while (0)
; #define PG8_MMA(ai, bj, At, Bt) do { __builtin_amdgcn_s_setprio(1); _Pragma("unroll") for (int m = 0; m < 4; ++m) _Pragma("unroll") for (int n = 0; n < 2; ++n) _Pragma("unroll") for (int k = 0; k < 2; ++k) \
;         acc[ai][bj][m][n] = __builtin_amdgcn_mfma_f32_16x16x32_bf16(Bt[n][k], At[m][k], acc[ai][bj][m][n], 0, 0, 0); __builtin_amdgcn_s_setprio(0); } while (0)
; #define PG8_WAIT_V(n) asm volatile("s_waitcnt vmcnt(" #n ")" ::: "memory")
; #define PG8_WAIT_L(n) asm volatile("s_waitcnt lgkmcnt(" #n ")" ::: "memory")
; #define PG8_BAR __builtin_amdgcn_s_barrier()
; #define PG8_SCHED __builtin_amdgcn_sched_barrier(0)
; template <class Epi>
; DEVINL void gemm_phase(LAS unsigned char* lds, const Gemm g, const Order& S, const Epi& E) {
;     ...
;             PG8_STAGE(PG8_SB(0, 1), b2 + hstepB, voffB);
;             PG8_WAIT_V(6); PG8_BAR; PG8_MMA(1, 1, At, B1); PG8_BAR;
;             PG8_LDB(B0, 1, 0); PG8_SCHED; PG8_LDA(At, 1, 0); PG8_STAGE(PG8_SA(0, 1), a2 + hstepA, voffA);
;             PG8_WAIT_L(8); PG8_BAR; PG8_WAIT_L(0); PG8_MMA(0, 0, At, B0); PG8_BAR; PG8_SCHED;
;             PG8_LDB(B1, 1, 1); PG8_STAGE(PG8_SB(1, 0), b3, voffB);
	s_add_u32 s2, s44, 0x30000
	s_addc_u32 s3, s45, 0
	s_add_i32 s68, s57, s30
	v_lshl_add_u64 v[150:151], s[2:3], 0, v[130:131]
	s_mov_b32 m0, s68
	s_nop 0
	global_load_lds_dwordx4 v[150:151], off
	v_lshl_add_u64 v[150:151], s[2:3], 0, v[134:135]
	s_add_i32 m0, s68, 0x2000
	s_nop 0
	global_load_lds_dwordx4 v[150:151], off
	s_waitcnt vmcnt(6)
	s_barrier
	v_mfma_f32_16x16x32_bf16 v[52:55], v[198:201], v[166:169], v[52:55]
	v_mfma_f32_16x16x32_bf16 v[52:55], v[202:205], v[170:173], v[52:55]
	v_mfma_f32_16x16x32_bf16 v[48:51], v[210:213], v[170:173], v[48:51]
	v_mfma_f32_16x16x32_bf16 v[48:51], v[206:209], v[166:169], v[48:51]
	v_mfma_f32_16x16x32_bf16 v[32:35], v[206:209], v[174:177], v[32:35]
	v_mfma_f32_16x16x32_bf16 v[32:35], v[210:213], v[178:181], v[32:35]
	v_mfma_f32_16x16x32_bf16 v[36:39], v[202:205], v[178:181], v[36:39]
	v_mfma_f32_16x16x32_bf16 v[36:39], v[198:201], v[174:177], v[36:39]
	v_mfma_f32_16x16x32_bf16 v[20:23], v[198:201], v[182:185], v[20:23]
	v_mfma_f32_16x16x32_bf16 v[20:23], v[202:205], v[186:189], v[20:23]
	v_mfma_f32_16x16x32_bf16 v[16:19], v[210:213], v[186:189], v[16:19]
	v_mfma_f32_16x16x32_bf16 v[16:19], v[206:209], v[182:185], v[16:19]
	v_mfma_f32_16x16x32_bf16 v[0:3], v[206:209], v[190:193], v[0:3]
	v_mfma_f32_16x16x32_bf16 v[0:3], v[210:213], v[194:197], v[0:3]
	v_mfma_f32_16x16x32_bf16 v[4:7], v[202:205], v[194:197], v[4:7]
	v_mfma_f32_16x16x32_bf16 v[4:7], v[198:201], v[190:193], v[4:7]
	s_add_i32 s68, 16, 0x18000
	v_add_u32_e32 v162, s68, v145
	s_barrier
	ds_read_b128 v[150:153], v162
	ds_read_b128 v[154:157], v162 offset:1024
	ds_read_b128 v[158:161], v162 offset:2048
	ds_read_b128 v[162:165], v162 offset:3072
	s_add_u32 s2, s46, 0x10000
	s_addc_u32 s3, s47, 0
	s_mov_b32 m0, s48
	v_lshl_add_u64 v[198:199], s[2:3], 0, v[128:129]
	ds_read_b128 v[166:169], v148 offset:32768
	ds_read_b128 v[170:173], v148 offset:33792
	ds_read_b128 v[174:177], v148 offset:34816
	ds_read_b128 v[178:181], v148 offset:35840
	ds_read_b128 v[182:185], v148 offset:36864
	ds_read_b128 v[186:189], v148 offset:37888
	ds_read_b128 v[190:193], v148 offset:38912
	ds_read_b128 v[194:197], v148 offset:39936
	global_load_lds_dwordx4 v[198:199], off
	v_lshl_add_u64 v[198:199], s[2:3], 0, v[132:133]
	s_mov_b32 m0, s49
	s_nop 0
	global_load_lds_dwordx4 v[198:199], off
	s_waitcnt lgkmcnt(8)
	s_barrier
	s_waitcnt lgkmcnt(0)
	s_waitcnt lgkmcnt(0)
	v_mfma_f32_16x16x32_bf16 v[120:123], v[150:153], v[166:169], v[120:123]
	v_mfma_f32_16x16x32_bf16 v[120:123], v[154:157], v[170:173], v[120:123]
	v_mfma_f32_16x16x32_bf16 v[124:127], v[162:165], v[170:173], v[124:127]
	v_mfma_f32_16x16x32_bf16 v[124:127], v[158:161], v[166:169], v[124:127]
	v_mfma_f32_16x16x32_bf16 v[104:107], v[158:161], v[174:177], v[104:107]
	v_mfma_f32_16x16x32_bf16 v[104:107], v[162:165], v[178:181], v[104:107]
	v_mfma_f32_16x16x32_bf16 v[108:111], v[154:157], v[178:181], v[108:111]
	v_mfma_f32_16x16x32_bf16 v[108:111], v[150:153], v[174:177], v[108:111]
	v_mfma_f32_16x16x32_bf16 v[92:95], v[150:153], v[182:185], v[92:95]
	v_mfma_f32_16x16x32_bf16 v[92:95], v[154:157], v[186:189], v[92:95]
	v_mfma_f32_16x16x32_bf16 v[88:91], v[162:165], v[186:189], v[88:91]
	v_mfma_f32_16x16x32_bf16 v[88:91], v[158:161], v[182:185], v[88:91]
	v_mfma_f32_16x16x32_bf16 v[72:75], v[158:161], v[190:193], v[72:75]
	v_mfma_f32_16x16x32_bf16 v[72:75], v[162:165], v[194:197], v[72:75]
	v_mfma_f32_16x16x32_bf16 v[76:79], v[154:157], v[194:197], v[76:79]
	v_mfma_f32_16x16x32_bf16 v[76:79], v[150:153], v[190:193], v[76:79]
	s_barrier
	s_add_i32 s46, 16, 0x1c000
	s_add_i32 s2, s68, s30
	v_add_u32_e32 v210, s46, v145
	v_lshl_add_u64 v[218:219], v[218:219], 0, s[6:7]
	s_mov_b32 m0, s2
	ds_read_b128 v[198:201], v210
	ds_read_b128 v[202:205], v210 offset:1024
	ds_read_b128 v[206:209], v210 offset:2048
	ds_read_b128 v[210:213], v210 offset:3072
	global_load_lds_dwordx4 v[218:219], off
	v_lshl_add_u64 v[218:219], v[220:221], 0, s[6:7]
	s_add_i32 m0, s2, 0x2000
	s_nop 0
	global_load_lds_dwordx4 v[218:219], off
	s_barrier
; #define PG8_STAGE(bufoff, gbase, voff) do { _Pragma("unroll") for (int _i = 0; _i < 2; ++_i) \
;         __builtin_amdgcn_global_load_lds((const unsigned*)((const char*)(gbase) + (voff)[_i]), (LAS unsigned*)(lds + (bufoff) + ldsw + _i * 8192), 16, 0, 0); } while (0)
; #define PG8_LDA(dst, b, h) do { _Pragma("unroll") for (int m = 0; m < 4; ++m) _Pragma("unroll") for (int k = 0; k < 2; ++k) dst[m][k] = *(const LAS bf16x8*)(lds + PG8_SA(b, h) + aoff + m * 2048 + k * 1024); } while (0)
; #define PG8_MMA(ai, bj, At, Bt) do { __builtin_amdgcn_s_setprio(1); _Pragma("unroll") for (int m = 0; m < 4; ++m) _Pragma("unroll") for (int n = 0; n < 2; ++n) _Pragma("unroll") for (int k = 0; k < 2; ++k) \
;         acc[ai][bj][m][n] = __builtin_amdgcn_mfma_f32_16x16x32_bf16(Bt[n][k], At[m][k], acc[ai][bj][m][n], 0, 0, 0); __builtin_amdgcn_s_setprio(0); } while (0)
; #define PG8_WAIT_V(n) asm volatile("s_waitcnt vmcnt(" #n ")" ::: "memory")
; #define PG8_WAIT_L(n) asm volatile("s_waitcnt lgkmcnt(" #n ")" ::: "memory")
; #define PG8_BAR __builtin_amdgcn_s_barrier()
; #define PG8_SCHED __builtin_amdgcn_sched_barrier(0)
; template <class Epi>
; DEVINL void gemm_phase(LAS unsigned char* lds, const Gemm g, const Order& S, const Epi& E) {
;     ...
;             PG8_BAR; PG8_WAIT_L(0); PG8_MMA(0, 1, At, B1); PG8_BAR;
;             PG8_LDA(At, 1, 1); PG8_STAGE(PG8_SA(1, 0), a3, voffA);
;             PG8_BAR; PG8_WAIT_L(0); PG8_MMA(1, 0, At, B0); PG8_BAR; PG8_SCHED;
;             PG8_STAGE(PG8_SB(1, 1), b3 + hstepB, voffB);
;             PG8_WAIT_V(6); PG8_BAR; PG8_MMA(1, 1, At, B1); PG8_BAR;
	s_waitcnt lgkmcnt(0)
	s_waitcnt lgkmcnt(0)
	v_mfma_f32_16x16x32_bf16 v[116:119], v[198:201], v[166:169], v[116:119]
	v_mfma_f32_16x16x32_bf16 v[116:119], v[202:205], v[170:173], v[116:119]
	v_mfma_f32_16x16x32_bf16 v[112:115], v[210:213], v[170:173], v[112:115]
	v_mfma_f32_16x16x32_bf16 v[112:115], v[206:209], v[166:169], v[112:115]
	v_mfma_f32_16x16x32_bf16 v[96:99], v[206:209], v[174:177], v[96:99]
	v_mfma_f32_16x16x32_bf16 v[96:99], v[210:213], v[178:181], v[96:99]
	v_mfma_f32_16x16x32_bf16 v[100:103], v[202:205], v[178:181], v[100:103]
	v_mfma_f32_16x16x32_bf16 v[100:103], v[198:201], v[174:177], v[100:103]
	v_mfma_f32_16x16x32_bf16 v[84:87], v[198:201], v[182:185], v[84:87]
	v_mfma_f32_16x16x32_bf16 v[84:87], v[202:205], v[186:189], v[84:87]
	v_mfma_f32_16x16x32_bf16 v[80:83], v[210:213], v[186:189], v[80:83]
	v_mfma_f32_16x16x32_bf16 v[80:83], v[206:209], v[182:185], v[80:83]
	v_mfma_f32_16x16x32_bf16 v[64:67], v[206:209], v[190:193], v[64:67]
	v_mfma_f32_16x16x32_bf16 v[64:67], v[210:213], v[194:197], v[64:67]
	v_mfma_f32_16x16x32_bf16 v[68:71], v[202:205], v[194:197], v[68:71]
	v_mfma_f32_16x16x32_bf16 v[68:71], v[198:201], v[190:193], v[68:71]
	s_mov_b32 m0, s52
	v_lshl_add_u64 v[218:219], v[222:223], 0, s[6:7]
	s_barrier
	ds_read_b128 v[166:169], v148 offset:49152
	ds_read_b128 v[170:173], v148 offset:50176
	ds_read_b128 v[174:177], v148 offset:51200
	ds_read_b128 v[178:181], v148 offset:52224
	ds_read_b128 v[182:185], v148 offset:53248
	ds_read_b128 v[186:189], v148 offset:54272
	ds_read_b128 v[190:193], v148 offset:55296
	ds_read_b128 v[194:197], v148 offset:56320
	global_load_lds_dwordx4 v[218:219], off
	v_lshl_add_u64 v[218:219], v[224:225], 0, s[6:7]
	s_mov_b32 m0, s53
	s_nop 0
	global_load_lds_dwordx4 v[218:219], off
	s_barrier
	s_waitcnt lgkmcnt(0)
	s_waitcnt lgkmcnt(0)
	v_mfma_f32_16x16x32_bf16 v[60:63], v[150:153], v[166:169], v[60:63]
	v_mfma_f32_16x16x32_bf16 v[60:63], v[154:157], v[170:173], v[60:63]
	v_mfma_f32_16x16x32_bf16 v[56:59], v[162:165], v[170:173], v[56:59]
	v_mfma_f32_16x16x32_bf16 v[56:59], v[158:161], v[166:169], v[56:59]
	v_mfma_f32_16x16x32_bf16 v[40:43], v[158:161], v[174:177], v[40:43]
	v_mfma_f32_16x16x32_bf16 v[40:43], v[162:165], v[178:181], v[40:43]
	v_mfma_f32_16x16x32_bf16 v[44:47], v[154:157], v[178:181], v[44:47]
	v_mfma_f32_16x16x32_bf16 v[44:47], v[150:153], v[174:177], v[44:47]
	v_mfma_f32_16x16x32_bf16 v[28:31], v[150:153], v[182:185], v[28:31]
	v_mfma_f32_16x16x32_bf16 v[28:31], v[154:157], v[186:189], v[28:31]
	v_mfma_f32_16x16x32_bf16 v[24:27], v[162:165], v[186:189], v[24:27]
	v_mfma_f32_16x16x32_bf16 v[24:27], v[158:161], v[182:185], v[24:27]
	v_mfma_f32_16x16x32_bf16 v[8:11], v[158:161], v[190:193], v[8:11]
	v_mfma_f32_16x16x32_bf16 v[8:11], v[162:165], v[194:197], v[8:11]
	v_mfma_f32_16x16x32_bf16 v[12:15], v[154:157], v[194:197], v[12:15]
	v_mfma_f32_16x16x32_bf16 v[12:15], v[150:153], v[190:193], v[12:15]
	s_barrier
	s_add_u32 s2, s44, 0x30080
	s_addc_u32 s3, s45, 0
	s_add_i32 s44, s46, s30
	v_lshl_add_u64 v[150:151], s[2:3], 0, v[130:131]
	s_mov_b32 m0, s44
	s_nop 0
	global_load_lds_dwordx4 v[150:151], off
	v_lshl_add_u64 v[150:151], s[2:3], 0, v[134:135]
	s_add_i32 m0, s44, 0x2000
	s_nop 0
	global_load_lds_dwordx4 v[150:151], off
	s_waitcnt vmcnt(6)
	s_barrier
	v_mfma_f32_16x16x32_bf16 v[52:55], v[198:201], v[166:169], v[52:55]
	v_mfma_f32_16x16x32_bf16 v[52:55], v[202:205], v[170:173], v[52:55]
	v_mfma_f32_16x16x32_bf16 v[48:51], v[210:213], v[170:173], v[48:51]
	v_mfma_f32_16x16x32_bf16 v[48:51], v[206:209], v[166:169], v[48:51]
	v_mfma_f32_16x16x32_bf16 v[32:35], v[206:209], v[174:177], v[32:35]
	v_mfma_f32_16x16x32_bf16 v[32:35], v[210:213], v[178:181], v[32:35]
	v_mfma_f32_16x16x32_bf16 v[36:39], v[202:205], v[178:181], v[36:39]
	v_mfma_f32_16x16x32_bf16 v[36:39], v[198:201], v[174:177], v[36:39]
	v_mfma_f32_16x16x32_bf16 v[20:23], v[198:201], v[182:185], v[20:23]
	v_mfma_f32_16x16x32_bf16 v[20:23], v[202:205], v[186:189], v[20:23]
	v_mfma_f32_16x16x32_bf16 v[16:19], v[210:213], v[186:189], v[16:19]
	v_mfma_f32_16x16x32_bf16 v[16:19], v[206:209], v[182:185], v[16:19]
	v_mfma_f32_16x16x32_bf16 v[0:3], v[206:209], v[190:193], v[0:3]
	v_mfma_f32_16x16x32_bf16 v[0:3], v[210:213], v[194:197], v[0:3]
	v_mfma_f32_16x16x32_bf16 v[4:7], v[202:205], v[194:197], v[4:7]
	v_mfma_f32_16x16x32_bf16 v[4:7], v[198:201], v[190:193], v[4:7]
	s_add_u32 s4, s4, 0x100
	s_addc_u32 s5, s5, 0
	s_add_u32 s65, s65, 0x100
	s_addc_u32 s66, s66, 0
	s_cmp_ge_i32 s67, s51
	s_mov_b32 s44, s67
	s_barrier
	s_cbranch_scc0 .LBB0_848
	s_branch .LBB0_837

; #define PG8_STAGE(bufoff, gbase, voff) do { _Pragma("unroll") for (int _i = 0; _i < 2; ++_i) \
;         __builtin_amdgcn_global_load_lds((const unsigned*)((const char*)(gbase) + (voff)[_i]), (LAS unsigned*)(lds + (bufoff) + ldsw + _i * 8192), 16, 0, 0); } while (0)
; #define PG8_LDA(dst, b, h) do { _Pragma("unroll") for (int m = 0; m < 4; ++m) _Pragma("unroll") for (int k = 0; k < 2; ++k) dst[m][k] = *(const LAS bf16x8*)(lds + PG8_SA(b, h) + aoff + m * 2048 + k * 1024); } while (0)
; #define PG8_LDB(dst, b, h) do { _Pragma("unroll") for (int n = 0; n < 2; ++n) _Pragma("unroll") for (int k = 0; k < 2; ++k) dst[n][k] = *(const LAS bf16x8*)(lds + PG8_SB(b, h) + boff + n * 2048 + k * 1024); } while (0)
; #define PG8_MMA(ai, bj, At, Bt) do { __builtin_amdgcn_s_setprio(1); _Pragma("unroll") for (int m = 0; m < 4; ++m) _Pragma("unroll") for (int n = 0; n < 2; ++n) _Pragma("unroll") for (int k = 0; k < 2; ++k) \
;         acc[ai][bj][m][n] = __builtin_amdgcn_mfma_f32_16x16x32_bf16(Bt[n][k], At[m][k], acc[ai][bj][m][n], 0, 0, 0); __builtin_amdgcn_s_setprio(0); } while (0)
; #define PG8_WAIT_L(n) asm volatile("s_waitcnt lgkmcnt(" #n ")" ::: "memory")
; #define PG8_BAR __builtin_amdgcn_s_barrier()
; #define PG8_SCHED __builtin_amdgcn_sched_barrier(0)
; template <class Epi>
; DEVINL void gemm_phase(LAS unsigned char* lds, const Gemm g, const Order& S, const Epi& E) {
;     ...
;         const char* nA = has_next ? (const char*)g.A + (size_t)nxt.pm * tstepA : cA; const char* nB = has_next ? (const char*)g.Bt + (size_t)nxt.pn * tstepB : cB;
;         for (int t = 0; t < nt; t += 2) {
;             const bool last = (t == nt - 2);
;             const char* a1 = cA + (size_t)(t + 1) * kstep;
;             const char* a2 = last ? nA : cA + (size_t)(t + 2) * kstep; const char* b2 = last ? nB : cB + (size_t)(t + 2) * kstep;
;             const char* a3 = a2 + kstep; const char* b3 = b2 + kstep;
;             PG8_LDB(B0, 0, 0); PG8_SCHED; PG8_LDA(At, 0, 0); PG8_STAGE(PG8_SA(1, 1), a1 + hstepA, voffA);
;             PG8_WAIT_L(8); PG8_BAR; PG8_WAIT_L(0); PG8_MMA(0, 0, At, B0); PG8_BAR; PG8_SCHED;
;             PG8_LDB(B1, 0, 1); PG8_STAGE(PG8_SB(0, 0), b2, voffB);
;             PG8_BAR; PG8_WAIT_L(0); PG8_MMA(0, 1, At, B1); PG8_BAR;
;             PG8_LDA(At, 0, 1); PG8_STAGE(PG8_SA(0, 0), a2, voffA);
;             PG8_BAR; PG8_WAIT_L(0); PG8_MMA(1, 0, At, B0); PG8_BAR; PG8_SCHED;
.LBB0_986:
	ds_read_b128 v[150:153], v147
	ds_read_b128 v[154:157], v147 offset:1024
	ds_read_b128 v[158:161], v147 offset:2048
	ds_read_b128 v[162:165], v147 offset:3072
	s_add_i32 s69, s46, 2
	s_add_u32 s2, s4, 0xffff0080
	s_addc_u32 s3, s5, -1
	s_cmp_eq_u32 s54, s46
	s_cselect_b32 s46, s66, s67
	s_cselect_b32 s49, s11, s3
	s_cselect_b32 s48, s13, s2
	s_cselect_b32 s47, s65, s68
	v_lshl_add_u64 v[198:199], s[4:5], 0, v[136:137]
	s_add_i32 m0, s30, 0xc000
	ds_read_b128 v[166:169], v148
	ds_read_b128 v[170:173], v148 offset:1024
	ds_read_b128 v[174:177], v148 offset:2048
	ds_read_b128 v[178:181], v148 offset:3072
	ds_read_b128 v[182:185], v148 offset:4096
	ds_read_b128 v[186:189], v148 offset:5120
	ds_read_b128 v[190:193], v148 offset:6144
	ds_read_b128 v[194:197], v148 offset:7168
	global_load_lds_dwordx4 v[198:199], off
	v_lshl_add_u64 v[198:199], s[4:5], 0, v[138:139]
	s_add_i32 m0, s30, 0xe000
	s_nop 0
	global_load_lds_dwordx4 v[198:199], off
	s_waitcnt lgkmcnt(8)
	s_barrier
	s_waitcnt lgkmcnt(0)
	s_waitcnt lgkmcnt(0)
	v_mfma_f32_16x16x32_bf16 v[124:127], v[150:153], v[166:169], v[124:127]
	v_mfma_f32_16x16x32_bf16 v[124:127], v[154:157], v[170:173], v[124:127]
	v_mfma_f32_16x16x32_bf16 v[120:123], v[162:165], v[170:173], v[120:123]
	v_mfma_f32_16x16x32_bf16 v[120:123], v[158:161], v[166:169], v[120:123]
	v_mfma_f32_16x16x32_bf16 v[112:115], v[158:161], v[174:177], v[112:115]
	v_mfma_f32_16x16x32_bf16 v[112:115], v[162:165], v[178:181], v[112:115]
	v_mfma_f32_16x16x32_bf16 v[116:119], v[154:157], v[178:181], v[116:119]
	v_mfma_f32_16x16x32_bf16 v[116:119], v[150:153], v[174:177], v[116:119]
	v_mfma_f32_16x16x32_bf16 v[108:111], v[150:153], v[182:185], v[108:111]
	v_mfma_f32_16x16x32_bf16 v[108:111], v[154:157], v[186:189], v[108:111]
	v_mfma_f32_16x16x32_bf16 v[104:107], v[162:165], v[186:189], v[104:107]
	v_mfma_f32_16x16x32_bf16 v[104:107], v[158:161], v[182:185], v[104:107]
	v_mfma_f32_16x16x32_bf16 v[96:99], v[158:161], v[190:193], v[96:99]
	v_mfma_f32_16x16x32_bf16 v[96:99], v[162:165], v[194:197], v[96:99]
	v_mfma_f32_16x16x32_bf16 v[100:103], v[154:157], v[194:197], v[100:103]
	v_mfma_f32_16x16x32_bf16 v[100:103], v[150:153], v[190:193], v[100:103]
	s_barrier
	s_add_i32 s2, s58, s29
	v_lshl_add_u64 v[218:219], s[46:47], 0, v[130:131]
	s_mov_b32 m0, s2
	ds_read_b128 v[198:201], v149
	ds_read_b128 v[202:205], v149 offset:1024
	ds_read_b128 v[206:209], v149 offset:2048
	ds_read_b128 v[210:213], v149 offset:3072
	global_load_lds_dwordx4 v[218:219], off
	v_lshl_add_u64 v[220:221], s[46:47], 0, v[134:135]
	s_add_i32 m0, s2, 0x2000
	s_nop 0
	global_load_lds_dwordx4 v[220:221], off
	s_barrier
	s_waitcnt lgkmcnt(0)
	s_waitcnt lgkmcnt(0)
	v_mfma_f32_16x16x32_bf16 v[60:63], v[198:201], v[166:169], v[60:63]
	v_mfma_f32_16x16x32_bf16 v[60:63], v[202:205], v[170:173], v[60:63]
	v_mfma_f32_16x16x32_bf16 v[56:59], v[210:213], v[170:173], v[56:59]
	v_mfma_f32_16x16x32_bf16 v[56:59], v[206:209], v[166:169], v[56:59]
	v_mfma_f32_16x16x32_bf16 v[48:51], v[206:209], v[174:177], v[48:51]
	v_mfma_f32_16x16x32_bf16 v[48:51], v[210:213], v[178:181], v[48:51]
	v_mfma_f32_16x16x32_bf16 v[52:55], v[202:205], v[178:181], v[52:55]
	v_mfma_f32_16x16x32_bf16 v[52:55], v[198:201], v[174:177], v[52:55]
	v_mfma_f32_16x16x32_bf16 v[44:47], v[198:201], v[182:185], v[44:47]
	v_mfma_f32_16x16x32_bf16 v[44:47], v[202:205], v[186:189], v[44:47]
	v_mfma_f32_16x16x32_bf16 v[40:43], v[210:213], v[186:189], v[40:43]
	v_mfma_f32_16x16x32_bf16 v[40:43], v[206:209], v[182:185], v[40:43]
	v_mfma_f32_16x16x32_bf16 v[32:35], v[206:209], v[190:193], v[32:35]
	v_mfma_f32_16x16x32_bf16 v[32:35], v[210:213], v[194:197], v[32:35]
	v_mfma_f32_16x16x32_bf16 v[36:39], v[202:205], v[194:197], v[36:39]
	v_mfma_f32_16x16x32_bf16 v[36:39], v[198:201], v[190:193], v[36:39]
	s_mov_b32 m0, s30
	v_lshl_add_u64 v[222:223], s[48:49], 0, v[128:129]
	s_barrier
	ds_read_b128 v[166:169], v148 offset:16384
	ds_read_b128 v[170:173], v148 offset:17408
	ds_read_b128 v[174:177], v148 offset:18432
	ds_read_b128 v[178:181], v148 offset:19456
	ds_read_b128 v[182:185], v148 offset:20480
	ds_read_b128 v[186:189], v148 offset:21504
	ds_read_b128 v[190:193], v148 offset:22528
	ds_read_b128 v[194:197], v148 offset:23552
	global_load_lds_dwordx4 v[222:223], off
	v_lshl_add_u64 v[224:225], s[48:49], 0, v[132:133]
	s_mov_b32 m0, s31
	s_nop 0
	global_load_lds_dwordx4 v[224:225], off
	s_barrier
	s_waitcnt lgkmcnt(0)
	s_waitcnt lgkmcnt(0)
	v_mfma_f32_16x16x32_bf16 v[92:95], v[150:153], v[166:169], v[92:95]
	v_mfma_f32_16x16x32_bf16 v[92:95], v[154:157], v[170:173], v[92:95]
	v_mfma_f32_16x16x32_bf16 v[88:91], v[162:165], v[170:173], v[88:91]
	v_mfma_f32_16x16x32_bf16 v[88:91], v[158:161], v[166:169], v[88:91]
	v_mfma_f32_16x16x32_bf16 v[80:83], v[158:161], v[174:177], v[80:83]
	v_mfma_f32_16x16x32_bf16 v[80:83], v[162:165], v[178:181], v[80:83]
	v_mfma_f32_16x16x32_bf16 v[84:87], v[154:157], v[178:181], v[84:87]
	v_mfma_f32_16x16x32_bf16 v[84:87], v[150:153], v[174:177], v[84:87]
	v_mfma_f32_16x16x32_bf16 v[76:79], v[150:153], v[182:185], v[76:79]
	v_mfma_f32_16x16x32_bf16 v[76:79], v[154:157], v[186:189], v[76:79]
	v_mfma_f32_16x16x32_bf16 v[72:75], v[162:165], v[186:189], v[72:75]
	v_mfma_f32_16x16x32_bf16 v[72:75], v[158:161], v[182:185], v[72:75]
	v_mfma_f32_16x16x32_bf16 v[64:67], v[158:161], v[190:193], v[64:67]
	v_mfma_f32_16x16x32_bf16 v[64:67], v[162:165], v[194:197], v[64:67]
	v_mfma_f32_16x16x32_bf16 v[68:71], v[154:157], v[194:197], v[68:71]
	v_mfma_f32_16x16x32_bf16 v[68:71], v[150:153], v[190:193], v[68:71]
	s_barrier
; #define PG8_STAGE(bufoff, gbase, voff) do { _Pragma("unroll") for (int _i = 0; _i < 2; ++_i) \
;         __builtin_amdgcn_global_load_lds((const unsigned*)((const char*)(gbase) + (voff)[_i]), (LAS unsigned*)(lds + (bufoff) + ldsw + _i * 8192), 16, 0, 0); } while (0)
; #define PG8_LDA(dst, b, h) do { _Pragma("unroll") for (int m = 0; m < 4; ++m) _Pragma("unroll") for (int k = 0; k < 2; ++k) dst[m][k] = *(const LAS bf16x8*)(lds + PG8_SA(b, h) + aoff + m * 2048 + k * 1024); } while (0)
; #define PG8_LDB(dst, b, h) do { _Pragma("unroll") for (int n = 0; n < 2; ++n) _Pragma("unroll") for (int k = 0; k < 2; ++k) dst[n][k] = *(const LAS bf16x8*)(lds + PG8_SB(b, h) + boff + n * 2048 + k * 1024); } while (0)
; #define PG8_MMA(ai, bj, At, Bt) do { __builtin_amdgcn_s_setprio(1); _Pragma("unroll") for (int m = 0; m < 4; ++m) _Pragma("unroll") for (int n = 0; n < 2; ++n) _Pragma("unroll") for (int k = 0; k < 2; ++k) \
;         acc[ai][bj][m][n] = __builtin_amdgcn_mfma_f32_16x16x32_bf16(Bt[n][k], At[m][k], acc[ai][bj][m][n], 0, 0, 0); __builtin_amdgcn_s_setprio(0); } while (0)
; #define PG8_WAIT_V(n) asm volatile("s_waitcnt vmcnt(" #n ")" ::: "memory")
; #define PG8_WAIT_L(n) asm volatile("s_waitcnt lgkmcnt(" #n ")" ::: "memory")
; #define PG8_BAR __builtin_amdgcn_s_barrier()
; #define PG8_SCHED __builtin_amdgcn_sched_barrier(0)
; template <class Epi>
; DEVINL void gemm_phase(LAS unsigned char* lds, const Gemm g, const Order& S, const Epi& E) {
;     ...
;             PG8_STAGE(PG8_SB(0, 1), b2 + hstepB, voffB);
;             PG8_WAIT_V(6); PG8_BAR; PG8_MMA(1, 1, At, B1); PG8_BAR;
;             PG8_LDB(B0, 1, 0); PG8_SCHED; PG8_LDA(At, 1, 0); PG8_STAGE(PG8_SA(0, 1), a2 + hstepA, voffA);
;             PG8_WAIT_L(8); PG8_BAR; PG8_WAIT_L(0); PG8_MMA(0, 0, At, B0); PG8_BAR; PG8_SCHED;
;             PG8_LDB(B1, 1, 1); PG8_STAGE(PG8_SB(1, 0), b3, voffB);
	s_add_u32 s2, s46, 0x10000
	s_addc_u32 s3, s47, 0
	s_add_i32 s70, s59, s29
	v_lshl_add_u64 v[150:151], s[2:3], 0, v[130:131]
	s_mov_b32 m0, s70
	s_nop 0
	global_load_lds_dwordx4 v[150:151], off
	v_lshl_add_u64 v[150:151], s[2:3], 0, v[134:135]
	s_add_i32 m0, s70, 0x2000
	s_nop 0
	global_load_lds_dwordx4 v[150:151], off
	s_waitcnt vmcnt(6)
	s_barrier
	v_mfma_f32_16x16x32_bf16 v[28:31], v[198:201], v[166:169], v[28:31]
	v_mfma_f32_16x16x32_bf16 v[28:31], v[202:205], v[170:173], v[28:31]
	v_mfma_f32_16x16x32_bf16 v[24:27], v[210:213], v[170:173], v[24:27]
	v_mfma_f32_16x16x32_bf16 v[24:27], v[206:209], v[166:169], v[24:27]
	v_mfma_f32_16x16x32_bf16 v[16:19], v[206:209], v[174:177], v[16:19]
	v_mfma_f32_16x16x32_bf16 v[16:19], v[210:213], v[178:181], v[16:19]
	v_mfma_f32_16x16x32_bf16 v[20:23], v[202:205], v[178:181], v[20:23]
	v_mfma_f32_16x16x32_bf16 v[20:23], v[198:201], v[174:177], v[20:23]
	v_mfma_f32_16x16x32_bf16 v[12:15], v[198:201], v[182:185], v[12:15]
	v_mfma_f32_16x16x32_bf16 v[12:15], v[202:205], v[186:189], v[12:15]
	v_mfma_f32_16x16x32_bf16 v[8:11], v[210:213], v[186:189], v[8:11]
	v_mfma_f32_16x16x32_bf16 v[8:11], v[206:209], v[182:185], v[8:11]
	v_mfma_f32_16x16x32_bf16 v[0:3], v[206:209], v[190:193], v[0:3]
	v_mfma_f32_16x16x32_bf16 v[0:3], v[210:213], v[194:197], v[0:3]
	v_mfma_f32_16x16x32_bf16 v[4:7], v[202:205], v[194:197], v[4:7]
	v_mfma_f32_16x16x32_bf16 v[4:7], v[198:201], v[190:193], v[4:7]
	s_add_i32 s70, 16, 0x18000
	v_add_u32_e32 v162, s70, v145
	s_barrier
	ds_read_b128 v[150:153], v162
	ds_read_b128 v[154:157], v162 offset:1024
	ds_read_b128 v[158:161], v162 offset:2048
	ds_read_b128 v[162:165], v162 offset:3072
	s_add_u32 s2, s48, 0x10000
	s_addc_u32 s3, s49, 0
	s_mov_b32 m0, s45
	v_lshl_add_u64 v[198:199], s[2:3], 0, v[128:129]
	ds_read_b128 v[166:169], v148 offset:32768
	ds_read_b128 v[170:173], v148 offset:33792
	ds_read_b128 v[174:177], v148 offset:34816
	ds_read_b128 v[178:181], v148 offset:35840
	ds_read_b128 v[182:185], v148 offset:36864
	ds_read_b128 v[186:189], v148 offset:37888
	ds_read_b128 v[190:193], v148 offset:38912
	ds_read_b128 v[194:197], v148 offset:39936
	global_load_lds_dwordx4 v[198:199], off
	v_lshl_add_u64 v[198:199], s[2:3], 0, v[132:133]
	s_mov_b32 m0, s50
	s_nop 0
	global_load_lds_dwordx4 v[198:199], off
	s_waitcnt lgkmcnt(8)
	s_barrier
	s_waitcnt lgkmcnt(0)
	s_waitcnt lgkmcnt(0)
	v_mfma_f32_16x16x32_bf16 v[124:127], v[150:153], v[166:169], v[124:127]
	v_mfma_f32_16x16x32_bf16 v[124:127], v[154:157], v[170:173], v[124:127]
	v_mfma_f32_16x16x32_bf16 v[120:123], v[162:165], v[170:173], v[120:123]
	v_mfma_f32_16x16x32_bf16 v[120:123], v[158:161], v[166:169], v[120:123]
	v_mfma_f32_16x16x32_bf16 v[112:115], v[158:161], v[174:177], v[112:115]
	v_mfma_f32_16x16x32_bf16 v[112:115], v[162:165], v[178:181], v[112:115]
	v_mfma_f32_16x16x32_bf16 v[116:119], v[154:157], v[178:181], v[116:119]
	v_mfma_f32_16x16x32_bf16 v[116:119], v[150:153], v[174:177], v[116:119]
	v_mfma_f32_16x16x32_bf16 v[108:111], v[150:153], v[182:185], v[108:111]
	v_mfma_f32_16x16x32_bf16 v[108:111], v[154:157], v[186:189], v[108:111]
	v_mfma_f32_16x16x32_bf16 v[104:107], v[162:165], v[186:189], v[104:107]
	v_mfma_f32_16x16x32_bf16 v[104:107], v[158:161], v[182:185], v[104:107]
	v_mfma_f32_16x16x32_bf16 v[96:99], v[158:161], v[190:193], v[96:99]
	v_mfma_f32_16x16x32_bf16 v[96:99], v[162:165], v[194:197], v[96:99]
	v_mfma_f32_16x16x32_bf16 v[100:103], v[154:157], v[194:197], v[100:103]
	v_mfma_f32_16x16x32_bf16 v[100:103], v[150:153], v[190:193], v[100:103]
	s_barrier
	s_add_i32 s48, 16, 0x1c000
	s_add_i32 s2, s70, s29
	v_add_u32_e32 v210, s48, v145
	v_lshl_add_u64 v[218:219], v[218:219], 0, s[6:7]
	s_mov_b32 m0, s2
	ds_read_b128 v[198:201], v210
	ds_read_b128 v[202:205], v210 offset:1024
	ds_read_b128 v[206:209], v210 offset:2048
	ds_read_b128 v[210:213], v210 offset:3072
	global_load_lds_dwordx4 v[218:219], off
	v_lshl_add_u64 v[218:219], v[220:221], 0, s[6:7]
	s_add_i32 m0, s2, 0x2000
	s_nop 0
	global_load_lds_dwordx4 v[218:219], off
	s_barrier
; #define PG8_STAGE(bufoff, gbase, voff) do { _Pragma("unroll") for (int _i = 0; _i < 2; ++_i) \
;         __builtin_amdgcn_global_load_lds((const unsigned*)((const char*)(gbase) + (voff)[_i]), (LAS unsigned*)(lds + (bufoff) + ldsw + _i * 8192), 16, 0, 0); } while (0)
; #define PG8_LDA(dst, b, h) do { _Pragma("unroll") for (int m = 0; m < 4; ++m) _Pragma("unroll") for (int k = 0; k < 2; ++k) dst[m][k] = *(const LAS bf16x8*)(lds + PG8_SA(b, h) + aoff + m * 2048 + k * 1024); } while (0)
; #define PG8_MMA(ai, bj, At, Bt) do { __builtin_amdgcn_s_setprio(1); _Pragma("unroll") for (int m = 0; m < 4; ++m) _Pragma("unroll") for (int n = 0; n < 2; ++n) _Pragma("unroll") for (int k = 0; k < 2; ++k) \
;         acc[ai][bj][m][n] = __builtin_amdgcn_mfma_f32_16x16x32_bf16(Bt[n][k], At[m][k], acc[ai][bj][m][n], 0, 0, 0); __builtin_amdgcn_s_setprio(0); } while (0)
; #define PG8_WAIT_V(n) asm volatile("s_waitcnt vmcnt(" #n ")" ::: "memory")
; #define PG8_WAIT_L(n) asm volatile("s_waitcnt lgkmcnt(" #n ")" ::: "memory")
; #define PG8_BAR __builtin_amdgcn_s_barrier()
; #define PG8_SCHED __builtin_amdgcn_sched_barrier(0)
; template <class Epi>
; DEVINL void gemm_phase(LAS unsigned char* lds, const Gemm g, const Order& S, const Epi& E) {
;     ...
;             PG8_BAR; PG8_WAIT_L(0); PG8_MMA(0, 1, At, B1); PG8_BAR;
;             PG8_LDA(At, 1, 1); PG8_STAGE(PG8_SA(1, 0), a3, voffA);
;             PG8_BAR; PG8_WAIT_L(0); PG8_MMA(1, 0, At, B0); PG8_BAR; PG8_SCHED;
;             PG8_STAGE(PG8_SB(1, 1), b3 + hstepB, voffB);
;             PG8_WAIT_V(6); PG8_BAR; PG8_MMA(1, 1, At, B1); PG8_BAR;
	s_waitcnt lgkmcnt(0)
	s_waitcnt lgkmcnt(0)
	v_mfma_f32_16x16x32_bf16 v[60:63], v[198:201], v[166:169], v[60:63]
	v_mfma_f32_16x16x32_bf16 v[60:63], v[202:205], v[170:173], v[60:63]
	v_mfma_f32_16x16x32_bf16 v[56:59], v[210:213], v[170:173], v[56:59]
	v_mfma_f32_16x16x32_bf16 v[56:59], v[206:209], v[166:169], v[56:59]
	v_mfma_f32_16x16x32_bf16 v[48:51], v[206:209], v[174:177], v[48:51]
	v_mfma_f32_16x16x32_bf16 v[48:51], v[210:213], v[178:181], v[48:51]
	v_mfma_f32_16x16x32_bf16 v[52:55], v[202:205], v[178:181], v[52:55]
	v_mfma_f32_16x16x32_bf16 v[52:55], v[198:201], v[174:177], v[52:55]
	v_mfma_f32_16x16x32_bf16 v[44:47], v[198:201], v[182:185], v[44:47]
	v_mfma_f32_16x16x32_bf16 v[44:47], v[202:205], v[186:189], v[44:47]
	v_mfma_f32_16x16x32_bf16 v[40:43], v[210:213], v[186:189], v[40:43]
	v_mfma_f32_16x16x32_bf16 v[40:43], v[206:209], v[182:185], v[40:43]
	v_mfma_f32_16x16x32_bf16 v[32:35], v[206:209], v[190:193], v[32:35]
	v_mfma_f32_16x16x32_bf16 v[32:35], v[210:213], v[194:197], v[32:35]
	v_mfma_f32_16x16x32_bf16 v[36:39], v[202:205], v[194:197], v[36:39]
	v_mfma_f32_16x16x32_bf16 v[36:39], v[198:201], v[190:193], v[36:39]
	s_mov_b32 m0, s52
	v_lshl_add_u64 v[218:219], v[222:223], 0, s[6:7]
	s_barrier
	ds_read_b128 v[166:169], v148 offset:49152
	ds_read_b128 v[170:173], v148 offset:50176
	ds_read_b128 v[174:177], v148 offset:51200
	ds_read_b128 v[178:181], v148 offset:52224
	ds_read_b128 v[182:185], v148 offset:53248
	ds_read_b128 v[186:189], v148 offset:54272
	ds_read_b128 v[190:193], v148 offset:55296
	ds_read_b128 v[194:197], v148 offset:56320
	global_load_lds_dwordx4 v[218:219], off
	v_lshl_add_u64 v[218:219], v[224:225], 0, s[6:7]
	s_mov_b32 m0, s53
	s_nop 0
	global_load_lds_dwordx4 v[218:219], off
	s_barrier
	s_waitcnt lgkmcnt(0)
	s_waitcnt lgkmcnt(0)
	v_mfma_f32_16x16x32_bf16 v[92:95], v[150:153], v[166:169], v[92:95]
	v_mfma_f32_16x16x32_bf16 v[92:95], v[154:157], v[170:173], v[92:95]
	v_mfma_f32_16x16x32_bf16 v[88:91], v[162:165], v[170:173], v[88:91]
	v_mfma_f32_16x16x32_bf16 v[88:91], v[158:161], v[166:169], v[88:91]
	v_mfma_f32_16x16x32_bf16 v[80:83], v[158:161], v[174:177], v[80:83]
	v_mfma_f32_16x16x32_bf16 v[80:83], v[162:165], v[178:181], v[80:83]
	v_mfma_f32_16x16x32_bf16 v[84:87], v[154:157], v[178:181], v[84:87]
	v_mfma_f32_16x16x32_bf16 v[84:87], v[150:153], v[174:177], v[84:87]
	v_mfma_f32_16x16x32_bf16 v[76:79], v[150:153], v[182:185], v[76:79]
	v_mfma_f32_16x16x32_bf16 v[76:79], v[154:157], v[186:189], v[76:79]
	v_mfma_f32_16x16x32_bf16 v[72:75], v[162:165], v[186:189], v[72:75]
	v_mfma_f32_16x16x32_bf16 v[72:75], v[158:161], v[182:185], v[72:75]
	v_mfma_f32_16x16x32_bf16 v[64:67], v[158:161], v[190:193], v[64:67]
	v_mfma_f32_16x16x32_bf16 v[64:67], v[162:165], v[194:197], v[64:67]
	v_mfma_f32_16x16x32_bf16 v[68:71], v[154:157], v[194:197], v[68:71]
	v_mfma_f32_16x16x32_bf16 v[68:71], v[150:153], v[190:193], v[68:71]
	s_barrier
	s_add_u32 s2, s46, 0x10080
	s_addc_u32 s3, s47, 0
	s_add_i32 s46, s48, s29
	v_lshl_add_u64 v[150:151], s[2:3], 0, v[130:131]
	s_mov_b32 m0, s46
	s_nop 0
	global_load_lds_dwordx4 v[150:151], off
	v_lshl_add_u64 v[150:151], s[2:3], 0, v[134:135]
	s_add_i32 m0, s46, 0x2000
	s_nop 0
	global_load_lds_dwordx4 v[150:151], off
	s_waitcnt vmcnt(6)
	s_barrier
	v_mfma_f32_16x16x32_bf16 v[28:31], v[198:201], v[166:169], v[28:31]
	v_mfma_f32_16x16x32_bf16 v[28:31], v[202:205], v[170:173], v[28:31]
	v_mfma_f32_16x16x32_bf16 v[24:27], v[210:213], v[170:173], v[24:27]
	v_mfma_f32_16x16x32_bf16 v[24:27], v[206:209], v[166:169], v[24:27]
	v_mfma_f32_16x16x32_bf16 v[16:19], v[206:209], v[174:177], v[16:19]
	v_mfma_f32_16x16x32_bf16 v[16:19], v[210:213], v[178:181], v[16:19]
	v_mfma_f32_16x16x32_bf16 v[20:23], v[202:205], v[178:181], v[20:23]
	v_mfma_f32_16x16x32_bf16 v[20:23], v[198:201], v[174:177], v[20:23]
	v_mfma_f32_16x16x32_bf16 v[12:15], v[198:201], v[182:185], v[12:15]
	v_mfma_f32_16x16x32_bf16 v[12:15], v[202:205], v[186:189], v[12:15]
	v_mfma_f32_16x16x32_bf16 v[8:11], v[210:213], v[186:189], v[8:11]
	v_mfma_f32_16x16x32_bf16 v[8:11], v[206:209], v[182:185], v[8:11]
	v_mfma_f32_16x16x32_bf16 v[0:3], v[206:209], v[190:193], v[0:3]
	v_mfma_f32_16x16x32_bf16 v[0:3], v[210:213], v[194:197], v[0:3]
	v_mfma_f32_16x16x32_bf16 v[4:7], v[202:205], v[194:197], v[4:7]
	v_mfma_f32_16x16x32_bf16 v[4:7], v[198:201], v[190:193], v[4:7]
	s_add_u32 s4, s4, 0x100
	s_addc_u32 s5, s5, 0
	s_add_u32 s67, s67, 0x100
	s_addc_u32 s68, s68, 0
	s_cmp_ge_i32 s69, s51
	s_mov_b32 s46, s69
	s_barrier
	s_cbranch_scc0 .LBB0_986
	v_readlane_b32 s66, v251, 56
	v_readlane_b32 s67, v251, 57
	s_branch .LBB0_977

; #define PG8_STAGE(bufoff, gbase, voff) do { _Pragma("unroll") for (int _i = 0; _i < 2; ++_i) \
;         __builtin_amdgcn_global_load_lds((const unsigned*)((const char*)(gbase) + (voff)[_i]), (LAS unsigned*)(lds + (bufoff) + ldsw + _i * 8192), 16, 0, 0); } while (0)
; #define PG8_LDA(dst, b, h) do { _Pragma("unroll") for (int m = 0; m < 4; ++m) _Pragma("unroll") for (int k = 0; k < 2; ++k) dst[m][k] = *(const LAS bf16x8*)(lds + PG8_SA(b, h) + aoff + m * 2048 + k * 1024); } while (0)
; #define PG8_LDB(dst, b, h) do { _Pragma("unroll") for (int n = 0; n < 2; ++n) _Pragma("unroll") for (int k = 0; k < 2; ++k) dst[n][k] = *(const LAS bf16x8*)(lds + PG8_SB(b, h) + boff + n * 2048 + k * 1024); } while (0)
; #define PG8_MMA(ai, bj, At, Bt) do { __builtin_amdgcn_s_setprio(1); _Pragma("unroll") for (int m = 0; m < 4; ++m) _Pragma("unroll") for (int n = 0; n < 2; ++n) _Pragma("unroll") for (int k = 0; k < 2; ++k) \
;         acc[ai][bj][m][n] = __builtin_amdgcn_mfma_f32_16x16x32_bf16(Bt[n][k], At[m][k], acc[ai][bj][m][n], 0, 0, 0); __builtin_amdgcn_s_setprio(0); } while (0)
; #define PG8_WAIT_L(n) asm volatile("s_waitcnt lgkmcnt(" #n ")" ::: "memory")
; #define PG8_BAR __builtin_amdgcn_s_barrier()
; #define PG8_SCHED __builtin_amdgcn_sched_barrier(0)
; template <class Epi>
; DEVINL void gemm_phase(LAS unsigned char* lds, const Gemm g, const Order& S, const Epi& E) {
;     ...
;         const char* nA = has_next ? (const char*)g.A + (size_t)nxt.pm * tstepA : cA; const char* nB = has_next ? (const char*)g.Bt + (size_t)nxt.pn * tstepB : cB;
;         for (int t = 0; t < nt; t += 2) {
;             const bool last = (t == nt - 2);
;             const char* a1 = cA + (size_t)(t + 1) * kstep;
;             const char* a2 = last ? nA : cA + (size_t)(t + 2) * kstep; const char* b2 = last ? nB : cB + (size_t)(t + 2) * kstep;
;             const char* a3 = a2 + kstep; const char* b3 = b2 + kstep;
;             PG8_LDB(B0, 0, 0); PG8_SCHED; PG8_LDA(At, 0, 0); PG8_STAGE(PG8_SA(1, 1), a1 + hstepA, voffA);
;             PG8_WAIT_L(8); PG8_BAR; PG8_WAIT_L(0); PG8_MMA(0, 0, At, B0); PG8_BAR; PG8_SCHED;
;             PG8_LDB(B1, 0, 1); PG8_STAGE(PG8_SB(0, 0), b2, voffB);
;             PG8_BAR; PG8_WAIT_L(0); PG8_MMA(0, 1, At, B1); PG8_BAR;
;             PG8_LDA(At, 0, 1); PG8_STAGE(PG8_SA(0, 0), a2, voffA);
;             PG8_BAR; PG8_WAIT_L(0); PG8_MMA(1, 0, At, B0); PG8_BAR; PG8_SCHED;
.LBB0_1008:
	ds_read_b128 v[150:153], v147
	ds_read_b128 v[154:157], v147 offset:1024
	ds_read_b128 v[158:161], v147 offset:2048
	ds_read_b128 v[162:165], v147 offset:3072
	s_add_i32 s68, s46, 2
	s_add_u32 s47, s4, 0xffff0080
	s_addc_u32 s48, s5, -1
	s_cmp_eq_u32 s26, s46
	s_cselect_b32 s46, s13, s66
	s_cselect_b32 s49, s2, s48
	s_cselect_b32 s48, s3, s47
	s_cselect_b32 s47, s11, s67
	v_lshl_add_u64 v[198:199], s[4:5], 0, v[136:137]
	s_add_i32 m0, s45, 0xc000
	ds_read_b128 v[166:169], v148
	ds_read_b128 v[170:173], v148 offset:1024
	ds_read_b128 v[174:177], v148 offset:2048
	ds_read_b128 v[178:181], v148 offset:3072
	ds_read_b128 v[182:185], v148 offset:4096
	ds_read_b128 v[186:189], v148 offset:5120
	ds_read_b128 v[190:193], v148 offset:6144
	ds_read_b128 v[194:197], v148 offset:7168
	global_load_lds_dwordx4 v[198:199], off
	v_lshl_add_u64 v[198:199], s[4:5], 0, v[138:139]
	s_add_i32 m0, s45, 0xe000
	s_nop 0
	global_load_lds_dwordx4 v[198:199], off
	s_waitcnt lgkmcnt(8)
	s_barrier
	s_waitcnt lgkmcnt(0)
	s_waitcnt lgkmcnt(0)
	v_mfma_f32_16x16x32_bf16 v[124:127], v[150:153], v[166:169], v[124:127]
	v_mfma_f32_16x16x32_bf16 v[124:127], v[154:157], v[170:173], v[124:127]
	v_mfma_f32_16x16x32_bf16 v[120:123], v[162:165], v[170:173], v[120:123]
	v_mfma_f32_16x16x32_bf16 v[120:123], v[158:161], v[166:169], v[120:123]
	v_mfma_f32_16x16x32_bf16 v[112:115], v[158:161], v[174:177], v[112:115]
	v_mfma_f32_16x16x32_bf16 v[112:115], v[162:165], v[178:181], v[112:115]
	v_mfma_f32_16x16x32_bf16 v[116:119], v[154:157], v[178:181], v[116:119]
	v_mfma_f32_16x16x32_bf16 v[116:119], v[150:153], v[174:177], v[116:119]
	v_mfma_f32_16x16x32_bf16 v[108:111], v[150:153], v[182:185], v[108:111]
	v_mfma_f32_16x16x32_bf16 v[108:111], v[154:157], v[186:189], v[108:111]
	v_mfma_f32_16x16x32_bf16 v[104:107], v[162:165], v[186:189], v[104:107]
	v_mfma_f32_16x16x32_bf16 v[104:107], v[158:161], v[182:185], v[104:107]
	v_mfma_f32_16x16x32_bf16 v[96:99], v[158:161], v[190:193], v[96:99]
	v_mfma_f32_16x16x32_bf16 v[96:99], v[162:165], v[194:197], v[96:99]
	v_mfma_f32_16x16x32_bf16 v[100:103], v[154:157], v[194:197], v[100:103]
	v_mfma_f32_16x16x32_bf16 v[100:103], v[150:153], v[190:193], v[100:103]
	s_barrier
	s_add_i32 s69, s59, s31
	v_lshl_add_u64 v[218:219], s[46:47], 0, v[130:131]
	s_mov_b32 m0, s69
	ds_read_b128 v[198:201], v149
	ds_read_b128 v[202:205], v149 offset:1024
	ds_read_b128 v[206:209], v149 offset:2048
	ds_read_b128 v[210:213], v149 offset:3072
	global_load_lds_dwordx4 v[218:219], off
	v_lshl_add_u64 v[220:221], s[46:47], 0, v[134:135]
	s_add_i32 m0, s69, 0x2000
	s_nop 0
	global_load_lds_dwordx4 v[220:221], off
	s_barrier
	s_waitcnt lgkmcnt(0)
	s_waitcnt lgkmcnt(0)
	v_mfma_f32_16x16x32_bf16 v[60:63], v[198:201], v[166:169], v[60:63]
	v_mfma_f32_16x16x32_bf16 v[60:63], v[202:205], v[170:173], v[60:63]
	v_mfma_f32_16x16x32_bf16 v[56:59], v[210:213], v[170:173], v[56:59]
	v_mfma_f32_16x16x32_bf16 v[56:59], v[206:209], v[166:169], v[56:59]
	v_mfma_f32_16x16x32_bf16 v[48:51], v[206:209], v[174:177], v[48:51]
	v_mfma_f32_16x16x32_bf16 v[48:51], v[210:213], v[178:181], v[48:51]
	v_mfma_f32_16x16x32_bf16 v[52:55], v[202:205], v[178:181], v[52:55]
	v_mfma_f32_16x16x32_bf16 v[52:55], v[198:201], v[174:177], v[52:55]
	v_mfma_f32_16x16x32_bf16 v[44:47], v[198:201], v[182:185], v[44:47]
	v_mfma_f32_16x16x32_bf16 v[44:47], v[202:205], v[186:189], v[44:47]
	v_mfma_f32_16x16x32_bf16 v[40:43], v[210:213], v[186:189], v[40:43]
	v_mfma_f32_16x16x32_bf16 v[40:43], v[206:209], v[182:185], v[40:43]
	v_mfma_f32_16x16x32_bf16 v[32:35], v[206:209], v[190:193], v[32:35]
	v_mfma_f32_16x16x32_bf16 v[32:35], v[210:213], v[194:197], v[32:35]
	v_mfma_f32_16x16x32_bf16 v[36:39], v[202:205], v[194:197], v[36:39]
	v_mfma_f32_16x16x32_bf16 v[36:39], v[198:201], v[190:193], v[36:39]
	s_mov_b32 m0, s45
	v_lshl_add_u64 v[222:223], s[48:49], 0, v[128:129]
	s_barrier
	ds_read_b128 v[166:169], v148 offset:16384
	ds_read_b128 v[170:173], v148 offset:17408
	ds_read_b128 v[174:177], v148 offset:18432
	ds_read_b128 v[178:181], v148 offset:19456
	ds_read_b128 v[182:185], v148 offset:20480
	ds_read_b128 v[186:189], v148 offset:21504
	ds_read_b128 v[190:193], v148 offset:22528
	ds_read_b128 v[194:197], v148 offset:23552
	global_load_lds_dwordx4 v[222:223], off
	v_lshl_add_u64 v[224:225], s[48:49], 0, v[132:133]
	s_mov_b32 m0, s50
	s_nop 0
	global_load_lds_dwordx4 v[224:225], off
	s_barrier
	s_waitcnt lgkmcnt(0)
	s_waitcnt lgkmcnt(0)
	v_mfma_f32_16x16x32_bf16 v[92:95], v[150:153], v[166:169], v[92:95]
	v_mfma_f32_16x16x32_bf16 v[92:95], v[154:157], v[170:173], v[92:95]
	v_mfma_f32_16x16x32_bf16 v[88:91], v[162:165], v[170:173], v[88:91]
	v_mfma_f32_16x16x32_bf16 v[88:91], v[158:161], v[166:169], v[88:91]
	v_mfma_f32_16x16x32_bf16 v[80:83], v[158:161], v[174:177], v[80:83]
	v_mfma_f32_16x16x32_bf16 v[80:83], v[162:165], v[178:181], v[80:83]
	v_mfma_f32_16x16x32_bf16 v[84:87], v[154:157], v[178:181], v[84:87]
	v_mfma_f32_16x16x32_bf16 v[84:87], v[150:153], v[174:177], v[84:87]
	v_mfma_f32_16x16x32_bf16 v[76:79], v[150:153], v[182:185], v[76:79]
	v_mfma_f32_16x16x32_bf16 v[76:79], v[154:157], v[186:189], v[76:79]
	v_mfma_f32_16x16x32_bf16 v[72:75], v[162:165], v[186:189], v[72:75]
	v_mfma_f32_16x16x32_bf16 v[72:75], v[158:161], v[182:185], v[72:75]
	v_mfma_f32_16x16x32_bf16 v[64:67], v[158:161], v[190:193], v[64:67]
	v_mfma_f32_16x16x32_bf16 v[64:67], v[162:165], v[194:197], v[64:67]
	v_mfma_f32_16x16x32_bf16 v[68:71], v[154:157], v[194:197], v[68:71]
	v_mfma_f32_16x16x32_bf16 v[68:71], v[150:153], v[190:193], v[68:71]
	s_barrier
; #define PG8_STAGE(bufoff, gbase, voff) do { _Pragma("unroll") for (int _i = 0; _i < 2; ++_i) \
;         __builtin_amdgcn_global_load_lds((const unsigned*)((const char*)(gbase) + (voff)[_i]), (LAS unsigned*)(lds + (bufoff) + ldsw + _i * 8192), 16, 0, 0); } while (0)
; #define PG8_LDA(dst, b, h) do { _Pragma("unroll") for (int m = 0; m < 4; ++m) _Pragma("unroll") for (int k = 0; k < 2; ++k) dst[m][k] = *(const LAS bf16x8*)(lds + PG8_SA(b, h) + aoff + m * 2048 + k * 1024); } while (0)
; #define PG8_LDB(dst, b, h) do { _Pragma("unroll") for (int n = 0; n < 2; ++n) _Pragma("unroll") for (int k = 0; k < 2; ++k) dst[n][k] = *(const LAS bf16x8*)(lds + PG8_SB(b, h) + boff + n * 2048 + k * 1024); } while (0)
; #define PG8_MMA(ai, bj, At, Bt) do { __builtin_amdgcn_s_setprio(1); _Pragma("unroll") for (int m = 0; m < 4; ++m) _Pragma("unroll") for (int n = 0; n < 2; ++n) _Pragma("unroll") for (int k = 0; k < 2; ++k) \
;         acc[ai][bj][m][n] = __builtin_amdgcn_mfma_f32_16x16x32_bf16(Bt[n][k], At[m][k], acc[ai][bj][m][n], 0, 0, 0); __builtin_amdgcn_s_setprio(0); } while (0)
; #define PG8_WAIT_V(n) asm volatile("s_waitcnt vmcnt(" #n ")" ::: "memory")
; #define PG8_WAIT_L(n) asm volatile("s_waitcnt lgkmcnt(" #n ")" ::: "memory")
; #define PG8_BAR __builtin_amdgcn_s_barrier()
; #define PG8_SCHED __builtin_amdgcn_sched_barrier(0)
; template <class Epi>
; DEVINL void gemm_phase(LAS unsigned char* lds, const Gemm g, const Order& S, const Epi& E) {
;     ...
;             PG8_STAGE(PG8_SB(0, 1), b2 + hstepB, voffB);
;             PG8_WAIT_V(6); PG8_BAR; PG8_MMA(1, 1, At, B1); PG8_BAR;
;             PG8_LDB(B0, 1, 0); PG8_SCHED; PG8_LDA(At, 1, 0); PG8_STAGE(PG8_SA(0, 1), a2 + hstepA, voffA);
;             PG8_WAIT_L(8); PG8_BAR; PG8_WAIT_L(0); PG8_MMA(0, 0, At, B0); PG8_BAR; PG8_SCHED;
;             PG8_LDB(B1, 1, 1); PG8_STAGE(PG8_SB(1, 0), b3, voffB);
	s_add_u32 s70, s46, 0x10000
	s_addc_u32 s71, s47, 0
	s_add_i32 s69, s64, s31
	v_lshl_add_u64 v[150:151], s[70:71], 0, v[130:131]
	s_mov_b32 m0, s69
	s_nop 0
	global_load_lds_dwordx4 v[150:151], off
	v_lshl_add_u64 v[150:151], s[70:71], 0, v[134:135]
	s_add_i32 m0, s69, 0x2000
	s_nop 0
	global_load_lds_dwordx4 v[150:151], off
	s_waitcnt vmcnt(6)
	s_barrier
	v_mfma_f32_16x16x32_bf16 v[28:31], v[198:201], v[166:169], v[28:31]
	v_mfma_f32_16x16x32_bf16 v[28:31], v[202:205], v[170:173], v[28:31]
	v_mfma_f32_16x16x32_bf16 v[24:27], v[210:213], v[170:173], v[24:27]
	v_mfma_f32_16x16x32_bf16 v[24:27], v[206:209], v[166:169], v[24:27]
	v_mfma_f32_16x16x32_bf16 v[16:19], v[206:209], v[174:177], v[16:19]
	v_mfma_f32_16x16x32_bf16 v[16:19], v[210:213], v[178:181], v[16:19]
	v_mfma_f32_16x16x32_bf16 v[20:23], v[202:205], v[178:181], v[20:23]
	v_mfma_f32_16x16x32_bf16 v[20:23], v[198:201], v[174:177], v[20:23]
	v_mfma_f32_16x16x32_bf16 v[12:15], v[198:201], v[182:185], v[12:15]
	v_mfma_f32_16x16x32_bf16 v[12:15], v[202:205], v[186:189], v[12:15]
	v_mfma_f32_16x16x32_bf16 v[8:11], v[210:213], v[186:189], v[8:11]
	v_mfma_f32_16x16x32_bf16 v[8:11], v[206:209], v[182:185], v[8:11]
	v_mfma_f32_16x16x32_bf16 v[0:3], v[206:209], v[190:193], v[0:3]
	v_mfma_f32_16x16x32_bf16 v[0:3], v[210:213], v[194:197], v[0:3]
	v_mfma_f32_16x16x32_bf16 v[4:7], v[202:205], v[194:197], v[4:7]
	v_mfma_f32_16x16x32_bf16 v[4:7], v[198:201], v[190:193], v[4:7]
	s_add_i32 s69, 16, 0x18000
	v_add_u32_e32 v162, s69, v145
	s_barrier
	ds_read_b128 v[150:153], v162
	ds_read_b128 v[154:157], v162 offset:1024
	ds_read_b128 v[158:161], v162 offset:2048
	ds_read_b128 v[162:165], v162 offset:3072
	s_add_u32 s48, s48, 0x10000
	s_addc_u32 s49, s49, 0
	s_mov_b32 m0, s51
	v_lshl_add_u64 v[198:199], s[48:49], 0, v[128:129]
	ds_read_b128 v[166:169], v148 offset:32768
	ds_read_b128 v[170:173], v148 offset:33792
	ds_read_b128 v[174:177], v148 offset:34816
	ds_read_b128 v[178:181], v148 offset:35840
	ds_read_b128 v[182:185], v148 offset:36864
	ds_read_b128 v[186:189], v148 offset:37888
	ds_read_b128 v[190:193], v148 offset:38912
	ds_read_b128 v[194:197], v148 offset:39936
	global_load_lds_dwordx4 v[198:199], off
	v_lshl_add_u64 v[198:199], s[48:49], 0, v[132:133]
	s_mov_b32 m0, s52
	s_nop 0
	global_load_lds_dwordx4 v[198:199], off
	s_waitcnt lgkmcnt(8)
	s_barrier
	s_waitcnt lgkmcnt(0)
	s_waitcnt lgkmcnt(0)
	v_mfma_f32_16x16x32_bf16 v[124:127], v[150:153], v[166:169], v[124:127]
	v_mfma_f32_16x16x32_bf16 v[124:127], v[154:157], v[170:173], v[124:127]
	v_mfma_f32_16x16x32_bf16 v[120:123], v[162:165], v[170:173], v[120:123]
	v_mfma_f32_16x16x32_bf16 v[120:123], v[158:161], v[166:169], v[120:123]
	v_mfma_f32_16x16x32_bf16 v[112:115], v[158:161], v[174:177], v[112:115]
	v_mfma_f32_16x16x32_bf16 v[112:115], v[162:165], v[178:181], v[112:115]
	v_mfma_f32_16x16x32_bf16 v[116:119], v[154:157], v[178:181], v[116:119]
	v_mfma_f32_16x16x32_bf16 v[116:119], v[150:153], v[174:177], v[116:119]
	v_mfma_f32_16x16x32_bf16 v[108:111], v[150:153], v[182:185], v[108:111]
	v_mfma_f32_16x16x32_bf16 v[108:111], v[154:157], v[186:189], v[108:111]
	v_mfma_f32_16x16x32_bf16 v[104:107], v[162:165], v[186:189], v[104:107]
	v_mfma_f32_16x16x32_bf16 v[104:107], v[158:161], v[182:185], v[104:107]
	v_mfma_f32_16x16x32_bf16 v[96:99], v[158:161], v[190:193], v[96:99]
	v_mfma_f32_16x16x32_bf16 v[96:99], v[162:165], v[194:197], v[96:99]
	v_mfma_f32_16x16x32_bf16 v[100:103], v[154:157], v[194:197], v[100:103]
	v_mfma_f32_16x16x32_bf16 v[100:103], v[150:153], v[190:193], v[100:103]
	s_barrier
	s_add_i32 s48, 16, 0x1c000
	s_add_i32 s49, s69, s31
	v_add_u32_e32 v210, s48, v145
	v_lshl_add_u64 v[218:219], v[218:219], 0, s[6:7]
	s_mov_b32 m0, s49
	ds_read_b128 v[198:201], v210
	ds_read_b128 v[202:205], v210 offset:1024
	ds_read_b128 v[206:209], v210 offset:2048
	ds_read_b128 v[210:213], v210 offset:3072
	global_load_lds_dwordx4 v[218:219], off
	v_lshl_add_u64 v[218:219], v[220:221], 0, s[6:7]
	s_add_i32 m0, s49, 0x2000
	s_nop 0
	global_load_lds_dwordx4 v[218:219], off
	s_barrier
; #define PG8_STAGE(bufoff, gbase, voff) do { _Pragma("unroll") for (int _i = 0; _i < 2; ++_i) \
;         __builtin_amdgcn_global_load_lds((const unsigned*)((const char*)(gbase) + (voff)[_i]), (LAS unsigned*)(lds + (bufoff) + ldsw + _i * 8192), 16, 0, 0); } while (0)
; #define PG8_LDA(dst, b, h) do { _Pragma("unroll") for (int m = 0; m < 4; ++m) _Pragma("unroll") for (int k = 0; k < 2; ++k) dst[m][k] = *(const LAS bf16x8*)(lds + PG8_SA(b, h) + aoff + m * 2048 + k * 1024); } while (0)
; #define PG8_MMA(ai, bj, At, Bt) do { __builtin_amdgcn_s_setprio(1); _Pragma("unroll") for (int m = 0; m < 4; ++m) _Pragma("unroll") for (int n = 0; n < 2; ++n) _Pragma("unroll") for (int k = 0; k < 2; ++k) \
;         acc[ai][bj][m][n] = __builtin_amdgcn_mfma_f32_16x16x32_bf16(Bt[n][k], At[m][k], acc[ai][bj][m][n], 0, 0, 0); __builtin_amdgcn_s_setprio(0); } while (0)
; #define PG8_WAIT_V(n) asm volatile("s_waitcnt vmcnt(" #n ")" ::: "memory")
; #define PG8_WAIT_L(n) asm volatile("s_waitcnt lgkmcnt(" #n ")" ::: "memory")
; #define PG8_BAR __builtin_amdgcn_s_barrier()
; #define PG8_SCHED __builtin_amdgcn_sched_barrier(0)
; template <class Epi>
; DEVINL void gemm_phase(LAS unsigned char* lds, const Gemm g, const Order& S, const Epi& E) {
;     ...
;             PG8_BAR; PG8_WAIT_L(0); PG8_MMA(0, 1, At, B1); PG8_BAR;
;             PG8_LDA(At, 1, 1); PG8_STAGE(PG8_SA(1, 0), a3, voffA);
;             PG8_BAR; PG8_WAIT_L(0); PG8_MMA(1, 0, At, B0); PG8_BAR; PG8_SCHED;
;             PG8_STAGE(PG8_SB(1, 1), b3 + hstepB, voffB);
;             PG8_WAIT_V(6); PG8_BAR; PG8_MMA(1, 1, At, B1); PG8_BAR;
	s_waitcnt lgkmcnt(0)
	s_waitcnt lgkmcnt(0)
	v_mfma_f32_16x16x32_bf16 v[60:63], v[198:201], v[166:169], v[60:63]
	v_mfma_f32_16x16x32_bf16 v[60:63], v[202:205], v[170:173], v[60:63]
	v_mfma_f32_16x16x32_bf16 v[56:59], v[210:213], v[170:173], v[56:59]
	v_mfma_f32_16x16x32_bf16 v[56:59], v[206:209], v[166:169], v[56:59]
	v_mfma_f32_16x16x32_bf16 v[48:51], v[206:209], v[174:177], v[48:51]
	v_mfma_f32_16x16x32_bf16 v[48:51], v[210:213], v[178:181], v[48:51]
	v_mfma_f32_16x16x32_bf16 v[52:55], v[202:205], v[178:181], v[52:55]
	v_mfma_f32_16x16x32_bf16 v[52:55], v[198:201], v[174:177], v[52:55]
	v_mfma_f32_16x16x32_bf16 v[44:47], v[198:201], v[182:185], v[44:47]
	v_mfma_f32_16x16x32_bf16 v[44:47], v[202:205], v[186:189], v[44:47]
	v_mfma_f32_16x16x32_bf16 v[40:43], v[210:213], v[186:189], v[40:43]
	v_mfma_f32_16x16x32_bf16 v[40:43], v[206:209], v[182:185], v[40:43]
	v_mfma_f32_16x16x32_bf16 v[32:35], v[206:209], v[190:193], v[32:35]
	v_mfma_f32_16x16x32_bf16 v[32:35], v[210:213], v[194:197], v[32:35]
	v_mfma_f32_16x16x32_bf16 v[36:39], v[202:205], v[194:197], v[36:39]
	v_mfma_f32_16x16x32_bf16 v[36:39], v[198:201], v[190:193], v[36:39]
	s_mov_b32 m0, s54
	v_lshl_add_u64 v[218:219], v[222:223], 0, s[6:7]
	s_barrier
	ds_read_b128 v[166:169], v148 offset:49152
	ds_read_b128 v[170:173], v148 offset:50176
	ds_read_b128 v[174:177], v148 offset:51200
	ds_read_b128 v[178:181], v148 offset:52224
	ds_read_b128 v[182:185], v148 offset:53248
	ds_read_b128 v[186:189], v148 offset:54272
	ds_read_b128 v[190:193], v148 offset:55296
	ds_read_b128 v[194:197], v148 offset:56320
	global_load_lds_dwordx4 v[218:219], off
	v_lshl_add_u64 v[218:219], v[224:225], 0, s[6:7]
	s_mov_b32 m0, s55
	s_nop 0
	global_load_lds_dwordx4 v[218:219], off
	s_barrier
	s_waitcnt lgkmcnt(0)
	s_waitcnt lgkmcnt(0)
	v_mfma_f32_16x16x32_bf16 v[92:95], v[150:153], v[166:169], v[92:95]
	v_mfma_f32_16x16x32_bf16 v[92:95], v[154:157], v[170:173], v[92:95]
	v_mfma_f32_16x16x32_bf16 v[88:91], v[162:165], v[170:173], v[88:91]
	v_mfma_f32_16x16x32_bf16 v[88:91], v[158:161], v[166:169], v[88:91]
	v_mfma_f32_16x16x32_bf16 v[80:83], v[158:161], v[174:177], v[80:83]
	v_mfma_f32_16x16x32_bf16 v[80:83], v[162:165], v[178:181], v[80:83]
	v_mfma_f32_16x16x32_bf16 v[84:87], v[154:157], v[178:181], v[84:87]
	v_mfma_f32_16x16x32_bf16 v[84:87], v[150:153], v[174:177], v[84:87]
	v_mfma_f32_16x16x32_bf16 v[76:79], v[150:153], v[182:185], v[76:79]
	v_mfma_f32_16x16x32_bf16 v[76:79], v[154:157], v[186:189], v[76:79]
	v_mfma_f32_16x16x32_bf16 v[72:75], v[162:165], v[186:189], v[72:75]
	v_mfma_f32_16x16x32_bf16 v[72:75], v[158:161], v[182:185], v[72:75]
	v_mfma_f32_16x16x32_bf16 v[64:67], v[158:161], v[190:193], v[64:67]
	v_mfma_f32_16x16x32_bf16 v[64:67], v[162:165], v[194:197], v[64:67]
	v_mfma_f32_16x16x32_bf16 v[68:71], v[154:157], v[194:197], v[68:71]
	v_mfma_f32_16x16x32_bf16 v[68:71], v[150:153], v[190:193], v[68:71]
	s_barrier
	s_add_u32 s46, s46, 0x10080
	s_addc_u32 s47, s47, 0
	s_add_i32 s48, s48, s31
	v_lshl_add_u64 v[150:151], s[46:47], 0, v[130:131]
	s_mov_b32 m0, s48
	s_nop 0
	global_load_lds_dwordx4 v[150:151], off
	v_lshl_add_u64 v[150:151], s[46:47], 0, v[134:135]
	s_add_i32 m0, s48, 0x2000
	s_nop 0
	global_load_lds_dwordx4 v[150:151], off
	s_waitcnt vmcnt(6)
	s_barrier
	v_mfma_f32_16x16x32_bf16 v[28:31], v[198:201], v[166:169], v[28:31]
	v_mfma_f32_16x16x32_bf16 v[28:31], v[202:205], v[170:173], v[28:31]
	v_mfma_f32_16x16x32_bf16 v[24:27], v[210:213], v[170:173], v[24:27]
	v_mfma_f32_16x16x32_bf16 v[24:27], v[206:209], v[166:169], v[24:27]
	v_mfma_f32_16x16x32_bf16 v[16:19], v[206:209], v[174:177], v[16:19]
	v_mfma_f32_16x16x32_bf16 v[16:19], v[210:213], v[178:181], v[16:19]
	v_mfma_f32_16x16x32_bf16 v[20:23], v[202:205], v[178:181], v[20:23]
	v_mfma_f32_16x16x32_bf16 v[20:23], v[198:201], v[174:177], v[20:23]
	v_mfma_f32_16x16x32_bf16 v[12:15], v[198:201], v[182:185], v[12:15]
	v_mfma_f32_16x16x32_bf16 v[12:15], v[202:205], v[186:189], v[12:15]
	v_mfma_f32_16x16x32_bf16 v[8:11], v[210:213], v[186:189], v[8:11]
	v_mfma_f32_16x16x32_bf16 v[8:11], v[206:209], v[182:185], v[8:11]
	v_mfma_f32_16x16x32_bf16 v[0:3], v[206:209], v[190:193], v[0:3]
	v_mfma_f32_16x16x32_bf16 v[0:3], v[210:213], v[194:197], v[0:3]
	v_mfma_f32_16x16x32_bf16 v[4:7], v[202:205], v[194:197], v[4:7]
	v_mfma_f32_16x16x32_bf16 v[4:7], v[198:201], v[190:193], v[4:7]
	s_add_u32 s4, s4, 0x100
	s_addc_u32 s5, s5, 0
	s_add_u32 s66, s66, 0x100
	s_addc_u32 s67, s67, 0
	s_cmp_ge_i32 s68, s53
	s_mov_b32 s46, s68
	s_barrier
	s_cbranch_scc0 .LBB0_1008
	s_branch .LBB0_999

; #define PG8_STAGE(bufoff, gbase, voff) do { _Pragma("unroll") for (int _i = 0; _i < 2; ++_i) \
;         __builtin_amdgcn_global_load_lds((const unsigned*)((const char*)(gbase) + (voff)[_i]), (LAS unsigned*)(lds + (bufoff) + ldsw + _i * 8192), 16, 0, 0); } while (0)
; #define PG8_LDA(dst, b, h) do { _Pragma("unroll") for (int m = 0; m < 4; ++m) _Pragma("unroll") for (int k = 0; k < 2; ++k) dst[m][k] = *(const LAS bf16x8*)(lds + PG8_SA(b, h) + aoff + m * 2048 + k * 1024); } while (0)
; #define PG8_LDB(dst, b, h) do { _Pragma("unroll") for (int n = 0; n < 2; ++n) _Pragma("unroll") for (int k = 0; k < 2; ++k) dst[n][k] = *(const LAS bf16x8*)(lds + PG8_SB(b, h) + boff + n * 2048 + k * 1024); } while (0)
; #define PG8_MMA(ai, bj, At, Bt) do { __builtin_amdgcn_s_setprio(1); _Pragma("unroll") for (int m = 0; m < 4; ++m) _Pragma("unroll") for (int n = 0; n < 2; ++n) _Pragma("unroll") for (int k = 0; k < 2; ++k) \
;         acc[ai][bj][m][n] = __builtin_amdgcn_mfma_f32_16x16x32_bf16(Bt[n][k], At[m][k], acc[ai][bj][m][n], 0, 0, 0); __builtin_amdgcn_s_setprio(0); } while (0)
; #define PG8_WAIT_L(n) asm volatile("s_waitcnt lgkmcnt(" #n ")" ::: "memory")
; #define PG8_BAR __builtin_amdgcn_s_barrier()
; #define PG8_SCHED __builtin_amdgcn_sched_barrier(0)
; template <class Epi>
; DEVINL void gemm_phase(LAS unsigned char* lds, const Gemm g, const Order& S, const Epi& E) {
;     ...
;         const char* nA = has_next ? (const char*)g.A + (size_t)nxt.pm * tstepA : cA; const char* nB = has_next ? (const char*)g.Bt + (size_t)nxt.pn * tstepB : cB;
;         for (int t = 0; t < nt; t += 2) {
;             const bool last = (t == nt - 2);
;             const char* a1 = cA + (size_t)(t + 1) * kstep;
;             const char* a2 = last ? nA : cA + (size_t)(t + 2) * kstep; const char* b2 = last ? nB : cB + (size_t)(t + 2) * kstep;
;             const char* a3 = a2 + kstep; const char* b3 = b2 + kstep;
;             PG8_LDB(B0, 0, 0); PG8_SCHED; PG8_LDA(At, 0, 0); PG8_STAGE(PG8_SA(1, 1), a1 + hstepA, voffA);
;             PG8_WAIT_L(8); PG8_BAR; PG8_WAIT_L(0); PG8_MMA(0, 0, At, B0); PG8_BAR; PG8_SCHED;
;             PG8_LDB(B1, 0, 1); PG8_STAGE(PG8_SB(0, 0), b2, voffB);
;             PG8_BAR; PG8_WAIT_L(0); PG8_MMA(0, 1, At, B1); PG8_BAR;
;             PG8_LDA(At, 0, 1); PG8_STAGE(PG8_SA(0, 0), a2, voffA);
;             PG8_BAR; PG8_WAIT_L(0); PG8_MMA(1, 0, At, B0); PG8_BAR; PG8_SCHED;
.LBB0_1029:
	ds_read_b128 v[150:153], v147
	ds_read_b128 v[154:157], v147 offset:1024
	ds_read_b128 v[158:161], v147 offset:2048
	ds_read_b128 v[162:165], v147 offset:3072
	s_add_i32 s70, s48, 2
	s_add_u32 s49, s4, 0xffff0080
	s_addc_u32 s50, s5, -1
	s_cmp_eq_u32 s57, s48
	s_cselect_b32 s48, s13, s68
	s_cselect_b32 s51, s2, s50
	s_cselect_b32 s50, s3, s49
	s_cselect_b32 s49, s11, s69
	v_lshl_add_u64 v[198:199], s[4:5], 0, v[136:137]
	s_add_i32 m0, s31, 0xc000
	ds_read_b128 v[166:169], v148
	ds_read_b128 v[170:173], v148 offset:1024
	ds_read_b128 v[174:177], v148 offset:2048
	ds_read_b128 v[178:181], v148 offset:3072
	ds_read_b128 v[182:185], v148 offset:4096
	ds_read_b128 v[186:189], v148 offset:5120
	ds_read_b128 v[190:193], v148 offset:6144
	ds_read_b128 v[194:197], v148 offset:7168
	global_load_lds_dwordx4 v[198:199], off
	v_lshl_add_u64 v[198:199], s[4:5], 0, v[138:139]
	s_add_i32 m0, s31, 0xe000
	s_nop 0
	global_load_lds_dwordx4 v[198:199], off
	s_waitcnt lgkmcnt(8)
	s_barrier
	s_waitcnt lgkmcnt(0)
	s_waitcnt lgkmcnt(0)
	v_mfma_f32_16x16x32_bf16 v[124:127], v[150:153], v[166:169], v[124:127]
	v_mfma_f32_16x16x32_bf16 v[124:127], v[154:157], v[170:173], v[124:127]
	v_mfma_f32_16x16x32_bf16 v[120:123], v[162:165], v[170:173], v[120:123]
	v_mfma_f32_16x16x32_bf16 v[120:123], v[158:161], v[166:169], v[120:123]
	v_mfma_f32_16x16x32_bf16 v[112:115], v[158:161], v[174:177], v[112:115]
	v_mfma_f32_16x16x32_bf16 v[112:115], v[162:165], v[178:181], v[112:115]
	v_mfma_f32_16x16x32_bf16 v[116:119], v[154:157], v[178:181], v[116:119]
	v_mfma_f32_16x16x32_bf16 v[116:119], v[150:153], v[174:177], v[116:119]
	v_mfma_f32_16x16x32_bf16 v[108:111], v[150:153], v[182:185], v[108:111]
	v_mfma_f32_16x16x32_bf16 v[108:111], v[154:157], v[186:189], v[108:111]
	v_mfma_f32_16x16x32_bf16 v[104:107], v[162:165], v[186:189], v[104:107]
	v_mfma_f32_16x16x32_bf16 v[104:107], v[158:161], v[182:185], v[104:107]
	v_mfma_f32_16x16x32_bf16 v[96:99], v[158:161], v[190:193], v[96:99]
	v_mfma_f32_16x16x32_bf16 v[96:99], v[162:165], v[194:197], v[96:99]
	v_mfma_f32_16x16x32_bf16 v[100:103], v[154:157], v[194:197], v[100:103]
	v_mfma_f32_16x16x32_bf16 v[100:103], v[150:153], v[190:193], v[100:103]
	s_barrier
	s_add_i32 s71, s65, s30
	v_lshl_add_u64 v[218:219], s[48:49], 0, v[130:131]
	s_mov_b32 m0, s71
	ds_read_b128 v[198:201], v149
	ds_read_b128 v[202:205], v149 offset:1024
	ds_read_b128 v[206:209], v149 offset:2048
	ds_read_b128 v[210:213], v149 offset:3072
	global_load_lds_dwordx4 v[218:219], off
	v_lshl_add_u64 v[220:221], s[48:49], 0, v[134:135]
	s_add_i32 m0, s71, 0x2000
	s_nop 0
	global_load_lds_dwordx4 v[220:221], off
	s_barrier
	s_waitcnt lgkmcnt(0)
	s_waitcnt lgkmcnt(0)
	v_mfma_f32_16x16x32_bf16 v[60:63], v[198:201], v[166:169], v[60:63]
	v_mfma_f32_16x16x32_bf16 v[60:63], v[202:205], v[170:173], v[60:63]
	v_mfma_f32_16x16x32_bf16 v[56:59], v[210:213], v[170:173], v[56:59]
	v_mfma_f32_16x16x32_bf16 v[56:59], v[206:209], v[166:169], v[56:59]
	v_mfma_f32_16x16x32_bf16 v[48:51], v[206:209], v[174:177], v[48:51]
	v_mfma_f32_16x16x32_bf16 v[48:51], v[210:213], v[178:181], v[48:51]
	v_mfma_f32_16x16x32_bf16 v[52:55], v[202:205], v[178:181], v[52:55]
	v_mfma_f32_16x16x32_bf16 v[52:55], v[198:201], v[174:177], v[52:55]
	v_mfma_f32_16x16x32_bf16 v[44:47], v[198:201], v[182:185], v[44:47]
	v_mfma_f32_16x16x32_bf16 v[44:47], v[202:205], v[186:189], v[44:47]
	v_mfma_f32_16x16x32_bf16 v[40:43], v[210:213], v[186:189], v[40:43]
	v_mfma_f32_16x16x32_bf16 v[40:43], v[206:209], v[182:185], v[40:43]
	v_mfma_f32_16x16x32_bf16 v[32:35], v[206:209], v[190:193], v[32:35]
	v_mfma_f32_16x16x32_bf16 v[32:35], v[210:213], v[194:197], v[32:35]
	v_mfma_f32_16x16x32_bf16 v[36:39], v[202:205], v[194:197], v[36:39]
	v_mfma_f32_16x16x32_bf16 v[36:39], v[198:201], v[190:193], v[36:39]
	s_mov_b32 m0, s31
	v_lshl_add_u64 v[222:223], s[50:51], 0, v[128:129]
	s_barrier
	ds_read_b128 v[166:169], v148 offset:16384
	ds_read_b128 v[170:173], v148 offset:17408
	ds_read_b128 v[174:177], v148 offset:18432
	ds_read_b128 v[178:181], v148 offset:19456
	ds_read_b128 v[182:185], v148 offset:20480
	ds_read_b128 v[186:189], v148 offset:21504
	ds_read_b128 v[190:193], v148 offset:22528
	ds_read_b128 v[194:197], v148 offset:23552
	global_load_lds_dwordx4 v[222:223], off
	v_lshl_add_u64 v[224:225], s[50:51], 0, v[132:133]
	s_mov_b32 m0, s47
	s_nop 0
	global_load_lds_dwordx4 v[224:225], off
	s_barrier
	s_waitcnt lgkmcnt(0)
	s_waitcnt lgkmcnt(0)
	v_mfma_f32_16x16x32_bf16 v[92:95], v[150:153], v[166:169], v[92:95]
	v_mfma_f32_16x16x32_bf16 v[92:95], v[154:157], v[170:173], v[92:95]
	v_mfma_f32_16x16x32_bf16 v[88:91], v[162:165], v[170:173], v[88:91]
	v_mfma_f32_16x16x32_bf16 v[88:91], v[158:161], v[166:169], v[88:91]
	v_mfma_f32_16x16x32_bf16 v[80:83], v[158:161], v[174:177], v[80:83]
	v_mfma_f32_16x16x32_bf16 v[80:83], v[162:165], v[178:181], v[80:83]
	v_mfma_f32_16x16x32_bf16 v[84:87], v[154:157], v[178:181], v[84:87]
	v_mfma_f32_16x16x32_bf16 v[84:87], v[150:153], v[174:177], v[84:87]
	v_mfma_f32_16x16x32_bf16 v[76:79], v[150:153], v[182:185], v[76:79]
	v_mfma_f32_16x16x32_bf16 v[76:79], v[154:157], v[186:189], v[76:79]
	v_mfma_f32_16x16x32_bf16 v[72:75], v[162:165], v[186:189], v[72:75]
	v_mfma_f32_16x16x32_bf16 v[72:75], v[158:161], v[182:185], v[72:75]
	v_mfma_f32_16x16x32_bf16 v[64:67], v[158:161], v[190:193], v[64:67]
	v_mfma_f32_16x16x32_bf16 v[64:67], v[162:165], v[194:197], v[64:67]
	v_mfma_f32_16x16x32_bf16 v[68:71], v[154:157], v[194:197], v[68:71]
	v_mfma_f32_16x16x32_bf16 v[68:71], v[150:153], v[190:193], v[68:71]
	s_barrier
; #define PG8_STAGE(bufoff, gbase, voff) do { _Pragma("unroll") for (int _i = 0; _i < 2; ++_i) \
;         __builtin_amdgcn_global_load_lds((const unsigned*)((const char*)(gbase) + (voff)[_i]), (LAS unsigned*)(lds + (bufoff) + ldsw + _i * 8192), 16, 0, 0); } while (0)
; #define PG8_LDA(dst, b, h) do { _Pragma("unroll") for (int m = 0; m < 4; ++m) _Pragma("unroll") for (int k = 0; k < 2; ++k) dst[m][k] = *(const LAS bf16x8*)(lds + PG8_SA(b, h) + aoff + m * 2048 + k * 1024); } while (0)
; #define PG8_LDB(dst, b, h) do { _Pragma("unroll") for (int n = 0; n < 2; ++n) _Pragma("unroll") for (int k = 0; k < 2; ++k) dst[n][k] = *(const LAS bf16x8*)(lds + PG8_SB(b, h) + boff + n * 2048 + k * 1024); } while (0)
; #define PG8_MMA(ai, bj, At, Bt) do { __builtin_amdgcn_s_setprio(1); _Pragma("unroll") for (int m = 0; m < 4; ++m) _Pragma("unroll") for (int n = 0; n < 2; ++n) _Pragma("unroll") for (int k = 0; k < 2; ++k) \
;         acc[ai][bj][m][n] = __builtin_amdgcn_mfma_f32_16x16x32_bf16(Bt[n][k], At[m][k], acc[ai][bj][m][n], 0, 0, 0); __builtin_amdgcn_s_setprio(0); } while (0)
; #define PG8_WAIT_V(n) asm volatile("s_waitcnt vmcnt(" #n ")" ::: "memory")
; #define PG8_WAIT_L(n) asm volatile("s_waitcnt lgkmcnt(" #n ")" ::: "memory")
; #define PG8_BAR __builtin_amdgcn_s_barrier()
; #define PG8_SCHED __builtin_amdgcn_sched_barrier(0)
; template <class Epi>
; DEVINL void gemm_phase(LAS unsigned char* lds, const Gemm g, const Order& S, const Epi& E) {
;     ...
;             PG8_STAGE(PG8_SB(0, 1), b2 + hstepB, voffB);
;             PG8_WAIT_V(6); PG8_BAR; PG8_MMA(1, 1, At, B1); PG8_BAR;
;             PG8_LDB(B0, 1, 0); PG8_SCHED; PG8_LDA(At, 1, 0); PG8_STAGE(PG8_SA(0, 1), a2 + hstepA, voffA);
;             PG8_WAIT_L(8); PG8_BAR; PG8_WAIT_L(0); PG8_MMA(0, 0, At, B0); PG8_BAR; PG8_SCHED;
;             PG8_LDB(B1, 1, 1); PG8_STAGE(PG8_SB(1, 0), b3, voffB);
	s_add_u32 s72, s48, 0x10000
	s_addc_u32 s73, s49, 0
	s_add_i32 s71, s66, s30
	v_lshl_add_u64 v[150:151], s[72:73], 0, v[130:131]
	s_mov_b32 m0, s71
	s_nop 0
	global_load_lds_dwordx4 v[150:151], off
	v_lshl_add_u64 v[150:151], s[72:73], 0, v[134:135]
	s_add_i32 m0, s71, 0x2000
	s_nop 0
	global_load_lds_dwordx4 v[150:151], off
	s_waitcnt vmcnt(6)
	s_barrier
	v_mfma_f32_16x16x32_bf16 v[28:31], v[198:201], v[166:169], v[28:31]
	v_mfma_f32_16x16x32_bf16 v[28:31], v[202:205], v[170:173], v[28:31]
	v_mfma_f32_16x16x32_bf16 v[24:27], v[210:213], v[170:173], v[24:27]
	v_mfma_f32_16x16x32_bf16 v[24:27], v[206:209], v[166:169], v[24:27]
	v_mfma_f32_16x16x32_bf16 v[16:19], v[206:209], v[174:177], v[16:19]
	v_mfma_f32_16x16x32_bf16 v[16:19], v[210:213], v[178:181], v[16:19]
	v_mfma_f32_16x16x32_bf16 v[20:23], v[202:205], v[178:181], v[20:23]
	v_mfma_f32_16x16x32_bf16 v[20:23], v[198:201], v[174:177], v[20:23]
	v_mfma_f32_16x16x32_bf16 v[12:15], v[198:201], v[182:185], v[12:15]
	v_mfma_f32_16x16x32_bf16 v[12:15], v[202:205], v[186:189], v[12:15]
	v_mfma_f32_16x16x32_bf16 v[8:11], v[210:213], v[186:189], v[8:11]
	v_mfma_f32_16x16x32_bf16 v[8:11], v[206:209], v[182:185], v[8:11]
	v_mfma_f32_16x16x32_bf16 v[0:3], v[206:209], v[190:193], v[0:3]
	v_mfma_f32_16x16x32_bf16 v[0:3], v[210:213], v[194:197], v[0:3]
	v_mfma_f32_16x16x32_bf16 v[4:7], v[202:205], v[194:197], v[4:7]
	v_mfma_f32_16x16x32_bf16 v[4:7], v[198:201], v[190:193], v[4:7]
	s_add_i32 s71, 16, 0x18000
	v_add_u32_e32 v162, s71, v145
	s_barrier
	ds_read_b128 v[150:153], v162
	ds_read_b128 v[154:157], v162 offset:1024
	ds_read_b128 v[158:161], v162 offset:2048
	ds_read_b128 v[162:165], v162 offset:3072
	s_add_u32 s50, s50, 0x10000
	s_addc_u32 s51, s51, 0
	s_mov_b32 m0, s52
	v_lshl_add_u64 v[198:199], s[50:51], 0, v[128:129]
	ds_read_b128 v[166:169], v148 offset:32768
	ds_read_b128 v[170:173], v148 offset:33792
	ds_read_b128 v[174:177], v148 offset:34816
	ds_read_b128 v[178:181], v148 offset:35840
	ds_read_b128 v[182:185], v148 offset:36864
	ds_read_b128 v[186:189], v148 offset:37888
	ds_read_b128 v[190:193], v148 offset:38912
	ds_read_b128 v[194:197], v148 offset:39936
	global_load_lds_dwordx4 v[198:199], off
	v_lshl_add_u64 v[198:199], s[50:51], 0, v[132:133]
	s_mov_b32 m0, s53
	s_nop 0
	global_load_lds_dwordx4 v[198:199], off
	s_waitcnt lgkmcnt(8)
	s_barrier
	s_waitcnt lgkmcnt(0)
	s_waitcnt lgkmcnt(0)
	v_mfma_f32_16x16x32_bf16 v[124:127], v[150:153], v[166:169], v[124:127]
	v_mfma_f32_16x16x32_bf16 v[124:127], v[154:157], v[170:173], v[124:127]
	v_mfma_f32_16x16x32_bf16 v[120:123], v[162:165], v[170:173], v[120:123]
	v_mfma_f32_16x16x32_bf16 v[120:123], v[158:161], v[166:169], v[120:123]
	v_mfma_f32_16x16x32_bf16 v[112:115], v[158:161], v[174:177], v[112:115]
	v_mfma_f32_16x16x32_bf16 v[112:115], v[162:165], v[178:181], v[112:115]
	v_mfma_f32_16x16x32_bf16 v[116:119], v[154:157], v[178:181], v[116:119]
	v_mfma_f32_16x16x32_bf16 v[116:119], v[150:153], v[174:177], v[116:119]
	v_mfma_f32_16x16x32_bf16 v[108:111], v[150:153], v[182:185], v[108:111]
	v_mfma_f32_16x16x32_bf16 v[108:111], v[154:157], v[186:189], v[108:111]
	v_mfma_f32_16x16x32_bf16 v[104:107], v[162:165], v[186:189], v[104:107]
	v_mfma_f32_16x16x32_bf16 v[104:107], v[158:161], v[182:185], v[104:107]
	v_mfma_f32_16x16x32_bf16 v[96:99], v[158:161], v[190:193], v[96:99]
	v_mfma_f32_16x16x32_bf16 v[96:99], v[162:165], v[194:197], v[96:99]
	v_mfma_f32_16x16x32_bf16 v[100:103], v[154:157], v[194:197], v[100:103]
	v_mfma_f32_16x16x32_bf16 v[100:103], v[150:153], v[190:193], v[100:103]
	s_barrier
	s_add_i32 s50, 16, 0x1c000
	s_add_i32 s51, s71, s30
	v_add_u32_e32 v210, s50, v145
	v_lshl_add_u64 v[218:219], v[218:219], 0, s[6:7]
	s_mov_b32 m0, s51
	ds_read_b128 v[198:201], v210
	ds_read_b128 v[202:205], v210 offset:1024
	ds_read_b128 v[206:209], v210 offset:2048
	ds_read_b128 v[210:213], v210 offset:3072
	global_load_lds_dwordx4 v[218:219], off
	v_lshl_add_u64 v[218:219], v[220:221], 0, s[6:7]
	s_add_i32 m0, s51, 0x2000
	s_nop 0
	global_load_lds_dwordx4 v[218:219], off
	s_barrier
; #define PG8_STAGE(bufoff, gbase, voff) do { _Pragma("unroll") for (int _i = 0; _i < 2; ++_i) \
;         __builtin_amdgcn_global_load_lds((const unsigned*)((const char*)(gbase) + (voff)[_i]), (LAS unsigned*)(lds + (bufoff) + ldsw + _i * 8192), 16, 0, 0); } while (0)
; #define PG8_LDA(dst, b, h) do { _Pragma("unroll") for (int m = 0; m < 4; ++m) _Pragma("unroll") for (int k = 0; k < 2; ++k) dst[m][k] = *(const LAS bf16x8*)(lds + PG8_SA(b, h) + aoff + m * 2048 + k * 1024); } while (0)
; #define PG8_MMA(ai, bj, At, Bt) do { __builtin_amdgcn_s_setprio(1); _Pragma("unroll") for (int m = 0; m < 4; ++m) _Pragma("unroll") for (int n = 0; n < 2; ++n) _Pragma("unroll") for (int k = 0; k < 2; ++k) \
;         acc[ai][bj][m][n] = __builtin_amdgcn_mfma_f32_16x16x32_bf16(Bt[n][k], At[m][k], acc[ai][bj][m][n], 0, 0, 0); __builtin_amdgcn_s_setprio(0); } while (0)
; #define PG8_WAIT_V(n) asm volatile("s_waitcnt vmcnt(" #n ")" ::: "memory")
; #define PG8_WAIT_L(n) asm volatile("s_waitcnt lgkmcnt(" #n ")" ::: "memory")
; #define PG8_BAR __builtin_amdgcn_s_barrier()
; #define PG8_SCHED __builtin_amdgcn_sched_barrier(0)
; template <class Epi>
; DEVINL void gemm_phase(LAS unsigned char* lds, const Gemm g, const Order& S, const Epi& E) {
;     ...
;             PG8_BAR; PG8_WAIT_L(0); PG8_MMA(0, 1, At, B1); PG8_BAR;
;             PG8_LDA(At, 1, 1); PG8_STAGE(PG8_SA(1, 0), a3, voffA);
;             PG8_BAR; PG8_WAIT_L(0); PG8_MMA(1, 0, At, B0); PG8_BAR; PG8_SCHED;
;             PG8_STAGE(PG8_SB(1, 1), b3 + hstepB, voffB);
;             PG8_WAIT_V(6); PG8_BAR; PG8_MMA(1, 1, At, B1); PG8_BAR;
	s_waitcnt lgkmcnt(0)
	s_waitcnt lgkmcnt(0)
	v_mfma_f32_16x16x32_bf16 v[60:63], v[198:201], v[166:169], v[60:63]
	v_mfma_f32_16x16x32_bf16 v[60:63], v[202:205], v[170:173], v[60:63]
	v_mfma_f32_16x16x32_bf16 v[56:59], v[210:213], v[170:173], v[56:59]
	v_mfma_f32_16x16x32_bf16 v[56:59], v[206:209], v[166:169], v[56:59]
	v_mfma_f32_16x16x32_bf16 v[48:51], v[206:209], v[174:177], v[48:51]
	v_mfma_f32_16x16x32_bf16 v[48:51], v[210:213], v[178:181], v[48:51]
	v_mfma_f32_16x16x32_bf16 v[52:55], v[202:205], v[178:181], v[52:55]
	v_mfma_f32_16x16x32_bf16 v[52:55], v[198:201], v[174:177], v[52:55]
	v_mfma_f32_16x16x32_bf16 v[44:47], v[198:201], v[182:185], v[44:47]
	v_mfma_f32_16x16x32_bf16 v[44:47], v[202:205], v[186:189], v[44:47]
	v_mfma_f32_16x16x32_bf16 v[40:43], v[210:213], v[186:189], v[40:43]
	v_mfma_f32_16x16x32_bf16 v[40:43], v[206:209], v[182:185], v[40:43]
	v_mfma_f32_16x16x32_bf16 v[32:35], v[206:209], v[190:193], v[32:35]
	v_mfma_f32_16x16x32_bf16 v[32:35], v[210:213], v[194:197], v[32:35]
	v_mfma_f32_16x16x32_bf16 v[36:39], v[202:205], v[194:197], v[36:39]
	v_mfma_f32_16x16x32_bf16 v[36:39], v[198:201], v[190:193], v[36:39]
	s_mov_b32 m0, s55
	v_lshl_add_u64 v[218:219], v[222:223], 0, s[6:7]
	s_barrier
	ds_read_b128 v[166:169], v148 offset:49152
	ds_read_b128 v[170:173], v148 offset:50176
	ds_read_b128 v[174:177], v148 offset:51200
	ds_read_b128 v[178:181], v148 offset:52224
	ds_read_b128 v[182:185], v148 offset:53248
	ds_read_b128 v[186:189], v148 offset:54272
	ds_read_b128 v[190:193], v148 offset:55296
	ds_read_b128 v[194:197], v148 offset:56320
	global_load_lds_dwordx4 v[218:219], off
	v_lshl_add_u64 v[218:219], v[224:225], 0, s[6:7]
	s_mov_b32 m0, s56
	s_nop 0
	global_load_lds_dwordx4 v[218:219], off
	s_barrier
	s_waitcnt lgkmcnt(0)
	s_waitcnt lgkmcnt(0)
	v_mfma_f32_16x16x32_bf16 v[92:95], v[150:153], v[166:169], v[92:95]
	v_mfma_f32_16x16x32_bf16 v[92:95], v[154:157], v[170:173], v[92:95]
	v_mfma_f32_16x16x32_bf16 v[88:91], v[162:165], v[170:173], v[88:91]
	v_mfma_f32_16x16x32_bf16 v[88:91], v[158:161], v[166:169], v[88:91]
	v_mfma_f32_16x16x32_bf16 v[80:83], v[158:161], v[174:177], v[80:83]
	v_mfma_f32_16x16x32_bf16 v[80:83], v[162:165], v[178:181], v[80:83]
	v_mfma_f32_16x16x32_bf16 v[84:87], v[154:157], v[178:181], v[84:87]
	v_mfma_f32_16x16x32_bf16 v[84:87], v[150:153], v[174:177], v[84:87]
	v_mfma_f32_16x16x32_bf16 v[76:79], v[150:153], v[182:185], v[76:79]
	v_mfma_f32_16x16x32_bf16 v[76:79], v[154:157], v[186:189], v[76:79]
	v_mfma_f32_16x16x32_bf16 v[72:75], v[162:165], v[186:189], v[72:75]
	v_mfma_f32_16x16x32_bf16 v[72:75], v[158:161], v[182:185], v[72:75]
	v_mfma_f32_16x16x32_bf16 v[64:67], v[158:161], v[190:193], v[64:67]
	v_mfma_f32_16x16x32_bf16 v[64:67], v[162:165], v[194:197], v[64:67]
	v_mfma_f32_16x16x32_bf16 v[68:71], v[154:157], v[194:197], v[68:71]
	v_mfma_f32_16x16x32_bf16 v[68:71], v[150:153], v[190:193], v[68:71]
	s_barrier
	s_add_u32 s48, s48, 0x10080
	s_addc_u32 s49, s49, 0
	s_add_i32 s50, s50, s30
	v_lshl_add_u64 v[150:151], s[48:49], 0, v[130:131]
	s_mov_b32 m0, s50
	s_nop 0
	global_load_lds_dwordx4 v[150:151], off
	v_lshl_add_u64 v[150:151], s[48:49], 0, v[134:135]
	s_add_i32 m0, s50, 0x2000
	s_nop 0
	global_load_lds_dwordx4 v[150:151], off
	s_waitcnt vmcnt(6)
	s_barrier
	v_mfma_f32_16x16x32_bf16 v[28:31], v[198:201], v[166:169], v[28:31]
	v_mfma_f32_16x16x32_bf16 v[28:31], v[202:205], v[170:173], v[28:31]
	v_mfma_f32_16x16x32_bf16 v[24:27], v[210:213], v[170:173], v[24:27]
	v_mfma_f32_16x16x32_bf16 v[24:27], v[206:209], v[166:169], v[24:27]
	v_mfma_f32_16x16x32_bf16 v[16:19], v[206:209], v[174:177], v[16:19]
	v_mfma_f32_16x16x32_bf16 v[16:19], v[210:213], v[178:181], v[16:19]
	v_mfma_f32_16x16x32_bf16 v[20:23], v[202:205], v[178:181], v[20:23]
	v_mfma_f32_16x16x32_bf16 v[20:23], v[198:201], v[174:177], v[20:23]
	v_mfma_f32_16x16x32_bf16 v[12:15], v[198:201], v[182:185], v[12:15]
	v_mfma_f32_16x16x32_bf16 v[12:15], v[202:205], v[186:189], v[12:15]
	v_mfma_f32_16x16x32_bf16 v[8:11], v[210:213], v[186:189], v[8:11]
	v_mfma_f32_16x16x32_bf16 v[8:11], v[206:209], v[182:185], v[8:11]
	v_mfma_f32_16x16x32_bf16 v[0:3], v[206:209], v[190:193], v[0:3]
	v_mfma_f32_16x16x32_bf16 v[0:3], v[210:213], v[194:197], v[0:3]
	v_mfma_f32_16x16x32_bf16 v[4:7], v[202:205], v[194:197], v[4:7]
	v_mfma_f32_16x16x32_bf16 v[4:7], v[198:201], v[190:193], v[4:7]
	s_add_u32 s4, s4, 0x100
	s_addc_u32 s5, s5, 0
	s_add_u32 s68, s68, 0x100
	s_addc_u32 s69, s69, 0
	s_cmp_ge_i32 s70, s54
	s_mov_b32 s48, s70
	s_barrier
	s_cbranch_scc0 .LBB0_1029
	s_branch .LBB0_1020

; #define PG8_STAGE(bufoff, gbase, voff) do { _Pragma("unroll") for (int _i = 0; _i < 2; ++_i) \
;         __builtin_amdgcn_global_load_lds((const unsigned*)((const char*)(gbase) + (voff)[_i]), (LAS unsigned*)(lds + (bufoff) + ldsw + _i * 8192), 16, 0, 0); } while (0)
; #define PG8_LDA(dst, b, h) do { _Pragma("unroll") for (int m = 0; m < 4; ++m) _Pragma("unroll") for (int k = 0; k < 2; ++k) dst[m][k] = *(const LAS bf16x8*)(lds + PG8_SA(b, h) + aoff + m * 2048 + k * 1024); } while (0)
; #define PG8_LDB(dst, b, h) do { _Pragma("unroll") for (int n = 0; n < 2; ++n) _Pragma("unroll") for (int k = 0; k < 2; ++k) dst[n][k] = *(const LAS bf16x8*)(lds + PG8_SB(b, h) + boff + n * 2048 + k * 1024); } while (0)
; #define PG8_MMA(ai, bj, At, Bt) do { __builtin_amdgcn_s_setprio(1); _Pragma("unroll") for (int m = 0; m < 4; ++m) _Pragma("unroll") for (int n = 0; n < 2; ++n) _Pragma("unroll") for (int k = 0; k < 2; ++k) \
;         acc[ai][bj][m][n] = __builtin_amdgcn_mfma_f32_16x16x32_bf16(Bt[n][k], At[m][k], acc[ai][bj][m][n], 0, 0, 0); __builtin_amdgcn_s_setprio(0); } while (0)
; #define PG8_WAIT_L(n) asm volatile("s_waitcnt lgkmcnt(" #n ")" ::: "memory")
; #define PG8_BAR __builtin_amdgcn_s_barrier()
; #define PG8_SCHED __builtin_amdgcn_sched_barrier(0)
; template <class Epi>
; DEVINL void gemm_phase(LAS unsigned char* lds, const Gemm g, const Order& S, const Epi& E) {
;     ...
;         const char* nA = has_next ? (const char*)g.A + (size_t)nxt.pm * tstepA : cA; const char* nB = has_next ? (const char*)g.Bt + (size_t)nxt.pn * tstepB : cB;
;         for (int t = 0; t < nt; t += 2) {
;             const bool last = (t == nt - 2);
;             const char* a1 = cA + (size_t)(t + 1) * kstep;
;             const char* a2 = last ? nA : cA + (size_t)(t + 2) * kstep; const char* b2 = last ? nB : cB + (size_t)(t + 2) * kstep;
;             const char* a3 = a2 + kstep; const char* b3 = b2 + kstep;
;             PG8_LDB(B0, 0, 0); PG8_SCHED; PG8_LDA(At, 0, 0); PG8_STAGE(PG8_SA(1, 1), a1 + hstepA, voffA);
;             PG8_WAIT_L(8); PG8_BAR; PG8_WAIT_L(0); PG8_MMA(0, 0, At, B0); PG8_BAR; PG8_SCHED;
;             PG8_LDB(B1, 0, 1); PG8_STAGE(PG8_SB(0, 0), b2, voffB);
;             PG8_BAR; PG8_WAIT_L(0); PG8_MMA(0, 1, At, B1); PG8_BAR;
;             PG8_LDA(At, 0, 1); PG8_STAGE(PG8_SA(0, 0), a2, voffA);
;             PG8_BAR; PG8_WAIT_L(0); PG8_MMA(1, 0, At, B0); PG8_BAR; PG8_SCHED;
.LBB0_1186:
	ds_read_b128 v[128:131], v159
	ds_read_b128 v[148:151], v159 offset:1024
	ds_read_b128 v[152:155], v159 offset:2048
	ds_read_b128 v[162:165], v159 offset:3072
	s_add_i32 s66, s30, 2
	s_add_u32 s31, s10, 0xfffc0080
	s_addc_u32 s40, s11, -1
	s_cmp_eq_u32 s53, s30
	s_cselect_b32 s30, s17, s64
	s_cselect_b32 s41, s2, s40
	s_cselect_b32 s40, s3, s31
	s_cselect_b32 s31, s13, s65
	v_lshl_add_u64 v[198:199], s[10:11], 0, v[140:141]
	s_add_i32 m0, s29, 0xc000
	ds_read_b128 v[166:169], v160
	ds_read_b128 v[170:173], v160 offset:1024
	ds_read_b128 v[174:177], v160 offset:2048
	ds_read_b128 v[178:181], v160 offset:3072
	ds_read_b128 v[182:185], v160 offset:4096
	ds_read_b128 v[186:189], v160 offset:5120
	ds_read_b128 v[190:193], v160 offset:6144
	ds_read_b128 v[194:197], v160 offset:7168
	global_load_lds_dwordx4 v[198:199], off
	v_lshl_add_u64 v[198:199], s[10:11], 0, v[142:143]
	s_add_i32 m0, s29, 0xe000
	s_nop 0
	global_load_lds_dwordx4 v[198:199], off
	s_waitcnt lgkmcnt(8)
	s_barrier
	s_waitcnt lgkmcnt(0)
	s_waitcnt lgkmcnt(0)
	v_mfma_f32_16x16x32_bf16 v[124:127], v[128:131], v[166:169], v[124:127]
	v_mfma_f32_16x16x32_bf16 v[124:127], v[148:151], v[170:173], v[124:127]
	v_mfma_f32_16x16x32_bf16 v[120:123], v[162:165], v[170:173], v[120:123]
	v_mfma_f32_16x16x32_bf16 v[120:123], v[152:155], v[166:169], v[120:123]
	v_mfma_f32_16x16x32_bf16 v[104:107], v[152:155], v[174:177], v[104:107]
	v_mfma_f32_16x16x32_bf16 v[104:107], v[162:165], v[178:181], v[104:107]
	v_mfma_f32_16x16x32_bf16 v[108:111], v[148:151], v[178:181], v[108:111]
	v_mfma_f32_16x16x32_bf16 v[108:111], v[128:131], v[174:177], v[108:111]
	v_mfma_f32_16x16x32_bf16 v[92:95], v[128:131], v[182:185], v[92:95]
	v_mfma_f32_16x16x32_bf16 v[92:95], v[148:151], v[186:189], v[92:95]
	v_mfma_f32_16x16x32_bf16 v[88:91], v[162:165], v[186:189], v[88:91]
	v_mfma_f32_16x16x32_bf16 v[88:91], v[152:155], v[182:185], v[88:91]
	v_mfma_f32_16x16x32_bf16 v[72:75], v[152:155], v[190:193], v[72:75]
	v_mfma_f32_16x16x32_bf16 v[72:75], v[162:165], v[194:197], v[72:75]
	v_mfma_f32_16x16x32_bf16 v[76:79], v[148:151], v[194:197], v[76:79]
	v_mfma_f32_16x16x32_bf16 v[76:79], v[128:131], v[190:193], v[76:79]
	s_barrier
	s_add_i32 s67, s57, s46
	v_lshl_add_u64 v[218:219], s[30:31], 0, v[134:135]
	s_mov_b32 m0, s67
	ds_read_b128 v[198:201], v161
	ds_read_b128 v[202:205], v161 offset:1024
	ds_read_b128 v[206:209], v161 offset:2048
	ds_read_b128 v[210:213], v161 offset:3072
	global_load_lds_dwordx4 v[218:219], off
	v_lshl_add_u64 v[220:221], s[30:31], 0, v[138:139]
	s_add_i32 m0, s67, 0x2000
	s_nop 0
	global_load_lds_dwordx4 v[220:221], off
	s_barrier
	s_waitcnt lgkmcnt(0)
	s_waitcnt lgkmcnt(0)
	v_mfma_f32_16x16x32_bf16 v[116:119], v[198:201], v[166:169], v[116:119]
	v_mfma_f32_16x16x32_bf16 v[116:119], v[202:205], v[170:173], v[116:119]
	v_mfma_f32_16x16x32_bf16 v[112:115], v[210:213], v[170:173], v[112:115]
	v_mfma_f32_16x16x32_bf16 v[112:115], v[206:209], v[166:169], v[112:115]
	v_mfma_f32_16x16x32_bf16 v[96:99], v[206:209], v[174:177], v[96:99]
	v_mfma_f32_16x16x32_bf16 v[96:99], v[210:213], v[178:181], v[96:99]
	v_mfma_f32_16x16x32_bf16 v[100:103], v[202:205], v[178:181], v[100:103]
	v_mfma_f32_16x16x32_bf16 v[100:103], v[198:201], v[174:177], v[100:103]
	v_mfma_f32_16x16x32_bf16 v[84:87], v[198:201], v[182:185], v[84:87]
	v_mfma_f32_16x16x32_bf16 v[84:87], v[202:205], v[186:189], v[84:87]
	v_mfma_f32_16x16x32_bf16 v[80:83], v[210:213], v[186:189], v[80:83]
	v_mfma_f32_16x16x32_bf16 v[80:83], v[206:209], v[182:185], v[80:83]
	v_mfma_f32_16x16x32_bf16 v[64:67], v[206:209], v[190:193], v[64:67]
	v_mfma_f32_16x16x32_bf16 v[64:67], v[210:213], v[194:197], v[64:67]
	v_mfma_f32_16x16x32_bf16 v[68:71], v[202:205], v[194:197], v[68:71]
	v_mfma_f32_16x16x32_bf16 v[68:71], v[198:201], v[190:193], v[68:71]
	s_mov_b32 m0, s29
	v_lshl_add_u64 v[222:223], s[40:41], 0, v[132:133]
	s_barrier
	ds_read_b128 v[166:169], v160 offset:16384
	ds_read_b128 v[170:173], v160 offset:17408
	ds_read_b128 v[174:177], v160 offset:18432
	ds_read_b128 v[178:181], v160 offset:19456
	ds_read_b128 v[182:185], v160 offset:20480
	ds_read_b128 v[186:189], v160 offset:21504
	ds_read_b128 v[190:193], v160 offset:22528
	ds_read_b128 v[194:197], v160 offset:23552
	global_load_lds_dwordx4 v[222:223], off
	v_lshl_add_u64 v[224:225], s[40:41], 0, v[136:137]
	s_mov_b32 m0, s47
	s_nop 0
	global_load_lds_dwordx4 v[224:225], off
	s_barrier
	s_waitcnt lgkmcnt(0)
	s_waitcnt lgkmcnt(0)
	v_mfma_f32_16x16x32_bf16 v[60:63], v[128:131], v[166:169], v[60:63]
	v_mfma_f32_16x16x32_bf16 v[60:63], v[148:151], v[170:173], v[60:63]
	v_mfma_f32_16x16x32_bf16 v[56:59], v[162:165], v[170:173], v[56:59]
	v_mfma_f32_16x16x32_bf16 v[56:59], v[152:155], v[166:169], v[56:59]
	v_mfma_f32_16x16x32_bf16 v[40:43], v[152:155], v[174:177], v[40:43]
	v_mfma_f32_16x16x32_bf16 v[40:43], v[162:165], v[178:181], v[40:43]
	v_mfma_f32_16x16x32_bf16 v[44:47], v[148:151], v[178:181], v[44:47]
	v_mfma_f32_16x16x32_bf16 v[44:47], v[128:131], v[174:177], v[44:47]
	v_mfma_f32_16x16x32_bf16 v[28:31], v[128:131], v[182:185], v[28:31]
	v_mfma_f32_16x16x32_bf16 v[28:31], v[148:151], v[186:189], v[28:31]
	v_mfma_f32_16x16x32_bf16 v[24:27], v[162:165], v[186:189], v[24:27]
	v_mfma_f32_16x16x32_bf16 v[24:27], v[152:155], v[182:185], v[24:27]
	v_mfma_f32_16x16x32_bf16 v[8:11], v[152:155], v[190:193], v[8:11]
	v_mfma_f32_16x16x32_bf16 v[8:11], v[162:165], v[194:197], v[8:11]
	v_mfma_f32_16x16x32_bf16 v[12:15], v[148:151], v[194:197], v[12:15]
	v_mfma_f32_16x16x32_bf16 v[12:15], v[128:131], v[190:193], v[12:15]
	s_barrier
; #define PG8_STAGE(bufoff, gbase, voff) do { _Pragma("unroll") for (int _i = 0; _i < 2; ++_i) \
;         __builtin_amdgcn_global_load_lds((const unsigned*)((const char*)(gbase) + (voff)[_i]), (LAS unsigned*)(lds + (bufoff) + ldsw + _i * 8192), 16, 0, 0); } while (0)
; #define PG8_LDA(dst, b, h) do { _Pragma("unroll") for (int m = 0; m < 4; ++m) _Pragma("unroll") for (int k = 0; k < 2; ++k) dst[m][k] = *(const LAS bf16x8*)(lds + PG8_SA(b, h) + aoff + m * 2048 + k * 1024); } while (0)
; #define PG8_LDB(dst, b, h) do { _Pragma("unroll") for (int n = 0; n < 2; ++n) _Pragma("unroll") for (int k = 0; k < 2; ++k) dst[n][k] = *(const LAS bf16x8*)(lds + PG8_SB(b, h) + boff + n * 2048 + k * 1024); } while (0)
; #define PG8_MMA(ai, bj, At, Bt) do { __builtin_amdgcn_s_setprio(1); _Pragma("unroll") for (int m = 0; m < 4; ++m) _Pragma("unroll") for (int n = 0; n < 2; ++n) _Pragma("unroll") for (int k = 0; k < 2; ++k) \
;         acc[ai][bj][m][n] = __builtin_amdgcn_mfma_f32_16x16x32_bf16(Bt[n][k], At[m][k], acc[ai][bj][m][n], 0, 0, 0); __builtin_amdgcn_s_setprio(0); } while (0)
; #define PG8_WAIT_V(n) asm volatile("s_waitcnt vmcnt(" #n ")" ::: "memory")
; #define PG8_WAIT_L(n) asm volatile("s_waitcnt lgkmcnt(" #n ")" ::: "memory")
; #define PG8_BAR __builtin_amdgcn_s_barrier()
; #define PG8_SCHED __builtin_amdgcn_sched_barrier(0)
; template <class Epi>
; DEVINL void gemm_phase(LAS unsigned char* lds, const Gemm g, const Order& S, const Epi& E) {
;     ...
;             PG8_STAGE(PG8_SB(0, 1), b2 + hstepB, voffB);
;             PG8_WAIT_V(6); PG8_BAR; PG8_MMA(1, 1, At, B1); PG8_BAR;
;             PG8_LDB(B0, 1, 0); PG8_SCHED; PG8_LDA(At, 1, 0); PG8_STAGE(PG8_SA(0, 1), a2 + hstepA, voffA);
;             PG8_WAIT_L(8); PG8_BAR; PG8_WAIT_L(0); PG8_MMA(0, 0, At, B0); PG8_BAR; PG8_SCHED;
;             PG8_LDB(B1, 1, 1); PG8_STAGE(PG8_SB(1, 0), b3, voffB);
	s_add_u32 s68, s30, 0x40000
	s_addc_u32 s69, s31, 0
	s_add_i32 s67, s58, s46
	v_lshl_add_u64 v[128:129], s[68:69], 0, v[134:135]
	s_mov_b32 m0, s67
	s_nop 0
	global_load_lds_dwordx4 v[128:129], off
	v_lshl_add_u64 v[128:129], s[68:69], 0, v[138:139]
	s_add_i32 m0, s67, 0x2000
	s_nop 0
	global_load_lds_dwordx4 v[128:129], off
	s_waitcnt vmcnt(6)
	s_barrier
	v_mfma_f32_16x16x32_bf16 v[52:55], v[198:201], v[166:169], v[52:55]
	v_mfma_f32_16x16x32_bf16 v[52:55], v[202:205], v[170:173], v[52:55]
	v_mfma_f32_16x16x32_bf16 v[48:51], v[210:213], v[170:173], v[48:51]
	v_mfma_f32_16x16x32_bf16 v[48:51], v[206:209], v[166:169], v[48:51]
	v_mfma_f32_16x16x32_bf16 v[32:35], v[206:209], v[174:177], v[32:35]
	v_mfma_f32_16x16x32_bf16 v[32:35], v[210:213], v[178:181], v[32:35]
	v_mfma_f32_16x16x32_bf16 v[36:39], v[202:205], v[178:181], v[36:39]
	v_mfma_f32_16x16x32_bf16 v[36:39], v[198:201], v[174:177], v[36:39]
	v_mfma_f32_16x16x32_bf16 v[20:23], v[198:201], v[182:185], v[20:23]
	v_mfma_f32_16x16x32_bf16 v[20:23], v[202:205], v[186:189], v[20:23]
	v_mfma_f32_16x16x32_bf16 v[16:19], v[210:213], v[186:189], v[16:19]
	v_mfma_f32_16x16x32_bf16 v[16:19], v[206:209], v[182:185], v[16:19]
	v_mfma_f32_16x16x32_bf16 v[0:3], v[206:209], v[190:193], v[0:3]
	v_mfma_f32_16x16x32_bf16 v[0:3], v[210:213], v[194:197], v[0:3]
	v_mfma_f32_16x16x32_bf16 v[4:7], v[202:205], v[194:197], v[4:7]
	v_mfma_f32_16x16x32_bf16 v[4:7], v[198:201], v[190:193], v[4:7]
	s_add_i32 s67, 16, 0x18000
	v_add_u32_e32 v162, s67, v157
	s_barrier
	ds_read_b128 v[128:131], v162
	ds_read_b128 v[148:151], v162 offset:1024
	ds_read_b128 v[152:155], v162 offset:2048
	ds_read_b128 v[162:165], v162 offset:3072
	s_add_u32 s40, s40, 0x40000
	s_addc_u32 s41, s41, 0
	s_mov_b32 m0, s48
	v_lshl_add_u64 v[198:199], s[40:41], 0, v[132:133]
	ds_read_b128 v[166:169], v160 offset:32768
	ds_read_b128 v[170:173], v160 offset:33792
	ds_read_b128 v[174:177], v160 offset:34816
	ds_read_b128 v[178:181], v160 offset:35840
	ds_read_b128 v[182:185], v160 offset:36864
	ds_read_b128 v[186:189], v160 offset:37888
	ds_read_b128 v[190:193], v160 offset:38912
	ds_read_b128 v[194:197], v160 offset:39936
	global_load_lds_dwordx4 v[198:199], off
	v_lshl_add_u64 v[198:199], s[40:41], 0, v[136:137]
	s_mov_b32 m0, s49
	s_nop 0
	global_load_lds_dwordx4 v[198:199], off
	s_waitcnt lgkmcnt(8)
	s_barrier
	s_waitcnt lgkmcnt(0)
	s_waitcnt lgkmcnt(0)
	v_mfma_f32_16x16x32_bf16 v[124:127], v[128:131], v[166:169], v[124:127]
	v_mfma_f32_16x16x32_bf16 v[124:127], v[148:151], v[170:173], v[124:127]
	v_mfma_f32_16x16x32_bf16 v[120:123], v[162:165], v[170:173], v[120:123]
	v_mfma_f32_16x16x32_bf16 v[120:123], v[152:155], v[166:169], v[120:123]
	v_mfma_f32_16x16x32_bf16 v[104:107], v[152:155], v[174:177], v[104:107]
	v_mfma_f32_16x16x32_bf16 v[104:107], v[162:165], v[178:181], v[104:107]
	v_mfma_f32_16x16x32_bf16 v[108:111], v[148:151], v[178:181], v[108:111]
	v_mfma_f32_16x16x32_bf16 v[108:111], v[128:131], v[174:177], v[108:111]
	v_mfma_f32_16x16x32_bf16 v[92:95], v[128:131], v[182:185], v[92:95]
	v_mfma_f32_16x16x32_bf16 v[92:95], v[148:151], v[186:189], v[92:95]
	v_mfma_f32_16x16x32_bf16 v[88:91], v[162:165], v[186:189], v[88:91]
	v_mfma_f32_16x16x32_bf16 v[88:91], v[152:155], v[182:185], v[88:91]
	v_mfma_f32_16x16x32_bf16 v[72:75], v[152:155], v[190:193], v[72:75]
	v_mfma_f32_16x16x32_bf16 v[72:75], v[162:165], v[194:197], v[72:75]
	v_mfma_f32_16x16x32_bf16 v[76:79], v[148:151], v[194:197], v[76:79]
	v_mfma_f32_16x16x32_bf16 v[76:79], v[128:131], v[190:193], v[76:79]
	s_barrier
	s_add_i32 s40, 16, 0x1c000
	s_add_i32 s41, s67, s46
	v_add_u32_e32 v210, s40, v157
	v_lshl_add_u64 v[218:219], v[218:219], 0, s[6:7]
	s_mov_b32 m0, s41
	ds_read_b128 v[198:201], v210
	ds_read_b128 v[202:205], v210 offset:1024
	ds_read_b128 v[206:209], v210 offset:2048
	ds_read_b128 v[210:213], v210 offset:3072
	global_load_lds_dwordx4 v[218:219], off
	v_lshl_add_u64 v[218:219], v[220:221], 0, s[6:7]
	s_add_i32 m0, s41, 0x2000
	s_nop 0
	global_load_lds_dwordx4 v[218:219], off
	s_barrier
; #define PG8_STAGE(bufoff, gbase, voff) do { _Pragma("unroll") for (int _i = 0; _i < 2; ++_i) \
;         __builtin_amdgcn_global_load_lds((const unsigned*)((const char*)(gbase) + (voff)[_i]), (LAS unsigned*)(lds + (bufoff) + ldsw + _i * 8192), 16, 0, 0); } while (0)
; #define PG8_LDA(dst, b, h) do { _Pragma("unroll") for (int m = 0; m < 4; ++m) _Pragma("unroll") for (int k = 0; k < 2; ++k) dst[m][k] = *(const LAS bf16x8*)(lds + PG8_SA(b, h) + aoff + m * 2048 + k * 1024); } while (0)
; #define PG8_MMA(ai, bj, At, Bt) do { __builtin_amdgcn_s_setprio(1); _Pragma("unroll") for (int m = 0; m < 4; ++m) _Pragma("unroll") for (int n = 0; n < 2; ++n) _Pragma("unroll") for (int k = 0; k < 2; ++k) \
;         acc[ai][bj][m][n] = __builtin_amdgcn_mfma_f32_16x16x32_bf16(Bt[n][k], At[m][k], acc[ai][bj][m][n], 0, 0, 0); __builtin_amdgcn_s_setprio(0); } while (0)
; #define PG8_WAIT_V(n) asm volatile("s_waitcnt vmcnt(" #n ")" ::: "memory")
; #define PG8_WAIT_L(n) asm volatile("s_waitcnt lgkmcnt(" #n ")" ::: "memory")
; #define PG8_BAR __builtin_amdgcn_s_barrier()
; #define PG8_SCHED __builtin_amdgcn_sched_barrier(0)
; template <class Epi>
; DEVINL void gemm_phase(LAS unsigned char* lds, const Gemm g, const Order& S, const Epi& E) {
;     ...
;             PG8_BAR; PG8_WAIT_L(0); PG8_MMA(0, 1, At, B1); PG8_BAR;
;             PG8_LDA(At, 1, 1); PG8_STAGE(PG8_SA(1, 0), a3, voffA);
;             PG8_BAR; PG8_WAIT_L(0); PG8_MMA(1, 0, At, B0); PG8_BAR; PG8_SCHED;
;             PG8_STAGE(PG8_SB(1, 1), b3 + hstepB, voffB);
;             PG8_WAIT_V(6); PG8_BAR; PG8_MMA(1, 1, At, B1); PG8_BAR;
	s_waitcnt lgkmcnt(0)
	s_waitcnt lgkmcnt(0)
	v_mfma_f32_16x16x32_bf16 v[116:119], v[198:201], v[166:169], v[116:119]
	v_mfma_f32_16x16x32_bf16 v[116:119], v[202:205], v[170:173], v[116:119]
	v_mfma_f32_16x16x32_bf16 v[112:115], v[210:213], v[170:173], v[112:115]
	v_mfma_f32_16x16x32_bf16 v[112:115], v[206:209], v[166:169], v[112:115]
	v_mfma_f32_16x16x32_bf16 v[96:99], v[206:209], v[174:177], v[96:99]
	v_mfma_f32_16x16x32_bf16 v[96:99], v[210:213], v[178:181], v[96:99]
	v_mfma_f32_16x16x32_bf16 v[100:103], v[202:205], v[178:181], v[100:103]
	v_mfma_f32_16x16x32_bf16 v[100:103], v[198:201], v[174:177], v[100:103]
	v_mfma_f32_16x16x32_bf16 v[84:87], v[198:201], v[182:185], v[84:87]
	v_mfma_f32_16x16x32_bf16 v[84:87], v[202:205], v[186:189], v[84:87]
	v_mfma_f32_16x16x32_bf16 v[80:83], v[210:213], v[186:189], v[80:83]
	v_mfma_f32_16x16x32_bf16 v[80:83], v[206:209], v[182:185], v[80:83]
	v_mfma_f32_16x16x32_bf16 v[64:67], v[206:209], v[190:193], v[64:67]
	v_mfma_f32_16x16x32_bf16 v[64:67], v[210:213], v[194:197], v[64:67]
	v_mfma_f32_16x16x32_bf16 v[68:71], v[202:205], v[194:197], v[68:71]
	v_mfma_f32_16x16x32_bf16 v[68:71], v[198:201], v[190:193], v[68:71]
	s_mov_b32 m0, s51
	v_lshl_add_u64 v[218:219], v[222:223], 0, s[6:7]
	s_barrier
	ds_read_b128 v[166:169], v160 offset:49152
	ds_read_b128 v[170:173], v160 offset:50176
	ds_read_b128 v[174:177], v160 offset:51200
	ds_read_b128 v[178:181], v160 offset:52224
	ds_read_b128 v[182:185], v160 offset:53248
	ds_read_b128 v[186:189], v160 offset:54272
	ds_read_b128 v[190:193], v160 offset:55296
	ds_read_b128 v[194:197], v160 offset:56320
	global_load_lds_dwordx4 v[218:219], off
	v_lshl_add_u64 v[218:219], v[224:225], 0, s[6:7]
	s_mov_b32 m0, s52
	s_nop 0
	global_load_lds_dwordx4 v[218:219], off
	s_barrier
	s_waitcnt lgkmcnt(0)
	s_waitcnt lgkmcnt(0)
	v_mfma_f32_16x16x32_bf16 v[60:63], v[128:131], v[166:169], v[60:63]
	v_mfma_f32_16x16x32_bf16 v[60:63], v[148:151], v[170:173], v[60:63]
	v_mfma_f32_16x16x32_bf16 v[56:59], v[162:165], v[170:173], v[56:59]
	v_mfma_f32_16x16x32_bf16 v[56:59], v[152:155], v[166:169], v[56:59]
	v_mfma_f32_16x16x32_bf16 v[40:43], v[152:155], v[174:177], v[40:43]
	v_mfma_f32_16x16x32_bf16 v[40:43], v[162:165], v[178:181], v[40:43]
	v_mfma_f32_16x16x32_bf16 v[44:47], v[148:151], v[178:181], v[44:47]
	v_mfma_f32_16x16x32_bf16 v[44:47], v[128:131], v[174:177], v[44:47]
	v_mfma_f32_16x16x32_bf16 v[28:31], v[128:131], v[182:185], v[28:31]
	v_mfma_f32_16x16x32_bf16 v[28:31], v[148:151], v[186:189], v[28:31]
	v_mfma_f32_16x16x32_bf16 v[24:27], v[162:165], v[186:189], v[24:27]
	v_mfma_f32_16x16x32_bf16 v[24:27], v[152:155], v[182:185], v[24:27]
	v_mfma_f32_16x16x32_bf16 v[8:11], v[152:155], v[190:193], v[8:11]
	v_mfma_f32_16x16x32_bf16 v[8:11], v[162:165], v[194:197], v[8:11]
	v_mfma_f32_16x16x32_bf16 v[12:15], v[148:151], v[194:197], v[12:15]
	v_mfma_f32_16x16x32_bf16 v[12:15], v[128:131], v[190:193], v[12:15]
	s_barrier
	s_add_u32 s30, s30, 0x40080
	s_addc_u32 s31, s31, 0
	s_add_i32 s40, s40, s46
	v_lshl_add_u64 v[128:129], s[30:31], 0, v[134:135]
	s_mov_b32 m0, s40
	s_nop 0
	global_load_lds_dwordx4 v[128:129], off
	v_lshl_add_u64 v[128:129], s[30:31], 0, v[138:139]
	s_add_i32 m0, s40, 0x2000
	s_nop 0
	global_load_lds_dwordx4 v[128:129], off
	s_waitcnt vmcnt(6)
	s_barrier
	v_mfma_f32_16x16x32_bf16 v[52:55], v[198:201], v[166:169], v[52:55]
	v_mfma_f32_16x16x32_bf16 v[52:55], v[202:205], v[170:173], v[52:55]
	v_mfma_f32_16x16x32_bf16 v[48:51], v[210:213], v[170:173], v[48:51]
	v_mfma_f32_16x16x32_bf16 v[48:51], v[206:209], v[166:169], v[48:51]
	v_mfma_f32_16x16x32_bf16 v[32:35], v[206:209], v[174:177], v[32:35]
	v_mfma_f32_16x16x32_bf16 v[32:35], v[210:213], v[178:181], v[32:35]
	v_mfma_f32_16x16x32_bf16 v[36:39], v[202:205], v[178:181], v[36:39]
	v_mfma_f32_16x16x32_bf16 v[36:39], v[198:201], v[174:177], v[36:39]
	v_mfma_f32_16x16x32_bf16 v[20:23], v[198:201], v[182:185], v[20:23]
	v_mfma_f32_16x16x32_bf16 v[20:23], v[202:205], v[186:189], v[20:23]
	v_mfma_f32_16x16x32_bf16 v[16:19], v[210:213], v[186:189], v[16:19]
	v_mfma_f32_16x16x32_bf16 v[16:19], v[206:209], v[182:185], v[16:19]
	v_mfma_f32_16x16x32_bf16 v[0:3], v[206:209], v[190:193], v[0:3]
	v_mfma_f32_16x16x32_bf16 v[0:3], v[210:213], v[194:197], v[0:3]
	v_mfma_f32_16x16x32_bf16 v[4:7], v[202:205], v[194:197], v[4:7]
	v_mfma_f32_16x16x32_bf16 v[4:7], v[198:201], v[190:193], v[4:7]
	s_add_u32 s10, s10, 0x100
	s_addc_u32 s11, s11, 0
	s_add_u32 s64, s64, 0x100
	s_addc_u32 s65, s65, 0
	s_cmp_ge_i32 s66, s50
	s_mov_b32 s30, s66
	s_barrier
	s_cbranch_scc0 .LBB0_1186
	s_branch .LBB0_1177

; #define PG8_STAGE(bufoff, gbase, voff) do { _Pragma("unroll") for (int _i = 0; _i < 2; ++_i) \
;         __builtin_amdgcn_global_load_lds((const unsigned*)((const char*)(gbase) + (voff)[_i]), (LAS unsigned*)(lds + (bufoff) + ldsw + _i * 8192), 16, 0, 0); } while (0)
; #define PG8_LDA(dst, b, h) do { _Pragma("unroll") for (int m = 0; m < 4; ++m) _Pragma("unroll") for (int k = 0; k < 2; ++k) dst[m][k] = *(const LAS bf16x8*)(lds + PG8_SA(b, h) + aoff + m * 2048 + k * 1024); } while (0)
; #define PG8_LDB(dst, b, h) do { _Pragma("unroll") for (int n = 0; n < 2; ++n) _Pragma("unroll") for (int k = 0; k < 2; ++k) dst[n][k] = *(const LAS bf16x8*)(lds + PG8_SB(b, h) + boff + n * 2048 + k * 1024); } while (0)
; #define PG8_MMA(ai, bj, At, Bt) do { __builtin_amdgcn_s_setprio(1); _Pragma("unroll") for (int m = 0; m < 4; ++m) _Pragma("unroll") for (int n = 0; n < 2; ++n) _Pragma("unroll") for (int k = 0; k < 2; ++k) \
;         acc[ai][bj][m][n] = __builtin_amdgcn_mfma_f32_16x16x32_bf16(Bt[n][k], At[m][k], acc[ai][bj][m][n], 0, 0, 0); __builtin_amdgcn_s_setprio(0); } while (0)
; #define PG8_WAIT_L(n) asm volatile("s_waitcnt lgkmcnt(" #n ")" ::: "memory")
; #define PG8_BAR __builtin_amdgcn_s_barrier()
; #define PG8_SCHED __builtin_amdgcn_sched_barrier(0)
; template <class Epi>
; DEVINL void gemm_phase(LAS unsigned char* lds, const Gemm g, const Order& S, const Epi& E) {
;     ...
;         const char* nA = has_next ? (const char*)g.A + (size_t)nxt.pm * tstepA : cA; const char* nB = has_next ? (const char*)g.Bt + (size_t)nxt.pn * tstepB : cB;
;         for (int t = 0; t < nt; t += 2) {
;             const bool last = (t == nt - 2);
;             const char* a1 = cA + (size_t)(t + 1) * kstep;
;             const char* a2 = last ? nA : cA + (size_t)(t + 2) * kstep; const char* b2 = last ? nB : cB + (size_t)(t + 2) * kstep;
;             const char* a3 = a2 + kstep; const char* b3 = b2 + kstep;
;             PG8_LDB(B0, 0, 0); PG8_SCHED; PG8_LDA(At, 0, 0); PG8_STAGE(PG8_SA(1, 1), a1 + hstepA, voffA);
;             PG8_WAIT_L(8); PG8_BAR; PG8_WAIT_L(0); PG8_MMA(0, 0, At, B0); PG8_BAR; PG8_SCHED;
;             PG8_LDB(B1, 0, 1); PG8_STAGE(PG8_SB(0, 0), b2, voffB);
;             PG8_BAR; PG8_WAIT_L(0); PG8_MMA(0, 1, At, B1); PG8_BAR;
;             PG8_LDA(At, 0, 1); PG8_STAGE(PG8_SA(0, 0), a2, voffA);
;             PG8_BAR; PG8_WAIT_L(0); PG8_MMA(1, 0, At, B0); PG8_BAR; PG8_SCHED;
.LBB0_1259:
	ds_read_b128 v[128:131], v183
	ds_read_b128 v[132:135], v183 offset:1024
	ds_read_b128 v[136:139], v183 offset:2048
	ds_read_b128 v[140:143], v183 offset:3072
	s_add_i32 s68, s40, 2
	s_add_u32 s41, s8, 0xfffc0080
	s_addc_u32 s42, s9, -1
	s_cmp_eq_u32 s55, s40
	s_cselect_b32 s40, s25, s66
	s_cselect_b32 s43, s2, s42
	s_cselect_b32 s42, s3, s41
	s_cselect_b32 s41, s17, s67
	v_lshl_add_u64 v[198:199], s[8:9], 0, v[160:161]
	s_add_i32 m0, s31, 0xc000
	ds_read_b128 v[144:147], v184
	ds_read_b128 v[148:151], v184 offset:1024
	ds_read_b128 v[168:171], v184 offset:2048
	ds_read_b128 v[172:175], v184 offset:3072
	ds_read_b128 v[176:179], v184 offset:4096
	ds_read_b128 v[186:189], v184 offset:5120
	ds_read_b128 v[190:193], v184 offset:6144
	ds_read_b128 v[194:197], v184 offset:7168
	global_load_lds_dwordx4 v[198:199], off
	v_lshl_add_u64 v[198:199], s[8:9], 0, v[162:163]
	s_add_i32 m0, s31, 0xe000
	s_nop 0
	global_load_lds_dwordx4 v[198:199], off
	s_waitcnt lgkmcnt(8)
	s_barrier
	s_waitcnt lgkmcnt(0)
	s_waitcnt lgkmcnt(0)
	v_mfma_f32_16x16x32_bf16 v[116:119], v[128:131], v[144:147], v[116:119]
	v_mfma_f32_16x16x32_bf16 v[116:119], v[132:135], v[148:151], v[116:119]
	v_mfma_f32_16x16x32_bf16 v[124:127], v[140:143], v[148:151], v[124:127]
	v_mfma_f32_16x16x32_bf16 v[124:127], v[136:139], v[144:147], v[124:127]
	v_mfma_f32_16x16x32_bf16 v[104:107], v[136:139], v[168:171], v[104:107]
	v_mfma_f32_16x16x32_bf16 v[104:107], v[140:143], v[172:175], v[104:107]
	v_mfma_f32_16x16x32_bf16 v[108:111], v[132:135], v[172:175], v[108:111]
	v_mfma_f32_16x16x32_bf16 v[108:111], v[128:131], v[168:171], v[108:111]
	v_mfma_f32_16x16x32_bf16 v[92:95], v[128:131], v[176:179], v[92:95]
	v_mfma_f32_16x16x32_bf16 v[92:95], v[132:135], v[186:189], v[92:95]
	v_mfma_f32_16x16x32_bf16 v[88:91], v[140:143], v[186:189], v[88:91]
	v_mfma_f32_16x16x32_bf16 v[88:91], v[136:139], v[176:179], v[88:91]
	v_mfma_f32_16x16x32_bf16 v[72:75], v[136:139], v[190:193], v[72:75]
	v_mfma_f32_16x16x32_bf16 v[72:75], v[140:143], v[194:197], v[72:75]
	v_mfma_f32_16x16x32_bf16 v[76:79], v[132:135], v[194:197], v[76:79]
	v_mfma_f32_16x16x32_bf16 v[76:79], v[128:131], v[190:193], v[76:79]
	s_barrier
	s_add_i32 s69, s59, s48
	v_lshl_add_u64 v[218:219], s[40:41], 0, v[154:155]
	s_mov_b32 m0, s69
	ds_read_b128 v[198:201], v185
	ds_read_b128 v[202:205], v185 offset:1024
	ds_read_b128 v[206:209], v185 offset:2048
	ds_read_b128 v[210:213], v185 offset:3072
	global_load_lds_dwordx4 v[218:219], off
	v_lshl_add_u64 v[220:221], s[40:41], 0, v[158:159]
	s_add_i32 m0, s69, 0x2000
	s_nop 0
	global_load_lds_dwordx4 v[220:221], off
	s_barrier
	s_waitcnt lgkmcnt(0)
	s_waitcnt lgkmcnt(0)
	v_mfma_f32_16x16x32_bf16 v[120:123], v[198:201], v[144:147], v[120:123]
	v_mfma_f32_16x16x32_bf16 v[120:123], v[202:205], v[148:151], v[120:123]
	v_mfma_f32_16x16x32_bf16 v[112:115], v[210:213], v[148:151], v[112:115]
	v_mfma_f32_16x16x32_bf16 v[112:115], v[206:209], v[144:147], v[112:115]
	v_mfma_f32_16x16x32_bf16 v[96:99], v[206:209], v[168:171], v[96:99]
	v_mfma_f32_16x16x32_bf16 v[96:99], v[210:213], v[172:175], v[96:99]
	v_mfma_f32_16x16x32_bf16 v[100:103], v[202:205], v[172:175], v[100:103]
	v_mfma_f32_16x16x32_bf16 v[100:103], v[198:201], v[168:171], v[100:103]
	v_mfma_f32_16x16x32_bf16 v[84:87], v[198:201], v[176:179], v[84:87]
	v_mfma_f32_16x16x32_bf16 v[84:87], v[202:205], v[186:189], v[84:87]
	v_mfma_f32_16x16x32_bf16 v[80:83], v[210:213], v[186:189], v[80:83]
	v_mfma_f32_16x16x32_bf16 v[80:83], v[206:209], v[176:179], v[80:83]
	v_mfma_f32_16x16x32_bf16 v[64:67], v[206:209], v[190:193], v[64:67]
	v_mfma_f32_16x16x32_bf16 v[64:67], v[210:213], v[194:197], v[64:67]
	v_mfma_f32_16x16x32_bf16 v[68:71], v[202:205], v[194:197], v[68:71]
	v_mfma_f32_16x16x32_bf16 v[68:71], v[198:201], v[190:193], v[68:71]
	s_mov_b32 m0, s31
	v_lshl_add_u64 v[222:223], s[42:43], 0, v[152:153]
	s_barrier
	ds_read_b128 v[144:147], v184 offset:16384
	ds_read_b128 v[148:151], v184 offset:17408
	ds_read_b128 v[168:171], v184 offset:18432
	ds_read_b128 v[172:175], v184 offset:19456
	ds_read_b128 v[176:179], v184 offset:20480
	ds_read_b128 v[186:189], v184 offset:21504
	ds_read_b128 v[190:193], v184 offset:22528
	ds_read_b128 v[194:197], v184 offset:23552
	global_load_lds_dwordx4 v[222:223], off
	v_lshl_add_u64 v[224:225], s[42:43], 0, v[156:157]
	s_mov_b32 m0, s49
	s_nop 0
	global_load_lds_dwordx4 v[224:225], off
	s_barrier
	s_waitcnt lgkmcnt(0)
	s_waitcnt lgkmcnt(0)
	v_mfma_f32_16x16x32_bf16 v[60:63], v[128:131], v[144:147], v[60:63]
	v_mfma_f32_16x16x32_bf16 v[60:63], v[132:135], v[148:151], v[60:63]
	v_mfma_f32_16x16x32_bf16 v[56:59], v[140:143], v[148:151], v[56:59]
	v_mfma_f32_16x16x32_bf16 v[56:59], v[136:139], v[144:147], v[56:59]
	v_mfma_f32_16x16x32_bf16 v[40:43], v[136:139], v[168:171], v[40:43]
	v_mfma_f32_16x16x32_bf16 v[40:43], v[140:143], v[172:175], v[40:43]
	v_mfma_f32_16x16x32_bf16 v[44:47], v[132:135], v[172:175], v[44:47]
	v_mfma_f32_16x16x32_bf16 v[44:47], v[128:131], v[168:171], v[44:47]
	v_mfma_f32_16x16x32_bf16 v[28:31], v[128:131], v[176:179], v[28:31]
	v_mfma_f32_16x16x32_bf16 v[28:31], v[132:135], v[186:189], v[28:31]
	v_mfma_f32_16x16x32_bf16 v[24:27], v[140:143], v[186:189], v[24:27]
	v_mfma_f32_16x16x32_bf16 v[24:27], v[136:139], v[176:179], v[24:27]
	v_mfma_f32_16x16x32_bf16 v[8:11], v[136:139], v[190:193], v[8:11]
	v_mfma_f32_16x16x32_bf16 v[8:11], v[140:143], v[194:197], v[8:11]
	v_mfma_f32_16x16x32_bf16 v[12:15], v[132:135], v[194:197], v[12:15]
	v_mfma_f32_16x16x32_bf16 v[12:15], v[128:131], v[190:193], v[12:15]
	s_barrier
; #define PG8_STAGE(bufoff, gbase, voff) do { _Pragma("unroll") for (int _i = 0; _i < 2; ++_i) \
;         __builtin_amdgcn_global_load_lds((const unsigned*)((const char*)(gbase) + (voff)[_i]), (LAS unsigned*)(lds + (bufoff) + ldsw + _i * 8192), 16, 0, 0); } while (0)
; #define PG8_LDA(dst, b, h) do { _Pragma("unroll") for (int m = 0; m < 4; ++m) _Pragma("unroll") for (int k = 0; k < 2; ++k) dst[m][k] = *(const LAS bf16x8*)(lds + PG8_SA(b, h) + aoff + m * 2048 + k * 1024); } while (0)
; #define PG8_LDB(dst, b, h) do { _Pragma("unroll") for (int n = 0; n < 2; ++n) _Pragma("unroll") for (int k = 0; k < 2; ++k) dst[n][k] = *(const LAS bf16x8*)(lds + PG8_SB(b, h) + boff + n * 2048 + k * 1024); } while (0)
; #define PG8_MMA(ai, bj, At, Bt) do { __builtin_amdgcn_s_setprio(1); _Pragma("unroll") for (int m = 0; m < 4; ++m) _Pragma("unroll") for (int n = 0; n < 2; ++n) _Pragma("unroll") for (int k = 0; k < 2; ++k) \
;         acc[ai][bj][m][n] = __builtin_amdgcn_mfma_f32_16x16x32_bf16(Bt[n][k], At[m][k], acc[ai][bj][m][n], 0, 0, 0); __builtin_amdgcn_s_setprio(0); } while (0)
; #define PG8_WAIT_V(n) asm volatile("s_waitcnt vmcnt(" #n ")" ::: "memory")
; #define PG8_WAIT_L(n) asm volatile("s_waitcnt lgkmcnt(" #n ")" ::: "memory")
; #define PG8_BAR __builtin_amdgcn_s_barrier()
; #define PG8_SCHED __builtin_amdgcn_sched_barrier(0)
; template <class Epi>
; DEVINL void gemm_phase(LAS unsigned char* lds, const Gemm g, const Order& S, const Epi& E) {
;     ...
;             PG8_STAGE(PG8_SB(0, 1), b2 + hstepB, voffB);
;             PG8_WAIT_V(6); PG8_BAR; PG8_MMA(1, 1, At, B1); PG8_BAR;
;             PG8_LDB(B0, 1, 0); PG8_SCHED; PG8_LDA(At, 1, 0); PG8_STAGE(PG8_SA(0, 1), a2 + hstepA, voffA);
;             PG8_WAIT_L(8); PG8_BAR; PG8_WAIT_L(0); PG8_MMA(0, 0, At, B0); PG8_BAR; PG8_SCHED;
;             PG8_LDB(B1, 1, 1); PG8_STAGE(PG8_SB(1, 0), b3, voffB);
	s_add_u32 s70, s40, 0x40000
	s_addc_u32 s71, s41, 0
	s_add_i32 s69, s64, s48
	v_lshl_add_u64 v[128:129], s[70:71], 0, v[154:155]
	s_mov_b32 m0, s69
	s_nop 0
	global_load_lds_dwordx4 v[128:129], off
	v_lshl_add_u64 v[128:129], s[70:71], 0, v[158:159]
	s_add_i32 m0, s69, 0x2000
	s_nop 0
	global_load_lds_dwordx4 v[128:129], off
	s_waitcnt vmcnt(6)
	s_barrier
	v_mfma_f32_16x16x32_bf16 v[52:55], v[198:201], v[144:147], v[52:55]
	v_mfma_f32_16x16x32_bf16 v[52:55], v[202:205], v[148:151], v[52:55]
	v_mfma_f32_16x16x32_bf16 v[48:51], v[210:213], v[148:151], v[48:51]
	v_mfma_f32_16x16x32_bf16 v[48:51], v[206:209], v[144:147], v[48:51]
	v_mfma_f32_16x16x32_bf16 v[32:35], v[206:209], v[168:171], v[32:35]
	v_mfma_f32_16x16x32_bf16 v[32:35], v[210:213], v[172:175], v[32:35]
	v_mfma_f32_16x16x32_bf16 v[36:39], v[202:205], v[172:175], v[36:39]
	v_mfma_f32_16x16x32_bf16 v[36:39], v[198:201], v[168:171], v[36:39]
	v_mfma_f32_16x16x32_bf16 v[20:23], v[198:201], v[176:179], v[20:23]
	v_mfma_f32_16x16x32_bf16 v[20:23], v[202:205], v[186:189], v[20:23]
	v_mfma_f32_16x16x32_bf16 v[16:19], v[210:213], v[186:189], v[16:19]
	v_mfma_f32_16x16x32_bf16 v[16:19], v[206:209], v[176:179], v[16:19]
	v_mfma_f32_16x16x32_bf16 v[0:3], v[206:209], v[190:193], v[0:3]
	v_mfma_f32_16x16x32_bf16 v[0:3], v[210:213], v[194:197], v[0:3]
	v_mfma_f32_16x16x32_bf16 v[4:7], v[202:205], v[194:197], v[4:7]
	v_mfma_f32_16x16x32_bf16 v[4:7], v[198:201], v[190:193], v[4:7]
	s_add_i32 s69, 16, 0x18000
	v_add_u32_e32 v140, s69, v181
	s_barrier
	ds_read_b128 v[128:131], v140
	ds_read_b128 v[132:135], v140 offset:1024
	ds_read_b128 v[136:139], v140 offset:2048
	ds_read_b128 v[140:143], v140 offset:3072
	s_add_u32 s42, s42, 0x40000
	s_addc_u32 s43, s43, 0
	s_mov_b32 m0, s50
	v_lshl_add_u64 v[198:199], s[42:43], 0, v[152:153]
	ds_read_b128 v[144:147], v184 offset:32768
	ds_read_b128 v[148:151], v184 offset:33792
	ds_read_b128 v[168:171], v184 offset:34816
	ds_read_b128 v[172:175], v184 offset:35840
	ds_read_b128 v[176:179], v184 offset:36864
	ds_read_b128 v[186:189], v184 offset:37888
	ds_read_b128 v[190:193], v184 offset:38912
	ds_read_b128 v[194:197], v184 offset:39936
	global_load_lds_dwordx4 v[198:199], off
	v_lshl_add_u64 v[198:199], s[42:43], 0, v[156:157]
	s_mov_b32 m0, s51
	s_nop 0
	global_load_lds_dwordx4 v[198:199], off
	s_waitcnt lgkmcnt(8)
	s_barrier
	s_waitcnt lgkmcnt(0)
	s_waitcnt lgkmcnt(0)
	v_mfma_f32_16x16x32_bf16 v[116:119], v[128:131], v[144:147], v[116:119]
	v_mfma_f32_16x16x32_bf16 v[116:119], v[132:135], v[148:151], v[116:119]
	v_mfma_f32_16x16x32_bf16 v[124:127], v[140:143], v[148:151], v[124:127]
	v_mfma_f32_16x16x32_bf16 v[124:127], v[136:139], v[144:147], v[124:127]
	v_mfma_f32_16x16x32_bf16 v[104:107], v[136:139], v[168:171], v[104:107]
	v_mfma_f32_16x16x32_bf16 v[104:107], v[140:143], v[172:175], v[104:107]
	v_mfma_f32_16x16x32_bf16 v[108:111], v[132:135], v[172:175], v[108:111]
	v_mfma_f32_16x16x32_bf16 v[108:111], v[128:131], v[168:171], v[108:111]
	v_mfma_f32_16x16x32_bf16 v[92:95], v[128:131], v[176:179], v[92:95]
	v_mfma_f32_16x16x32_bf16 v[92:95], v[132:135], v[186:189], v[92:95]
	v_mfma_f32_16x16x32_bf16 v[88:91], v[140:143], v[186:189], v[88:91]
	v_mfma_f32_16x16x32_bf16 v[88:91], v[136:139], v[176:179], v[88:91]
	v_mfma_f32_16x16x32_bf16 v[72:75], v[136:139], v[190:193], v[72:75]
	v_mfma_f32_16x16x32_bf16 v[72:75], v[140:143], v[194:197], v[72:75]
	v_mfma_f32_16x16x32_bf16 v[76:79], v[132:135], v[194:197], v[76:79]
	v_mfma_f32_16x16x32_bf16 v[76:79], v[128:131], v[190:193], v[76:79]
	s_barrier
	s_add_i32 s42, 16, 0x1c000
	s_add_i32 s43, s69, s48
	v_add_u32_e32 v210, s42, v181
	v_lshl_add_u64 v[218:219], v[218:219], 0, s[10:11]
	s_mov_b32 m0, s43
	ds_read_b128 v[198:201], v210
	ds_read_b128 v[202:205], v210 offset:1024
	ds_read_b128 v[206:209], v210 offset:2048
	ds_read_b128 v[210:213], v210 offset:3072
	global_load_lds_dwordx4 v[218:219], off
	v_lshl_add_u64 v[218:219], v[220:221], 0, s[10:11]
	s_add_i32 m0, s43, 0x2000
	s_nop 0
	global_load_lds_dwordx4 v[218:219], off
	s_barrier
; #define PG8_STAGE(bufoff, gbase, voff) do { _Pragma("unroll") for (int _i = 0; _i < 2; ++_i) \
;         __builtin_amdgcn_global_load_lds((const unsigned*)((const char*)(gbase) + (voff)[_i]), (LAS unsigned*)(lds + (bufoff) + ldsw + _i * 8192), 16, 0, 0); } while (0)
; #define PG8_LDA(dst, b, h) do { _Pragma("unroll") for (int m = 0; m < 4; ++m) _Pragma("unroll") for (int k = 0; k < 2; ++k) dst[m][k] = *(const LAS bf16x8*)(lds + PG8_SA(b, h) + aoff + m * 2048 + k * 1024); } while (0)
; #define PG8_MMA(ai, bj, At, Bt) do { __builtin_amdgcn_s_setprio(1); _Pragma("unroll") for (int m = 0; m < 4; ++m) _Pragma("unroll") for (int n = 0; n < 2; ++n) _Pragma("unroll") for (int k = 0; k < 2; ++k) \
;         acc[ai][bj][m][n] = __builtin_amdgcn_mfma_f32_16x16x32_bf16(Bt[n][k], At[m][k], acc[ai][bj][m][n], 0, 0, 0); __builtin_amdgcn_s_setprio(0); } while (0)
; #define PG8_WAIT_V(n) asm volatile("s_waitcnt vmcnt(" #n ")" ::: "memory")
; #define PG8_WAIT_L(n) asm volatile("s_waitcnt lgkmcnt(" #n ")" ::: "memory")
; #define PG8_BAR __builtin_amdgcn_s_barrier()
; #define PG8_SCHED __builtin_amdgcn_sched_barrier(0)
; template <class Epi>
; DEVINL void gemm_phase(LAS unsigned char* lds, const Gemm g, const Order& S, const Epi& E) {
;     ...
;             PG8_BAR; PG8_WAIT_L(0); PG8_MMA(0, 1, At, B1); PG8_BAR;
;             PG8_LDA(At, 1, 1); PG8_STAGE(PG8_SA(1, 0), a3, voffA);
;             PG8_BAR; PG8_WAIT_L(0); PG8_MMA(1, 0, At, B0); PG8_BAR; PG8_SCHED;
;             PG8_STAGE(PG8_SB(1, 1), b3 + hstepB, voffB);
;             PG8_WAIT_V(6); PG8_BAR; PG8_MMA(1, 1, At, B1); PG8_BAR;
	s_waitcnt lgkmcnt(0)
	s_waitcnt lgkmcnt(0)
	v_mfma_f32_16x16x32_bf16 v[120:123], v[198:201], v[144:147], v[120:123]
	v_mfma_f32_16x16x32_bf16 v[120:123], v[202:205], v[148:151], v[120:123]
	v_mfma_f32_16x16x32_bf16 v[112:115], v[210:213], v[148:151], v[112:115]
	v_mfma_f32_16x16x32_bf16 v[112:115], v[206:209], v[144:147], v[112:115]
	v_mfma_f32_16x16x32_bf16 v[96:99], v[206:209], v[168:171], v[96:99]
	v_mfma_f32_16x16x32_bf16 v[96:99], v[210:213], v[172:175], v[96:99]
	v_mfma_f32_16x16x32_bf16 v[100:103], v[202:205], v[172:175], v[100:103]
	v_mfma_f32_16x16x32_bf16 v[100:103], v[198:201], v[168:171], v[100:103]
	v_mfma_f32_16x16x32_bf16 v[84:87], v[198:201], v[176:179], v[84:87]
	v_mfma_f32_16x16x32_bf16 v[84:87], v[202:205], v[186:189], v[84:87]
	v_mfma_f32_16x16x32_bf16 v[80:83], v[210:213], v[186:189], v[80:83]
	v_mfma_f32_16x16x32_bf16 v[80:83], v[206:209], v[176:179], v[80:83]
	v_mfma_f32_16x16x32_bf16 v[64:67], v[206:209], v[190:193], v[64:67]
	v_mfma_f32_16x16x32_bf16 v[64:67], v[210:213], v[194:197], v[64:67]
	v_mfma_f32_16x16x32_bf16 v[68:71], v[202:205], v[194:197], v[68:71]
	v_mfma_f32_16x16x32_bf16 v[68:71], v[198:201], v[190:193], v[68:71]
	s_mov_b32 m0, s53
	v_lshl_add_u64 v[218:219], v[222:223], 0, s[10:11]
	s_barrier
	ds_read_b128 v[144:147], v184 offset:49152
	ds_read_b128 v[148:151], v184 offset:50176
	ds_read_b128 v[168:171], v184 offset:51200
	ds_read_b128 v[172:175], v184 offset:52224
	ds_read_b128 v[176:179], v184 offset:53248
	ds_read_b128 v[186:189], v184 offset:54272
	ds_read_b128 v[190:193], v184 offset:55296
	ds_read_b128 v[194:197], v184 offset:56320
	global_load_lds_dwordx4 v[218:219], off
	v_lshl_add_u64 v[218:219], v[224:225], 0, s[10:11]
	s_mov_b32 m0, s54
	s_nop 0
	global_load_lds_dwordx4 v[218:219], off
	s_barrier
	s_waitcnt lgkmcnt(0)
	s_waitcnt lgkmcnt(0)
	v_mfma_f32_16x16x32_bf16 v[60:63], v[128:131], v[144:147], v[60:63]
	v_mfma_f32_16x16x32_bf16 v[60:63], v[132:135], v[148:151], v[60:63]
	v_mfma_f32_16x16x32_bf16 v[56:59], v[140:143], v[148:151], v[56:59]
	v_mfma_f32_16x16x32_bf16 v[56:59], v[136:139], v[144:147], v[56:59]
	v_mfma_f32_16x16x32_bf16 v[40:43], v[136:139], v[168:171], v[40:43]
	v_mfma_f32_16x16x32_bf16 v[40:43], v[140:143], v[172:175], v[40:43]
	v_mfma_f32_16x16x32_bf16 v[44:47], v[132:135], v[172:175], v[44:47]
	v_mfma_f32_16x16x32_bf16 v[44:47], v[128:131], v[168:171], v[44:47]
	v_mfma_f32_16x16x32_bf16 v[28:31], v[128:131], v[176:179], v[28:31]
	v_mfma_f32_16x16x32_bf16 v[28:31], v[132:135], v[186:189], v[28:31]
	v_mfma_f32_16x16x32_bf16 v[24:27], v[140:143], v[186:189], v[24:27]
	v_mfma_f32_16x16x32_bf16 v[24:27], v[136:139], v[176:179], v[24:27]
	v_mfma_f32_16x16x32_bf16 v[8:11], v[136:139], v[190:193], v[8:11]
	v_mfma_f32_16x16x32_bf16 v[8:11], v[140:143], v[194:197], v[8:11]
	v_mfma_f32_16x16x32_bf16 v[12:15], v[132:135], v[194:197], v[12:15]
	v_mfma_f32_16x16x32_bf16 v[12:15], v[128:131], v[190:193], v[12:15]
	s_barrier
	s_add_u32 s40, s40, 0x40080
	s_addc_u32 s41, s41, 0
	s_add_i32 s42, s42, s48
	v_lshl_add_u64 v[128:129], s[40:41], 0, v[154:155]
	s_mov_b32 m0, s42
	s_nop 0
	global_load_lds_dwordx4 v[128:129], off
	v_lshl_add_u64 v[128:129], s[40:41], 0, v[158:159]
	s_add_i32 m0, s42, 0x2000
	s_nop 0
	global_load_lds_dwordx4 v[128:129], off
	s_waitcnt vmcnt(6)
	s_barrier
	v_mfma_f32_16x16x32_bf16 v[52:55], v[198:201], v[144:147], v[52:55]
	v_mfma_f32_16x16x32_bf16 v[52:55], v[202:205], v[148:151], v[52:55]
	v_mfma_f32_16x16x32_bf16 v[48:51], v[210:213], v[148:151], v[48:51]
	v_mfma_f32_16x16x32_bf16 v[48:51], v[206:209], v[144:147], v[48:51]
	v_mfma_f32_16x16x32_bf16 v[32:35], v[206:209], v[168:171], v[32:35]
	v_mfma_f32_16x16x32_bf16 v[32:35], v[210:213], v[172:175], v[32:35]
	v_mfma_f32_16x16x32_bf16 v[36:39], v[202:205], v[172:175], v[36:39]
	v_mfma_f32_16x16x32_bf16 v[36:39], v[198:201], v[168:171], v[36:39]
	v_mfma_f32_16x16x32_bf16 v[20:23], v[198:201], v[176:179], v[20:23]
	v_mfma_f32_16x16x32_bf16 v[20:23], v[202:205], v[186:189], v[20:23]
	v_mfma_f32_16x16x32_bf16 v[16:19], v[210:213], v[186:189], v[16:19]
	v_mfma_f32_16x16x32_bf16 v[16:19], v[206:209], v[176:179], v[16:19]
	v_mfma_f32_16x16x32_bf16 v[0:3], v[206:209], v[190:193], v[0:3]
	v_mfma_f32_16x16x32_bf16 v[0:3], v[210:213], v[194:197], v[0:3]
	v_mfma_f32_16x16x32_bf16 v[4:7], v[202:205], v[194:197], v[4:7]
	v_mfma_f32_16x16x32_bf16 v[4:7], v[198:201], v[190:193], v[4:7]
	s_add_u32 s8, s8, 0x100
	s_addc_u32 s9, s9, 0
	s_add_u32 s66, s66, 0x100
	s_addc_u32 s67, s67, 0
	s_cmp_ge_i32 s68, s52
	s_mov_b32 s40, s68
	s_barrier
	s_cbranch_scc0 .LBB0_1259
	s_branch .LBB0_1250

; #define PG8_STAGE(bufoff, gbase, voff) do { _Pragma("unroll") for (int _i = 0; _i < 2; ++_i) \
;         __builtin_amdgcn_global_load_lds((const unsigned*)((const char*)(gbase) + (voff)[_i]), (LAS unsigned*)(lds + (bufoff) + ldsw + _i * 8192), 16, 0, 0); } while (0)
; #define PG8_LDA(dst, b, h) do { _Pragma("unroll") for (int m = 0; m < 4; ++m) _Pragma("unroll") for (int k = 0; k < 2; ++k) dst[m][k] = *(const LAS bf16x8*)(lds + PG8_SA(b, h) + aoff + m * 2048 + k * 1024); } while (0)
; #define PG8_LDB(dst, b, h) do { _Pragma("unroll") for (int n = 0; n < 2; ++n) _Pragma("unroll") for (int k = 0; k < 2; ++k) dst[n][k] = *(const LAS bf16x8*)(lds + PG8_SB(b, h) + boff + n * 2048 + k * 1024); } while (0)
; #define PG8_MMA(ai, bj, At, Bt) do { __builtin_amdgcn_s_setprio(1); _Pragma("unroll") for (int m = 0; m < 4; ++m) _Pragma("unroll") for (int n = 0; n < 2; ++n) _Pragma("unroll") for (int k = 0; k < 2; ++k) \
;         acc[ai][bj][m][n] = __builtin_amdgcn_mfma_f32_16x16x32_bf16(Bt[n][k], At[m][k], acc[ai][bj][m][n], 0, 0, 0); __builtin_amdgcn_s_setprio(0); } while (0)
; #define PG8_WAIT_L(n) asm volatile("s_waitcnt lgkmcnt(" #n ")" ::: "memory")
; #define PG8_BAR __builtin_amdgcn_s_barrier()
; #define PG8_SCHED __builtin_amdgcn_sched_barrier(0)
; template <class Epi>
; DEVINL void gemm_phase(LAS unsigned char* lds, const Gemm g, const Order& S, const Epi& E) {
;     ...
;         const char* nA = has_next ? (const char*)g.A + (size_t)nxt.pm * tstepA : cA; const char* nB = has_next ? (const char*)g.Bt + (size_t)nxt.pn * tstepB : cB;
;         for (int t = 0; t < nt; t += 2) {
;             const bool last = (t == nt - 2);
;             const char* a1 = cA + (size_t)(t + 1) * kstep;
;             const char* a2 = last ? nA : cA + (size_t)(t + 2) * kstep; const char* b2 = last ? nB : cB + (size_t)(t + 2) * kstep;
;             const char* a3 = a2 + kstep; const char* b3 = b2 + kstep;
;             PG8_LDB(B0, 0, 0); PG8_SCHED; PG8_LDA(At, 0, 0); PG8_STAGE(PG8_SA(1, 1), a1 + hstepA, voffA);
;             PG8_WAIT_L(8); PG8_BAR; PG8_WAIT_L(0); PG8_MMA(0, 0, At, B0); PG8_BAR; PG8_SCHED;
;             PG8_LDB(B1, 0, 1); PG8_STAGE(PG8_SB(0, 0), b2, voffB);
;             PG8_BAR; PG8_WAIT_L(0); PG8_MMA(0, 1, At, B1); PG8_BAR;
;             PG8_LDA(At, 0, 1); PG8_STAGE(PG8_SA(0, 0), a2, voffA);
;             PG8_BAR; PG8_WAIT_L(0); PG8_MMA(1, 0, At, B0); PG8_BAR; PG8_SCHED;
.LBB0_1332:
	ds_read_b128 v[150:153], v147
	ds_read_b128 v[154:157], v147 offset:1024
	ds_read_b128 v[158:161], v147 offset:2048
	ds_read_b128 v[162:165], v147 offset:3072
	s_add_i32 s71, s40, 2
	s_add_u32 s41, s8, 0xfff80080
	s_addc_u32 s42, s9, -1
	s_cmp_eq_u32 s55, s40
	s_cselect_b32 s40, s29, s69
	s_cselect_b32 s43, s2, s42
	s_cselect_b32 s42, s3, s41
	s_cselect_b32 s41, s27, s70
	v_lshl_add_u64 v[198:199], s[8:9], 0, v[136:137]
	s_add_i32 m0, s25, 0xc000
	ds_read_b128 v[166:169], v148
	ds_read_b128 v[170:173], v148 offset:1024
	ds_read_b128 v[174:177], v148 offset:2048
	ds_read_b128 v[178:181], v148 offset:3072
	ds_read_b128 v[182:185], v148 offset:4096
	ds_read_b128 v[186:189], v148 offset:5120
	ds_read_b128 v[190:193], v148 offset:6144
	ds_read_b128 v[194:197], v148 offset:7168
	global_load_lds_dwordx4 v[198:199], off
	v_lshl_add_u64 v[198:199], s[8:9], 0, v[138:139]
	s_add_i32 m0, s25, 0xe000
	s_nop 0
	global_load_lds_dwordx4 v[198:199], off
	s_waitcnt lgkmcnt(8)
	s_barrier
	s_waitcnt lgkmcnt(0)
	s_waitcnt lgkmcnt(0)
	v_mfma_f32_16x16x32_bf16 v[120:123], v[150:153], v[166:169], v[120:123]
	v_mfma_f32_16x16x32_bf16 v[120:123], v[154:157], v[170:173], v[120:123]
	v_mfma_f32_16x16x32_bf16 v[124:127], v[162:165], v[170:173], v[124:127]
	v_mfma_f32_16x16x32_bf16 v[124:127], v[158:161], v[166:169], v[124:127]
	v_mfma_f32_16x16x32_bf16 v[104:107], v[158:161], v[174:177], v[104:107]
	v_mfma_f32_16x16x32_bf16 v[104:107], v[162:165], v[178:181], v[104:107]
	v_mfma_f32_16x16x32_bf16 v[108:111], v[154:157], v[178:181], v[108:111]
	v_mfma_f32_16x16x32_bf16 v[108:111], v[150:153], v[174:177], v[108:111]
	v_mfma_f32_16x16x32_bf16 v[92:95], v[150:153], v[182:185], v[92:95]
	v_mfma_f32_16x16x32_bf16 v[92:95], v[154:157], v[186:189], v[92:95]
	v_mfma_f32_16x16x32_bf16 v[88:91], v[162:165], v[186:189], v[88:91]
	v_mfma_f32_16x16x32_bf16 v[88:91], v[158:161], v[182:185], v[88:91]
	v_mfma_f32_16x16x32_bf16 v[72:75], v[158:161], v[190:193], v[72:75]
	v_mfma_f32_16x16x32_bf16 v[72:75], v[162:165], v[194:197], v[72:75]
	v_mfma_f32_16x16x32_bf16 v[76:79], v[154:157], v[194:197], v[76:79]
	v_mfma_f32_16x16x32_bf16 v[76:79], v[150:153], v[190:193], v[76:79]
	s_barrier
	s_add_i32 s72, s59, s48
	v_lshl_add_u64 v[218:219], s[40:41], 0, v[130:131]
	s_mov_b32 m0, s72
	ds_read_b128 v[198:201], v149
	ds_read_b128 v[202:205], v149 offset:1024
	ds_read_b128 v[206:209], v149 offset:2048
	ds_read_b128 v[210:213], v149 offset:3072
	global_load_lds_dwordx4 v[218:219], off
	v_lshl_add_u64 v[220:221], s[40:41], 0, v[134:135]
	s_add_i32 m0, s72, 0x2000
	s_nop 0
	global_load_lds_dwordx4 v[220:221], off
	s_barrier
	s_waitcnt lgkmcnt(0)
	s_waitcnt lgkmcnt(0)
	v_mfma_f32_16x16x32_bf16 v[116:119], v[198:201], v[166:169], v[116:119]
	v_mfma_f32_16x16x32_bf16 v[116:119], v[202:205], v[170:173], v[116:119]
	v_mfma_f32_16x16x32_bf16 v[112:115], v[210:213], v[170:173], v[112:115]
	v_mfma_f32_16x16x32_bf16 v[112:115], v[206:209], v[166:169], v[112:115]
	v_mfma_f32_16x16x32_bf16 v[96:99], v[206:209], v[174:177], v[96:99]
	v_mfma_f32_16x16x32_bf16 v[96:99], v[210:213], v[178:181], v[96:99]
	v_mfma_f32_16x16x32_bf16 v[100:103], v[202:205], v[178:181], v[100:103]
	v_mfma_f32_16x16x32_bf16 v[100:103], v[198:201], v[174:177], v[100:103]
	v_mfma_f32_16x16x32_bf16 v[84:87], v[198:201], v[182:185], v[84:87]
	v_mfma_f32_16x16x32_bf16 v[84:87], v[202:205], v[186:189], v[84:87]
	v_mfma_f32_16x16x32_bf16 v[80:83], v[210:213], v[186:189], v[80:83]
	v_mfma_f32_16x16x32_bf16 v[80:83], v[206:209], v[182:185], v[80:83]
	v_mfma_f32_16x16x32_bf16 v[64:67], v[206:209], v[190:193], v[64:67]
	v_mfma_f32_16x16x32_bf16 v[64:67], v[210:213], v[194:197], v[64:67]
	v_mfma_f32_16x16x32_bf16 v[68:71], v[202:205], v[194:197], v[68:71]
	v_mfma_f32_16x16x32_bf16 v[68:71], v[198:201], v[190:193], v[68:71]
	s_mov_b32 m0, s25
	v_lshl_add_u64 v[222:223], s[42:43], 0, v[128:129]
	s_barrier
	ds_read_b128 v[166:169], v148 offset:16384
	ds_read_b128 v[170:173], v148 offset:17408
	ds_read_b128 v[174:177], v148 offset:18432
	ds_read_b128 v[178:181], v148 offset:19456
	ds_read_b128 v[182:185], v148 offset:20480
	ds_read_b128 v[186:189], v148 offset:21504
	ds_read_b128 v[190:193], v148 offset:22528
	ds_read_b128 v[194:197], v148 offset:23552
	global_load_lds_dwordx4 v[222:223], off
	v_lshl_add_u64 v[224:225], s[42:43], 0, v[132:133]
	s_mov_b32 m0, s49
	s_nop 0
	global_load_lds_dwordx4 v[224:225], off
	s_barrier
	s_waitcnt lgkmcnt(0)
	s_waitcnt lgkmcnt(0)
	v_mfma_f32_16x16x32_bf16 v[60:63], v[150:153], v[166:169], v[60:63]
	v_mfma_f32_16x16x32_bf16 v[60:63], v[154:157], v[170:173], v[60:63]
	v_mfma_f32_16x16x32_bf16 v[56:59], v[162:165], v[170:173], v[56:59]
	v_mfma_f32_16x16x32_bf16 v[56:59], v[158:161], v[166:169], v[56:59]
	v_mfma_f32_16x16x32_bf16 v[40:43], v[158:161], v[174:177], v[40:43]
	v_mfma_f32_16x16x32_bf16 v[40:43], v[162:165], v[178:181], v[40:43]
	v_mfma_f32_16x16x32_bf16 v[44:47], v[154:157], v[178:181], v[44:47]
	v_mfma_f32_16x16x32_bf16 v[44:47], v[150:153], v[174:177], v[44:47]
	v_mfma_f32_16x16x32_bf16 v[28:31], v[150:153], v[182:185], v[28:31]
	v_mfma_f32_16x16x32_bf16 v[28:31], v[154:157], v[186:189], v[28:31]
	v_mfma_f32_16x16x32_bf16 v[24:27], v[162:165], v[186:189], v[24:27]
	v_mfma_f32_16x16x32_bf16 v[24:27], v[158:161], v[182:185], v[24:27]
	v_mfma_f32_16x16x32_bf16 v[8:11], v[158:161], v[190:193], v[8:11]
	v_mfma_f32_16x16x32_bf16 v[8:11], v[162:165], v[194:197], v[8:11]
	v_mfma_f32_16x16x32_bf16 v[12:15], v[154:157], v[194:197], v[12:15]
	v_mfma_f32_16x16x32_bf16 v[12:15], v[150:153], v[190:193], v[12:15]
	s_barrier
; #define PG8_STAGE(bufoff, gbase, voff) do { _Pragma("unroll") for (int _i = 0; _i < 2; ++_i) \
;         __builtin_amdgcn_global_load_lds((const unsigned*)((const char*)(gbase) + (voff)[_i]), (LAS unsigned*)(lds + (bufoff) + ldsw + _i * 8192), 16, 0, 0); } while (0)
; #define PG8_LDA(dst, b, h) do { _Pragma("unroll") for (int m = 0; m < 4; ++m) _Pragma("unroll") for (int k = 0; k < 2; ++k) dst[m][k] = *(const LAS bf16x8*)(lds + PG8_SA(b, h) + aoff + m * 2048 + k * 1024); } while (0)
; #define PG8_LDB(dst, b, h) do { _Pragma("unroll") for (int n = 0; n < 2; ++n) _Pragma("unroll") for (int k = 0; k < 2; ++k) dst[n][k] = *(const LAS bf16x8*)(lds + PG8_SB(b, h) + boff + n * 2048 + k * 1024); } while (0)
; #define PG8_MMA(ai, bj, At, Bt) do { __builtin_amdgcn_s_setprio(1); _Pragma("unroll") for (int m = 0; m < 4; ++m) _Pragma("unroll") for (int n = 0; n < 2; ++n) _Pragma("unroll") for (int k = 0; k < 2; ++k) \
;         acc[ai][bj][m][n] = __builtin_amdgcn_mfma_f32_16x16x32_bf16(Bt[n][k], At[m][k], acc[ai][bj][m][n], 0, 0, 0); __builtin_amdgcn_s_setprio(0); } while (0)
; #define PG8_WAIT_V(n) asm volatile("s_waitcnt vmcnt(" #n ")" ::: "memory")
; #define PG8_WAIT_L(n) asm volatile("s_waitcnt lgkmcnt(" #n ")" ::: "memory")
; #define PG8_BAR __builtin_amdgcn_s_barrier()
; #define PG8_SCHED __builtin_amdgcn_sched_barrier(0)
; template <class Epi>
; DEVINL void gemm_phase(LAS unsigned char* lds, const Gemm g, const Order& S, const Epi& E) {
;     ...
;             PG8_STAGE(PG8_SB(0, 1), b2 + hstepB, voffB);
;             PG8_WAIT_V(6); PG8_BAR; PG8_MMA(1, 1, At, B1); PG8_BAR;
;             PG8_LDB(B0, 1, 0); PG8_SCHED; PG8_LDA(At, 1, 0); PG8_STAGE(PG8_SA(0, 1), a2 + hstepA, voffA);
;             PG8_WAIT_L(8); PG8_BAR; PG8_WAIT_L(0); PG8_MMA(0, 0, At, B0); PG8_BAR; PG8_SCHED;
;             PG8_LDB(B1, 1, 1); PG8_STAGE(PG8_SB(1, 0), b3, voffB);
	s_add_u32 s72, s40, 0x80000
	s_addc_u32 s73, s41, 0
	s_add_i32 s74, s64, s48
	v_lshl_add_u64 v[150:151], s[72:73], 0, v[130:131]
	s_mov_b32 m0, s74
	s_nop 0
	global_load_lds_dwordx4 v[150:151], off
	v_lshl_add_u64 v[150:151], s[72:73], 0, v[134:135]
	s_add_i32 m0, s74, 0x2000
	s_nop 0
	global_load_lds_dwordx4 v[150:151], off
	s_waitcnt vmcnt(6)
	s_barrier
	v_mfma_f32_16x16x32_bf16 v[52:55], v[198:201], v[166:169], v[52:55]
	v_mfma_f32_16x16x32_bf16 v[52:55], v[202:205], v[170:173], v[52:55]
	v_mfma_f32_16x16x32_bf16 v[48:51], v[210:213], v[170:173], v[48:51]
	v_mfma_f32_16x16x32_bf16 v[48:51], v[206:209], v[166:169], v[48:51]
	v_mfma_f32_16x16x32_bf16 v[32:35], v[206:209], v[174:177], v[32:35]
	v_mfma_f32_16x16x32_bf16 v[32:35], v[210:213], v[178:181], v[32:35]
	v_mfma_f32_16x16x32_bf16 v[36:39], v[202:205], v[178:181], v[36:39]
	v_mfma_f32_16x16x32_bf16 v[36:39], v[198:201], v[174:177], v[36:39]
	v_mfma_f32_16x16x32_bf16 v[20:23], v[198:201], v[182:185], v[20:23]
	v_mfma_f32_16x16x32_bf16 v[20:23], v[202:205], v[186:189], v[20:23]
	v_mfma_f32_16x16x32_bf16 v[16:19], v[210:213], v[186:189], v[16:19]
	v_mfma_f32_16x16x32_bf16 v[16:19], v[206:209], v[182:185], v[16:19]
	v_mfma_f32_16x16x32_bf16 v[0:3], v[206:209], v[190:193], v[0:3]
	v_mfma_f32_16x16x32_bf16 v[0:3], v[210:213], v[194:197], v[0:3]
	v_mfma_f32_16x16x32_bf16 v[4:7], v[202:205], v[194:197], v[4:7]
	v_mfma_f32_16x16x32_bf16 v[4:7], v[198:201], v[190:193], v[4:7]
	s_add_i32 s72, 16, 0x18000
	v_add_u32_e32 v162, s72, v145
	s_barrier
	ds_read_b128 v[150:153], v162
	ds_read_b128 v[154:157], v162 offset:1024
	ds_read_b128 v[158:161], v162 offset:2048
	ds_read_b128 v[162:165], v162 offset:3072
	s_add_u32 s42, s42, 0x80000
	s_addc_u32 s43, s43, 0
	s_mov_b32 m0, s50
	v_lshl_add_u64 v[198:199], s[42:43], 0, v[128:129]
	ds_read_b128 v[166:169], v148 offset:32768
	ds_read_b128 v[170:173], v148 offset:33792
	ds_read_b128 v[174:177], v148 offset:34816
	ds_read_b128 v[178:181], v148 offset:35840
	ds_read_b128 v[182:185], v148 offset:36864
	ds_read_b128 v[186:189], v148 offset:37888
	ds_read_b128 v[190:193], v148 offset:38912
	ds_read_b128 v[194:197], v148 offset:39936
	global_load_lds_dwordx4 v[198:199], off
	v_lshl_add_u64 v[198:199], s[42:43], 0, v[132:133]
	s_mov_b32 m0, s51
	s_nop 0
	global_load_lds_dwordx4 v[198:199], off
	s_waitcnt lgkmcnt(8)
	s_barrier
	s_waitcnt lgkmcnt(0)
	s_waitcnt lgkmcnt(0)
	v_mfma_f32_16x16x32_bf16 v[120:123], v[150:153], v[166:169], v[120:123]
	v_mfma_f32_16x16x32_bf16 v[120:123], v[154:157], v[170:173], v[120:123]
	v_mfma_f32_16x16x32_bf16 v[124:127], v[162:165], v[170:173], v[124:127]
	v_mfma_f32_16x16x32_bf16 v[124:127], v[158:161], v[166:169], v[124:127]
	v_mfma_f32_16x16x32_bf16 v[104:107], v[158:161], v[174:177], v[104:107]
	v_mfma_f32_16x16x32_bf16 v[104:107], v[162:165], v[178:181], v[104:107]
	v_mfma_f32_16x16x32_bf16 v[108:111], v[154:157], v[178:181], v[108:111]
	v_mfma_f32_16x16x32_bf16 v[108:111], v[150:153], v[174:177], v[108:111]
	v_mfma_f32_16x16x32_bf16 v[92:95], v[150:153], v[182:185], v[92:95]
	v_mfma_f32_16x16x32_bf16 v[92:95], v[154:157], v[186:189], v[92:95]
	v_mfma_f32_16x16x32_bf16 v[88:91], v[162:165], v[186:189], v[88:91]
	v_mfma_f32_16x16x32_bf16 v[88:91], v[158:161], v[182:185], v[88:91]
	v_mfma_f32_16x16x32_bf16 v[72:75], v[158:161], v[190:193], v[72:75]
	v_mfma_f32_16x16x32_bf16 v[72:75], v[162:165], v[194:197], v[72:75]
	v_mfma_f32_16x16x32_bf16 v[76:79], v[154:157], v[194:197], v[76:79]
	v_mfma_f32_16x16x32_bf16 v[76:79], v[150:153], v[190:193], v[76:79]
	s_barrier
	s_add_i32 s42, 16, 0x1c000
	s_add_i32 s43, s72, s48
	v_add_u32_e32 v210, s42, v145
	v_lshl_add_u64 v[218:219], v[218:219], 0, s[6:7]
	s_mov_b32 m0, s43
	ds_read_b128 v[198:201], v210
	ds_read_b128 v[202:205], v210 offset:1024
	ds_read_b128 v[206:209], v210 offset:2048
	ds_read_b128 v[210:213], v210 offset:3072
	global_load_lds_dwordx4 v[218:219], off
	v_lshl_add_u64 v[218:219], v[220:221], 0, s[6:7]
	s_add_i32 m0, s43, 0x2000
	s_nop 0
	global_load_lds_dwordx4 v[218:219], off
	s_barrier
; #define PG8_STAGE(bufoff, gbase, voff) do { _Pragma("unroll") for (int _i = 0; _i < 2; ++_i) \
;         __builtin_amdgcn_global_load_lds((const unsigned*)((const char*)(gbase) + (voff)[_i]), (LAS unsigned*)(lds + (bufoff) + ldsw + _i * 8192), 16, 0, 0); } while (0)
; #define PG8_LDA(dst, b, h) do { _Pragma("unroll") for (int m = 0; m < 4; ++m) _Pragma("unroll") for (int k = 0; k < 2; ++k) dst[m][k] = *(const LAS bf16x8*)(lds + PG8_SA(b, h) + aoff + m * 2048 + k * 1024); } while (0)
; #define PG8_MMA(ai, bj, At, Bt) do { __builtin_amdgcn_s_setprio(1); _Pragma("unroll") for (int m = 0; m < 4; ++m) _Pragma("unroll") for (int n = 0; n < 2; ++n) _Pragma("unroll") for (int k = 0; k < 2; ++k) \
;         acc[ai][bj][m][n] = __builtin_amdgcn_mfma_f32_16x16x32_bf16(Bt[n][k], At[m][k], acc[ai][bj][m][n], 0, 0, 0); __builtin_amdgcn_s_setprio(0); } while (0)
; #define PG8_WAIT_V(n) asm volatile("s_waitcnt vmcnt(" #n ")" ::: "memory")
; #define PG8_WAIT_L(n) asm volatile("s_waitcnt lgkmcnt(" #n ")" ::: "memory")
; #define PG8_BAR __builtin_amdgcn_s_barrier()
; #define PG8_SCHED __builtin_amdgcn_sched_barrier(0)
; template <class Epi>
; DEVINL void gemm_phase(LAS unsigned char* lds, const Gemm g, const Order& S, const Epi& E) {
;     ...
;             PG8_BAR; PG8_WAIT_L(0); PG8_MMA(0, 1, At, B1); PG8_BAR;
;             PG8_LDA(At, 1, 1); PG8_STAGE(PG8_SA(1, 0), a3, voffA);
;             PG8_BAR; PG8_WAIT_L(0); PG8_MMA(1, 0, At, B0); PG8_BAR; PG8_SCHED;
;             PG8_STAGE(PG8_SB(1, 1), b3 + hstepB, voffB);
;             PG8_WAIT_V(6); PG8_BAR; PG8_MMA(1, 1, At, B1); PG8_BAR;
	s_waitcnt lgkmcnt(0)
	s_waitcnt lgkmcnt(0)
	v_mfma_f32_16x16x32_bf16 v[116:119], v[198:201], v[166:169], v[116:119]
	v_mfma_f32_16x16x32_bf16 v[116:119], v[202:205], v[170:173], v[116:119]
	v_mfma_f32_16x16x32_bf16 v[112:115], v[210:213], v[170:173], v[112:115]
	v_mfma_f32_16x16x32_bf16 v[112:115], v[206:209], v[166:169], v[112:115]
	v_mfma_f32_16x16x32_bf16 v[96:99], v[206:209], v[174:177], v[96:99]
	v_mfma_f32_16x16x32_bf16 v[96:99], v[210:213], v[178:181], v[96:99]
	v_mfma_f32_16x16x32_bf16 v[100:103], v[202:205], v[178:181], v[100:103]
	v_mfma_f32_16x16x32_bf16 v[100:103], v[198:201], v[174:177], v[100:103]
	v_mfma_f32_16x16x32_bf16 v[84:87], v[198:201], v[182:185], v[84:87]
	v_mfma_f32_16x16x32_bf16 v[84:87], v[202:205], v[186:189], v[84:87]
	v_mfma_f32_16x16x32_bf16 v[80:83], v[210:213], v[186:189], v[80:83]
	v_mfma_f32_16x16x32_bf16 v[80:83], v[206:209], v[182:185], v[80:83]
	v_mfma_f32_16x16x32_bf16 v[64:67], v[206:209], v[190:193], v[64:67]
	v_mfma_f32_16x16x32_bf16 v[64:67], v[210:213], v[194:197], v[64:67]
	v_mfma_f32_16x16x32_bf16 v[68:71], v[202:205], v[194:197], v[68:71]
	v_mfma_f32_16x16x32_bf16 v[68:71], v[198:201], v[190:193], v[68:71]
	s_mov_b32 m0, s53
	v_lshl_add_u64 v[218:219], v[222:223], 0, s[6:7]
	s_barrier
	ds_read_b128 v[166:169], v148 offset:49152
	ds_read_b128 v[170:173], v148 offset:50176
	ds_read_b128 v[174:177], v148 offset:51200
	ds_read_b128 v[178:181], v148 offset:52224
	ds_read_b128 v[182:185], v148 offset:53248
	ds_read_b128 v[186:189], v148 offset:54272
	ds_read_b128 v[190:193], v148 offset:55296
	ds_read_b128 v[194:197], v148 offset:56320
	global_load_lds_dwordx4 v[218:219], off
	v_lshl_add_u64 v[218:219], v[224:225], 0, s[6:7]
	s_mov_b32 m0, s54
	s_nop 0
	global_load_lds_dwordx4 v[218:219], off
	s_barrier
	s_waitcnt lgkmcnt(0)
	s_waitcnt lgkmcnt(0)
	v_mfma_f32_16x16x32_bf16 v[60:63], v[150:153], v[166:169], v[60:63]
	v_mfma_f32_16x16x32_bf16 v[60:63], v[154:157], v[170:173], v[60:63]
	v_mfma_f32_16x16x32_bf16 v[56:59], v[162:165], v[170:173], v[56:59]
	v_mfma_f32_16x16x32_bf16 v[56:59], v[158:161], v[166:169], v[56:59]
	v_mfma_f32_16x16x32_bf16 v[40:43], v[158:161], v[174:177], v[40:43]
	v_mfma_f32_16x16x32_bf16 v[40:43], v[162:165], v[178:181], v[40:43]
	v_mfma_f32_16x16x32_bf16 v[44:47], v[154:157], v[178:181], v[44:47]
	v_mfma_f32_16x16x32_bf16 v[44:47], v[150:153], v[174:177], v[44:47]
	v_mfma_f32_16x16x32_bf16 v[28:31], v[150:153], v[182:185], v[28:31]
	v_mfma_f32_16x16x32_bf16 v[28:31], v[154:157], v[186:189], v[28:31]
	v_mfma_f32_16x16x32_bf16 v[24:27], v[162:165], v[186:189], v[24:27]
	v_mfma_f32_16x16x32_bf16 v[24:27], v[158:161], v[182:185], v[24:27]
	v_mfma_f32_16x16x32_bf16 v[8:11], v[158:161], v[190:193], v[8:11]
	v_mfma_f32_16x16x32_bf16 v[8:11], v[162:165], v[194:197], v[8:11]
	v_mfma_f32_16x16x32_bf16 v[12:15], v[154:157], v[194:197], v[12:15]
	v_mfma_f32_16x16x32_bf16 v[12:15], v[150:153], v[190:193], v[12:15]
	s_barrier
	s_add_u32 s40, s40, 0x80080
	s_addc_u32 s41, s41, 0
	s_add_i32 s42, s42, s48
	v_lshl_add_u64 v[150:151], s[40:41], 0, v[130:131]
	s_mov_b32 m0, s42
	s_nop 0
	global_load_lds_dwordx4 v[150:151], off
	v_lshl_add_u64 v[150:151], s[40:41], 0, v[134:135]
	s_add_i32 m0, s42, 0x2000
	s_nop 0
	global_load_lds_dwordx4 v[150:151], off
	s_waitcnt vmcnt(6)
	s_barrier
	v_mfma_f32_16x16x32_bf16 v[52:55], v[198:201], v[166:169], v[52:55]
	v_mfma_f32_16x16x32_bf16 v[52:55], v[202:205], v[170:173], v[52:55]
	v_mfma_f32_16x16x32_bf16 v[48:51], v[210:213], v[170:173], v[48:51]
	v_mfma_f32_16x16x32_bf16 v[48:51], v[206:209], v[166:169], v[48:51]
	v_mfma_f32_16x16x32_bf16 v[32:35], v[206:209], v[174:177], v[32:35]
	v_mfma_f32_16x16x32_bf16 v[32:35], v[210:213], v[178:181], v[32:35]
	v_mfma_f32_16x16x32_bf16 v[36:39], v[202:205], v[178:181], v[36:39]
	v_mfma_f32_16x16x32_bf16 v[36:39], v[198:201], v[174:177], v[36:39]
	v_mfma_f32_16x16x32_bf16 v[20:23], v[198:201], v[182:185], v[20:23]
	v_mfma_f32_16x16x32_bf16 v[20:23], v[202:205], v[186:189], v[20:23]
	v_mfma_f32_16x16x32_bf16 v[16:19], v[210:213], v[186:189], v[16:19]
	v_mfma_f32_16x16x32_bf16 v[16:19], v[206:209], v[182:185], v[16:19]
	v_mfma_f32_16x16x32_bf16 v[0:3], v[206:209], v[190:193], v[0:3]
	v_mfma_f32_16x16x32_bf16 v[0:3], v[210:213], v[194:197], v[0:3]
	v_mfma_f32_16x16x32_bf16 v[4:7], v[202:205], v[194:197], v[4:7]
	v_mfma_f32_16x16x32_bf16 v[4:7], v[198:201], v[190:193], v[4:7]
	s_add_u32 s8, s8, 0x100
	s_addc_u32 s9, s9, 0
	s_add_u32 s69, s69, 0x100
	s_addc_u32 s70, s70, 0
	s_cmp_ge_i32 s71, s52
	s_mov_b32 s40, s71
	s_barrier
	s_cbranch_scc0 .LBB0_1332
	s_branch .LBB0_1323

; #define PG8_STAGE(bufoff, gbase, voff) do { _Pragma("unroll") for (int _i = 0; _i < 2; ++_i) \
;         __builtin_amdgcn_global_load_lds((const unsigned*)((const char*)(gbase) + (voff)[_i]), (LAS unsigned*)(lds + (bufoff) + ldsw + _i * 8192), 16, 0, 0); } while (0)
; #define PG8_LDA(dst, b, h) do { _Pragma("unroll") for (int m = 0; m < 4; ++m) _Pragma("unroll") for (int k = 0; k < 2; ++k) dst[m][k] = *(const LAS bf16x8*)(lds + PG8_SA(b, h) + aoff + m * 2048 + k * 1024); } while (0)
; #define PG8_LDB(dst, b, h) do { _Pragma("unroll") for (int n = 0; n < 2; ++n) _Pragma("unroll") for (int k = 0; k < 2; ++k) dst[n][k] = *(const LAS bf16x8*)(lds + PG8_SB(b, h) + boff + n * 2048 + k * 1024); } while (0)
; #define PG8_MMA(ai, bj, At, Bt) do { __builtin_amdgcn_s_setprio(1); _Pragma("unroll") for (int m = 0; m < 4; ++m) _Pragma("unroll") for (int n = 0; n < 2; ++n) _Pragma("unroll") for (int k = 0; k < 2; ++k) \
;         acc[ai][bj][m][n] = __builtin_amdgcn_mfma_f32_16x16x32_bf16(Bt[n][k], At[m][k], acc[ai][bj][m][n], 0, 0, 0); __builtin_amdgcn_s_setprio(0); } while (0)
; #define PG8_WAIT_L(n) asm volatile("s_waitcnt lgkmcnt(" #n ")" ::: "memory")
; #define PG8_BAR __builtin_amdgcn_s_barrier()
; #define PG8_SCHED __builtin_amdgcn_sched_barrier(0)
; template <class Epi>
; DEVINL void gemm_phase(LAS unsigned char* lds, const Gemm g, const Order& S, const Epi& E) {
;     ...
;             const bool last = (t == nt - 2);
;             const char* a1 = cA + (size_t)(t + 1) * kstep;
;             const char* a2 = last ? nA : cA + (size_t)(t + 2) * kstep; const char* b2 = last ? nB : cB + (size_t)(t + 2) * kstep;
;             const char* a3 = a2 + kstep; const char* b3 = b2 + kstep;
;             PG8_LDB(B0, 0, 0); PG8_SCHED; PG8_LDA(At, 0, 0); PG8_STAGE(PG8_SA(1, 1), a1 + hstepA, voffA);
;             PG8_WAIT_L(8); PG8_BAR; PG8_WAIT_L(0); PG8_MMA(0, 0, At, B0); PG8_BAR; PG8_SCHED;
;             PG8_LDB(B1, 0, 1); PG8_STAGE(PG8_SB(0, 0), b2, voffB);
;             PG8_BAR; PG8_WAIT_L(0); PG8_MMA(0, 1, At, B1); PG8_BAR;
;             PG8_LDA(At, 0, 1); PG8_STAGE(PG8_SA(0, 0), a2, voffA);
;             PG8_BAR; PG8_WAIT_L(0); PG8_MMA(1, 0, At, B0); PG8_BAR; PG8_SCHED;
.LBB0_1492:
	ds_read_b128 v[150:153], v147
	ds_read_b128 v[154:157], v147 offset:1024
	ds_read_b128 v[158:161], v147 offset:2048
	ds_read_b128 v[162:165], v147 offset:3072
	s_add_i32 s74, s42, 2
	s_add_u32 s43, s8, 0xfff80080
	s_addc_u32 s44, s9, -1
	s_cmp_eq_u32 s57, s42
	s_cselect_b32 s42, s37, s72
	s_cselect_b32 s45, s2, s44
	s_cselect_b32 s44, s3, s43
	s_cselect_b32 s43, s31, s73
	v_lshl_add_u64 v[198:199], s[8:9], 0, v[136:137]
	s_add_i32 m0, s29, 0xc000
	ds_read_b128 v[166:169], v148
	ds_read_b128 v[170:173], v148 offset:1024
	ds_read_b128 v[174:177], v148 offset:2048
	ds_read_b128 v[178:181], v148 offset:3072
	ds_read_b128 v[182:185], v148 offset:4096
	ds_read_b128 v[186:189], v148 offset:5120
	ds_read_b128 v[190:193], v148 offset:6144
	ds_read_b128 v[194:197], v148 offset:7168
	global_load_lds_dwordx4 v[198:199], off
	v_lshl_add_u64 v[198:199], s[8:9], 0, v[138:139]
	s_add_i32 m0, s29, 0xe000
	s_nop 0
	global_load_lds_dwordx4 v[198:199], off
	s_waitcnt lgkmcnt(8)
	s_barrier
	s_waitcnt lgkmcnt(0)
	s_waitcnt lgkmcnt(0)
	v_mfma_f32_16x16x32_bf16 v[120:123], v[150:153], v[166:169], v[120:123]
	v_mfma_f32_16x16x32_bf16 v[120:123], v[154:157], v[170:173], v[120:123]
	v_mfma_f32_16x16x32_bf16 v[124:127], v[162:165], v[170:173], v[124:127]
	v_mfma_f32_16x16x32_bf16 v[124:127], v[158:161], v[166:169], v[124:127]
	v_mfma_f32_16x16x32_bf16 v[104:107], v[158:161], v[174:177], v[104:107]
	v_mfma_f32_16x16x32_bf16 v[104:107], v[162:165], v[178:181], v[104:107]
	v_mfma_f32_16x16x32_bf16 v[108:111], v[154:157], v[178:181], v[108:111]
	v_mfma_f32_16x16x32_bf16 v[108:111], v[150:153], v[174:177], v[108:111]
	v_mfma_f32_16x16x32_bf16 v[92:95], v[150:153], v[182:185], v[92:95]
	v_mfma_f32_16x16x32_bf16 v[92:95], v[154:157], v[186:189], v[92:95]
	v_mfma_f32_16x16x32_bf16 v[88:91], v[162:165], v[186:189], v[88:91]
	v_mfma_f32_16x16x32_bf16 v[88:91], v[158:161], v[182:185], v[88:91]
	v_mfma_f32_16x16x32_bf16 v[72:75], v[158:161], v[190:193], v[72:75]
	v_mfma_f32_16x16x32_bf16 v[72:75], v[162:165], v[194:197], v[72:75]
	v_mfma_f32_16x16x32_bf16 v[76:79], v[154:157], v[194:197], v[76:79]
	v_mfma_f32_16x16x32_bf16 v[76:79], v[150:153], v[190:193], v[76:79]
	s_barrier
	s_add_i32 s75, s65, s50
	v_lshl_add_u64 v[218:219], s[42:43], 0, v[130:131]
	s_mov_b32 m0, s75
	ds_read_b128 v[198:201], v149
	ds_read_b128 v[202:205], v149 offset:1024
	ds_read_b128 v[206:209], v149 offset:2048
	ds_read_b128 v[210:213], v149 offset:3072
	global_load_lds_dwordx4 v[218:219], off
	v_lshl_add_u64 v[220:221], s[42:43], 0, v[134:135]
	s_add_i32 m0, s75, 0x2000
	s_nop 0
	global_load_lds_dwordx4 v[220:221], off
	s_barrier
	s_waitcnt lgkmcnt(0)
	s_waitcnt lgkmcnt(0)
	v_mfma_f32_16x16x32_bf16 v[116:119], v[198:201], v[166:169], v[116:119]
	v_mfma_f32_16x16x32_bf16 v[116:119], v[202:205], v[170:173], v[116:119]
	v_mfma_f32_16x16x32_bf16 v[112:115], v[210:213], v[170:173], v[112:115]
	v_mfma_f32_16x16x32_bf16 v[112:115], v[206:209], v[166:169], v[112:115]
	v_mfma_f32_16x16x32_bf16 v[96:99], v[206:209], v[174:177], v[96:99]
	v_mfma_f32_16x16x32_bf16 v[96:99], v[210:213], v[178:181], v[96:99]
	v_mfma_f32_16x16x32_bf16 v[100:103], v[202:205], v[178:181], v[100:103]
	v_mfma_f32_16x16x32_bf16 v[100:103], v[198:201], v[174:177], v[100:103]
	v_mfma_f32_16x16x32_bf16 v[84:87], v[198:201], v[182:185], v[84:87]
	v_mfma_f32_16x16x32_bf16 v[84:87], v[202:205], v[186:189], v[84:87]
	v_mfma_f32_16x16x32_bf16 v[80:83], v[210:213], v[186:189], v[80:83]
	v_mfma_f32_16x16x32_bf16 v[80:83], v[206:209], v[182:185], v[80:83]
	v_mfma_f32_16x16x32_bf16 v[64:67], v[206:209], v[190:193], v[64:67]
	v_mfma_f32_16x16x32_bf16 v[64:67], v[210:213], v[194:197], v[64:67]
	v_mfma_f32_16x16x32_bf16 v[68:71], v[202:205], v[194:197], v[68:71]
	v_mfma_f32_16x16x32_bf16 v[68:71], v[198:201], v[190:193], v[68:71]
	s_mov_b32 m0, s29
	v_lshl_add_u64 v[222:223], s[44:45], 0, v[128:129]
	s_barrier
	ds_read_b128 v[166:169], v148 offset:16384
	ds_read_b128 v[170:173], v148 offset:17408
	ds_read_b128 v[174:177], v148 offset:18432
	ds_read_b128 v[178:181], v148 offset:19456
	ds_read_b128 v[182:185], v148 offset:20480
	ds_read_b128 v[186:189], v148 offset:21504
	ds_read_b128 v[190:193], v148 offset:22528
	ds_read_b128 v[194:197], v148 offset:23552
	global_load_lds_dwordx4 v[222:223], off
	v_lshl_add_u64 v[224:225], s[44:45], 0, v[132:133]
	s_mov_b32 m0, s51
	s_nop 0
	global_load_lds_dwordx4 v[224:225], off
	s_barrier
	s_waitcnt lgkmcnt(0)
	s_waitcnt lgkmcnt(0)
	v_mfma_f32_16x16x32_bf16 v[60:63], v[150:153], v[166:169], v[60:63]
	v_mfma_f32_16x16x32_bf16 v[60:63], v[154:157], v[170:173], v[60:63]
	v_mfma_f32_16x16x32_bf16 v[56:59], v[162:165], v[170:173], v[56:59]
	v_mfma_f32_16x16x32_bf16 v[56:59], v[158:161], v[166:169], v[56:59]
	v_mfma_f32_16x16x32_bf16 v[40:43], v[158:161], v[174:177], v[40:43]
	v_mfma_f32_16x16x32_bf16 v[40:43], v[162:165], v[178:181], v[40:43]
	v_mfma_f32_16x16x32_bf16 v[44:47], v[154:157], v[178:181], v[44:47]
	v_mfma_f32_16x16x32_bf16 v[44:47], v[150:153], v[174:177], v[44:47]
	v_mfma_f32_16x16x32_bf16 v[28:31], v[150:153], v[182:185], v[28:31]
	v_mfma_f32_16x16x32_bf16 v[28:31], v[154:157], v[186:189], v[28:31]
	v_mfma_f32_16x16x32_bf16 v[24:27], v[162:165], v[186:189], v[24:27]
	v_mfma_f32_16x16x32_bf16 v[24:27], v[158:161], v[182:185], v[24:27]
	v_mfma_f32_16x16x32_bf16 v[8:11], v[158:161], v[190:193], v[8:11]
	v_mfma_f32_16x16x32_bf16 v[8:11], v[162:165], v[194:197], v[8:11]
	v_mfma_f32_16x16x32_bf16 v[12:15], v[154:157], v[194:197], v[12:15]
	v_mfma_f32_16x16x32_bf16 v[12:15], v[150:153], v[190:193], v[12:15]
	s_barrier
; #define PG8_STAGE(bufoff, gbase, voff) do { _Pragma("unroll") for (int _i = 0; _i < 2; ++_i) \
;         __builtin_amdgcn_global_load_lds((const unsigned*)((const char*)(gbase) + (voff)[_i]), (LAS unsigned*)(lds + (bufoff) + ldsw + _i * 8192), 16, 0, 0); } while (0)
; #define PG8_LDA(dst, b, h) do { _Pragma("unroll") for (int m = 0; m < 4; ++m) _Pragma("unroll") for (int k = 0; k < 2; ++k) dst[m][k] = *(const LAS bf16x8*)(lds + PG8_SA(b, h) + aoff + m * 2048 + k * 1024); } while (0)
; #define PG8_LDB(dst, b, h) do { _Pragma("unroll") for (int n = 0; n < 2; ++n) _Pragma("unroll") for (int k = 0; k < 2; ++k) dst[n][k] = *(const LAS bf16x8*)(lds + PG8_SB(b, h) + boff + n * 2048 + k * 1024); } while (0)
; #define PG8_MMA(ai, bj, At, Bt) do { __builtin_amdgcn_s_setprio(1); _Pragma("unroll") for (int m = 0; m < 4; ++m) _Pragma("unroll") for (int n = 0; n < 2; ++n) _Pragma("unroll") for (int k = 0; k < 2; ++k) \
;         acc[ai][bj][m][n] = __builtin_amdgcn_mfma_f32_16x16x32_bf16(Bt[n][k], At[m][k], acc[ai][bj][m][n], 0, 0, 0); __builtin_amdgcn_s_setprio(0); } while (0)
; #define PG8_WAIT_V(n) asm volatile("s_waitcnt vmcnt(" #n ")" ::: "memory")
; #define PG8_WAIT_L(n) asm volatile("s_waitcnt lgkmcnt(" #n ")" ::: "memory")
; #define PG8_BAR __builtin_amdgcn_s_barrier()
; #define PG8_SCHED __builtin_amdgcn_sched_barrier(0)
; template <class Epi>
; DEVINL void gemm_phase(LAS unsigned char* lds, const Gemm g, const Order& S, const Epi& E) {
;     ...
;             PG8_STAGE(PG8_SB(0, 1), b2 + hstepB, voffB);
;             PG8_WAIT_V(6); PG8_BAR; PG8_MMA(1, 1, At, B1); PG8_BAR;
;             PG8_LDB(B0, 1, 0); PG8_SCHED; PG8_LDA(At, 1, 0); PG8_STAGE(PG8_SA(0, 1), a2 + hstepA, voffA);
;             PG8_WAIT_L(8); PG8_BAR; PG8_WAIT_L(0); PG8_MMA(0, 0, At, B0); PG8_BAR; PG8_SCHED;
;             PG8_LDB(B1, 1, 1); PG8_STAGE(PG8_SB(1, 0), b3, voffB);
	s_add_u32 s76, s42, 0x80000
	s_addc_u32 s77, s43, 0
	s_add_i32 s75, s66, s50
	v_lshl_add_u64 v[150:151], s[76:77], 0, v[130:131]
	s_mov_b32 m0, s75
	s_nop 0
	global_load_lds_dwordx4 v[150:151], off
	v_lshl_add_u64 v[150:151], s[76:77], 0, v[134:135]
	s_add_i32 m0, s75, 0x2000
	s_nop 0
	global_load_lds_dwordx4 v[150:151], off
	s_waitcnt vmcnt(6)
	s_barrier
	v_mfma_f32_16x16x32_bf16 v[52:55], v[198:201], v[166:169], v[52:55]
	v_mfma_f32_16x16x32_bf16 v[52:55], v[202:205], v[170:173], v[52:55]
	v_mfma_f32_16x16x32_bf16 v[48:51], v[210:213], v[170:173], v[48:51]
	v_mfma_f32_16x16x32_bf16 v[48:51], v[206:209], v[166:169], v[48:51]
	v_mfma_f32_16x16x32_bf16 v[32:35], v[206:209], v[174:177], v[32:35]
	v_mfma_f32_16x16x32_bf16 v[32:35], v[210:213], v[178:181], v[32:35]
	v_mfma_f32_16x16x32_bf16 v[36:39], v[202:205], v[178:181], v[36:39]
	v_mfma_f32_16x16x32_bf16 v[36:39], v[198:201], v[174:177], v[36:39]
	v_mfma_f32_16x16x32_bf16 v[20:23], v[198:201], v[182:185], v[20:23]
	v_mfma_f32_16x16x32_bf16 v[20:23], v[202:205], v[186:189], v[20:23]
	v_mfma_f32_16x16x32_bf16 v[16:19], v[210:213], v[186:189], v[16:19]
	v_mfma_f32_16x16x32_bf16 v[16:19], v[206:209], v[182:185], v[16:19]
	v_mfma_f32_16x16x32_bf16 v[0:3], v[206:209], v[190:193], v[0:3]
	v_mfma_f32_16x16x32_bf16 v[0:3], v[210:213], v[194:197], v[0:3]
	v_mfma_f32_16x16x32_bf16 v[4:7], v[202:205], v[194:197], v[4:7]
	v_mfma_f32_16x16x32_bf16 v[4:7], v[198:201], v[190:193], v[4:7]
	s_add_i32 s75, 16, 0x18000
	v_add_u32_e32 v162, s75, v145
	s_barrier
	ds_read_b128 v[150:153], v162
	ds_read_b128 v[154:157], v162 offset:1024
	ds_read_b128 v[158:161], v162 offset:2048
	ds_read_b128 v[162:165], v162 offset:3072
	s_add_u32 s44, s44, 0x80000
	s_addc_u32 s45, s45, 0
	s_mov_b32 m0, s52
	v_lshl_add_u64 v[198:199], s[44:45], 0, v[128:129]
	ds_read_b128 v[166:169], v148 offset:32768
	ds_read_b128 v[170:173], v148 offset:33792
	ds_read_b128 v[174:177], v148 offset:34816
	ds_read_b128 v[178:181], v148 offset:35840
	ds_read_b128 v[182:185], v148 offset:36864
	ds_read_b128 v[186:189], v148 offset:37888
	ds_read_b128 v[190:193], v148 offset:38912
	ds_read_b128 v[194:197], v148 offset:39936
	global_load_lds_dwordx4 v[198:199], off
	v_lshl_add_u64 v[198:199], s[44:45], 0, v[132:133]
	s_mov_b32 m0, s53
	s_nop 0
	global_load_lds_dwordx4 v[198:199], off
	s_waitcnt lgkmcnt(8)
	s_barrier
	s_waitcnt lgkmcnt(0)
	s_waitcnt lgkmcnt(0)
	v_mfma_f32_16x16x32_bf16 v[120:123], v[150:153], v[166:169], v[120:123]
	v_mfma_f32_16x16x32_bf16 v[120:123], v[154:157], v[170:173], v[120:123]
	v_mfma_f32_16x16x32_bf16 v[124:127], v[162:165], v[170:173], v[124:127]
	v_mfma_f32_16x16x32_bf16 v[124:127], v[158:161], v[166:169], v[124:127]
	v_mfma_f32_16x16x32_bf16 v[104:107], v[158:161], v[174:177], v[104:107]
	v_mfma_f32_16x16x32_bf16 v[104:107], v[162:165], v[178:181], v[104:107]
	v_mfma_f32_16x16x32_bf16 v[108:111], v[154:157], v[178:181], v[108:111]
	v_mfma_f32_16x16x32_bf16 v[108:111], v[150:153], v[174:177], v[108:111]
	v_mfma_f32_16x16x32_bf16 v[92:95], v[150:153], v[182:185], v[92:95]
	v_mfma_f32_16x16x32_bf16 v[92:95], v[154:157], v[186:189], v[92:95]
	v_mfma_f32_16x16x32_bf16 v[88:91], v[162:165], v[186:189], v[88:91]
	v_mfma_f32_16x16x32_bf16 v[88:91], v[158:161], v[182:185], v[88:91]
	v_mfma_f32_16x16x32_bf16 v[72:75], v[158:161], v[190:193], v[72:75]
	v_mfma_f32_16x16x32_bf16 v[72:75], v[162:165], v[194:197], v[72:75]
	v_mfma_f32_16x16x32_bf16 v[76:79], v[154:157], v[194:197], v[76:79]
	v_mfma_f32_16x16x32_bf16 v[76:79], v[150:153], v[190:193], v[76:79]
	s_barrier
	s_add_i32 s44, 16, 0x1c000
	s_add_i32 s45, s75, s50
	v_add_u32_e32 v210, s44, v145
	v_lshl_add_u64 v[218:219], v[218:219], 0, s[6:7]
	s_mov_b32 m0, s45
	ds_read_b128 v[198:201], v210
	ds_read_b128 v[202:205], v210 offset:1024
	ds_read_b128 v[206:209], v210 offset:2048
	ds_read_b128 v[210:213], v210 offset:3072
	global_load_lds_dwordx4 v[218:219], off
	v_lshl_add_u64 v[218:219], v[220:221], 0, s[6:7]
	s_add_i32 m0, s45, 0x2000
	s_nop 0
	global_load_lds_dwordx4 v[218:219], off
	s_barrier
; #define PG8_STAGE(bufoff, gbase, voff) do { _Pragma("unroll") for (int _i = 0; _i < 2; ++_i) \
;         __builtin_amdgcn_global_load_lds((const unsigned*)((const char*)(gbase) + (voff)[_i]), (LAS unsigned*)(lds + (bufoff) + ldsw + _i * 8192), 16, 0, 0); } while (0)
; #define PG8_LDA(dst, b, h) do { _Pragma("unroll") for (int m = 0; m < 4; ++m) _Pragma("unroll") for (int k = 0; k < 2; ++k) dst[m][k] = *(const LAS bf16x8*)(lds + PG8_SA(b, h) + aoff + m * 2048 + k * 1024); } while (0)
; #define PG8_MMA(ai, bj, At, Bt) do { __builtin_amdgcn_s_setprio(1); _Pragma("unroll") for (int m = 0; m < 4; ++m) _Pragma("unroll") for (int n = 0; n < 2; ++n) _Pragma("unroll") for (int k = 0; k < 2; ++k) \
;         acc[ai][bj][m][n] = __builtin_amdgcn_mfma_f32_16x16x32_bf16(Bt[n][k], At[m][k], acc[ai][bj][m][n], 0, 0, 0); __builtin_amdgcn_s_setprio(0); } while (0)
; #define PG8_WAIT_V(n) asm volatile("s_waitcnt vmcnt(" #n ")" ::: "memory")
; #define PG8_WAIT_L(n) asm volatile("s_waitcnt lgkmcnt(" #n ")" ::: "memory")
; #define PG8_BAR __builtin_amdgcn_s_barrier()
; #define PG8_SCHED __builtin_amdgcn_sched_barrier(0)
; template <class Epi>
; DEVINL void gemm_phase(LAS unsigned char* lds, const Gemm g, const Order& S, const Epi& E) {
;     ...
;             PG8_BAR; PG8_WAIT_L(0); PG8_MMA(0, 1, At, B1); PG8_BAR;
;             PG8_LDA(At, 1, 1); PG8_STAGE(PG8_SA(1, 0), a3, voffA);
;             PG8_BAR; PG8_WAIT_L(0); PG8_MMA(1, 0, At, B0); PG8_BAR; PG8_SCHED;
;             PG8_STAGE(PG8_SB(1, 1), b3 + hstepB, voffB);
;             PG8_WAIT_V(6); PG8_BAR; PG8_MMA(1, 1, At, B1); PG8_BAR;
	s_waitcnt lgkmcnt(0)
	s_waitcnt lgkmcnt(0)
	v_mfma_f32_16x16x32_bf16 v[116:119], v[198:201], v[166:169], v[116:119]
	v_mfma_f32_16x16x32_bf16 v[116:119], v[202:205], v[170:173], v[116:119]
	v_mfma_f32_16x16x32_bf16 v[112:115], v[210:213], v[170:173], v[112:115]
	v_mfma_f32_16x16x32_bf16 v[112:115], v[206:209], v[166:169], v[112:115]
	v_mfma_f32_16x16x32_bf16 v[96:99], v[206:209], v[174:177], v[96:99]
	v_mfma_f32_16x16x32_bf16 v[96:99], v[210:213], v[178:181], v[96:99]
	v_mfma_f32_16x16x32_bf16 v[100:103], v[202:205], v[178:181], v[100:103]
	v_mfma_f32_16x16x32_bf16 v[100:103], v[198:201], v[174:177], v[100:103]
	v_mfma_f32_16x16x32_bf16 v[84:87], v[198:201], v[182:185], v[84:87]
	v_mfma_f32_16x16x32_bf16 v[84:87], v[202:205], v[186:189], v[84:87]
	v_mfma_f32_16x16x32_bf16 v[80:83], v[210:213], v[186:189], v[80:83]
	v_mfma_f32_16x16x32_bf16 v[80:83], v[206:209], v[182:185], v[80:83]
	v_mfma_f32_16x16x32_bf16 v[64:67], v[206:209], v[190:193], v[64:67]
	v_mfma_f32_16x16x32_bf16 v[64:67], v[210:213], v[194:197], v[64:67]
	v_mfma_f32_16x16x32_bf16 v[68:71], v[202:205], v[194:197], v[68:71]
	v_mfma_f32_16x16x32_bf16 v[68:71], v[198:201], v[190:193], v[68:71]
	s_mov_b32 m0, s55
	v_lshl_add_u64 v[218:219], v[222:223], 0, s[6:7]
	s_barrier
	ds_read_b128 v[166:169], v148 offset:49152
	ds_read_b128 v[170:173], v148 offset:50176
	ds_read_b128 v[174:177], v148 offset:51200
	ds_read_b128 v[178:181], v148 offset:52224
	ds_read_b128 v[182:185], v148 offset:53248
	ds_read_b128 v[186:189], v148 offset:54272
	ds_read_b128 v[190:193], v148 offset:55296
	ds_read_b128 v[194:197], v148 offset:56320
	global_load_lds_dwordx4 v[218:219], off
	v_lshl_add_u64 v[218:219], v[224:225], 0, s[6:7]
	s_mov_b32 m0, s56
	s_nop 0
	global_load_lds_dwordx4 v[218:219], off
	s_barrier
	s_waitcnt lgkmcnt(0)
	s_waitcnt lgkmcnt(0)
	v_mfma_f32_16x16x32_bf16 v[60:63], v[150:153], v[166:169], v[60:63]
	v_mfma_f32_16x16x32_bf16 v[60:63], v[154:157], v[170:173], v[60:63]
	v_mfma_f32_16x16x32_bf16 v[56:59], v[162:165], v[170:173], v[56:59]
	v_mfma_f32_16x16x32_bf16 v[56:59], v[158:161], v[166:169], v[56:59]
	v_mfma_f32_16x16x32_bf16 v[40:43], v[158:161], v[174:177], v[40:43]
	v_mfma_f32_16x16x32_bf16 v[40:43], v[162:165], v[178:181], v[40:43]
	v_mfma_f32_16x16x32_bf16 v[44:47], v[154:157], v[178:181], v[44:47]
	v_mfma_f32_16x16x32_bf16 v[44:47], v[150:153], v[174:177], v[44:47]
	v_mfma_f32_16x16x32_bf16 v[28:31], v[150:153], v[182:185], v[28:31]
	v_mfma_f32_16x16x32_bf16 v[28:31], v[154:157], v[186:189], v[28:31]
	v_mfma_f32_16x16x32_bf16 v[24:27], v[162:165], v[186:189], v[24:27]
	v_mfma_f32_16x16x32_bf16 v[24:27], v[158:161], v[182:185], v[24:27]
	v_mfma_f32_16x16x32_bf16 v[8:11], v[158:161], v[190:193], v[8:11]
	v_mfma_f32_16x16x32_bf16 v[8:11], v[162:165], v[194:197], v[8:11]
	v_mfma_f32_16x16x32_bf16 v[12:15], v[154:157], v[194:197], v[12:15]
	v_mfma_f32_16x16x32_bf16 v[12:15], v[150:153], v[190:193], v[12:15]
	s_barrier
	s_add_u32 s42, s42, 0x80080
	s_addc_u32 s43, s43, 0
	s_add_i32 s44, s44, s50
	v_lshl_add_u64 v[150:151], s[42:43], 0, v[130:131]
	s_mov_b32 m0, s44
	s_nop 0
	global_load_lds_dwordx4 v[150:151], off
	v_lshl_add_u64 v[150:151], s[42:43], 0, v[134:135]
	s_add_i32 m0, s44, 0x2000
	s_nop 0
	global_load_lds_dwordx4 v[150:151], off
	s_waitcnt vmcnt(6)
	s_barrier
	v_mfma_f32_16x16x32_bf16 v[52:55], v[198:201], v[166:169], v[52:55]
	v_mfma_f32_16x16x32_bf16 v[52:55], v[202:205], v[170:173], v[52:55]
	v_mfma_f32_16x16x32_bf16 v[48:51], v[210:213], v[170:173], v[48:51]
	v_mfma_f32_16x16x32_bf16 v[48:51], v[206:209], v[166:169], v[48:51]
	v_mfma_f32_16x16x32_bf16 v[32:35], v[206:209], v[174:177], v[32:35]
	v_mfma_f32_16x16x32_bf16 v[32:35], v[210:213], v[178:181], v[32:35]
	v_mfma_f32_16x16x32_bf16 v[36:39], v[202:205], v[178:181], v[36:39]
	v_mfma_f32_16x16x32_bf16 v[36:39], v[198:201], v[174:177], v[36:39]
	v_mfma_f32_16x16x32_bf16 v[20:23], v[198:201], v[182:185], v[20:23]
	v_mfma_f32_16x16x32_bf16 v[20:23], v[202:205], v[186:189], v[20:23]
	v_mfma_f32_16x16x32_bf16 v[16:19], v[210:213], v[186:189], v[16:19]
	v_mfma_f32_16x16x32_bf16 v[16:19], v[206:209], v[182:185], v[16:19]
	v_mfma_f32_16x16x32_bf16 v[0:3], v[206:209], v[190:193], v[0:3]
	v_mfma_f32_16x16x32_bf16 v[0:3], v[210:213], v[194:197], v[0:3]
	v_mfma_f32_16x16x32_bf16 v[4:7], v[202:205], v[194:197], v[4:7]
	v_mfma_f32_16x16x32_bf16 v[4:7], v[198:201], v[190:193], v[4:7]
	s_add_u32 s8, s8, 0x100
	s_addc_u32 s9, s9, 0
	s_add_u32 s72, s72, 0x100
	s_addc_u32 s73, s73, 0
	s_cmp_ge_i32 s74, s54
	s_mov_b32 s42, s74
	s_barrier
	s_cbranch_scc0 .LBB0_1492
	v_readlane_b32 s75, v250, 1
	s_branch .LBB0_1483

; #define PG8_STAGE(bufoff, gbase, voff) do { _Pragma("unroll") for (int _i = 0; _i < 2; ++_i) \
;         __builtin_amdgcn_global_load_lds((const unsigned*)((const char*)(gbase) + (voff)[_i]), (LAS unsigned*)(lds + (bufoff) + ldsw + _i * 8192), 16, 0, 0); } while (0)
; #define PG8_LDA(dst, b, h) do { _Pragma("unroll") for (int m = 0; m < 4; ++m) _Pragma("unroll") for (int k = 0; k < 2; ++k) dst[m][k] = *(const LAS bf16x8*)(lds + PG8_SA(b, h) + aoff + m * 2048 + k * 1024); } while (0)
; #define PG8_LDB(dst, b, h) do { _Pragma("unroll") for (int n = 0; n < 2; ++n) _Pragma("unroll") for (int k = 0; k < 2; ++k) dst[n][k] = *(const LAS bf16x8*)(lds + PG8_SB(b, h) + boff + n * 2048 + k * 1024); } while (0)
; #define PG8_MMA(ai, bj, At, Bt) do { __builtin_amdgcn_s_setprio(1); _Pragma("unroll") for (int m = 0; m < 4; ++m) _Pragma("unroll") for (int n = 0; n < 2; ++n) _Pragma("unroll") for (int k = 0; k < 2; ++k) \
;         acc[ai][bj][m][n] = __builtin_amdgcn_mfma_f32_16x16x32_bf16(Bt[n][k], At[m][k], acc[ai][bj][m][n], 0, 0, 0); __builtin_amdgcn_s_setprio(0); } while (0)
; #define PG8_WAIT_L(n) asm volatile("s_waitcnt lgkmcnt(" #n ")" ::: "memory")
; #define PG8_BAR __builtin_amdgcn_s_barrier()
; #define PG8_SCHED __builtin_amdgcn_sched_barrier(0)
; template <class Epi>
; DEVINL void gemm_phase(LAS unsigned char* lds, const Gemm g, const Order& S, const Epi& E) {
;     ...
;             const bool last = (t == nt - 2);
;             const char* a1 = cA + (size_t)(t + 1) * kstep;
;             const char* a2 = last ? nA : cA + (size_t)(t + 2) * kstep; const char* b2 = last ? nB : cB + (size_t)(t + 2) * kstep;
;             const char* a3 = a2 + kstep; const char* b3 = b2 + kstep;
;             PG8_LDB(B0, 0, 0); PG8_SCHED; PG8_LDA(At, 0, 0); PG8_STAGE(PG8_SA(1, 1), a1 + hstepA, voffA);
;             PG8_WAIT_L(8); PG8_BAR; PG8_WAIT_L(0); PG8_MMA(0, 0, At, B0); PG8_BAR; PG8_SCHED;
;             PG8_LDB(B1, 0, 1); PG8_STAGE(PG8_SB(0, 0), b2, voffB);
;             PG8_BAR; PG8_WAIT_L(0); PG8_MMA(0, 1, At, B1); PG8_BAR;
;             PG8_LDA(At, 0, 1); PG8_STAGE(PG8_SA(0, 0), a2, voffA);
;             PG8_BAR; PG8_WAIT_L(0); PG8_MMA(1, 0, At, B0); PG8_BAR; PG8_SCHED;
.LBB0_1623:
	ds_read_b128 v[150:153], v147
	ds_read_b128 v[154:157], v147 offset:1024
	ds_read_b128 v[158:161], v147 offset:2048
	ds_read_b128 v[162:165], v147 offset:3072
	s_add_i32 s69, s38, 2
	s_add_u32 s39, s2, 0xfffc0080
	s_addc_u32 s40, s3, -1
	s_cmp_eq_u32 s52, s38
	s_cselect_b32 s38, s66, s67
	s_cselect_b32 s41, s27, s40
	s_cselect_b32 s40, s29, s39
	s_cselect_b32 s39, s65, s68
	v_lshl_add_u64 v[198:199], s[2:3], 0, v[136:137]
	s_add_i32 m0, s25, 0xc000
	ds_read_b128 v[166:169], v148
	ds_read_b128 v[170:173], v148 offset:1024
	ds_read_b128 v[174:177], v148 offset:2048
	ds_read_b128 v[178:181], v148 offset:3072
	ds_read_b128 v[182:185], v148 offset:4096
	ds_read_b128 v[186:189], v148 offset:5120
	ds_read_b128 v[190:193], v148 offset:6144
	ds_read_b128 v[194:197], v148 offset:7168
	global_load_lds_dwordx4 v[198:199], off
	v_lshl_add_u64 v[198:199], s[2:3], 0, v[138:139]
	s_add_i32 m0, s25, 0xe000
	s_nop 0
	global_load_lds_dwordx4 v[198:199], off
	s_waitcnt lgkmcnt(8)
	s_barrier
	s_waitcnt lgkmcnt(0)
	s_waitcnt lgkmcnt(0)
	v_mfma_f32_16x16x32_bf16 v[120:123], v[150:153], v[166:169], v[120:123]
	v_mfma_f32_16x16x32_bf16 v[120:123], v[154:157], v[170:173], v[120:123]
	v_mfma_f32_16x16x32_bf16 v[124:127], v[162:165], v[170:173], v[124:127]
	v_mfma_f32_16x16x32_bf16 v[124:127], v[158:161], v[166:169], v[124:127]
	v_mfma_f32_16x16x32_bf16 v[104:107], v[158:161], v[174:177], v[104:107]
	v_mfma_f32_16x16x32_bf16 v[104:107], v[162:165], v[178:181], v[104:107]
	v_mfma_f32_16x16x32_bf16 v[108:111], v[154:157], v[178:181], v[108:111]
	v_mfma_f32_16x16x32_bf16 v[108:111], v[150:153], v[174:177], v[108:111]
	v_mfma_f32_16x16x32_bf16 v[92:95], v[150:153], v[182:185], v[92:95]
	v_mfma_f32_16x16x32_bf16 v[92:95], v[154:157], v[186:189], v[92:95]
	v_mfma_f32_16x16x32_bf16 v[88:91], v[162:165], v[186:189], v[88:91]
	v_mfma_f32_16x16x32_bf16 v[88:91], v[158:161], v[182:185], v[88:91]
	v_mfma_f32_16x16x32_bf16 v[72:75], v[158:161], v[190:193], v[72:75]
	v_mfma_f32_16x16x32_bf16 v[72:75], v[162:165], v[194:197], v[72:75]
	v_mfma_f32_16x16x32_bf16 v[76:79], v[154:157], v[194:197], v[76:79]
	v_mfma_f32_16x16x32_bf16 v[76:79], v[150:153], v[190:193], v[76:79]
	s_barrier
	s_add_i32 s70, s58, s45
	v_lshl_add_u64 v[218:219], s[38:39], 0, v[130:131]
	s_mov_b32 m0, s70
	ds_read_b128 v[198:201], v149
	ds_read_b128 v[202:205], v149 offset:1024
	ds_read_b128 v[206:209], v149 offset:2048
	ds_read_b128 v[210:213], v149 offset:3072
	global_load_lds_dwordx4 v[218:219], off
	v_lshl_add_u64 v[220:221], s[38:39], 0, v[134:135]
	s_add_i32 m0, s70, 0x2000
	s_nop 0
	global_load_lds_dwordx4 v[220:221], off
	s_barrier
	s_waitcnt lgkmcnt(0)
	s_waitcnt lgkmcnt(0)
	v_mfma_f32_16x16x32_bf16 v[116:119], v[198:201], v[166:169], v[116:119]
	v_mfma_f32_16x16x32_bf16 v[116:119], v[202:205], v[170:173], v[116:119]
	v_mfma_f32_16x16x32_bf16 v[112:115], v[210:213], v[170:173], v[112:115]
	v_mfma_f32_16x16x32_bf16 v[112:115], v[206:209], v[166:169], v[112:115]
	v_mfma_f32_16x16x32_bf16 v[96:99], v[206:209], v[174:177], v[96:99]
	v_mfma_f32_16x16x32_bf16 v[96:99], v[210:213], v[178:181], v[96:99]
	v_mfma_f32_16x16x32_bf16 v[100:103], v[202:205], v[178:181], v[100:103]
	v_mfma_f32_16x16x32_bf16 v[100:103], v[198:201], v[174:177], v[100:103]
	v_mfma_f32_16x16x32_bf16 v[84:87], v[198:201], v[182:185], v[84:87]
	v_mfma_f32_16x16x32_bf16 v[84:87], v[202:205], v[186:189], v[84:87]
	v_mfma_f32_16x16x32_bf16 v[80:83], v[210:213], v[186:189], v[80:83]
	v_mfma_f32_16x16x32_bf16 v[80:83], v[206:209], v[182:185], v[80:83]
	v_mfma_f32_16x16x32_bf16 v[64:67], v[206:209], v[190:193], v[64:67]
	v_mfma_f32_16x16x32_bf16 v[64:67], v[210:213], v[194:197], v[64:67]
	v_mfma_f32_16x16x32_bf16 v[68:71], v[202:205], v[194:197], v[68:71]
	v_mfma_f32_16x16x32_bf16 v[68:71], v[198:201], v[190:193], v[68:71]
	s_mov_b32 m0, s25
	v_lshl_add_u64 v[222:223], s[40:41], 0, v[128:129]
	s_barrier
	ds_read_b128 v[166:169], v148 offset:16384
	ds_read_b128 v[170:173], v148 offset:17408
	ds_read_b128 v[174:177], v148 offset:18432
	ds_read_b128 v[178:181], v148 offset:19456
	ds_read_b128 v[182:185], v148 offset:20480
	ds_read_b128 v[186:189], v148 offset:21504
	ds_read_b128 v[190:193], v148 offset:22528
	ds_read_b128 v[194:197], v148 offset:23552
	global_load_lds_dwordx4 v[222:223], off
	v_lshl_add_u64 v[224:225], s[40:41], 0, v[132:133]
	s_mov_b32 m0, s46
	s_nop 0
	global_load_lds_dwordx4 v[224:225], off
	s_barrier
	s_waitcnt lgkmcnt(0)
	s_waitcnt lgkmcnt(0)
	v_mfma_f32_16x16x32_bf16 v[60:63], v[150:153], v[166:169], v[60:63]
	v_mfma_f32_16x16x32_bf16 v[60:63], v[154:157], v[170:173], v[60:63]
	v_mfma_f32_16x16x32_bf16 v[56:59], v[162:165], v[170:173], v[56:59]
	v_mfma_f32_16x16x32_bf16 v[56:59], v[158:161], v[166:169], v[56:59]
	v_mfma_f32_16x16x32_bf16 v[40:43], v[158:161], v[174:177], v[40:43]
	v_mfma_f32_16x16x32_bf16 v[40:43], v[162:165], v[178:181], v[40:43]
	v_mfma_f32_16x16x32_bf16 v[44:47], v[154:157], v[178:181], v[44:47]
	v_mfma_f32_16x16x32_bf16 v[44:47], v[150:153], v[174:177], v[44:47]
	v_mfma_f32_16x16x32_bf16 v[28:31], v[150:153], v[182:185], v[28:31]
	v_mfma_f32_16x16x32_bf16 v[28:31], v[154:157], v[186:189], v[28:31]
	v_mfma_f32_16x16x32_bf16 v[24:27], v[162:165], v[186:189], v[24:27]
	v_mfma_f32_16x16x32_bf16 v[24:27], v[158:161], v[182:185], v[24:27]
	v_mfma_f32_16x16x32_bf16 v[8:11], v[158:161], v[190:193], v[8:11]
	v_mfma_f32_16x16x32_bf16 v[8:11], v[162:165], v[194:197], v[8:11]
	v_mfma_f32_16x16x32_bf16 v[12:15], v[154:157], v[194:197], v[12:15]
	v_mfma_f32_16x16x32_bf16 v[12:15], v[150:153], v[190:193], v[12:15]
	s_barrier
; #define PG8_STAGE(bufoff, gbase, voff) do { _Pragma("unroll") for (int _i = 0; _i < 2; ++_i) \
;         __builtin_amdgcn_global_load_lds((const unsigned*)((const char*)(gbase) + (voff)[_i]), (LAS unsigned*)(lds + (bufoff) + ldsw + _i * 8192), 16, 0, 0); } while (0)
; #define PG8_LDA(dst, b, h) do { _Pragma("unroll") for (int m = 0; m < 4; ++m) _Pragma("unroll") for (int k = 0; k < 2; ++k) dst[m][k] = *(const LAS bf16x8*)(lds + PG8_SA(b, h) + aoff + m * 2048 + k * 1024); } while (0)
; #define PG8_LDB(dst, b, h) do { _Pragma("unroll") for (int n = 0; n < 2; ++n) _Pragma("unroll") for (int k = 0; k < 2; ++k) dst[n][k] = *(const LAS bf16x8*)(lds + PG8_SB(b, h) + boff + n * 2048 + k * 1024); } while (0)
; #define PG8_MMA(ai, bj, At, Bt) do { __builtin_amdgcn_s_setprio(1); _Pragma("unroll") for (int m = 0; m < 4; ++m) _Pragma("unroll") for (int n = 0; n < 2; ++n) _Pragma("unroll") for (int k = 0; k < 2; ++k) \
;         acc[ai][bj][m][n] = __builtin_amdgcn_mfma_f32_16x16x32_bf16(Bt[n][k], At[m][k], acc[ai][bj][m][n], 0, 0, 0); __builtin_amdgcn_s_setprio(0); } while (0)
; #define PG8_WAIT_V(n) asm volatile("s_waitcnt vmcnt(" #n ")" ::: "memory")
; #define PG8_WAIT_L(n) asm volatile("s_waitcnt lgkmcnt(" #n ")" ::: "memory")
; #define PG8_BAR __builtin_amdgcn_s_barrier()
; #define PG8_SCHED __builtin_amdgcn_sched_barrier(0)
; template <class Epi>
; DEVINL void gemm_phase(LAS unsigned char* lds, const Gemm g, const Order& S, const Epi& E) {
;     ...
;             PG8_STAGE(PG8_SB(0, 1), b2 + hstepB, voffB);
;             PG8_WAIT_V(6); PG8_BAR; PG8_MMA(1, 1, At, B1); PG8_BAR;
;             PG8_LDB(B0, 1, 0); PG8_SCHED; PG8_LDA(At, 1, 0); PG8_STAGE(PG8_SA(0, 1), a2 + hstepA, voffA);
;             PG8_WAIT_L(8); PG8_BAR; PG8_WAIT_L(0); PG8_MMA(0, 0, At, B0); PG8_BAR; PG8_SCHED;
;             PG8_LDB(B1, 1, 1); PG8_STAGE(PG8_SB(1, 0), b3, voffB);
	s_add_u32 s70, s38, 0x40000
	s_addc_u32 s71, s39, 0
	s_add_i32 s72, s59, s45
	v_lshl_add_u64 v[150:151], s[70:71], 0, v[130:131]
	s_mov_b32 m0, s72
	s_nop 0
	global_load_lds_dwordx4 v[150:151], off
	v_lshl_add_u64 v[150:151], s[70:71], 0, v[134:135]
	s_add_i32 m0, s72, 0x2000
	s_nop 0
	global_load_lds_dwordx4 v[150:151], off
	s_waitcnt vmcnt(6)
	s_barrier
	v_mfma_f32_16x16x32_bf16 v[52:55], v[198:201], v[166:169], v[52:55]
	v_mfma_f32_16x16x32_bf16 v[52:55], v[202:205], v[170:173], v[52:55]
	v_mfma_f32_16x16x32_bf16 v[48:51], v[210:213], v[170:173], v[48:51]
	v_mfma_f32_16x16x32_bf16 v[48:51], v[206:209], v[166:169], v[48:51]
	v_mfma_f32_16x16x32_bf16 v[32:35], v[206:209], v[174:177], v[32:35]
	v_mfma_f32_16x16x32_bf16 v[32:35], v[210:213], v[178:181], v[32:35]
	v_mfma_f32_16x16x32_bf16 v[36:39], v[202:205], v[178:181], v[36:39]
	v_mfma_f32_16x16x32_bf16 v[36:39], v[198:201], v[174:177], v[36:39]
	v_mfma_f32_16x16x32_bf16 v[20:23], v[198:201], v[182:185], v[20:23]
	v_mfma_f32_16x16x32_bf16 v[20:23], v[202:205], v[186:189], v[20:23]
	v_mfma_f32_16x16x32_bf16 v[16:19], v[210:213], v[186:189], v[16:19]
	v_mfma_f32_16x16x32_bf16 v[16:19], v[206:209], v[182:185], v[16:19]
	v_mfma_f32_16x16x32_bf16 v[0:3], v[206:209], v[190:193], v[0:3]
	v_mfma_f32_16x16x32_bf16 v[0:3], v[210:213], v[194:197], v[0:3]
	v_mfma_f32_16x16x32_bf16 v[4:7], v[202:205], v[194:197], v[4:7]
	v_mfma_f32_16x16x32_bf16 v[4:7], v[198:201], v[190:193], v[4:7]
	s_add_i32 s70, 16, 0x18000
	v_add_u32_e32 v162, s70, v145
	s_barrier
	ds_read_b128 v[150:153], v162
	ds_read_b128 v[154:157], v162 offset:1024
	ds_read_b128 v[158:161], v162 offset:2048
	ds_read_b128 v[162:165], v162 offset:3072
	s_add_u32 s40, s40, 0x40000
	s_addc_u32 s41, s41, 0
	s_mov_b32 m0, s47
	v_lshl_add_u64 v[198:199], s[40:41], 0, v[128:129]
	ds_read_b128 v[166:169], v148 offset:32768
	ds_read_b128 v[170:173], v148 offset:33792
	ds_read_b128 v[174:177], v148 offset:34816
	ds_read_b128 v[178:181], v148 offset:35840
	ds_read_b128 v[182:185], v148 offset:36864
	ds_read_b128 v[186:189], v148 offset:37888
	ds_read_b128 v[190:193], v148 offset:38912
	ds_read_b128 v[194:197], v148 offset:39936
	global_load_lds_dwordx4 v[198:199], off
	v_lshl_add_u64 v[198:199], s[40:41], 0, v[132:133]
	s_mov_b32 m0, s48
	s_nop 0
	global_load_lds_dwordx4 v[198:199], off
	s_waitcnt lgkmcnt(8)
	s_barrier
	s_waitcnt lgkmcnt(0)
	s_waitcnt lgkmcnt(0)
	v_mfma_f32_16x16x32_bf16 v[120:123], v[150:153], v[166:169], v[120:123]
	v_mfma_f32_16x16x32_bf16 v[120:123], v[154:157], v[170:173], v[120:123]
	v_mfma_f32_16x16x32_bf16 v[124:127], v[162:165], v[170:173], v[124:127]
	v_mfma_f32_16x16x32_bf16 v[124:127], v[158:161], v[166:169], v[124:127]
	v_mfma_f32_16x16x32_bf16 v[104:107], v[158:161], v[174:177], v[104:107]
	v_mfma_f32_16x16x32_bf16 v[104:107], v[162:165], v[178:181], v[104:107]
	v_mfma_f32_16x16x32_bf16 v[108:111], v[154:157], v[178:181], v[108:111]
	v_mfma_f32_16x16x32_bf16 v[108:111], v[150:153], v[174:177], v[108:111]
	v_mfma_f32_16x16x32_bf16 v[92:95], v[150:153], v[182:185], v[92:95]
	v_mfma_f32_16x16x32_bf16 v[92:95], v[154:157], v[186:189], v[92:95]
	v_mfma_f32_16x16x32_bf16 v[88:91], v[162:165], v[186:189], v[88:91]
	v_mfma_f32_16x16x32_bf16 v[88:91], v[158:161], v[182:185], v[88:91]
	v_mfma_f32_16x16x32_bf16 v[72:75], v[158:161], v[190:193], v[72:75]
	v_mfma_f32_16x16x32_bf16 v[72:75], v[162:165], v[194:197], v[72:75]
	v_mfma_f32_16x16x32_bf16 v[76:79], v[154:157], v[194:197], v[76:79]
	v_mfma_f32_16x16x32_bf16 v[76:79], v[150:153], v[190:193], v[76:79]
	s_barrier
	s_add_i32 s40, 16, 0x1c000
	s_add_i32 s41, s70, s45
	v_add_u32_e32 v210, s40, v145
	v_lshl_add_u64 v[218:219], v[218:219], 0, s[6:7]
	s_mov_b32 m0, s41
	ds_read_b128 v[198:201], v210
	ds_read_b128 v[202:205], v210 offset:1024
	ds_read_b128 v[206:209], v210 offset:2048
	ds_read_b128 v[210:213], v210 offset:3072
	global_load_lds_dwordx4 v[218:219], off
	v_lshl_add_u64 v[218:219], v[220:221], 0, s[6:7]
	s_add_i32 m0, s41, 0x2000
	s_nop 0
	global_load_lds_dwordx4 v[218:219], off
	s_barrier
; #define PG8_STAGE(bufoff, gbase, voff) do { _Pragma("unroll") for (int _i = 0; _i < 2; ++_i) \
;         __builtin_amdgcn_global_load_lds((const unsigned*)((const char*)(gbase) + (voff)[_i]), (LAS unsigned*)(lds + (bufoff) + ldsw + _i * 8192), 16, 0, 0); } while (0)
; #define PG8_LDA(dst, b, h) do { _Pragma("unroll") for (int m = 0; m < 4; ++m) _Pragma("unroll") for (int k = 0; k < 2; ++k) dst[m][k] = *(const LAS bf16x8*)(lds + PG8_SA(b, h) + aoff + m * 2048 + k * 1024); } while (0)
; #define PG8_MMA(ai, bj, At, Bt) do { __builtin_amdgcn_s_setprio(1); _Pragma("unroll") for (int m = 0; m < 4; ++m) _Pragma("unroll") for (int n = 0; n < 2; ++n) _Pragma("unroll") for (int k = 0; k < 2; ++k) \
;         acc[ai][bj][m][n] = __builtin_amdgcn_mfma_f32_16x16x32_bf16(Bt[n][k], At[m][k], acc[ai][bj][m][n], 0, 0, 0); __builtin_amdgcn_s_setprio(0); } while (0)
; #define PG8_WAIT_V(n) asm volatile("s_waitcnt vmcnt(" #n ")" ::: "memory")
; #define PG8_WAIT_L(n) asm volatile("s_waitcnt lgkmcnt(" #n ")" ::: "memory")
; #define PG8_BAR __builtin_amdgcn_s_barrier()
; #define PG8_SCHED __builtin_amdgcn_sched_barrier(0)
; template <class Epi>
; DEVINL void gemm_phase(LAS unsigned char* lds, const Gemm g, const Order& S, const Epi& E) {
;     ...
;             PG8_BAR; PG8_WAIT_L(0); PG8_MMA(0, 1, At, B1); PG8_BAR;
;             PG8_LDA(At, 1, 1); PG8_STAGE(PG8_SA(1, 0), a3, voffA);
;             PG8_BAR; PG8_WAIT_L(0); PG8_MMA(1, 0, At, B0); PG8_BAR; PG8_SCHED;
;             PG8_STAGE(PG8_SB(1, 1), b3 + hstepB, voffB);
;             PG8_WAIT_V(6); PG8_BAR; PG8_MMA(1, 1, At, B1); PG8_BAR;
	s_waitcnt lgkmcnt(0)
	s_waitcnt lgkmcnt(0)
	v_mfma_f32_16x16x32_bf16 v[116:119], v[198:201], v[166:169], v[116:119]
	v_mfma_f32_16x16x32_bf16 v[116:119], v[202:205], v[170:173], v[116:119]
	v_mfma_f32_16x16x32_bf16 v[112:115], v[210:213], v[170:173], v[112:115]
	v_mfma_f32_16x16x32_bf16 v[112:115], v[206:209], v[166:169], v[112:115]
	v_mfma_f32_16x16x32_bf16 v[96:99], v[206:209], v[174:177], v[96:99]
	v_mfma_f32_16x16x32_bf16 v[96:99], v[210:213], v[178:181], v[96:99]
	v_mfma_f32_16x16x32_bf16 v[100:103], v[202:205], v[178:181], v[100:103]
	v_mfma_f32_16x16x32_bf16 v[100:103], v[198:201], v[174:177], v[100:103]
	v_mfma_f32_16x16x32_bf16 v[84:87], v[198:201], v[182:185], v[84:87]
	v_mfma_f32_16x16x32_bf16 v[84:87], v[202:205], v[186:189], v[84:87]
	v_mfma_f32_16x16x32_bf16 v[80:83], v[210:213], v[186:189], v[80:83]
	v_mfma_f32_16x16x32_bf16 v[80:83], v[206:209], v[182:185], v[80:83]
	v_mfma_f32_16x16x32_bf16 v[64:67], v[206:209], v[190:193], v[64:67]
	v_mfma_f32_16x16x32_bf16 v[64:67], v[210:213], v[194:197], v[64:67]
	v_mfma_f32_16x16x32_bf16 v[68:71], v[202:205], v[194:197], v[68:71]
	v_mfma_f32_16x16x32_bf16 v[68:71], v[198:201], v[190:193], v[68:71]
	s_mov_b32 m0, s50
	v_lshl_add_u64 v[218:219], v[222:223], 0, s[6:7]
	s_barrier
	ds_read_b128 v[166:169], v148 offset:49152
	ds_read_b128 v[170:173], v148 offset:50176
	ds_read_b128 v[174:177], v148 offset:51200
	ds_read_b128 v[178:181], v148 offset:52224
	ds_read_b128 v[182:185], v148 offset:53248
	ds_read_b128 v[186:189], v148 offset:54272
	ds_read_b128 v[190:193], v148 offset:55296
	ds_read_b128 v[194:197], v148 offset:56320
	global_load_lds_dwordx4 v[218:219], off
	v_lshl_add_u64 v[218:219], v[224:225], 0, s[6:7]
	s_mov_b32 m0, s51
	s_nop 0
	global_load_lds_dwordx4 v[218:219], off
	s_barrier
	s_waitcnt lgkmcnt(0)
	s_waitcnt lgkmcnt(0)
	v_mfma_f32_16x16x32_bf16 v[60:63], v[150:153], v[166:169], v[60:63]
	v_mfma_f32_16x16x32_bf16 v[60:63], v[154:157], v[170:173], v[60:63]
	v_mfma_f32_16x16x32_bf16 v[56:59], v[162:165], v[170:173], v[56:59]
	v_mfma_f32_16x16x32_bf16 v[56:59], v[158:161], v[166:169], v[56:59]
	v_mfma_f32_16x16x32_bf16 v[40:43], v[158:161], v[174:177], v[40:43]
	v_mfma_f32_16x16x32_bf16 v[40:43], v[162:165], v[178:181], v[40:43]
	v_mfma_f32_16x16x32_bf16 v[44:47], v[154:157], v[178:181], v[44:47]
	v_mfma_f32_16x16x32_bf16 v[44:47], v[150:153], v[174:177], v[44:47]
	v_mfma_f32_16x16x32_bf16 v[28:31], v[150:153], v[182:185], v[28:31]
	v_mfma_f32_16x16x32_bf16 v[28:31], v[154:157], v[186:189], v[28:31]
	v_mfma_f32_16x16x32_bf16 v[24:27], v[162:165], v[186:189], v[24:27]
	v_mfma_f32_16x16x32_bf16 v[24:27], v[158:161], v[182:185], v[24:27]
	v_mfma_f32_16x16x32_bf16 v[8:11], v[158:161], v[190:193], v[8:11]
	v_mfma_f32_16x16x32_bf16 v[8:11], v[162:165], v[194:197], v[8:11]
	v_mfma_f32_16x16x32_bf16 v[12:15], v[154:157], v[194:197], v[12:15]
	v_mfma_f32_16x16x32_bf16 v[12:15], v[150:153], v[190:193], v[12:15]
	s_barrier
	s_add_u32 s38, s38, 0x40080
	s_addc_u32 s39, s39, 0
	s_add_i32 s40, s40, s45
	v_lshl_add_u64 v[150:151], s[38:39], 0, v[130:131]
	s_mov_b32 m0, s40
	s_nop 0
	global_load_lds_dwordx4 v[150:151], off
	v_lshl_add_u64 v[150:151], s[38:39], 0, v[134:135]
	s_add_i32 m0, s40, 0x2000
	s_nop 0
	global_load_lds_dwordx4 v[150:151], off
	s_waitcnt vmcnt(6)
	s_barrier
	v_mfma_f32_16x16x32_bf16 v[52:55], v[198:201], v[166:169], v[52:55]
	v_mfma_f32_16x16x32_bf16 v[52:55], v[202:205], v[170:173], v[52:55]
	v_mfma_f32_16x16x32_bf16 v[48:51], v[210:213], v[170:173], v[48:51]
	v_mfma_f32_16x16x32_bf16 v[48:51], v[206:209], v[166:169], v[48:51]
	v_mfma_f32_16x16x32_bf16 v[32:35], v[206:209], v[174:177], v[32:35]
	v_mfma_f32_16x16x32_bf16 v[32:35], v[210:213], v[178:181], v[32:35]
	v_mfma_f32_16x16x32_bf16 v[36:39], v[202:205], v[178:181], v[36:39]
	v_mfma_f32_16x16x32_bf16 v[36:39], v[198:201], v[174:177], v[36:39]
	v_mfma_f32_16x16x32_bf16 v[20:23], v[198:201], v[182:185], v[20:23]
	v_mfma_f32_16x16x32_bf16 v[20:23], v[202:205], v[186:189], v[20:23]
	v_mfma_f32_16x16x32_bf16 v[16:19], v[210:213], v[186:189], v[16:19]
	v_mfma_f32_16x16x32_bf16 v[16:19], v[206:209], v[182:185], v[16:19]
	v_mfma_f32_16x16x32_bf16 v[0:3], v[206:209], v[190:193], v[0:3]
	v_mfma_f32_16x16x32_bf16 v[0:3], v[210:213], v[194:197], v[0:3]
	v_mfma_f32_16x16x32_bf16 v[4:7], v[202:205], v[194:197], v[4:7]
	v_mfma_f32_16x16x32_bf16 v[4:7], v[198:201], v[190:193], v[4:7]
	s_add_u32 s2, s2, 0x100
	s_addc_u32 s3, s3, 0
	s_add_u32 s67, s67, 0x100
	s_addc_u32 s68, s68, 0
	s_cmp_ge_i32 s69, s49
	s_mov_b32 s38, s69
	s_barrier
	s_cbranch_scc0 .LBB0_1623
	s_branch .LBB0_1614

; #define PG8_STAGE(bufoff, gbase, voff) do { _Pragma("unroll") for (int _i = 0; _i < 2; ++_i) \
;         __builtin_amdgcn_global_load_lds((const unsigned*)((const char*)(gbase) + (voff)[_i]), (LAS unsigned*)(lds + (bufoff) + ldsw + _i * 8192), 16, 0, 0); } while (0)
; #define PG8_LDA(dst, b, h) do { _Pragma("unroll") for (int m = 0; m < 4; ++m) _Pragma("unroll") for (int k = 0; k < 2; ++k) dst[m][k] = *(const LAS bf16x8*)(lds + PG8_SA(b, h) + aoff + m * 2048 + k * 1024); } while (0)
; #define PG8_LDB(dst, b, h) do { _Pragma("unroll") for (int n = 0; n < 2; ++n) _Pragma("unroll") for (int k = 0; k < 2; ++k) dst[n][k] = *(const LAS bf16x8*)(lds + PG8_SB(b, h) + boff + n * 2048 + k * 1024); } while (0)
; #define PG8_MMA(ai, bj, At, Bt) do { __builtin_amdgcn_s_setprio(1); _Pragma("unroll") for (int m = 0; m < 4; ++m) _Pragma("unroll") for (int n = 0; n < 2; ++n) _Pragma("unroll") for (int k = 0; k < 2; ++k) \
;         acc[ai][bj][m][n] = __builtin_amdgcn_mfma_f32_16x16x32_bf16(Bt[n][k], At[m][k], acc[ai][bj][m][n], 0, 0, 0); __builtin_amdgcn_s_setprio(0); } while (0)
; #define PG8_WAIT_L(n) asm volatile("s_waitcnt lgkmcnt(" #n ")" ::: "memory")
; #define PG8_BAR __builtin_amdgcn_s_barrier()
; #define PG8_SCHED __builtin_amdgcn_sched_barrier(0)
; template <class Epi>
; DEVINL void gemm_phase(LAS unsigned char* lds, const Gemm g, const Order& S, const Epi& E) {
;     ...
;             const bool last = (t == nt - 2);
;             const char* a1 = cA + (size_t)(t + 1) * kstep;
;             const char* a2 = last ? nA : cA + (size_t)(t + 2) * kstep; const char* b2 = last ? nB : cB + (size_t)(t + 2) * kstep;
;             const char* a3 = a2 + kstep; const char* b3 = b2 + kstep;
;             PG8_LDB(B0, 0, 0); PG8_SCHED; PG8_LDA(At, 0, 0); PG8_STAGE(PG8_SA(1, 1), a1 + hstepA, voffA);
;             PG8_WAIT_L(8); PG8_BAR; PG8_WAIT_L(0); PG8_MMA(0, 0, At, B0); PG8_BAR; PG8_SCHED;
;             PG8_LDB(B1, 0, 1); PG8_STAGE(PG8_SB(0, 0), b2, voffB);
;             PG8_BAR; PG8_WAIT_L(0); PG8_MMA(0, 1, At, B1); PG8_BAR;
;             PG8_LDA(At, 0, 1); PG8_STAGE(PG8_SA(0, 0), a2, voffA);
;             PG8_BAR; PG8_WAIT_L(0); PG8_MMA(1, 0, At, B0); PG8_BAR; PG8_SCHED;
.LBB0_1775:
	ds_read_b128 v[152:155], v149
	ds_read_b128 v[156:159], v149 offset:1024
	ds_read_b128 v[160:163], v149 offset:2048
	ds_read_b128 v[164:167], v149 offset:3072
	s_add_i32 s55, s26, 2
	s_add_u32 s27, s24, 0xfff80080
	s_addc_u32 s28, s25, -1
	s_cmp_eq_u32 s44, s26
	s_cselect_b32 s26, s52, s53
	s_cselect_b32 s29, s9, s28
	s_cselect_b32 s28, s11, s27
	s_cselect_b32 s27, s51, s54
	v_lshl_add_u64 v[144:145], s[24:25], 0, v[136:137]
	s_add_i32 m0, s17, 0xc000
	ds_read_b128 v[168:171], v150
	ds_read_b128 v[172:175], v150 offset:1024
	ds_read_b128 v[176:179], v150 offset:2048
	ds_read_b128 v[180:183], v150 offset:3072
	ds_read_b128 v[184:187], v150 offset:4096
	ds_read_b128 v[188:191], v150 offset:5120
	ds_read_b128 v[192:195], v150 offset:6144
	ds_read_b128 v[196:199], v150 offset:7168
	global_load_lds_dwordx4 v[144:145], off
	v_lshl_add_u64 v[144:145], s[24:25], 0, v[138:139]
	s_add_i32 m0, s17, 0xe000
	s_nop 0
	global_load_lds_dwordx4 v[144:145], off
	s_waitcnt lgkmcnt(8)
	s_barrier
	s_waitcnt lgkmcnt(0)
	s_waitcnt lgkmcnt(0)
	v_mfma_f32_16x16x32_bf16 v[124:127], v[152:155], v[168:171], v[124:127]
	v_mfma_f32_16x16x32_bf16 v[124:127], v[156:159], v[172:175], v[124:127]
	v_mfma_f32_16x16x32_bf16 v[116:119], v[164:167], v[172:175], v[116:119]
	v_mfma_f32_16x16x32_bf16 v[116:119], v[160:163], v[168:171], v[116:119]
	v_mfma_f32_16x16x32_bf16 v[100:103], v[160:163], v[176:179], v[100:103]
	v_mfma_f32_16x16x32_bf16 v[100:103], v[164:167], v[180:183], v[100:103]
	v_mfma_f32_16x16x32_bf16 v[108:111], v[156:159], v[180:183], v[108:111]
	v_mfma_f32_16x16x32_bf16 v[108:111], v[152:155], v[176:179], v[108:111]
	v_mfma_f32_16x16x32_bf16 v[92:95], v[152:155], v[184:187], v[92:95]
	v_mfma_f32_16x16x32_bf16 v[92:95], v[156:159], v[188:191], v[92:95]
	v_mfma_f32_16x16x32_bf16 v[84:87], v[164:167], v[188:191], v[84:87]
	v_mfma_f32_16x16x32_bf16 v[84:87], v[160:163], v[184:187], v[84:87]
	v_mfma_f32_16x16x32_bf16 v[68:71], v[160:163], v[192:195], v[68:71]
	v_mfma_f32_16x16x32_bf16 v[68:71], v[164:167], v[196:199], v[68:71]
	v_mfma_f32_16x16x32_bf16 v[76:79], v[156:159], v[196:199], v[76:79]
	v_mfma_f32_16x16x32_bf16 v[76:79], v[152:155], v[192:195], v[76:79]
	s_barrier
	s_add_i32 s56, s47, s30
	v_lshl_add_u64 v[144:145], s[26:27], 0, v[132:133]
	s_mov_b32 m0, s56
	ds_read_b128 v[200:203], v151
	ds_read_b128 v[204:207], v151 offset:1024
	ds_read_b128 v[208:211], v151 offset:2048
	ds_read_b128 v[218:221], v151 offset:3072
	global_load_lds_dwordx4 v[144:145], off
	v_lshl_add_u64 v[212:213], s[26:27], 0, v[128:129]
	s_add_i32 m0, s56, 0x2000
	s_nop 0
	global_load_lds_dwordx4 v[212:213], off
	s_barrier
	s_waitcnt lgkmcnt(0)
	s_waitcnt lgkmcnt(0)
	v_mfma_f32_16x16x32_bf16 v[120:123], v[200:203], v[168:171], v[120:123]
	v_mfma_f32_16x16x32_bf16 v[120:123], v[204:207], v[172:175], v[120:123]
	v_mfma_f32_16x16x32_bf16 v[112:115], v[218:221], v[172:175], v[112:115]
	v_mfma_f32_16x16x32_bf16 v[112:115], v[208:211], v[168:171], v[112:115]
	v_mfma_f32_16x16x32_bf16 v[96:99], v[208:211], v[176:179], v[96:99]
	v_mfma_f32_16x16x32_bf16 v[96:99], v[218:221], v[180:183], v[96:99]
	v_mfma_f32_16x16x32_bf16 v[104:107], v[204:207], v[180:183], v[104:107]
	v_mfma_f32_16x16x32_bf16 v[104:107], v[200:203], v[176:179], v[104:107]
	v_mfma_f32_16x16x32_bf16 v[88:91], v[200:203], v[184:187], v[88:91]
	v_mfma_f32_16x16x32_bf16 v[88:91], v[204:207], v[188:191], v[88:91]
	v_mfma_f32_16x16x32_bf16 v[80:83], v[218:221], v[188:191], v[80:83]
	v_mfma_f32_16x16x32_bf16 v[80:83], v[208:211], v[184:187], v[80:83]
	v_mfma_f32_16x16x32_bf16 v[64:67], v[208:211], v[192:195], v[64:67]
	v_mfma_f32_16x16x32_bf16 v[64:67], v[218:221], v[196:199], v[64:67]
	v_mfma_f32_16x16x32_bf16 v[72:75], v[204:207], v[196:199], v[72:75]
	v_mfma_f32_16x16x32_bf16 v[72:75], v[200:203], v[192:195], v[72:75]
	s_mov_b32 m0, s17
	v_lshl_add_u64 v[222:223], s[28:29], 0, v[134:135]
	s_barrier
	ds_read_b128 v[168:171], v150 offset:16384
	ds_read_b128 v[172:175], v150 offset:17408
	ds_read_b128 v[176:179], v150 offset:18432
	ds_read_b128 v[180:183], v150 offset:19456
	ds_read_b128 v[184:187], v150 offset:20480
	ds_read_b128 v[188:191], v150 offset:21504
	ds_read_b128 v[192:195], v150 offset:22528
	ds_read_b128 v[196:199], v150 offset:23552
	global_load_lds_dwordx4 v[222:223], off
	v_lshl_add_u64 v[224:225], s[28:29], 0, v[130:131]
	s_mov_b32 m0, s37
	s_nop 0
	global_load_lds_dwordx4 v[224:225], off
	s_barrier
	s_waitcnt lgkmcnt(0)
	s_waitcnt lgkmcnt(0)
	v_mfma_f32_16x16x32_bf16 v[60:63], v[152:155], v[168:171], v[60:63]
	v_mfma_f32_16x16x32_bf16 v[60:63], v[156:159], v[172:175], v[60:63]
	v_mfma_f32_16x16x32_bf16 v[52:55], v[164:167], v[172:175], v[52:55]
	v_mfma_f32_16x16x32_bf16 v[52:55], v[160:163], v[168:171], v[52:55]
	v_mfma_f32_16x16x32_bf16 v[36:39], v[160:163], v[176:179], v[36:39]
	v_mfma_f32_16x16x32_bf16 v[36:39], v[164:167], v[180:183], v[36:39]
	v_mfma_f32_16x16x32_bf16 v[44:47], v[156:159], v[180:183], v[44:47]
	v_mfma_f32_16x16x32_bf16 v[44:47], v[152:155], v[176:179], v[44:47]
	v_mfma_f32_16x16x32_bf16 v[28:31], v[152:155], v[184:187], v[28:31]
	v_mfma_f32_16x16x32_bf16 v[28:31], v[156:159], v[188:191], v[28:31]
	v_mfma_f32_16x16x32_bf16 v[20:23], v[164:167], v[188:191], v[20:23]
	v_mfma_f32_16x16x32_bf16 v[20:23], v[160:163], v[184:187], v[20:23]
	v_mfma_f32_16x16x32_bf16 v[4:7], v[160:163], v[192:195], v[4:7]
	v_mfma_f32_16x16x32_bf16 v[4:7], v[164:167], v[196:199], v[4:7]
	v_mfma_f32_16x16x32_bf16 v[12:15], v[156:159], v[196:199], v[12:15]
	v_mfma_f32_16x16x32_bf16 v[12:15], v[152:155], v[192:195], v[12:15]
	s_barrier
; #define PG8_STAGE(bufoff, gbase, voff) do { _Pragma("unroll") for (int _i = 0; _i < 2; ++_i) \
;         __builtin_amdgcn_global_load_lds((const unsigned*)((const char*)(gbase) + (voff)[_i]), (LAS unsigned*)(lds + (bufoff) + ldsw + _i * 8192), 16, 0, 0); } while (0)
; #define PG8_LDA(dst, b, h) do { _Pragma("unroll") for (int m = 0; m < 4; ++m) _Pragma("unroll") for (int k = 0; k < 2; ++k) dst[m][k] = *(const LAS bf16x8*)(lds + PG8_SA(b, h) + aoff + m * 2048 + k * 1024); } while (0)
; #define PG8_LDB(dst, b, h) do { _Pragma("unroll") for (int n = 0; n < 2; ++n) _Pragma("unroll") for (int k = 0; k < 2; ++k) dst[n][k] = *(const LAS bf16x8*)(lds + PG8_SB(b, h) + boff + n * 2048 + k * 1024); } while (0)
; #define PG8_MMA(ai, bj, At, Bt) do { __builtin_amdgcn_s_setprio(1); _Pragma("unroll") for (int m = 0; m < 4; ++m) _Pragma("unroll") for (int n = 0; n < 2; ++n) _Pragma("unroll") for (int k = 0; k < 2; ++k) \
;         acc[ai][bj][m][n] = __builtin_amdgcn_mfma_f32_16x16x32_bf16(Bt[n][k], At[m][k], acc[ai][bj][m][n], 0, 0, 0); __builtin_amdgcn_s_setprio(0); } while (0)
; #define PG8_WAIT_V(n) asm volatile("s_waitcnt vmcnt(" #n ")" ::: "memory")
; #define PG8_WAIT_L(n) asm volatile("s_waitcnt lgkmcnt(" #n ")" ::: "memory")
; #define PG8_BAR __builtin_amdgcn_s_barrier()
; #define PG8_SCHED __builtin_amdgcn_sched_barrier(0)
; template <class Epi>
; DEVINL void gemm_phase(LAS unsigned char* lds, const Gemm g, const Order& S, const Epi& E) {
;     ...
;             PG8_STAGE(PG8_SB(0, 1), b2 + hstepB, voffB);
;             PG8_WAIT_V(6); PG8_BAR; PG8_MMA(1, 1, At, B1); PG8_BAR;
;             PG8_LDB(B0, 1, 0); PG8_SCHED; PG8_LDA(At, 1, 0); PG8_STAGE(PG8_SA(0, 1), a2 + hstepA, voffA);
;             PG8_WAIT_L(8); PG8_BAR; PG8_WAIT_L(0); PG8_MMA(0, 0, At, B0); PG8_BAR; PG8_SCHED;
;             PG8_LDB(B1, 1, 1); PG8_STAGE(PG8_SB(1, 0), b3, voffB);
	s_add_u32 s56, s26, 0x80000
	s_addc_u32 s57, s27, 0
	s_add_i32 s58, s48, s30
	v_lshl_add_u64 v[152:153], s[56:57], 0, v[132:133]
	s_mov_b32 m0, s58
	s_nop 0
	global_load_lds_dwordx4 v[152:153], off
	v_lshl_add_u64 v[152:153], s[56:57], 0, v[128:129]
	s_add_i32 m0, s58, 0x2000
	s_nop 0
	global_load_lds_dwordx4 v[152:153], off
	s_waitcnt vmcnt(6)
	s_barrier
	v_mfma_f32_16x16x32_bf16 v[56:59], v[200:203], v[168:171], v[56:59]
	v_mfma_f32_16x16x32_bf16 v[56:59], v[204:207], v[172:175], v[56:59]
	v_mfma_f32_16x16x32_bf16 v[48:51], v[218:221], v[172:175], v[48:51]
	v_mfma_f32_16x16x32_bf16 v[48:51], v[208:211], v[168:171], v[48:51]
	v_mfma_f32_16x16x32_bf16 v[32:35], v[208:211], v[176:179], v[32:35]
	v_mfma_f32_16x16x32_bf16 v[32:35], v[218:221], v[180:183], v[32:35]
	v_mfma_f32_16x16x32_bf16 v[40:43], v[204:207], v[180:183], v[40:43]
	v_mfma_f32_16x16x32_bf16 v[40:43], v[200:203], v[176:179], v[40:43]
	v_mfma_f32_16x16x32_bf16 v[24:27], v[200:203], v[184:187], v[24:27]
	v_mfma_f32_16x16x32_bf16 v[24:27], v[204:207], v[188:191], v[24:27]
	v_mfma_f32_16x16x32_bf16 v[16:19], v[218:221], v[188:191], v[16:19]
	v_mfma_f32_16x16x32_bf16 v[16:19], v[208:211], v[184:187], v[16:19]
	v_mfma_f32_16x16x32_bf16 v[0:3], v[208:211], v[192:195], v[0:3]
	v_mfma_f32_16x16x32_bf16 v[0:3], v[218:221], v[196:199], v[0:3]
	v_mfma_f32_16x16x32_bf16 v[8:11], v[204:207], v[196:199], v[8:11]
	v_mfma_f32_16x16x32_bf16 v[8:11], v[200:203], v[192:195], v[8:11]
	s_add_i32 s56, 16, 0x18000
	v_add_u32_e32 v164, s56, v147
	s_barrier
	ds_read_b128 v[152:155], v164
	ds_read_b128 v[156:159], v164 offset:1024
	ds_read_b128 v[160:163], v164 offset:2048
	ds_read_b128 v[164:167], v164 offset:3072
	s_add_u32 s28, s28, 0x80000
	s_addc_u32 s29, s29, 0
	s_mov_b32 m0, s38
	v_lshl_add_u64 v[200:201], s[28:29], 0, v[134:135]
	ds_read_b128 v[168:171], v150 offset:32768
	ds_read_b128 v[172:175], v150 offset:33792
	ds_read_b128 v[176:179], v150 offset:34816
	ds_read_b128 v[180:183], v150 offset:35840
	ds_read_b128 v[184:187], v150 offset:36864
	ds_read_b128 v[188:191], v150 offset:37888
	ds_read_b128 v[192:195], v150 offset:38912
	ds_read_b128 v[196:199], v150 offset:39936
	global_load_lds_dwordx4 v[200:201], off
	v_lshl_add_u64 v[200:201], s[28:29], 0, v[130:131]
	s_mov_b32 m0, s39
	s_nop 0
	global_load_lds_dwordx4 v[200:201], off
	s_waitcnt lgkmcnt(8)
	s_barrier
	s_waitcnt lgkmcnt(0)
	s_waitcnt lgkmcnt(0)
	v_mfma_f32_16x16x32_bf16 v[124:127], v[152:155], v[168:171], v[124:127]
	v_mfma_f32_16x16x32_bf16 v[124:127], v[156:159], v[172:175], v[124:127]
	v_mfma_f32_16x16x32_bf16 v[116:119], v[164:167], v[172:175], v[116:119]
	v_mfma_f32_16x16x32_bf16 v[116:119], v[160:163], v[168:171], v[116:119]
	v_mfma_f32_16x16x32_bf16 v[100:103], v[160:163], v[176:179], v[100:103]
	v_mfma_f32_16x16x32_bf16 v[100:103], v[164:167], v[180:183], v[100:103]
	v_mfma_f32_16x16x32_bf16 v[108:111], v[156:159], v[180:183], v[108:111]
	v_mfma_f32_16x16x32_bf16 v[108:111], v[152:155], v[176:179], v[108:111]
	v_mfma_f32_16x16x32_bf16 v[92:95], v[152:155], v[184:187], v[92:95]
	v_mfma_f32_16x16x32_bf16 v[92:95], v[156:159], v[188:191], v[92:95]
	v_mfma_f32_16x16x32_bf16 v[84:87], v[164:167], v[188:191], v[84:87]
	v_mfma_f32_16x16x32_bf16 v[84:87], v[160:163], v[184:187], v[84:87]
	v_mfma_f32_16x16x32_bf16 v[68:71], v[160:163], v[192:195], v[68:71]
	v_mfma_f32_16x16x32_bf16 v[68:71], v[164:167], v[196:199], v[68:71]
	v_mfma_f32_16x16x32_bf16 v[76:79], v[156:159], v[196:199], v[76:79]
	v_mfma_f32_16x16x32_bf16 v[76:79], v[152:155], v[192:195], v[76:79]
	s_barrier
	s_add_i32 s28, 16, 0x1c000
	s_add_i32 s29, s56, s30
	v_add_u32_e32 v214, s28, v147
	v_lshl_add_u64 v[144:145], v[144:145], 0, s[6:7]
	s_mov_b32 m0, s29
	ds_read_b128 v[200:203], v214
	ds_read_b128 v[204:207], v214 offset:1024
	ds_read_b128 v[208:211], v214 offset:2048
	ds_read_b128 v[218:221], v214 offset:3072
	global_load_lds_dwordx4 v[144:145], off
	v_lshl_add_u64 v[144:145], v[212:213], 0, s[6:7]
	s_add_i32 m0, s29, 0x2000
	s_nop 0
	global_load_lds_dwordx4 v[144:145], off
	s_barrier
; #define PG8_STAGE(bufoff, gbase, voff) do { _Pragma("unroll") for (int _i = 0; _i < 2; ++_i) \
;         __builtin_amdgcn_global_load_lds((const unsigned*)((const char*)(gbase) + (voff)[_i]), (LAS unsigned*)(lds + (bufoff) + ldsw + _i * 8192), 16, 0, 0); } while (0)
; #define PG8_LDA(dst, b, h) do { _Pragma("unroll") for (int m = 0; m < 4; ++m) _Pragma("unroll") for (int k = 0; k < 2; ++k) dst[m][k] = *(const LAS bf16x8*)(lds + PG8_SA(b, h) + aoff + m * 2048 + k * 1024); } while (0)
; #define PG8_MMA(ai, bj, At, Bt) do { __builtin_amdgcn_s_setprio(1); _Pragma("unroll") for (int m = 0; m < 4; ++m) _Pragma("unroll") for (int n = 0; n < 2; ++n) _Pragma("unroll") for (int k = 0; k < 2; ++k) \
;         acc[ai][bj][m][n] = __builtin_amdgcn_mfma_f32_16x16x32_bf16(Bt[n][k], At[m][k], acc[ai][bj][m][n], 0, 0, 0); __builtin_amdgcn_s_setprio(0); } while (0)
; #define PG8_WAIT_V(n) asm volatile("s_waitcnt vmcnt(" #n ")" ::: "memory")
; #define PG8_WAIT_L(n) asm volatile("s_waitcnt lgkmcnt(" #n ")" ::: "memory")
; #define PG8_BAR __builtin_amdgcn_s_barrier()
; #define PG8_SCHED __builtin_amdgcn_sched_barrier(0)
; template <class Epi>
; DEVINL void gemm_phase(LAS unsigned char* lds, const Gemm g, const Order& S, const Epi& E) {
;     ...
;             PG8_BAR; PG8_WAIT_L(0); PG8_MMA(0, 1, At, B1); PG8_BAR;
;             PG8_LDA(At, 1, 1); PG8_STAGE(PG8_SA(1, 0), a3, voffA);
;             PG8_BAR; PG8_WAIT_L(0); PG8_MMA(1, 0, At, B0); PG8_BAR; PG8_SCHED;
;             PG8_STAGE(PG8_SB(1, 1), b3 + hstepB, voffB);
;             PG8_WAIT_V(6); PG8_BAR; PG8_MMA(1, 1, At, B1); PG8_BAR;
	s_waitcnt lgkmcnt(0)
	s_waitcnt lgkmcnt(0)
	v_mfma_f32_16x16x32_bf16 v[120:123], v[200:203], v[168:171], v[120:123]
	v_mfma_f32_16x16x32_bf16 v[120:123], v[204:207], v[172:175], v[120:123]
	v_mfma_f32_16x16x32_bf16 v[112:115], v[218:221], v[172:175], v[112:115]
	v_mfma_f32_16x16x32_bf16 v[112:115], v[208:211], v[168:171], v[112:115]
	v_mfma_f32_16x16x32_bf16 v[96:99], v[208:211], v[176:179], v[96:99]
	v_mfma_f32_16x16x32_bf16 v[96:99], v[218:221], v[180:183], v[96:99]
	v_mfma_f32_16x16x32_bf16 v[104:107], v[204:207], v[180:183], v[104:107]
	v_mfma_f32_16x16x32_bf16 v[104:107], v[200:203], v[176:179], v[104:107]
	v_mfma_f32_16x16x32_bf16 v[88:91], v[200:203], v[184:187], v[88:91]
	v_mfma_f32_16x16x32_bf16 v[88:91], v[204:207], v[188:191], v[88:91]
	v_mfma_f32_16x16x32_bf16 v[80:83], v[218:221], v[188:191], v[80:83]
	v_mfma_f32_16x16x32_bf16 v[80:83], v[208:211], v[184:187], v[80:83]
	v_mfma_f32_16x16x32_bf16 v[64:67], v[208:211], v[192:195], v[64:67]
	v_mfma_f32_16x16x32_bf16 v[64:67], v[218:221], v[196:199], v[64:67]
	v_mfma_f32_16x16x32_bf16 v[72:75], v[204:207], v[196:199], v[72:75]
	v_mfma_f32_16x16x32_bf16 v[72:75], v[200:203], v[192:195], v[72:75]
	s_mov_b32 m0, s42
	v_lshl_add_u64 v[144:145], v[222:223], 0, s[6:7]
	s_barrier
	ds_read_b128 v[168:171], v150 offset:49152
	ds_read_b128 v[172:175], v150 offset:50176
	ds_read_b128 v[176:179], v150 offset:51200
	ds_read_b128 v[180:183], v150 offset:52224
	ds_read_b128 v[184:187], v150 offset:53248
	ds_read_b128 v[188:191], v150 offset:54272
	ds_read_b128 v[192:195], v150 offset:55296
	ds_read_b128 v[196:199], v150 offset:56320
	global_load_lds_dwordx4 v[144:145], off
	v_lshl_add_u64 v[144:145], v[224:225], 0, s[6:7]
	s_mov_b32 m0, s43
	s_nop 0
	global_load_lds_dwordx4 v[144:145], off
	s_barrier
	s_waitcnt lgkmcnt(0)
	s_waitcnt lgkmcnt(0)
	v_mfma_f32_16x16x32_bf16 v[60:63], v[152:155], v[168:171], v[60:63]
	v_mfma_f32_16x16x32_bf16 v[60:63], v[156:159], v[172:175], v[60:63]
	v_mfma_f32_16x16x32_bf16 v[52:55], v[164:167], v[172:175], v[52:55]
	v_mfma_f32_16x16x32_bf16 v[52:55], v[160:163], v[168:171], v[52:55]
	v_mfma_f32_16x16x32_bf16 v[36:39], v[160:163], v[176:179], v[36:39]
	v_mfma_f32_16x16x32_bf16 v[36:39], v[164:167], v[180:183], v[36:39]
	v_mfma_f32_16x16x32_bf16 v[44:47], v[156:159], v[180:183], v[44:47]
	v_mfma_f32_16x16x32_bf16 v[44:47], v[152:155], v[176:179], v[44:47]
	v_mfma_f32_16x16x32_bf16 v[28:31], v[152:155], v[184:187], v[28:31]
	v_mfma_f32_16x16x32_bf16 v[28:31], v[156:159], v[188:191], v[28:31]
	v_mfma_f32_16x16x32_bf16 v[20:23], v[164:167], v[188:191], v[20:23]
	v_mfma_f32_16x16x32_bf16 v[20:23], v[160:163], v[184:187], v[20:23]
	v_mfma_f32_16x16x32_bf16 v[4:7], v[160:163], v[192:195], v[4:7]
	v_mfma_f32_16x16x32_bf16 v[4:7], v[164:167], v[196:199], v[4:7]
	v_mfma_f32_16x16x32_bf16 v[12:15], v[156:159], v[196:199], v[12:15]
	v_mfma_f32_16x16x32_bf16 v[12:15], v[152:155], v[192:195], v[12:15]
	s_barrier
	s_add_u32 s26, s26, 0x80080
	s_addc_u32 s27, s27, 0
	s_add_i32 s28, s28, s30
	v_lshl_add_u64 v[144:145], s[26:27], 0, v[132:133]
	s_mov_b32 m0, s28
	s_nop 0
	global_load_lds_dwordx4 v[144:145], off
	v_lshl_add_u64 v[144:145], s[26:27], 0, v[128:129]
	s_add_i32 m0, s28, 0x2000
	s_nop 0
	global_load_lds_dwordx4 v[144:145], off
	s_waitcnt vmcnt(6)
	s_barrier
	v_mfma_f32_16x16x32_bf16 v[56:59], v[200:203], v[168:171], v[56:59]
	v_mfma_f32_16x16x32_bf16 v[56:59], v[204:207], v[172:175], v[56:59]
	v_mfma_f32_16x16x32_bf16 v[48:51], v[218:221], v[172:175], v[48:51]
	v_mfma_f32_16x16x32_bf16 v[48:51], v[208:211], v[168:171], v[48:51]
	v_mfma_f32_16x16x32_bf16 v[32:35], v[208:211], v[176:179], v[32:35]
	v_mfma_f32_16x16x32_bf16 v[32:35], v[218:221], v[180:183], v[32:35]
	v_mfma_f32_16x16x32_bf16 v[40:43], v[204:207], v[180:183], v[40:43]
	v_mfma_f32_16x16x32_bf16 v[40:43], v[200:203], v[176:179], v[40:43]
	v_mfma_f32_16x16x32_bf16 v[24:27], v[200:203], v[184:187], v[24:27]
	v_mfma_f32_16x16x32_bf16 v[24:27], v[204:207], v[188:191], v[24:27]
	v_mfma_f32_16x16x32_bf16 v[16:19], v[218:221], v[188:191], v[16:19]
	v_mfma_f32_16x16x32_bf16 v[16:19], v[208:211], v[184:187], v[16:19]
	v_mfma_f32_16x16x32_bf16 v[0:3], v[208:211], v[192:195], v[0:3]
	v_mfma_f32_16x16x32_bf16 v[0:3], v[218:221], v[196:199], v[0:3]
	v_mfma_f32_16x16x32_bf16 v[8:11], v[204:207], v[196:199], v[8:11]
	v_mfma_f32_16x16x32_bf16 v[8:11], v[200:203], v[192:195], v[8:11]
	s_add_u32 s24, s24, 0x100
	s_addc_u32 s25, s25, 0
	s_add_u32 s53, s53, 0x100
	s_addc_u32 s54, s54, 0
	s_cmp_ge_i32 s55, s41
	s_mov_b32 s26, s55
	s_barrier
	s_cbranch_scc0 .LBB0_1775
	s_branch .LBB0_1770

; #define PG8_STAGE(bufoff, gbase, voff) do { _Pragma("unroll") for (int _i = 0; _i < 2; ++_i) \
;         __builtin_amdgcn_global_load_lds((const unsigned*)((const char*)(gbase) + (voff)[_i]), (LAS unsigned*)(lds + (bufoff) + ldsw + _i * 8192), 16, 0, 0); } while (0)
; #define PG8_LDA(dst, b, h) do { _Pragma("unroll") for (int m = 0; m < 4; ++m) _Pragma("unroll") for (int k = 0; k < 2; ++k) dst[m][k] = *(const LAS bf16x8*)(lds + PG8_SA(b, h) + aoff + m * 2048 + k * 1024); } while (0)
; #define PG8_LDB(dst, b, h) do { _Pragma("unroll") for (int n = 0; n < 2; ++n) _Pragma("unroll") for (int k = 0; k < 2; ++k) dst[n][k] = *(const LAS bf16x8*)(lds + PG8_SB(b, h) + boff + n * 2048 + k * 1024); } while (0)
; #define PG8_MMA(ai, bj, At, Bt) do { __builtin_amdgcn_s_setprio(1); _Pragma("unroll") for (int m = 0; m < 4; ++m) _Pragma("unroll") for (int n = 0; n < 2; ++n) _Pragma("unroll") for (int k = 0; k < 2; ++k) \
;         acc[ai][bj][m][n] = __builtin_amdgcn_mfma_f32_16x16x32_bf16(Bt[n][k], At[m][k], acc[ai][bj][m][n], 0, 0, 0); __builtin_amdgcn_s_setprio(0); } while (0)
; #define PG8_WAIT_L(n) asm volatile("s_waitcnt lgkmcnt(" #n ")" ::: "memory")
; #define PG8_BAR __builtin_amdgcn_s_barrier()
; #define PG8_SCHED __builtin_amdgcn_sched_barrier(0)
; template <class Epi>
; DEVINL void gemm_phase(LAS unsigned char* lds, const Gemm g, const Order& S, const Epi& E) {
;     ...
;             const bool last = (t == nt - 2);
;             const char* a1 = cA + (size_t)(t + 1) * kstep;
;             const char* a2 = last ? nA : cA + (size_t)(t + 2) * kstep; const char* b2 = last ? nB : cB + (size_t)(t + 2) * kstep;
;             const char* a3 = a2 + kstep; const char* b3 = b2 + kstep;
;             PG8_LDB(B0, 0, 0); PG8_SCHED; PG8_LDA(At, 0, 0); PG8_STAGE(PG8_SA(1, 1), a1 + hstepA, voffA);
;             PG8_WAIT_L(8); PG8_BAR; PG8_WAIT_L(0); PG8_MMA(0, 0, At, B0); PG8_BAR; PG8_SCHED;
;             PG8_LDB(B1, 0, 1); PG8_STAGE(PG8_SB(0, 0), b2, voffB);
;             PG8_BAR; PG8_WAIT_L(0); PG8_MMA(0, 1, At, B1); PG8_BAR;
;             PG8_LDA(At, 0, 1); PG8_STAGE(PG8_SA(0, 0), a2, voffA);
;             PG8_BAR; PG8_WAIT_L(0); PG8_MMA(1, 0, At, B0); PG8_BAR; PG8_SCHED;
.LBB0_1852:
	ds_read_b128 v[150:153], v147
	ds_read_b128 v[154:157], v147 offset:1024
	ds_read_b128 v[158:161], v147 offset:2048
	ds_read_b128 v[162:165], v147 offset:3072
	s_add_i32 s61, s28, 2
	s_add_u32 s26, s24, 0x100
	s_addc_u32 s27, s25, 0
	s_cmp_eq_u32 s45, s28
	s_cselect_b32 s28, s4, s59
	s_cselect_b32 s31, s3, s27
	s_cselect_b32 s30, s2, s26
	s_cselect_b32 s29, s5, s60
	v_lshl_add_u64 v[198:199], s[24:25], 0, v[136:137]
	s_add_i32 m0, s38, 0xc000
	ds_read_b128 v[166:169], v148
	ds_read_b128 v[170:173], v148 offset:1024
	ds_read_b128 v[174:177], v148 offset:2048
	ds_read_b128 v[178:181], v148 offset:3072
	ds_read_b128 v[182:185], v148 offset:4096
	ds_read_b128 v[186:189], v148 offset:5120
	ds_read_b128 v[190:193], v148 offset:6144
	ds_read_b128 v[194:197], v148 offset:7168
	global_load_lds_dwordx4 v[198:199], off
	v_lshl_add_u64 v[198:199], s[24:25], 0, v[138:139]
	s_add_i32 m0, s38, 0xe000
	s_nop 0
	global_load_lds_dwordx4 v[198:199], off
	s_waitcnt lgkmcnt(8)
	s_barrier
	s_waitcnt lgkmcnt(0)
	s_waitcnt lgkmcnt(0)
	v_mfma_f32_16x16x32_bf16 v[120:123], v[150:153], v[166:169], v[120:123]
	v_mfma_f32_16x16x32_bf16 v[120:123], v[154:157], v[170:173], v[120:123]
	v_mfma_f32_16x16x32_bf16 v[124:127], v[162:165], v[170:173], v[124:127]
	v_mfma_f32_16x16x32_bf16 v[124:127], v[158:161], v[166:169], v[124:127]
	v_mfma_f32_16x16x32_bf16 v[104:107], v[158:161], v[174:177], v[104:107]
	v_mfma_f32_16x16x32_bf16 v[104:107], v[162:165], v[178:181], v[104:107]
	v_mfma_f32_16x16x32_bf16 v[108:111], v[154:157], v[178:181], v[108:111]
	v_mfma_f32_16x16x32_bf16 v[108:111], v[150:153], v[174:177], v[108:111]
	v_mfma_f32_16x16x32_bf16 v[92:95], v[150:153], v[182:185], v[92:95]
	v_mfma_f32_16x16x32_bf16 v[92:95], v[154:157], v[186:189], v[92:95]
	v_mfma_f32_16x16x32_bf16 v[88:91], v[162:165], v[186:189], v[88:91]
	v_mfma_f32_16x16x32_bf16 v[88:91], v[158:161], v[182:185], v[88:91]
	v_mfma_f32_16x16x32_bf16 v[72:75], v[158:161], v[190:193], v[72:75]
	v_mfma_f32_16x16x32_bf16 v[72:75], v[162:165], v[194:197], v[72:75]
	v_mfma_f32_16x16x32_bf16 v[76:79], v[154:157], v[194:197], v[76:79]
	v_mfma_f32_16x16x32_bf16 v[76:79], v[150:153], v[190:193], v[76:79]
	s_barrier
	s_add_i32 s24, s49, s37
	v_lshl_add_u64 v[218:219], s[28:29], 0, v[130:131]
	s_mov_b32 m0, s24
	ds_read_b128 v[198:201], v149
	ds_read_b128 v[202:205], v149 offset:1024
	ds_read_b128 v[206:209], v149 offset:2048
	ds_read_b128 v[210:213], v149 offset:3072
	global_load_lds_dwordx4 v[218:219], off
	v_lshl_add_u64 v[220:221], s[28:29], 0, v[134:135]
	s_add_i32 m0, s24, 0x2000
	s_nop 0
	global_load_lds_dwordx4 v[220:221], off
	s_barrier
	s_waitcnt lgkmcnt(0)
	s_waitcnt lgkmcnt(0)
	v_mfma_f32_16x16x32_bf16 v[116:119], v[198:201], v[166:169], v[116:119]
	v_mfma_f32_16x16x32_bf16 v[116:119], v[202:205], v[170:173], v[116:119]
	v_mfma_f32_16x16x32_bf16 v[112:115], v[210:213], v[170:173], v[112:115]
	v_mfma_f32_16x16x32_bf16 v[112:115], v[206:209], v[166:169], v[112:115]
	v_mfma_f32_16x16x32_bf16 v[96:99], v[206:209], v[174:177], v[96:99]
	v_mfma_f32_16x16x32_bf16 v[96:99], v[210:213], v[178:181], v[96:99]
	v_mfma_f32_16x16x32_bf16 v[100:103], v[202:205], v[178:181], v[100:103]
	v_mfma_f32_16x16x32_bf16 v[100:103], v[198:201], v[174:177], v[100:103]
	v_mfma_f32_16x16x32_bf16 v[84:87], v[198:201], v[182:185], v[84:87]
	v_mfma_f32_16x16x32_bf16 v[84:87], v[202:205], v[186:189], v[84:87]
	v_mfma_f32_16x16x32_bf16 v[80:83], v[210:213], v[186:189], v[80:83]
	v_mfma_f32_16x16x32_bf16 v[80:83], v[206:209], v[182:185], v[80:83]
	v_mfma_f32_16x16x32_bf16 v[64:67], v[206:209], v[190:193], v[64:67]
	v_mfma_f32_16x16x32_bf16 v[64:67], v[210:213], v[194:197], v[64:67]
	v_mfma_f32_16x16x32_bf16 v[68:71], v[202:205], v[194:197], v[68:71]
	v_mfma_f32_16x16x32_bf16 v[68:71], v[198:201], v[190:193], v[68:71]
	s_mov_b32 m0, s38
	v_lshl_add_u64 v[222:223], s[30:31], 0, v[128:129]
	s_barrier
	ds_read_b128 v[166:169], v148 offset:16384
	ds_read_b128 v[170:173], v148 offset:17408
	ds_read_b128 v[174:177], v148 offset:18432
	ds_read_b128 v[178:181], v148 offset:19456
	ds_read_b128 v[182:185], v148 offset:20480
	ds_read_b128 v[186:189], v148 offset:21504
	ds_read_b128 v[190:193], v148 offset:22528
	ds_read_b128 v[194:197], v148 offset:23552
	global_load_lds_dwordx4 v[222:223], off
	v_lshl_add_u64 v[224:225], s[30:31], 0, v[132:133]
	s_mov_b32 m0, s39
	s_nop 0
	global_load_lds_dwordx4 v[224:225], off
	s_barrier
	s_waitcnt lgkmcnt(0)
	s_waitcnt lgkmcnt(0)
	v_mfma_f32_16x16x32_bf16 v[60:63], v[150:153], v[166:169], v[60:63]
	v_mfma_f32_16x16x32_bf16 v[60:63], v[154:157], v[170:173], v[60:63]
	v_mfma_f32_16x16x32_bf16 v[56:59], v[162:165], v[170:173], v[56:59]
	v_mfma_f32_16x16x32_bf16 v[56:59], v[158:161], v[166:169], v[56:59]
	v_mfma_f32_16x16x32_bf16 v[40:43], v[158:161], v[174:177], v[40:43]
	v_mfma_f32_16x16x32_bf16 v[40:43], v[162:165], v[178:181], v[40:43]
	v_mfma_f32_16x16x32_bf16 v[44:47], v[154:157], v[178:181], v[44:47]
	v_mfma_f32_16x16x32_bf16 v[44:47], v[150:153], v[174:177], v[44:47]
	v_mfma_f32_16x16x32_bf16 v[28:31], v[150:153], v[182:185], v[28:31]
	v_mfma_f32_16x16x32_bf16 v[28:31], v[154:157], v[186:189], v[28:31]
	v_mfma_f32_16x16x32_bf16 v[24:27], v[162:165], v[186:189], v[24:27]
	v_mfma_f32_16x16x32_bf16 v[24:27], v[158:161], v[182:185], v[24:27]
	v_mfma_f32_16x16x32_bf16 v[8:11], v[158:161], v[190:193], v[8:11]
	v_mfma_f32_16x16x32_bf16 v[8:11], v[162:165], v[194:197], v[8:11]
	v_mfma_f32_16x16x32_bf16 v[12:15], v[154:157], v[194:197], v[12:15]
	v_mfma_f32_16x16x32_bf16 v[12:15], v[150:153], v[190:193], v[12:15]
	s_barrier
; #define PG8_STAGE(bufoff, gbase, voff) do { _Pragma("unroll") for (int _i = 0; _i < 2; ++_i) \
;         __builtin_amdgcn_global_load_lds((const unsigned*)((const char*)(gbase) + (voff)[_i]), (LAS unsigned*)(lds + (bufoff) + ldsw + _i * 8192), 16, 0, 0); } while (0)
; #define PG8_LDA(dst, b, h) do { _Pragma("unroll") for (int m = 0; m < 4; ++m) _Pragma("unroll") for (int k = 0; k < 2; ++k) dst[m][k] = *(const LAS bf16x8*)(lds + PG8_SA(b, h) + aoff + m * 2048 + k * 1024); } while (0)
; #define PG8_LDB(dst, b, h) do { _Pragma("unroll") for (int n = 0; n < 2; ++n) _Pragma("unroll") for (int k = 0; k < 2; ++k) dst[n][k] = *(const LAS bf16x8*)(lds + PG8_SB(b, h) + boff + n * 2048 + k * 1024); } while (0)
; #define PG8_MMA(ai, bj, At, Bt) do { __builtin_amdgcn_s_setprio(1); _Pragma("unroll") for (int m = 0; m < 4; ++m) _Pragma("unroll") for (int n = 0; n < 2; ++n) _Pragma("unroll") for (int k = 0; k < 2; ++k) \
;         acc[ai][bj][m][n] = __builtin_amdgcn_mfma_f32_16x16x32_bf16(Bt[n][k], At[m][k], acc[ai][bj][m][n], 0, 0, 0); __builtin_amdgcn_s_setprio(0); } while (0)
; #define PG8_WAIT_V(n) asm volatile("s_waitcnt vmcnt(" #n ")" ::: "memory")
; #define PG8_WAIT_L(n) asm volatile("s_waitcnt lgkmcnt(" #n ")" ::: "memory")
; #define PG8_BAR __builtin_amdgcn_s_barrier()
; #define PG8_SCHED __builtin_amdgcn_sched_barrier(0)
; template <class Epi>
; DEVINL void gemm_phase(LAS unsigned char* lds, const Gemm g, const Order& S, const Epi& E) {
;     ...
;             PG8_STAGE(PG8_SB(0, 1), b2 + hstepB, voffB);
;             PG8_WAIT_V(6); PG8_BAR; PG8_MMA(1, 1, At, B1); PG8_BAR;
;             PG8_LDB(B0, 1, 0); PG8_SCHED; PG8_LDA(At, 1, 0); PG8_STAGE(PG8_SA(0, 1), a2 + hstepA, voffA);
;             PG8_WAIT_L(8); PG8_BAR; PG8_WAIT_L(0); PG8_MMA(0, 0, At, B0); PG8_BAR; PG8_SCHED;
;             PG8_LDB(B1, 1, 1); PG8_STAGE(PG8_SB(1, 0), b3, voffB);
	s_add_u32 s24, s28, 0x158000
	s_addc_u32 s25, s29, 0
	s_add_i32 s62, s50, s37
	v_lshl_add_u64 v[150:151], s[24:25], 0, v[130:131]
	s_mov_b32 m0, s62
	s_nop 0
	global_load_lds_dwordx4 v[150:151], off
	v_lshl_add_u64 v[150:151], s[24:25], 0, v[134:135]
	s_add_i32 m0, s62, 0x2000
	s_nop 0
	global_load_lds_dwordx4 v[150:151], off
	s_waitcnt vmcnt(6)
	s_barrier
	v_mfma_f32_16x16x32_bf16 v[52:55], v[198:201], v[166:169], v[52:55]
	v_mfma_f32_16x16x32_bf16 v[52:55], v[202:205], v[170:173], v[52:55]
	v_mfma_f32_16x16x32_bf16 v[48:51], v[210:213], v[170:173], v[48:51]
	v_mfma_f32_16x16x32_bf16 v[48:51], v[206:209], v[166:169], v[48:51]
	v_mfma_f32_16x16x32_bf16 v[32:35], v[206:209], v[174:177], v[32:35]
	v_mfma_f32_16x16x32_bf16 v[32:35], v[210:213], v[178:181], v[32:35]
	v_mfma_f32_16x16x32_bf16 v[36:39], v[202:205], v[178:181], v[36:39]
	v_mfma_f32_16x16x32_bf16 v[36:39], v[198:201], v[174:177], v[36:39]
	v_mfma_f32_16x16x32_bf16 v[20:23], v[198:201], v[182:185], v[20:23]
	v_mfma_f32_16x16x32_bf16 v[20:23], v[202:205], v[186:189], v[20:23]
	v_mfma_f32_16x16x32_bf16 v[16:19], v[210:213], v[186:189], v[16:19]
	v_mfma_f32_16x16x32_bf16 v[16:19], v[206:209], v[182:185], v[16:19]
	v_mfma_f32_16x16x32_bf16 v[0:3], v[206:209], v[190:193], v[0:3]
	v_mfma_f32_16x16x32_bf16 v[0:3], v[210:213], v[194:197], v[0:3]
	v_mfma_f32_16x16x32_bf16 v[4:7], v[202:205], v[194:197], v[4:7]
	v_mfma_f32_16x16x32_bf16 v[4:7], v[198:201], v[190:193], v[4:7]
	s_add_i32 s62, 16, 0x18000
	v_add_u32_e32 v162, s62, v145
	s_barrier
	ds_read_b128 v[150:153], v162
	ds_read_b128 v[154:157], v162 offset:1024
	ds_read_b128 v[158:161], v162 offset:2048
	ds_read_b128 v[162:165], v162 offset:3072
	s_add_u32 s24, s30, 0x158000
	s_addc_u32 s25, s31, 0
	s_mov_b32 m0, s40
	v_lshl_add_u64 v[198:199], s[24:25], 0, v[128:129]
	ds_read_b128 v[166:169], v148 offset:32768
	ds_read_b128 v[170:173], v148 offset:33792
	ds_read_b128 v[174:177], v148 offset:34816
	ds_read_b128 v[178:181], v148 offset:35840
	ds_read_b128 v[182:185], v148 offset:36864
	ds_read_b128 v[186:189], v148 offset:37888
	ds_read_b128 v[190:193], v148 offset:38912
	ds_read_b128 v[194:197], v148 offset:39936
	global_load_lds_dwordx4 v[198:199], off
	v_lshl_add_u64 v[198:199], s[24:25], 0, v[132:133]
	s_mov_b32 m0, s41
	s_nop 0
	global_load_lds_dwordx4 v[198:199], off
	s_waitcnt lgkmcnt(8)
	s_barrier
	s_waitcnt lgkmcnt(0)
	s_waitcnt lgkmcnt(0)
	v_mfma_f32_16x16x32_bf16 v[120:123], v[150:153], v[166:169], v[120:123]
	v_mfma_f32_16x16x32_bf16 v[120:123], v[154:157], v[170:173], v[120:123]
	v_mfma_f32_16x16x32_bf16 v[124:127], v[162:165], v[170:173], v[124:127]
	v_mfma_f32_16x16x32_bf16 v[124:127], v[158:161], v[166:169], v[124:127]
	v_mfma_f32_16x16x32_bf16 v[104:107], v[158:161], v[174:177], v[104:107]
	v_mfma_f32_16x16x32_bf16 v[104:107], v[162:165], v[178:181], v[104:107]
	v_mfma_f32_16x16x32_bf16 v[108:111], v[154:157], v[178:181], v[108:111]
	v_mfma_f32_16x16x32_bf16 v[108:111], v[150:153], v[174:177], v[108:111]
	v_mfma_f32_16x16x32_bf16 v[92:95], v[150:153], v[182:185], v[92:95]
	v_mfma_f32_16x16x32_bf16 v[92:95], v[154:157], v[186:189], v[92:95]
	v_mfma_f32_16x16x32_bf16 v[88:91], v[162:165], v[186:189], v[88:91]
	v_mfma_f32_16x16x32_bf16 v[88:91], v[158:161], v[182:185], v[88:91]
	v_mfma_f32_16x16x32_bf16 v[72:75], v[158:161], v[190:193], v[72:75]
	v_mfma_f32_16x16x32_bf16 v[72:75], v[162:165], v[194:197], v[72:75]
	v_mfma_f32_16x16x32_bf16 v[76:79], v[154:157], v[194:197], v[76:79]
	v_mfma_f32_16x16x32_bf16 v[76:79], v[150:153], v[190:193], v[76:79]
	s_barrier
	s_add_i32 s30, 16, 0x1c000
	s_add_i32 s24, s62, s37
	v_add_u32_e32 v210, s30, v145
	v_lshl_add_u64 v[218:219], v[218:219], 0, s[6:7]
	s_mov_b32 m0, s24
	ds_read_b128 v[198:201], v210
	ds_read_b128 v[202:205], v210 offset:1024
	ds_read_b128 v[206:209], v210 offset:2048
	ds_read_b128 v[210:213], v210 offset:3072
	global_load_lds_dwordx4 v[218:219], off
	v_lshl_add_u64 v[218:219], v[220:221], 0, s[6:7]
	s_add_i32 m0, s24, 0x2000
	s_nop 0
	global_load_lds_dwordx4 v[218:219], off
	s_barrier
; #define PG8_STAGE(bufoff, gbase, voff) do { _Pragma("unroll") for (int _i = 0; _i < 2; ++_i) \
;         __builtin_amdgcn_global_load_lds((const unsigned*)((const char*)(gbase) + (voff)[_i]), (LAS unsigned*)(lds + (bufoff) + ldsw + _i * 8192), 16, 0, 0); } while (0)
; #define PG8_LDA(dst, b, h) do { _Pragma("unroll") for (int m = 0; m < 4; ++m) _Pragma("unroll") for (int k = 0; k < 2; ++k) dst[m][k] = *(const LAS bf16x8*)(lds + PG8_SA(b, h) + aoff + m * 2048 + k * 1024); } while (0)
; #define PG8_MMA(ai, bj, At, Bt) do { __builtin_amdgcn_s_setprio(1); _Pragma("unroll") for (int m = 0; m < 4; ++m) _Pragma("unroll") for (int n = 0; n < 2; ++n) _Pragma("unroll") for (int k = 0; k < 2; ++k) \
;         acc[ai][bj][m][n] = __builtin_amdgcn_mfma_f32_16x16x32_bf16(Bt[n][k], At[m][k], acc[ai][bj][m][n], 0, 0, 0); __builtin_amdgcn_s_setprio(0); } while (0)
; #define PG8_WAIT_V(n) asm volatile("s_waitcnt vmcnt(" #n ")" ::: "memory")
; #define PG8_WAIT_L(n) asm volatile("s_waitcnt lgkmcnt(" #n ")" ::: "memory")
; #define PG8_BAR __builtin_amdgcn_s_barrier()
; #define PG8_SCHED __builtin_amdgcn_sched_barrier(0)
; template <class Epi>
; DEVINL void gemm_phase(LAS unsigned char* lds, const Gemm g, const Order& S, const Epi& E) {
;     ...
;             PG8_BAR; PG8_WAIT_L(0); PG8_MMA(0, 1, At, B1); PG8_BAR;
;             PG8_LDA(At, 1, 1); PG8_STAGE(PG8_SA(1, 0), a3, voffA);
;             PG8_BAR; PG8_WAIT_L(0); PG8_MMA(1, 0, At, B0); PG8_BAR; PG8_SCHED;
;             PG8_STAGE(PG8_SB(1, 1), b3 + hstepB, voffB);
;             PG8_WAIT_V(6); PG8_BAR; PG8_MMA(1, 1, At, B1); PG8_BAR;
	s_waitcnt lgkmcnt(0)
	s_waitcnt lgkmcnt(0)
	v_mfma_f32_16x16x32_bf16 v[116:119], v[198:201], v[166:169], v[116:119]
	v_mfma_f32_16x16x32_bf16 v[116:119], v[202:205], v[170:173], v[116:119]
	v_mfma_f32_16x16x32_bf16 v[112:115], v[210:213], v[170:173], v[112:115]
	v_mfma_f32_16x16x32_bf16 v[112:115], v[206:209], v[166:169], v[112:115]
	v_mfma_f32_16x16x32_bf16 v[96:99], v[206:209], v[174:177], v[96:99]
	v_mfma_f32_16x16x32_bf16 v[96:99], v[210:213], v[178:181], v[96:99]
	v_mfma_f32_16x16x32_bf16 v[100:103], v[202:205], v[178:181], v[100:103]
	v_mfma_f32_16x16x32_bf16 v[100:103], v[198:201], v[174:177], v[100:103]
	v_mfma_f32_16x16x32_bf16 v[84:87], v[198:201], v[182:185], v[84:87]
	v_mfma_f32_16x16x32_bf16 v[84:87], v[202:205], v[186:189], v[84:87]
	v_mfma_f32_16x16x32_bf16 v[80:83], v[210:213], v[186:189], v[80:83]
	v_mfma_f32_16x16x32_bf16 v[80:83], v[206:209], v[182:185], v[80:83]
	v_mfma_f32_16x16x32_bf16 v[64:67], v[206:209], v[190:193], v[64:67]
	v_mfma_f32_16x16x32_bf16 v[64:67], v[210:213], v[194:197], v[64:67]
	v_mfma_f32_16x16x32_bf16 v[68:71], v[202:205], v[194:197], v[68:71]
	v_mfma_f32_16x16x32_bf16 v[68:71], v[198:201], v[190:193], v[68:71]
	s_mov_b32 m0, s43
	v_lshl_add_u64 v[218:219], v[222:223], 0, s[6:7]
	s_barrier
	ds_read_b128 v[166:169], v148 offset:49152
	ds_read_b128 v[170:173], v148 offset:50176
	ds_read_b128 v[174:177], v148 offset:51200
	ds_read_b128 v[178:181], v148 offset:52224
	ds_read_b128 v[182:185], v148 offset:53248
	ds_read_b128 v[186:189], v148 offset:54272
	ds_read_b128 v[190:193], v148 offset:55296
	ds_read_b128 v[194:197], v148 offset:56320
	global_load_lds_dwordx4 v[218:219], off
	v_lshl_add_u64 v[218:219], v[224:225], 0, s[6:7]
	s_mov_b32 m0, s44
	s_nop 0
	global_load_lds_dwordx4 v[218:219], off
	s_barrier
	s_waitcnt lgkmcnt(0)
	s_waitcnt lgkmcnt(0)
	v_mfma_f32_16x16x32_bf16 v[60:63], v[150:153], v[166:169], v[60:63]
	v_mfma_f32_16x16x32_bf16 v[60:63], v[154:157], v[170:173], v[60:63]
	v_mfma_f32_16x16x32_bf16 v[56:59], v[162:165], v[170:173], v[56:59]
	v_mfma_f32_16x16x32_bf16 v[56:59], v[158:161], v[166:169], v[56:59]
	v_mfma_f32_16x16x32_bf16 v[40:43], v[158:161], v[174:177], v[40:43]
	v_mfma_f32_16x16x32_bf16 v[40:43], v[162:165], v[178:181], v[40:43]
	v_mfma_f32_16x16x32_bf16 v[44:47], v[154:157], v[178:181], v[44:47]
	v_mfma_f32_16x16x32_bf16 v[44:47], v[150:153], v[174:177], v[44:47]
	v_mfma_f32_16x16x32_bf16 v[28:31], v[150:153], v[182:185], v[28:31]
	v_mfma_f32_16x16x32_bf16 v[28:31], v[154:157], v[186:189], v[28:31]
	v_mfma_f32_16x16x32_bf16 v[24:27], v[162:165], v[186:189], v[24:27]
	v_mfma_f32_16x16x32_bf16 v[24:27], v[158:161], v[182:185], v[24:27]
	v_mfma_f32_16x16x32_bf16 v[8:11], v[158:161], v[190:193], v[8:11]
	v_mfma_f32_16x16x32_bf16 v[8:11], v[162:165], v[194:197], v[8:11]
	v_mfma_f32_16x16x32_bf16 v[12:15], v[154:157], v[194:197], v[12:15]
	v_mfma_f32_16x16x32_bf16 v[12:15], v[150:153], v[190:193], v[12:15]
	s_barrier
	s_add_u32 s24, s28, 0x158080
	s_addc_u32 s25, s29, 0
	s_add_i32 s28, s30, s37
	v_lshl_add_u64 v[150:151], s[24:25], 0, v[130:131]
	s_mov_b32 m0, s28
	s_nop 0
	global_load_lds_dwordx4 v[150:151], off
	v_lshl_add_u64 v[150:151], s[24:25], 0, v[134:135]
	s_add_i32 m0, s28, 0x2000
	s_nop 0
	global_load_lds_dwordx4 v[150:151], off
	s_waitcnt vmcnt(6)
	s_barrier
	v_mfma_f32_16x16x32_bf16 v[52:55], v[198:201], v[166:169], v[52:55]
	v_mfma_f32_16x16x32_bf16 v[52:55], v[202:205], v[170:173], v[52:55]
	v_mfma_f32_16x16x32_bf16 v[48:51], v[210:213], v[170:173], v[48:51]
	v_mfma_f32_16x16x32_bf16 v[48:51], v[206:209], v[166:169], v[48:51]
	v_mfma_f32_16x16x32_bf16 v[32:35], v[206:209], v[174:177], v[32:35]
	v_mfma_f32_16x16x32_bf16 v[32:35], v[210:213], v[178:181], v[32:35]
	v_mfma_f32_16x16x32_bf16 v[36:39], v[202:205], v[178:181], v[36:39]
	v_mfma_f32_16x16x32_bf16 v[36:39], v[198:201], v[174:177], v[36:39]
	v_mfma_f32_16x16x32_bf16 v[20:23], v[198:201], v[182:185], v[20:23]
	v_mfma_f32_16x16x32_bf16 v[20:23], v[202:205], v[186:189], v[20:23]
	v_mfma_f32_16x16x32_bf16 v[16:19], v[210:213], v[186:189], v[16:19]
	v_mfma_f32_16x16x32_bf16 v[16:19], v[206:209], v[182:185], v[16:19]
	v_mfma_f32_16x16x32_bf16 v[0:3], v[206:209], v[190:193], v[0:3]
	v_mfma_f32_16x16x32_bf16 v[0:3], v[210:213], v[194:197], v[0:3]
	v_mfma_f32_16x16x32_bf16 v[4:7], v[202:205], v[194:197], v[4:7]
	v_mfma_f32_16x16x32_bf16 v[4:7], v[198:201], v[190:193], v[4:7]
	s_add_u32 s59, s59, 0x100
	s_addc_u32 s60, s60, 0
	s_cmp_ge_i32 s61, s42
	s_mov_b64 s[24:25], s[26:27]
	s_mov_b32 s28, s61
	s_barrier
	s_cbranch_scc0 .LBB0_1852
	s_branch .LBB0_1839
